# barrier-adjacent setprio reorder, deferred restore barrier, EpiRes residual loads issued as one batch (counted vmcnt)
# speedup vs baseline: 1.0027x; 1.0027x over previous
; #define LAS __attribute__((address_space(3)))
; __global__ void __launch_bounds__(512, 2) fwd_kernel(Args args) {
;     extern __shared__ __attribute__((aligned(16))) unsigned char lds[];
;     LAS unsigned char* L = (LAS unsigned char*)lds;
;     volatile LAS unsigned* MISC = (volatile LAS unsigned*)(L + MISC_OFF);
;     const int tid = threadIdx.x, wave = __builtin_amdgcn_readfirstlane(tid >> 6);
;     ...
;     const int G = gridDim.x, bx = blockIdx.x;
;     const int vcu = (G % 8 == 0) ? (bx % 8) * (G / 8) + bx / 8 : bx;
;     const int gw = vcu * 8 + wave, NGW = G * 8;
;     for (int u = tid; u < 64; u += 512) ((LAS unsigned*)(L + MISC_OFF))[u] = 0u;
;     __syncthreads();
;     XcdBarrier bar = xcd_barrier_post((unsigned*)(args.ws + WS_CTL) + CW_BAR, MISC + 8);
_Z10fwd_kernel4Args:
	s_mov_b32 s100, 0
	s_mov_b32 s101, 0
	s_load_dword s31, s[0:1], 0xe0
	s_load_dwordx2 s[14:15], s[0:1], 0xd8
	s_add_u32 s4, s0, 0xe0
	v_writelane_b32 v253, s0, 0
	s_addc_u32 s5, s1, 0
	s_waitcnt lgkmcnt(0)
	s_and_b32 s3, s31, 7
	v_writelane_b32 v253, s1, 1
	v_writelane_b32 v253, s4, 2
	v_readfirstlane_b32 s10, v0
	s_cmp_lg_u32 s3, 0
	v_writelane_b32 v253, s5, 3
	v_writelane_b32 v253, s2, 4
	s_cbranch_scc1 .LBB0_1
	s_getpc_b64 s[98:99]

; __device__ __forceinline__ const char* a_tile(const Gemm& g, const Unit& u) { return (const char*)(g.A + ((long)u.z1 * g.aS1 + (long)u.z2 * g.aS2 + (long)u.pm * BM * g.lda)); }
; __device__ __forceinline__ const char* b_tile(const Gemm& g, const Unit& u) { return (const char*)(g.Bt + ((long)u.z1 * g.bS1 + (long)u.z2 * g.bS2 + (long)u.pn * BM * g.ldb)); }
; __device__ __forceinline__ int lane_id_opq() { int l; asm volatile("v_mbcnt_lo_u32_b32 %0, -1, 0\n\tv_mbcnt_hi_u32_b32 %0, -1, %0" : "=v"(l)); return l; }
; #define PG8_WAIT_V(n) asm volatile("s_waitcnt vmcnt(" #n ")" ::: "memory")
; #define PG8_BAR __builtin_amdgcn_s_barrier()
; template <class Epi>
; __device__ __forceinline__ void gemm_phase(PG8_LAS unsigned char* lds, PG8_LAS unsigned char* xl, const Gemm g, const Sched& S, const Epi& E, const int wid) {
;     ...
;         const bool has_next = S.next(ui + 1, nxt);
;         const char* nA = has_next ? a_tile(g, nxt) : cA; const char* nB = has_next ? b_tile(g, nxt) : cB;
;         for (int t = 0; t < nt; t += 2) {
;             const bool last = (t == nt - 2);
;             const bool do0 = !blkdiag_v<Epi> || t == 0, do1 = !blkdiag_v<Epi> || t != 0;
;             long j1 = 0, ja2 = 0, jb2 = 0;
;             if constexpr (Epi::MID) {
;                 if (t == g.tj) { const int lnM = lane_id_opq(); E.mid(acc, cur, wr, wc, lnM & 15, lnM >> 4); }
;                 if (t >= g.tj) j1 = g.jA;
;                 if (t + 2 >= g.tj) { ja2 = g.jA; jb2 = g.jB; } }
;             const char* a1 = cA + (size_t)(t + 1) * kstep + j1;
;             const char* a2 = last ? nA : cA + (size_t)(t + 2) * kstep + ja2; const char* b2 = last ? nB : cB + (size_t)(t + 2) * kstep + jb2;
;             const char* a3 = a2 + kstep; const char* b3 = b2 + kstep;
;             PG8_LDB(B0, 0, 0); PG8_LDB(B1, 0, 1); PG8_SCHED; PG8_LDA(At, 0, 0); PG8_STAGE(PG8_SA(1, 1), a1 + hstepA, voffA);
;             PG8_WAIT_V(8); PG8_WAIT_L(0); PG8_BAR; if (do0) { PG8_MMA(0, 0, At, B0); PG8_MMA(0, 1, At, B1); } PG8_BAR; PG8_SCHED;
;     ...
; #pragma unroll
;         for (int a = 0; a < 2; ++a)
; #pragma unroll
;             for (int b = 0; b < 2; ++b)
; #pragma unroll
;                 for (int m = 0; m < 4; ++m)
; #pragma unroll
;                     for (int n = 0; n < 2; ++n) acc[a][b][m][n] = (f32x4){0.f, 0.f, 0.f, 0.f};
;         cur = nxt; cA = nA; cB = nB; ++ui;
;         if (wr == 1) PG8_BAR;
.LBB0_219:
	s_ashr_i32 s21, s20, 31
	s_lshl_b64 s[8:9], s[20:21], 20
	s_add_u32 s30, s60, s8
	s_addc_u32 s31, s61, s9
	s_and_b64 s[8:9], s[40:41], exec
	s_cselect_b32 s8, s31, s51
	s_cselect_b32 s9, s30, s50
	s_ashr_i32 s13, s12, 31
	s_lshl_b64 s[10:11], s[12:13], 20
	s_add_u32 s48, s62, s10
	s_addc_u32 s49, s66, s11
	s_and_b64 s[10:11], s[40:41], exec
	s_cselect_b32 s10, s49, s53
	s_cselect_b32 s11, s48, s52
	s_add_u32 s13, s52, 0x100
	v_mov_b32_e32 v0, 0
	s_addc_u32 s21, s53, 0
	s_mov_b32 s43, -2
	v_mov_b32_e32 v1, v0
	v_mov_b32_e32 v2, v0
	v_mov_b32_e32 v3, v0
	v_mov_b32_e32 v4, v0
	v_mov_b32_e32 v5, v0
	v_mov_b32_e32 v6, v0
	v_mov_b32_e32 v7, v0
	v_mov_b32_e32 v8, v0
	v_mov_b32_e32 v9, v0
	v_mov_b32_e32 v10, v0
	v_mov_b32_e32 v11, v0
	v_mov_b32_e32 v16, v0
	v_mov_b32_e32 v17, v0
	v_mov_b32_e32 v18, v0
	v_mov_b32_e32 v19, v0
	v_mov_b32_e32 v24, v0
	v_mov_b32_e32 v25, v0
	v_mov_b32_e32 v26, v0
	v_mov_b32_e32 v27, v0
	v_mov_b32_e32 v32, v0
	v_mov_b32_e32 v33, v0
	v_mov_b32_e32 v34, v0
	v_mov_b32_e32 v35, v0
	v_mov_b32_e32 v40, v0
	v_mov_b32_e32 v41, v0
	v_mov_b32_e32 v42, v0
	v_mov_b32_e32 v43, v0
	v_mov_b32_e32 v48, v0
	v_mov_b32_e32 v49, v0
	v_mov_b32_e32 v50, v0
	v_mov_b32_e32 v51, v0
	v_mov_b32_e32 v12, v0
	v_mov_b32_e32 v13, v0
	v_mov_b32_e32 v14, v0
	v_mov_b32_e32 v15, v0
	v_mov_b32_e32 v20, v0
	v_mov_b32_e32 v21, v0
	v_mov_b32_e32 v22, v0
	v_mov_b32_e32 v23, v0
	v_mov_b32_e32 v28, v0
	v_mov_b32_e32 v29, v0
	v_mov_b32_e32 v30, v0
	v_mov_b32_e32 v31, v0
	v_mov_b32_e32 v36, v0
	v_mov_b32_e32 v37, v0
	v_mov_b32_e32 v38, v0
	v_mov_b32_e32 v39, v0
	v_mov_b32_e32 v44, v0
	v_mov_b32_e32 v45, v0
	v_mov_b32_e32 v46, v0
	v_mov_b32_e32 v47, v0
	v_mov_b32_e32 v52, v0
	v_mov_b32_e32 v53, v0
	v_mov_b32_e32 v54, v0
	v_mov_b32_e32 v55, v0
	v_mov_b32_e32 v56, v0
	v_mov_b32_e32 v57, v0
	v_mov_b32_e32 v58, v0
	v_mov_b32_e32 v59, v0
	v_mov_b32_e32 v60, v0
	v_mov_b32_e32 v61, v0
	v_mov_b32_e32 v62, v0
	v_mov_b32_e32 v63, v0
	v_mov_b32_e32 v64, v0
	v_mov_b32_e32 v65, v0
	v_mov_b32_e32 v66, v0
	v_mov_b32_e32 v67, v0
	v_mov_b32_e32 v68, v0
	v_mov_b32_e32 v69, v0
	v_mov_b32_e32 v70, v0
	v_mov_b32_e32 v71, v0
	v_mov_b32_e32 v72, v0
	v_mov_b32_e32 v73, v0
	v_mov_b32_e32 v74, v0
	v_mov_b32_e32 v75, v0
	v_mov_b32_e32 v80, v0
	v_mov_b32_e32 v81, v0
	v_mov_b32_e32 v82, v0
	v_mov_b32_e32 v83, v0
	v_mov_b32_e32 v88, v0
	v_mov_b32_e32 v89, v0
	v_mov_b32_e32 v90, v0
	v_mov_b32_e32 v91, v0
	v_mov_b32_e32 v96, v0
	v_mov_b32_e32 v97, v0
	v_mov_b32_e32 v98, v0
	v_mov_b32_e32 v99, v0
	v_mov_b32_e32 v104, v0
	v_mov_b32_e32 v105, v0
	v_mov_b32_e32 v106, v0
	v_mov_b32_e32 v107, v0
	v_mov_b32_e32 v112, v0
	v_mov_b32_e32 v113, v0
	v_mov_b32_e32 v114, v0
	v_mov_b32_e32 v115, v0
	v_mov_b32_e32 v76, v0
	v_mov_b32_e32 v77, v0
	v_mov_b32_e32 v78, v0
	v_mov_b32_e32 v79, v0
	v_mov_b32_e32 v84, v0
	v_mov_b32_e32 v85, v0
	v_mov_b32_e32 v86, v0
	v_mov_b32_e32 v87, v0
	v_mov_b32_e32 v92, v0
	v_mov_b32_e32 v93, v0
	v_mov_b32_e32 v94, v0
	v_mov_b32_e32 v95, v0
	v_mov_b32_e32 v100, v0
	v_mov_b32_e32 v101, v0
	v_mov_b32_e32 v102, v0
	v_mov_b32_e32 v103, v0
	v_mov_b32_e32 v108, v0
	v_mov_b32_e32 v109, v0
	v_mov_b32_e32 v110, v0
	v_mov_b32_e32 v111, v0
	v_mov_b32_e32 v116, v0
	v_mov_b32_e32 v117, v0
	v_mov_b32_e32 v118, v0
	v_mov_b32_e32 v119, v0
	v_mov_b32_e32 v120, v0
	v_mov_b32_e32 v121, v0
	v_mov_b32_e32 v122, v0
	v_mov_b32_e32 v123, v0
	v_mov_b32_e32 v124, v0
	v_mov_b32_e32 v125, v0
	v_mov_b32_e32 v126, v0
	v_mov_b32_e32 v127, v0
	s_cmp_lg_u32 s100, 1
	s_cbranch_scc1 .Ldefbar_skip_0
	s_mov_b32 s100, 0
	s_barrier
.Ldefbar_skip_0:
.LBB0_220:
	s_add_u32 s52, s50, 0x100
	s_addc_u32 s53, s51, 0
	s_add_i32 s54, 0, 0x10000
	s_cmp_eq_u32 s43, 28
	s_cselect_b32 s59, s8, s53
	s_cselect_b32 s58, s9, s52
	v_add_u32_e32 v140, s54, v142
	s_cselect_b32 s57, s10, s21
	s_cselect_b32 s56, s11, s13
	s_add_i32 s55, 0, 0x14000
	ds_read_b128 v[144:147], v140
	ds_read_b128 v[148:151], v140 offset:1024
	ds_read_b128 v[152:155], v140 offset:2048
	ds_read_b128 v[156:159], v140 offset:3072
	v_add_u32_e32 v140, s55, v142
	ds_read_b128 v[160:163], v140
	ds_read_b128 v[164:167], v140 offset:1024
	ds_read_b128 v[168:171], v140 offset:2048
	ds_read_b128 v[172:175], v140 offset:3072
	v_lshl_add_u64 v[140:141], s[50:51], 0, v[136:137]
	s_add_i32 m0, s37, 0xc000
	ds_read_b128 v[176:179], v143
	ds_read_b128 v[180:183], v143 offset:1024
	ds_read_b128 v[184:187], v143 offset:2048
	ds_read_b128 v[188:191], v143 offset:3072
	ds_read_b128 v[210:213], v143 offset:4096
	ds_read_b128 v[214:217], v143 offset:5120
	ds_read_b128 v[218:221], v143 offset:6144
	ds_read_b128 v[222:225], v143 offset:7168
	global_load_lds_dwordx4 v[140:141], off
	v_lshl_add_u64 v[140:141], s[50:51], 0, v[138:139]
	s_add_i32 m0, s37, 0xe000
	s_nop 0
	global_load_lds_dwordx4 v[140:141], off
	s_waitcnt vmcnt(8)
	s_waitcnt lgkmcnt(0)
	s_setprio 1
	s_barrier
; #define PG8_STAGE(bufoff, gbase, voff) do { _Pragma("unroll") for (int _i = 0; _i < 2; ++_i) \
;         __builtin_amdgcn_global_load_lds((const unsigned*)((const char*)(gbase) + (voff)[_i]), (PG8_LAS unsigned*)(lds + (bufoff) + ldsw + _i * 8192), 16, 0, 0); } while (0)
; #define PG8_LDA(dst, b, h) do { _Pragma("unroll") for (int m = 0; m < 4; ++m) _Pragma("unroll") for (int k = 0; k < 2; ++k) dst[m][k] = *(const PG8_LAS bf16x8*)(lds + PG8_SA(b, h) + aoff + m * 2048 + k * 1024); } while (0)
; #define PG8_LDB(dst, b, h) do { _Pragma("unroll") for (int n = 0; n < 2; ++n) _Pragma("unroll") for (int k = 0; k < 2; ++k) dst[n][k] = *(const PG8_LAS bf16x8*)(lds + PG8_SB(b, h) + boff + n * 2048 + k * 1024); } while (0)
; #define PG8_MMA(ai, bj, At, Bt) do { __builtin_amdgcn_s_setprio(1); _Pragma("unroll") for (int m = 0; m < 4; ++m) _Pragma("unroll") for (int n = 0; n < 2; ++n) _Pragma("unroll") for (int k = 0; k < 2; ++k) \
;         acc[ai][bj][m][n] = __builtin_amdgcn_mfma_f32_16x16x32_bf16(Bt[n][k], At[m][k], acc[ai][bj][m][n], 0, 0, 0); __builtin_amdgcn_s_setprio(0); } while (0)
; #define PG8_WAIT_V(n) asm volatile("s_waitcnt vmcnt(" #n ")" ::: "memory")
; #define PG8_WAIT_L(n) asm volatile("s_waitcnt lgkmcnt(" #n ")" ::: "memory")
; #define PG8_BAR __builtin_amdgcn_s_barrier()
; #define PG8_SCHED __builtin_amdgcn_sched_barrier(0)
; template <class Epi>
; __device__ __forceinline__ void gemm_phase(PG8_LAS unsigned char* lds, PG8_LAS unsigned char* xl, const Gemm g, const Sched& S, const Epi& E, const int wid) {
;     ...
;             PG8_LDB(B0, 0, 0); PG8_LDB(B1, 0, 1); PG8_SCHED; PG8_LDA(At, 0, 0); PG8_STAGE(PG8_SA(1, 1), a1 + hstepA, voffA);
;             PG8_WAIT_V(8); PG8_WAIT_L(0); PG8_BAR; if (do0) { PG8_MMA(0, 0, At, B0); PG8_MMA(0, 1, At, B1); } PG8_BAR; PG8_SCHED;
;             PG8_LDA(At, 0, 1); PG8_STAGE(PG8_SB(0, 0), b2, voffB); PG8_STAGE(PG8_SB(0, 1), b2 + hstepB, voffB); PG8_STAGE(PG8_SA(0, 0), a2, voffA);
;             PG8_WAIT_V(8); PG8_WAIT_L(0); PG8_BAR; if (do1) { PG8_MMA(1, 0, At, B0); PG8_MMA(1, 1, At, B1); } PG8_BAR; PG8_SCHED;
	v_mfma_f32_16x16x32_bf16 v[124:127], v[144:147], v[176:179], v[124:127]
	v_mfma_f32_16x16x32_bf16 v[120:123], v[152:155], v[176:179], v[120:123]
	v_mfma_f32_16x16x32_bf16 v[116:119], v[144:147], v[184:187], v[116:119]
	v_mfma_f32_16x16x32_bf16 v[108:111], v[152:155], v[184:187], v[108:111]
	v_mfma_f32_16x16x32_bf16 v[100:103], v[144:147], v[210:213], v[100:103]
	v_mfma_f32_16x16x32_bf16 v[92:95], v[152:155], v[210:213], v[92:95]
	v_mfma_f32_16x16x32_bf16 v[84:87], v[144:147], v[218:221], v[84:87]
	v_mfma_f32_16x16x32_bf16 v[76:79], v[152:155], v[218:221], v[76:79]
	v_mfma_f32_16x16x32_bf16 v[124:127], v[148:151], v[180:183], v[124:127]
	v_mfma_f32_16x16x32_bf16 v[120:123], v[156:159], v[180:183], v[120:123]
	v_mfma_f32_16x16x32_bf16 v[116:119], v[148:151], v[188:191], v[116:119]
	v_mfma_f32_16x16x32_bf16 v[108:111], v[156:159], v[188:191], v[108:111]
	v_mfma_f32_16x16x32_bf16 v[100:103], v[148:151], v[214:217], v[100:103]
	v_mfma_f32_16x16x32_bf16 v[92:95], v[156:159], v[214:217], v[92:95]
	v_mfma_f32_16x16x32_bf16 v[84:87], v[148:151], v[222:225], v[84:87]
	v_mfma_f32_16x16x32_bf16 v[76:79], v[156:159], v[222:225], v[76:79]
	s_setprio 0
	s_setprio 1
	v_mfma_f32_16x16x32_bf16 v[112:115], v[160:163], v[176:179], v[112:115]
	v_mfma_f32_16x16x32_bf16 v[104:107], v[168:171], v[176:179], v[104:107]
	v_mfma_f32_16x16x32_bf16 v[96:99], v[160:163], v[184:187], v[96:99]
	v_mfma_f32_16x16x32_bf16 v[88:91], v[168:171], v[184:187], v[88:91]
	v_mfma_f32_16x16x32_bf16 v[80:83], v[160:163], v[210:213], v[80:83]
	v_mfma_f32_16x16x32_bf16 v[72:75], v[168:171], v[210:213], v[72:75]
	v_mfma_f32_16x16x32_bf16 v[68:71], v[160:163], v[218:221], v[68:71]
	v_mfma_f32_16x16x32_bf16 v[64:67], v[168:171], v[218:221], v[64:67]
	v_mfma_f32_16x16x32_bf16 v[112:115], v[164:167], v[180:183], v[112:115]
	v_mfma_f32_16x16x32_bf16 v[104:107], v[172:175], v[180:183], v[104:107]
	v_mfma_f32_16x16x32_bf16 v[96:99], v[164:167], v[188:191], v[96:99]
	v_mfma_f32_16x16x32_bf16 v[88:91], v[172:175], v[188:191], v[88:91]
	v_mfma_f32_16x16x32_bf16 v[80:83], v[164:167], v[214:217], v[80:83]
	v_mfma_f32_16x16x32_bf16 v[72:75], v[172:175], v[214:217], v[72:75]
	v_mfma_f32_16x16x32_bf16 v[68:71], v[164:167], v[222:225], v[68:71]
	v_mfma_f32_16x16x32_bf16 v[64:67], v[172:175], v[222:225], v[64:67]
	s_barrier
	s_setprio 0
	s_add_i32 s50, s54, s29
	v_lshl_add_u64 v[140:141], s[56:57], 0, v[132:133]
	s_mov_b32 m0, s50
	ds_read_b128 v[176:179], v143 offset:16384
	ds_read_b128 v[180:183], v143 offset:17408
	ds_read_b128 v[184:187], v143 offset:18432
	ds_read_b128 v[188:191], v143 offset:19456
	ds_read_b128 v[210:213], v143 offset:20480
	ds_read_b128 v[214:217], v143 offset:21504
	ds_read_b128 v[218:221], v143 offset:22528
	ds_read_b128 v[222:225], v143 offset:23552
	global_load_lds_dwordx4 v[140:141], off
	s_add_i32 m0, s50, 0x2000
	s_add_u32 s50, s56, 0x80000
	v_lshl_add_u64 v[226:227], s[56:57], 0, v[128:129]
	s_addc_u32 s51, s57, 0
	s_add_i32 s54, s55, s29
	global_load_lds_dwordx4 v[226:227], off
	v_lshl_add_u64 v[228:229], s[50:51], 0, v[132:133]
	s_mov_b32 m0, s54
	v_lshl_add_u64 v[230:231], s[58:59], 0, v[130:131]
	global_load_lds_dwordx4 v[228:229], off
	v_lshl_add_u64 v[228:229], s[50:51], 0, v[128:129]
	s_add_i32 m0, s54, 0x2000
	s_nop 0
	global_load_lds_dwordx4 v[228:229], off
	v_lshl_add_u64 v[228:229], s[58:59], 0, v[134:135]
	s_mov_b32 m0, s37
	s_nop 0
	global_load_lds_dwordx4 v[228:229], off
	s_mov_b32 m0, s68
	s_nop 0
	global_load_lds_dwordx4 v[230:231], off
	s_waitcnt vmcnt(8)
	s_waitcnt lgkmcnt(0)
	s_setprio 1
	s_barrier
	v_mfma_f32_16x16x32_bf16 v[60:63], v[144:147], v[176:179], v[60:63]
	v_mfma_f32_16x16x32_bf16 v[56:59], v[152:155], v[176:179], v[56:59]
	v_mfma_f32_16x16x32_bf16 v[52:55], v[144:147], v[184:187], v[52:55]
	v_mfma_f32_16x16x32_bf16 v[44:47], v[152:155], v[184:187], v[44:47]
	v_mfma_f32_16x16x32_bf16 v[36:39], v[144:147], v[210:213], v[36:39]
	v_mfma_f32_16x16x32_bf16 v[28:31], v[152:155], v[210:213], v[28:31]
	v_mfma_f32_16x16x32_bf16 v[20:23], v[144:147], v[218:221], v[20:23]
	v_mfma_f32_16x16x32_bf16 v[12:15], v[152:155], v[218:221], v[12:15]
	v_mfma_f32_16x16x32_bf16 v[60:63], v[148:151], v[180:183], v[60:63]
	v_mfma_f32_16x16x32_bf16 v[56:59], v[156:159], v[180:183], v[56:59]
	v_mfma_f32_16x16x32_bf16 v[52:55], v[148:151], v[188:191], v[52:55]
	v_mfma_f32_16x16x32_bf16 v[44:47], v[156:159], v[188:191], v[44:47]
	v_mfma_f32_16x16x32_bf16 v[36:39], v[148:151], v[214:217], v[36:39]
	v_mfma_f32_16x16x32_bf16 v[28:31], v[156:159], v[214:217], v[28:31]
	v_mfma_f32_16x16x32_bf16 v[20:23], v[148:151], v[222:225], v[20:23]
	v_mfma_f32_16x16x32_bf16 v[12:15], v[156:159], v[222:225], v[12:15]
	s_setprio 0
	s_setprio 1
	v_mfma_f32_16x16x32_bf16 v[48:51], v[160:163], v[176:179], v[48:51]
	v_mfma_f32_16x16x32_bf16 v[40:43], v[168:171], v[176:179], v[40:43]
	v_mfma_f32_16x16x32_bf16 v[32:35], v[160:163], v[184:187], v[32:35]
	v_mfma_f32_16x16x32_bf16 v[24:27], v[168:171], v[184:187], v[24:27]
	v_mfma_f32_16x16x32_bf16 v[16:19], v[160:163], v[210:213], v[16:19]
	v_mfma_f32_16x16x32_bf16 v[8:11], v[168:171], v[210:213], v[8:11]
	v_mfma_f32_16x16x32_bf16 v[4:7], v[160:163], v[218:221], v[4:7]
	v_mfma_f32_16x16x32_bf16 v[0:3], v[168:171], v[218:221], v[0:3]
	v_mfma_f32_16x16x32_bf16 v[48:51], v[164:167], v[180:183], v[48:51]
	v_mfma_f32_16x16x32_bf16 v[40:43], v[172:175], v[180:183], v[40:43]
	v_mfma_f32_16x16x32_bf16 v[32:35], v[164:167], v[188:191], v[32:35]
	v_mfma_f32_16x16x32_bf16 v[24:27], v[172:175], v[188:191], v[24:27]
	v_mfma_f32_16x16x32_bf16 v[16:19], v[164:167], v[214:217], v[16:19]
	v_mfma_f32_16x16x32_bf16 v[8:11], v[172:175], v[214:217], v[8:11]
	v_mfma_f32_16x16x32_bf16 v[4:7], v[164:167], v[222:225], v[4:7]
	v_mfma_f32_16x16x32_bf16 v[0:3], v[172:175], v[222:225], v[0:3]
	s_barrier
; #define PG8_STAGE(bufoff, gbase, voff) do { _Pragma("unroll") for (int _i = 0; _i < 2; ++_i) \
;         __builtin_amdgcn_global_load_lds((const unsigned*)((const char*)(gbase) + (voff)[_i]), (PG8_LAS unsigned*)(lds + (bufoff) + ldsw + _i * 8192), 16, 0, 0); } while (0)
; #define PG8_LDA(dst, b, h) do { _Pragma("unroll") for (int m = 0; m < 4; ++m) _Pragma("unroll") for (int k = 0; k < 2; ++k) dst[m][k] = *(const PG8_LAS bf16x8*)(lds + PG8_SA(b, h) + aoff + m * 2048 + k * 1024); } while (0)
; #define PG8_LDB(dst, b, h) do { _Pragma("unroll") for (int n = 0; n < 2; ++n) _Pragma("unroll") for (int k = 0; k < 2; ++k) dst[n][k] = *(const PG8_LAS bf16x8*)(lds + PG8_SB(b, h) + boff + n * 2048 + k * 1024); } while (0)
; #define PG8_MMA(ai, bj, At, Bt) do { __builtin_amdgcn_s_setprio(1); _Pragma("unroll") for (int m = 0; m < 4; ++m) _Pragma("unroll") for (int n = 0; n < 2; ++n) _Pragma("unroll") for (int k = 0; k < 2; ++k) \
;         acc[ai][bj][m][n] = __builtin_amdgcn_mfma_f32_16x16x32_bf16(Bt[n][k], At[m][k], acc[ai][bj][m][n], 0, 0, 0); __builtin_amdgcn_s_setprio(0); } while (0)
; #define PG8_WAIT_V(n) asm volatile("s_waitcnt vmcnt(" #n ")" ::: "memory")
; #define PG8_WAIT_L(n) asm volatile("s_waitcnt lgkmcnt(" #n ")" ::: "memory")
; #define PG8_BAR __builtin_amdgcn_s_barrier()
; #define PG8_SCHED __builtin_amdgcn_sched_barrier(0)
; template <class Epi>
; __device__ __forceinline__ void gemm_phase(PG8_LAS unsigned char* lds, PG8_LAS unsigned char* xl, const Gemm g, const Sched& S, const Epi& E, const int wid) {
;     ...
;             PG8_WAIT_V(8); PG8_WAIT_L(0); PG8_BAR; if (do1) { PG8_MMA(1, 0, At, B0); PG8_MMA(1, 1, At, B1); } PG8_BAR; PG8_SCHED;
;             PG8_LDB(B0, 1, 0); PG8_LDB(B1, 1, 1); PG8_SCHED; PG8_LDA(At, 1, 0); PG8_STAGE(PG8_SA(0, 1), a2 + hstepA, voffA);
;             PG8_WAIT_V(8); PG8_WAIT_L(0); PG8_BAR; if (do0) { PG8_MMA(0, 0, At, B0); PG8_MMA(0, 1, At, B1); } PG8_BAR; PG8_SCHED;
;             PG8_LDA(At, 1, 1); PG8_STAGE(PG8_SB(1, 0), b3, voffB); PG8_STAGE(PG8_SB(1, 1), b3 + hstepB, voffB); PG8_STAGE(PG8_SA(1, 0), a3, voffA);
	s_setprio 0
	s_add_i32 s54, 0, 0x18000
	s_add_i32 s55, 0, 0x1c000
	v_add_u32_e32 v156, s54, v142
	v_add_u32_e32 v172, s55, v142
	ds_read_b128 v[144:147], v156
	ds_read_b128 v[148:151], v156 offset:1024
	ds_read_b128 v[152:155], v156 offset:2048
	ds_read_b128 v[156:159], v156 offset:3072
	ds_read_b128 v[160:163], v172
	ds_read_b128 v[164:167], v172 offset:1024
	ds_read_b128 v[168:171], v172 offset:2048
	ds_read_b128 v[172:175], v172 offset:3072
	s_add_u32 s50, s58, 0x80000
	s_addc_u32 s51, s59, 0
	s_mov_b32 m0, s69
	v_lshl_add_u64 v[232:233], s[50:51], 0, v[134:135]
	ds_read_b128 v[176:179], v143 offset:32768
	ds_read_b128 v[180:183], v143 offset:33792
	ds_read_b128 v[184:187], v143 offset:34816
	ds_read_b128 v[188:191], v143 offset:35840
	ds_read_b128 v[210:213], v143 offset:36864
	ds_read_b128 v[214:217], v143 offset:37888
	ds_read_b128 v[218:221], v143 offset:38912
	ds_read_b128 v[222:225], v143 offset:39936
	global_load_lds_dwordx4 v[232:233], off
	v_lshl_add_u64 v[232:233], s[50:51], 0, v[130:131]
	s_mov_b32 m0, s70
	s_nop 0
	global_load_lds_dwordx4 v[232:233], off
	s_waitcnt vmcnt(8)
	s_waitcnt lgkmcnt(0)
	s_setprio 1
	s_barrier
	v_mfma_f32_16x16x32_bf16 v[124:127], v[144:147], v[176:179], v[124:127]
	v_mfma_f32_16x16x32_bf16 v[120:123], v[152:155], v[176:179], v[120:123]
	v_mfma_f32_16x16x32_bf16 v[116:119], v[144:147], v[184:187], v[116:119]
	v_mfma_f32_16x16x32_bf16 v[108:111], v[152:155], v[184:187], v[108:111]
	v_mfma_f32_16x16x32_bf16 v[100:103], v[144:147], v[210:213], v[100:103]
	v_mfma_f32_16x16x32_bf16 v[92:95], v[152:155], v[210:213], v[92:95]
	v_mfma_f32_16x16x32_bf16 v[84:87], v[144:147], v[218:221], v[84:87]
	v_mfma_f32_16x16x32_bf16 v[76:79], v[152:155], v[218:221], v[76:79]
	v_mfma_f32_16x16x32_bf16 v[124:127], v[148:151], v[180:183], v[124:127]
	v_mfma_f32_16x16x32_bf16 v[120:123], v[156:159], v[180:183], v[120:123]
	v_mfma_f32_16x16x32_bf16 v[116:119], v[148:151], v[188:191], v[116:119]
	v_mfma_f32_16x16x32_bf16 v[108:111], v[156:159], v[188:191], v[108:111]
	v_mfma_f32_16x16x32_bf16 v[100:103], v[148:151], v[214:217], v[100:103]
	v_mfma_f32_16x16x32_bf16 v[92:95], v[156:159], v[214:217], v[92:95]
	v_mfma_f32_16x16x32_bf16 v[84:87], v[148:151], v[222:225], v[84:87]
	v_mfma_f32_16x16x32_bf16 v[76:79], v[156:159], v[222:225], v[76:79]
	s_setprio 0
	s_setprio 1
	v_mfma_f32_16x16x32_bf16 v[112:115], v[160:163], v[176:179], v[112:115]
	v_mfma_f32_16x16x32_bf16 v[104:107], v[168:171], v[176:179], v[104:107]
	v_mfma_f32_16x16x32_bf16 v[96:99], v[160:163], v[184:187], v[96:99]
	v_mfma_f32_16x16x32_bf16 v[88:91], v[168:171], v[184:187], v[88:91]
	v_mfma_f32_16x16x32_bf16 v[80:83], v[160:163], v[210:213], v[80:83]
	v_mfma_f32_16x16x32_bf16 v[72:75], v[168:171], v[210:213], v[72:75]
	v_mfma_f32_16x16x32_bf16 v[68:71], v[160:163], v[218:221], v[68:71]
	v_mfma_f32_16x16x32_bf16 v[64:67], v[168:171], v[218:221], v[64:67]
	v_mfma_f32_16x16x32_bf16 v[112:115], v[164:167], v[180:183], v[112:115]
	v_mfma_f32_16x16x32_bf16 v[104:107], v[172:175], v[180:183], v[104:107]
	v_mfma_f32_16x16x32_bf16 v[96:99], v[164:167], v[188:191], v[96:99]
	v_mfma_f32_16x16x32_bf16 v[88:91], v[172:175], v[188:191], v[88:91]
	v_mfma_f32_16x16x32_bf16 v[80:83], v[164:167], v[214:217], v[80:83]
	v_mfma_f32_16x16x32_bf16 v[72:75], v[172:175], v[214:217], v[72:75]
	v_mfma_f32_16x16x32_bf16 v[68:71], v[164:167], v[222:225], v[68:71]
	v_mfma_f32_16x16x32_bf16 v[64:67], v[172:175], v[222:225], v[64:67]
	s_barrier
	s_setprio 0
	s_add_i32 s50, s54, s29
	v_lshl_add_u64 v[140:141], v[140:141], 0, s[22:23]
	s_mov_b32 m0, s50
	ds_read_b128 v[176:179], v143 offset:49152
	ds_read_b128 v[180:183], v143 offset:50176
	ds_read_b128 v[184:187], v143 offset:51200
	ds_read_b128 v[188:191], v143 offset:52224
	ds_read_b128 v[210:213], v143 offset:53248
	ds_read_b128 v[214:217], v143 offset:54272
	ds_read_b128 v[218:221], v143 offset:55296
	ds_read_b128 v[222:225], v143 offset:56320
	global_load_lds_dwordx4 v[140:141], off
	s_add_i32 m0, s50, 0x2000
	s_add_u32 s50, s56, 0x80080
	v_lshl_add_u64 v[140:141], v[226:227], 0, s[22:23]
	s_addc_u32 s51, s57, 0
	s_add_i32 s54, s55, s29
	global_load_lds_dwordx4 v[140:141], off
	v_lshl_add_u64 v[140:141], s[50:51], 0, v[132:133]
	s_mov_b32 m0, s54
	s_nop 0
	global_load_lds_dwordx4 v[140:141], off
	v_lshl_add_u64 v[140:141], s[50:51], 0, v[128:129]
	s_add_i32 m0, s54, 0x2000
	s_nop 0
	global_load_lds_dwordx4 v[140:141], off
	v_lshl_add_u64 v[140:141], v[228:229], 0, s[22:23]
	s_mov_b32 m0, s77
	s_nop 0
	global_load_lds_dwordx4 v[140:141], off
	v_lshl_add_u64 v[140:141], v[230:231], 0, s[22:23]
	s_mov_b32 m0, s87
	s_nop 0
	global_load_lds_dwordx4 v[140:141], off
	s_waitcnt vmcnt(8)
	s_waitcnt lgkmcnt(0)
	s_setprio 1
	s_barrier
; #define ACT4(v, F) do { const f32x2 _lo = F((f32x2){v[0], v[1]}), _hi = F((f32x2){v[2], v[3]}); v = (f32x4){_lo.x, _lo.y, _hi.x, _hi.y}; } while (0)
; __device__ __forceinline__ int lane_id_opq() { int l; asm volatile("v_mbcnt_lo_u32_b32 %0, -1, 0\n\tv_mbcnt_hi_u32_b32 %0, -1, %0" : "=v"(l)); return l; }
; #define PG8_BAR __builtin_amdgcn_s_barrier()
;     __device__ __forceinline__ void operator()(EPI_ARGS) const {
;     ...
; #pragma unroll
;         for (int ai = 0; ai < 2; ++ai)
; #pragma unroll
;             for (int m = 0; m < 4; ++m) { char* rb = ub + (size_t)(ai * HALF + m) * ldc * 2;
;                 float s1 = 0.f, s2 = 0.f;
; #pragma unroll
;                 for (int bj = 0; bj < 2; ++bj) { f32x4 v0 = acc[ai][bj][m][0] * rs[ai][m], v1 = acc[ai][bj][m][1] * rs[ai][m];
;                     if (act == 1) { ACT4(v0, gelu_t2); ACT4(v1, gelu_t2); }
;                     else if (act == 2) { ACT4(v0, sigm2); ACT4(v1, sigm2); }
;                     u32x4 w; PACK8(w, v0, v1);
;                     *(u32x4*)(rb + lo + bj * 256) = w;
; template <class Epi>
; __device__ __forceinline__ void gemm_phase(PG8_LAS unsigned char* lds, PG8_LAS unsigned char* xl, const Gemm g, const Sched& S, const Epi& E, const int wid) {
;     ...
;             PG8_WAIT_V(8); PG8_WAIT_L(0); PG8_BAR; if (do1) { PG8_MMA(1, 0, At, B0); PG8_MMA(1, 1, At, B1); } PG8_BAR; PG8_SCHED;
;         }
;         if (wr == 0) PG8_BAR;
;         { const int lnE = lane_id_opq(); const int frE = lnE & 15, fqE = lnE >> 4;
;           float prn[8];
; #pragma unroll
;           for (int k = 0; k < 8; ++k) prn[k] = 1.0f;
;           if constexpr (Epi::PRE) { if (has_next) { const float* pb = E.pre_base(nxt) + wr * 64 + 4 * frE;
; #pragma unroll
;               for (int k = 0; k < 8; ++k) prn[k] = pb[(k >> 2) * HALF + (k & 3)]; } }
;           E(acc, cur, wr, wc, frE, fqE, xl, prc);
;           if constexpr (Epi::PRE) {
; #pragma unroll
;               for (int k = 0; k < 8; ++k) prc[k] = prn[k]; } }
;         if (!has_next) break;
; #pragma unroll
;         for (int a = 0; a < 2; ++a)
; #pragma unroll
;             for (int b = 0; b < 2; ++b)
; #pragma unroll
;                 for (int m = 0; m < 4; ++m)
; #pragma unroll
;                     for (int n = 0; n < 2; ++n) acc[a][b][m][n] = (f32x4){0.f, 0.f, 0.f, 0.f};
;         cur = nxt; cA = nA; cB = nB; ++ui;
;         if (wr == 1) PG8_BAR;
	v_mfma_f32_16x16x32_bf16 v[60:63], v[144:147], v[176:179], v[60:63]
	v_mfma_f32_16x16x32_bf16 v[56:59], v[152:155], v[176:179], v[56:59]
	v_mfma_f32_16x16x32_bf16 v[52:55], v[144:147], v[184:187], v[52:55]
	v_mfma_f32_16x16x32_bf16 v[44:47], v[152:155], v[184:187], v[44:47]
	v_mfma_f32_16x16x32_bf16 v[36:39], v[144:147], v[210:213], v[36:39]
	v_mfma_f32_16x16x32_bf16 v[28:31], v[152:155], v[210:213], v[28:31]
	v_mfma_f32_16x16x32_bf16 v[20:23], v[144:147], v[218:221], v[20:23]
	v_mfma_f32_16x16x32_bf16 v[12:15], v[152:155], v[218:221], v[12:15]
	v_mfma_f32_16x16x32_bf16 v[60:63], v[148:151], v[180:183], v[60:63]
	v_mfma_f32_16x16x32_bf16 v[56:59], v[156:159], v[180:183], v[56:59]
	v_mfma_f32_16x16x32_bf16 v[52:55], v[148:151], v[188:191], v[52:55]
	v_mfma_f32_16x16x32_bf16 v[44:47], v[156:159], v[188:191], v[44:47]
	v_mfma_f32_16x16x32_bf16 v[36:39], v[148:151], v[214:217], v[36:39]
	v_mfma_f32_16x16x32_bf16 v[28:31], v[156:159], v[214:217], v[28:31]
	v_mfma_f32_16x16x32_bf16 v[20:23], v[148:151], v[222:225], v[20:23]
	v_mfma_f32_16x16x32_bf16 v[12:15], v[156:159], v[222:225], v[12:15]
	s_setprio 0
	s_setprio 1
	v_mfma_f32_16x16x32_bf16 v[48:51], v[160:163], v[176:179], v[48:51]
	v_mfma_f32_16x16x32_bf16 v[40:43], v[168:171], v[176:179], v[40:43]
	v_mfma_f32_16x16x32_bf16 v[32:35], v[160:163], v[184:187], v[32:35]
	v_mfma_f32_16x16x32_bf16 v[24:27], v[168:171], v[184:187], v[24:27]
	v_mfma_f32_16x16x32_bf16 v[16:19], v[160:163], v[210:213], v[16:19]
	v_mfma_f32_16x16x32_bf16 v[8:11], v[168:171], v[210:213], v[8:11]
	v_mfma_f32_16x16x32_bf16 v[4:7], v[160:163], v[218:221], v[4:7]
	v_mfma_f32_16x16x32_bf16 v[0:3], v[168:171], v[218:221], v[0:3]
	v_mfma_f32_16x16x32_bf16 v[48:51], v[164:167], v[180:183], v[48:51]
	v_mfma_f32_16x16x32_bf16 v[40:43], v[172:175], v[180:183], v[40:43]
	v_mfma_f32_16x16x32_bf16 v[32:35], v[164:167], v[188:191], v[32:35]
	v_mfma_f32_16x16x32_bf16 v[24:27], v[172:175], v[188:191], v[24:27]
	v_mfma_f32_16x16x32_bf16 v[16:19], v[164:167], v[214:217], v[16:19]
	v_mfma_f32_16x16x32_bf16 v[8:11], v[172:175], v[214:217], v[8:11]
	v_mfma_f32_16x16x32_bf16 v[4:7], v[164:167], v[222:225], v[4:7]
	v_mfma_f32_16x16x32_bf16 v[0:3], v[172:175], v[222:225], v[0:3]
	s_barrier
	s_setprio 0
	s_add_i32 s43, s43, 2
	s_add_u32 s13, s13, 0x100
	s_addc_u32 s21, s21, 0
	s_cmp_gt_u32 s43, 29
	s_mov_b64 s[50:51], s[52:53]
	s_cbranch_scc0 .LBB0_220
	s_and_b64 vcc, exec, s[14:15]
	s_cbranch_vccz .LBB0_223
	s_barrier
.LBB0_223:
	s_ashr_i32 s43, s42, 31
	s_lshl_b64 s[8:9], s[42:43], 21
	s_add_u32 s10, s71, s8
	s_addc_u32 s11, s76, s9
	s_lshl_b32 s8, s36, 8
	v_mbcnt_lo_u32_b32 v140, -1, 0
	v_mbcnt_hi_u32_b32 v140, -1, v140
	s_ashr_i32 s9, s8, 31
	v_lshlrev_b32_e32 v141, 2, v140
	v_and_or_b32 v141, v141, 60, s3
	s_lshl_b64 s[8:9], s[8:9], 1
	v_and_b32_e32 v140, -16, v140
	v_lshlrev_b32_e32 v141, 13, v141
	s_add_u32 s8, s10, s8
	v_add3_u32 v192, v140, s75, v141
	s_addc_u32 s9, s11, s9
	v_lshl_add_u64 v[140:141], s[8:9], 0, v[192:193]
	v_cvt_pk_bf16_f32 v124, v124, v125
	v_cvt_pk_bf16_f32 v125, v126, v127
	v_cvt_pk_bf16_f32 v126, v120, v121
	v_cvt_pk_bf16_f32 v127, v122, v123
	global_store_dwordx4 v192, v[124:127], s[8:9]
	v_cvt_pk_bf16_f32 v112, v112, v113
	v_cvt_pk_bf16_f32 v113, v114, v115
	v_cvt_pk_bf16_f32 v114, v104, v105
	v_cvt_pk_bf16_f32 v115, v106, v107
	global_store_dwordx4 v192, v[112:115], s[8:9] offset:256
	v_cvt_pk_bf16_f32 v104, v116, v117
	v_cvt_pk_bf16_f32 v105, v118, v119
	v_cvt_pk_bf16_f32 v106, v108, v109
	v_add_co_u32_e32 v108, vcc, s78, v140
	v_cvt_pk_bf16_f32 v107, v110, v111
	s_mov_b32 s8, 0x100000
	s_nop 0
	v_addc_co_u32_e32 v109, vcc, 0, v141, vcc
	global_store_dwordx4 v[108:109], v[104:107], off
	v_cvt_pk_bf16_f32 v96, v96, v97
	v_cvt_pk_bf16_f32 v97, v98, v99
	v_cvt_pk_bf16_f32 v98, v88, v89
	v_cvt_pk_bf16_f32 v99, v90, v91
	global_store_dwordx4 v[108:109], v[96:99], off offset:256
	v_cvt_pk_bf16_f32 v88, v100, v101
	v_cvt_pk_bf16_f32 v89, v102, v103
	v_cvt_pk_bf16_f32 v90, v92, v93
	v_add_co_u32_e32 v92, vcc, s4, v140
	v_cvt_pk_bf16_f32 v91, v94, v95
	s_nop 1
	v_addc_co_u32_e32 v93, vcc, 0, v141, vcc
	global_store_dwordx4 v[92:93], v[88:91], off
	v_cvt_pk_bf16_f32 v80, v80, v81
	v_cvt_pk_bf16_f32 v81, v82, v83
	v_cvt_pk_bf16_f32 v82, v72, v73
	v_cvt_pk_bf16_f32 v83, v74, v75
	global_store_dwordx4 v[92:93], v[80:83], off offset:256
	v_cvt_pk_bf16_f32 v72, v84, v85
	v_cvt_pk_bf16_f32 v73, v86, v87
	v_cvt_pk_bf16_f32 v74, v76, v77
	v_add_co_u32_e32 v76, vcc, s5, v140
	v_cvt_pk_bf16_f32 v75, v78, v79
	s_nop 1
	v_addc_co_u32_e32 v77, vcc, 0, v141, vcc
	global_store_dwordx4 v[76:77], v[72:75], off
	v_cvt_pk_bf16_f32 v68, v68, v69
	v_cvt_pk_bf16_f32 v69, v70, v71
	v_cvt_pk_bf16_f32 v70, v64, v65
	v_cvt_pk_bf16_f32 v71, v66, v67
	global_store_dwordx4 v[76:77], v[68:71], off offset:256
	v_cvt_pk_bf16_f32 v60, v60, v61
	v_cvt_pk_bf16_f32 v61, v62, v63
	v_cvt_pk_bf16_f32 v62, v56, v57
	v_add_co_u32_e32 v56, vcc, s8, v140
	s_mov_b32 s8, 0x102000
	s_nop 0
	v_addc_co_u32_e32 v57, vcc, 0, v141, vcc
	v_cvt_pk_bf16_f32 v63, v58, v59
	global_store_dwordx4 v[56:57], v[60:63], off
	v_cvt_pk_bf16_f32 v48, v48, v49
	v_cvt_pk_bf16_f32 v49, v50, v51
	v_cvt_pk_bf16_f32 v50, v40, v41
	v_cvt_pk_bf16_f32 v51, v42, v43
	global_store_dwordx4 v[56:57], v[48:51], off offset:256
	v_cvt_pk_bf16_f32 v40, v52, v53
	v_cvt_pk_bf16_f32 v41, v54, v55
	v_cvt_pk_bf16_f32 v42, v44, v45
	v_add_co_u32_e32 v44, vcc, s8, v140
	s_mov_b32 s8, 0x104000
	s_nop 0
	v_addc_co_u32_e32 v45, vcc, 0, v141, vcc
	v_cvt_pk_bf16_f32 v43, v46, v47
	global_store_dwordx4 v[44:45], v[40:43], off
	v_cvt_pk_bf16_f32 v32, v32, v33
	v_cvt_pk_bf16_f32 v33, v34, v35
	v_cvt_pk_bf16_f32 v34, v24, v25
	v_cvt_pk_bf16_f32 v35, v26, v27
	global_store_dwordx4 v[44:45], v[32:35], off offset:256
	v_cvt_pk_bf16_f32 v24, v36, v37
	v_cvt_pk_bf16_f32 v25, v38, v39
	v_cvt_pk_bf16_f32 v26, v28, v29
	v_add_co_u32_e32 v28, vcc, s8, v140
	s_mov_b32 s8, 0x106000
	s_nop 0
	v_addc_co_u32_e32 v29, vcc, 0, v141, vcc
	v_cvt_pk_bf16_f32 v27, v30, v31
	global_store_dwordx4 v[28:29], v[24:27], off
	v_cvt_pk_bf16_f32 v16, v16, v17
	v_cvt_pk_bf16_f32 v17, v18, v19
	v_cvt_pk_bf16_f32 v18, v8, v9
	v_cvt_pk_bf16_f32 v19, v10, v11
	global_store_dwordx4 v[28:29], v[16:19], off offset:256
	v_cvt_pk_bf16_f32 v8, v20, v21
	v_cvt_pk_bf16_f32 v9, v22, v23
	v_cvt_pk_bf16_f32 v10, v12, v13
	v_add_co_u32_e32 v12, vcc, s8, v140
	s_mov_b64 s[8:9], -1
	s_nop 0
	v_addc_co_u32_e32 v13, vcc, 0, v141, vcc
	s_andn2_b64 vcc, exec, s[40:41]
	v_cvt_pk_bf16_f32 v11, v14, v15
	global_store_dwordx4 v[12:13], v[8:11], off
	v_cvt_pk_bf16_f32 v4, v4, v5
	v_cvt_pk_bf16_f32 v5, v6, v7
	v_cvt_pk_bf16_f32 v6, v0, v1
	v_cvt_pk_bf16_f32 v7, v2, v3
	global_store_dwordx4 v[12:13], v[4:7], off offset:256
	s_cbranch_vccnz .LBB0_216
	s_and_b64 vcc, exec, s[38:39]
	s_cbranch_vccnz .LBB0_215
	s_mov_b32 s100, 1
	s_branch .LBB0_215

; __device__ __forceinline__ const char* a_tile(const Gemm& g, const Unit& u) { return (const char*)(g.A + ((long)u.z1 * g.aS1 + (long)u.z2 * g.aS2 + (long)u.pm * BM * g.lda)); }
; __device__ __forceinline__ const char* b_tile(const Gemm& g, const Unit& u) { return (const char*)(g.Bt + ((long)u.z1 * g.bS1 + (long)u.z2 * g.bS2 + (long)u.pn * BM * g.ldb)); }
; __device__ __forceinline__ int lane_id_opq() { int l; asm volatile("v_mbcnt_lo_u32_b32 %0, -1, 0\n\tv_mbcnt_hi_u32_b32 %0, -1, %0" : "=v"(l)); return l; }
; #define PG8_WAIT_V(n) asm volatile("s_waitcnt vmcnt(" #n ")" ::: "memory")
; #define PG8_BAR __builtin_amdgcn_s_barrier()
; template <class Epi>
; __device__ __forceinline__ void gemm_phase(PG8_LAS unsigned char* lds, PG8_LAS unsigned char* xl, const Gemm g, const Sched& S, const Epi& E, const int wid) {
;     ...
;         const bool has_next = S.next(ui + 1, nxt);
;         const char* nA = has_next ? a_tile(g, nxt) : cA; const char* nB = has_next ? b_tile(g, nxt) : cB;
;         for (int t = 0; t < nt; t += 2) {
;             const bool last = (t == nt - 2);
;             const bool do0 = !blkdiag_v<Epi> || t == 0, do1 = !blkdiag_v<Epi> || t != 0;
;             long j1 = 0, ja2 = 0, jb2 = 0;
;             if constexpr (Epi::MID) {
;                 if (t == g.tj) { const int lnM = lane_id_opq(); E.mid(acc, cur, wr, wc, lnM & 15, lnM >> 4); }
;                 if (t >= g.tj) j1 = g.jA;
;                 if (t + 2 >= g.tj) { ja2 = g.jA; jb2 = g.jB; } }
;             const char* a1 = cA + (size_t)(t + 1) * kstep + j1;
;             const char* a2 = last ? nA : cA + (size_t)(t + 2) * kstep + ja2; const char* b2 = last ? nB : cB + (size_t)(t + 2) * kstep + jb2;
;             const char* a3 = a2 + kstep; const char* b3 = b2 + kstep;
;             PG8_LDB(B0, 0, 0); PG8_LDB(B1, 0, 1); PG8_SCHED; PG8_LDA(At, 0, 0); PG8_STAGE(PG8_SA(1, 1), a1 + hstepA, voffA);
;             PG8_WAIT_V(8); PG8_WAIT_L(0); PG8_BAR; if (do0) { PG8_MMA(0, 0, At, B0); PG8_MMA(0, 1, At, B1); } PG8_BAR; PG8_SCHED;
;     ...
; #pragma unroll
;         for (int a = 0; a < 2; ++a)
; #pragma unroll
;             for (int b = 0; b < 2; ++b)
; #pragma unroll
;                 for (int m = 0; m < 4; ++m)
; #pragma unroll
;                     for (int n = 0; n < 2; ++n) acc[a][b][m][n] = (f32x4){0.f, 0.f, 0.f, 0.f};
;         cur = nxt; cA = nA; cB = nB; ++ui;
;         if (wr == 1) PG8_BAR;
.LBB0_237:
	s_ashr_i32 s59, s58, 31
	s_lshl_b64 s[8:9], s[58:59], 20
	s_add_u32 s36, s61, s8
	s_addc_u32 s37, s76, s9
	s_and_b64 s[8:9], s[40:41], exec
	s_cselect_b32 s8, s37, s21
	s_cselect_b32 s9, s36, s20
	s_ashr_i32 s57, s56, 31
	s_lshl_b64 s[10:11], s[56:57], 20
	s_add_u32 s52, s1, s10
	s_addc_u32 s53, s60, s11
	s_and_b64 s[10:11], s[40:41], exec
	s_cselect_b32 s10, s53, s31
	s_cselect_b32 s11, s52, s30
	s_add_u32 s13, s30, 0x100
	v_mov_b32_e32 v0, 0
	s_addc_u32 s57, s31, 0
	s_mov_b32 s62, -2
	v_mov_b32_e32 v1, v0
	s_waitcnt lgkmcnt(0)
	v_mov_b32_e32 v2, v0
	v_mov_b32_e32 v3, v0
	v_mov_b32_e32 v4, v0
	v_mov_b32_e32 v5, v0
	v_mov_b32_e32 v6, v0
	v_mov_b32_e32 v7, v0
	v_mov_b32_e32 v26, v0
	v_mov_b32_e32 v27, v0
	v_mov_b32_e32 v28, v0
	v_mov_b32_e32 v29, v0
	v_mov_b32_e32 v30, v0
	v_mov_b32_e32 v31, v0
	v_mov_b32_e32 v32, v0
	v_mov_b32_e32 v33, v0
	v_mov_b32_e32 v42, v0
	v_mov_b32_e32 v43, v0
	v_mov_b32_e32 v44, v0
	v_mov_b32_e32 v45, v0
	v_mov_b32_e32 v46, v0
	v_mov_b32_e32 v47, v0
	v_mov_b32_e32 v48, v0
	v_mov_b32_e32 v49, v0
	v_mov_b32_e32 v58, v0
	v_mov_b32_e32 v59, v0
	v_mov_b32_e32 v60, v0
	v_mov_b32_e32 v61, v0
	v_mov_b32_e32 v62, v0
	v_mov_b32_e32 v63, v0
	v_mov_b32_e32 v64, v0
	v_mov_b32_e32 v65, v0
	v_mov_b32_e32 v8, v0
	v_mov_b32_e32 v9, v0
	v_mov_b32_e32 v10, v0
	v_mov_b32_e32 v11, v0
	v_mov_b32_e32 v12, v0
	v_mov_b32_e32 v13, v0
	v_mov_b32_e32 v14, v0
	v_mov_b32_e32 v15, v0
	v_mov_b32_e32 v34, v0
	v_mov_b32_e32 v35, v0
	v_mov_b32_e32 v36, v0
	v_mov_b32_e32 v37, v0
	v_mov_b32_e32 v38, v0
	v_mov_b32_e32 v39, v0
	v_mov_b32_e32 v40, v0
	v_mov_b32_e32 v41, v0
	v_mov_b32_e32 v50, v0
	v_mov_b32_e32 v51, v0
	v_mov_b32_e32 v52, v0
	v_mov_b32_e32 v53, v0
	v_mov_b32_e32 v54, v0
	v_mov_b32_e32 v55, v0
	v_mov_b32_e32 v56, v0
	v_mov_b32_e32 v57, v0
	v_mov_b32_e32 v66, v0
	v_mov_b32_e32 v67, v0
	v_mov_b32_e32 v68, v0
	v_mov_b32_e32 v69, v0
	v_mov_b32_e32 v70, v0
	v_mov_b32_e32 v71, v0
	v_mov_b32_e32 v72, v0
	v_mov_b32_e32 v73, v0
	v_mov_b32_e32 v74, v0
	v_mov_b32_e32 v75, v0
	v_mov_b32_e32 v76, v0
	v_mov_b32_e32 v77, v0
	v_mov_b32_e32 v78, v0
	v_mov_b32_e32 v79, v0
	v_mov_b32_e32 v80, v0
	v_mov_b32_e32 v81, v0
	v_mov_b32_e32 v92, v0
	v_mov_b32_e32 v93, v0
	v_mov_b32_e32 v94, v0
	v_mov_b32_e32 v95, v0
	v_mov_b32_e32 v96, v0
	v_mov_b32_e32 v97, v0
	v_mov_b32_e32 v98, v0
	v_mov_b32_e32 v99, v0
	v_mov_b32_e32 v108, v0
	v_mov_b32_e32 v109, v0
	v_mov_b32_e32 v110, v0
	v_mov_b32_e32 v111, v0
	v_mov_b32_e32 v112, v0
	v_mov_b32_e32 v113, v0
	v_mov_b32_e32 v114, v0
	v_mov_b32_e32 v115, v0
	v_mov_b32_e32 v124, v0
	v_mov_b32_e32 v125, v0
	v_mov_b32_e32 v126, v0
	v_mov_b32_e32 v127, v0
	v_mov_b32_e32 v128, v0
	v_mov_b32_e32 v129, v0
	v_mov_b32_e32 v130, v0
	v_mov_b32_e32 v131, v0
	v_mov_b32_e32 v82, v0
	v_mov_b32_e32 v83, v0
	v_mov_b32_e32 v84, v0
	v_mov_b32_e32 v85, v0
	v_mov_b32_e32 v86, v0
	v_mov_b32_e32 v87, v0
	v_mov_b32_e32 v88, v0
	v_mov_b32_e32 v89, v0
	v_mov_b32_e32 v100, v0
	v_mov_b32_e32 v101, v0
	v_mov_b32_e32 v102, v0
	v_mov_b32_e32 v103, v0
	v_mov_b32_e32 v104, v0
	v_mov_b32_e32 v105, v0
	v_mov_b32_e32 v106, v0
	v_mov_b32_e32 v107, v0
	v_mov_b32_e32 v116, v0
	v_mov_b32_e32 v117, v0
	v_mov_b32_e32 v118, v0
	v_mov_b32_e32 v119, v0
	v_mov_b32_e32 v120, v0
	v_mov_b32_e32 v121, v0
	v_mov_b32_e32 v122, v0
	v_mov_b32_e32 v123, v0
	v_mov_b32_e32 v132, v0
	v_mov_b32_e32 v133, v0
	v_mov_b32_e32 v134, v0
	v_mov_b32_e32 v135, v0
	v_mov_b32_e32 v136, v0
	v_mov_b32_e32 v137, v0
	v_mov_b32_e32 v138, v0
	v_mov_b32_e32 v139, v0
	s_cmp_lg_u32 s100, 1
	s_cbranch_scc1 .Ldefbar_skip_1
	s_mov_b32 s100, 0
	s_barrier
.Ldefbar_skip_1:
.LBB0_238:
	s_add_u32 s30, s20, 0x100
	s_addc_u32 s31, s21, 0
	s_add_i32 s54, 0, 0x10000
	s_cmp_eq_u32 s62, 28
	s_cselect_b32 s47, s8, s31
	s_cselect_b32 s46, s9, s30
	v_add_u32_e32 v156, s54, v158
	s_cselect_b32 s45, s10, s57
	s_cselect_b32 s44, s11, s13
	s_add_i32 s55, 0, 0x14000
	ds_read_b128 v[18:21], v156
	ds_read_b128 v[22:25], v156 offset:1024
	ds_read_b128 v[160:163], v156 offset:2048
	ds_read_b128 v[164:167], v156 offset:3072
	v_add_u32_e32 v156, s55, v158
	ds_read_b128 v[168:171], v156
	ds_read_b128 v[172:175], v156 offset:1024
	ds_read_b128 v[176:179], v156 offset:2048
	ds_read_b128 v[180:183], v156 offset:3072
	v_lshl_add_u64 v[156:157], s[20:21], 0, v[148:149]
	s_add_i32 m0, s77, 0xc000
	ds_read_b128 v[184:187], v159
	ds_read_b128 v[188:191], v159 offset:1024
	ds_read_b128 v[210:213], v159 offset:2048
	ds_read_b128 v[214:217], v159 offset:3072
	ds_read_b128 v[218:221], v159 offset:4096
	ds_read_b128 v[222:225], v159 offset:5120
	ds_read_b128 v[226:229], v159 offset:6144
	ds_read_b128 v[230:233], v159 offset:7168
	global_load_lds_dwordx4 v[156:157], off
	v_lshl_add_u64 v[156:157], s[20:21], 0, v[150:151]
	s_add_i32 m0, s77, 0xe000
	s_nop 0
	global_load_lds_dwordx4 v[156:157], off
	s_waitcnt vmcnt(8)
	s_waitcnt lgkmcnt(0)
	s_setprio 1
	s_barrier
; #define PG8_STAGE(bufoff, gbase, voff) do { _Pragma("unroll") for (int _i = 0; _i < 2; ++_i) \
;         __builtin_amdgcn_global_load_lds((const unsigned*)((const char*)(gbase) + (voff)[_i]), (PG8_LAS unsigned*)(lds + (bufoff) + ldsw + _i * 8192), 16, 0, 0); } while (0)
; #define PG8_LDA(dst, b, h) do { _Pragma("unroll") for (int m = 0; m < 4; ++m) _Pragma("unroll") for (int k = 0; k < 2; ++k) dst[m][k] = *(const PG8_LAS bf16x8*)(lds + PG8_SA(b, h) + aoff + m * 2048 + k * 1024); } while (0)
; #define PG8_LDB(dst, b, h) do { _Pragma("unroll") for (int n = 0; n < 2; ++n) _Pragma("unroll") for (int k = 0; k < 2; ++k) dst[n][k] = *(const PG8_LAS bf16x8*)(lds + PG8_SB(b, h) + boff + n * 2048 + k * 1024); } while (0)
; #define PG8_MMA(ai, bj, At, Bt) do { __builtin_amdgcn_s_setprio(1); _Pragma("unroll") for (int m = 0; m < 4; ++m) _Pragma("unroll") for (int n = 0; n < 2; ++n) _Pragma("unroll") for (int k = 0; k < 2; ++k) \
;         acc[ai][bj][m][n] = __builtin_amdgcn_mfma_f32_16x16x32_bf16(Bt[n][k], At[m][k], acc[ai][bj][m][n], 0, 0, 0); __builtin_amdgcn_s_setprio(0); } while (0)
; #define PG8_WAIT_V(n) asm volatile("s_waitcnt vmcnt(" #n ")" ::: "memory")
; #define PG8_WAIT_L(n) asm volatile("s_waitcnt lgkmcnt(" #n ")" ::: "memory")
; #define PG8_BAR __builtin_amdgcn_s_barrier()
; #define PG8_SCHED __builtin_amdgcn_sched_barrier(0)
; template <class Epi>
; __device__ __forceinline__ void gemm_phase(PG8_LAS unsigned char* lds, PG8_LAS unsigned char* xl, const Gemm g, const Sched& S, const Epi& E, const int wid) {
;     ...
;             PG8_WAIT_V(8); PG8_WAIT_L(0); PG8_BAR; if (do0) { PG8_MMA(0, 0, At, B0); PG8_MMA(0, 1, At, B1); } PG8_BAR; PG8_SCHED;
;             PG8_LDA(At, 0, 1); PG8_STAGE(PG8_SB(0, 0), b2, voffB); PG8_STAGE(PG8_SB(0, 1), b2 + hstepB, voffB); PG8_STAGE(PG8_SA(0, 0), a2, voffA);
;             PG8_WAIT_V(8); PG8_WAIT_L(0); PG8_BAR; if (do1) { PG8_MMA(1, 0, At, B0); PG8_MMA(1, 1, At, B1); } PG8_BAR; PG8_SCHED;
;             PG8_LDB(B0, 1, 0); PG8_LDB(B1, 1, 1); PG8_SCHED; PG8_LDA(At, 1, 0); PG8_STAGE(PG8_SA(0, 1), a2 + hstepA, voffA);
	v_mfma_f32_16x16x32_bf16 v[136:139], v[18:21], v[184:187], v[136:139]
	v_mfma_f32_16x16x32_bf16 v[132:135], v[160:163], v[184:187], v[132:135]
	v_mfma_f32_16x16x32_bf16 v[120:123], v[18:21], v[210:213], v[120:123]
	v_mfma_f32_16x16x32_bf16 v[116:119], v[160:163], v[210:213], v[116:119]
	v_mfma_f32_16x16x32_bf16 v[104:107], v[18:21], v[218:221], v[104:107]
	v_mfma_f32_16x16x32_bf16 v[100:103], v[160:163], v[218:221], v[100:103]
	v_mfma_f32_16x16x32_bf16 v[86:89], v[18:21], v[226:229], v[86:89]
	v_mfma_f32_16x16x32_bf16 v[82:85], v[160:163], v[226:229], v[82:85]
	v_mfma_f32_16x16x32_bf16 v[136:139], v[22:25], v[188:191], v[136:139]
	v_mfma_f32_16x16x32_bf16 v[132:135], v[164:167], v[188:191], v[132:135]
	v_mfma_f32_16x16x32_bf16 v[120:123], v[22:25], v[214:217], v[120:123]
	v_mfma_f32_16x16x32_bf16 v[116:119], v[164:167], v[214:217], v[116:119]
	v_mfma_f32_16x16x32_bf16 v[104:107], v[22:25], v[222:225], v[104:107]
	v_mfma_f32_16x16x32_bf16 v[100:103], v[164:167], v[222:225], v[100:103]
	v_mfma_f32_16x16x32_bf16 v[86:89], v[22:25], v[230:233], v[86:89]
	v_mfma_f32_16x16x32_bf16 v[82:85], v[164:167], v[230:233], v[82:85]
	s_setprio 0
	s_setprio 1
	v_mfma_f32_16x16x32_bf16 v[128:131], v[168:171], v[184:187], v[128:131]
	v_mfma_f32_16x16x32_bf16 v[124:127], v[176:179], v[184:187], v[124:127]
	v_mfma_f32_16x16x32_bf16 v[112:115], v[168:171], v[210:213], v[112:115]
	v_mfma_f32_16x16x32_bf16 v[108:111], v[176:179], v[210:213], v[108:111]
	v_mfma_f32_16x16x32_bf16 v[96:99], v[168:171], v[218:221], v[96:99]
	v_mfma_f32_16x16x32_bf16 v[92:95], v[176:179], v[218:221], v[92:95]
	v_mfma_f32_16x16x32_bf16 v[78:81], v[168:171], v[226:229], v[78:81]
	v_mfma_f32_16x16x32_bf16 v[74:77], v[176:179], v[226:229], v[74:77]
	v_mfma_f32_16x16x32_bf16 v[128:131], v[172:175], v[188:191], v[128:131]
	v_mfma_f32_16x16x32_bf16 v[124:127], v[180:183], v[188:191], v[124:127]
	v_mfma_f32_16x16x32_bf16 v[112:115], v[172:175], v[214:217], v[112:115]
	v_mfma_f32_16x16x32_bf16 v[108:111], v[180:183], v[214:217], v[108:111]
	v_mfma_f32_16x16x32_bf16 v[96:99], v[172:175], v[222:225], v[96:99]
	v_mfma_f32_16x16x32_bf16 v[92:95], v[180:183], v[222:225], v[92:95]
	v_mfma_f32_16x16x32_bf16 v[78:81], v[172:175], v[230:233], v[78:81]
	v_mfma_f32_16x16x32_bf16 v[74:77], v[180:183], v[230:233], v[74:77]
	s_barrier
	s_setprio 0
	s_add_i32 s20, s54, s29
	v_lshl_add_u64 v[156:157], s[44:45], 0, v[142:143]
	s_mov_b32 m0, s20
	ds_read_b128 v[184:187], v159 offset:16384
	ds_read_b128 v[188:191], v159 offset:17408
	ds_read_b128 v[210:213], v159 offset:18432
	ds_read_b128 v[214:217], v159 offset:19456
	ds_read_b128 v[218:221], v159 offset:20480
	ds_read_b128 v[222:225], v159 offset:21504
	ds_read_b128 v[226:229], v159 offset:22528
	ds_read_b128 v[230:233], v159 offset:23552
	global_load_lds_dwordx4 v[156:157], off
	s_add_i32 m0, s20, 0x2000
	s_add_u32 s20, s44, 0x80000
	v_lshl_add_u64 v[234:235], s[44:45], 0, v[146:147]
	s_addc_u32 s21, s45, 0
	s_add_i32 s54, s55, s29
	global_load_lds_dwordx4 v[234:235], off
	v_lshl_add_u64 v[236:237], s[20:21], 0, v[142:143]
	s_mov_b32 m0, s54
	v_lshl_add_u64 v[238:239], s[46:47], 0, v[144:145]
	global_load_lds_dwordx4 v[236:237], off
	v_lshl_add_u64 v[236:237], s[20:21], 0, v[146:147]
	s_add_i32 m0, s54, 0x2000
	s_nop 0
	global_load_lds_dwordx4 v[236:237], off
	v_lshl_add_u64 v[236:237], s[46:47], 0, v[140:141]
	s_mov_b32 m0, s77
	s_nop 0
	global_load_lds_dwordx4 v[236:237], off
	s_mov_b32 m0, s49
	s_nop 0
	global_load_lds_dwordx4 v[238:239], off
	s_waitcnt vmcnt(8)
	s_waitcnt lgkmcnt(0)
	s_setprio 1
	s_barrier
	v_mfma_f32_16x16x32_bf16 v[70:73], v[18:21], v[184:187], v[70:73]
	v_mfma_f32_16x16x32_bf16 v[66:69], v[160:163], v[184:187], v[66:69]
	v_mfma_f32_16x16x32_bf16 v[54:57], v[18:21], v[210:213], v[54:57]
	v_mfma_f32_16x16x32_bf16 v[50:53], v[160:163], v[210:213], v[50:53]
	v_mfma_f32_16x16x32_bf16 v[38:41], v[18:21], v[218:221], v[38:41]
	v_mfma_f32_16x16x32_bf16 v[34:37], v[160:163], v[218:221], v[34:37]
	v_mfma_f32_16x16x32_bf16 v[12:15], v[18:21], v[226:229], v[12:15]
	v_mfma_f32_16x16x32_bf16 v[8:11], v[160:163], v[226:229], v[8:11]
	v_mfma_f32_16x16x32_bf16 v[70:73], v[22:25], v[188:191], v[70:73]
	v_mfma_f32_16x16x32_bf16 v[66:69], v[164:167], v[188:191], v[66:69]
	v_mfma_f32_16x16x32_bf16 v[54:57], v[22:25], v[214:217], v[54:57]
	v_mfma_f32_16x16x32_bf16 v[50:53], v[164:167], v[214:217], v[50:53]
	v_mfma_f32_16x16x32_bf16 v[38:41], v[22:25], v[222:225], v[38:41]
	v_mfma_f32_16x16x32_bf16 v[34:37], v[164:167], v[222:225], v[34:37]
	v_mfma_f32_16x16x32_bf16 v[12:15], v[22:25], v[230:233], v[12:15]
	v_mfma_f32_16x16x32_bf16 v[8:11], v[164:167], v[230:233], v[8:11]
	s_setprio 0
	s_setprio 1
	v_mfma_f32_16x16x32_bf16 v[46:49], v[168:171], v[210:213], v[46:49]
	v_mfma_f32_16x16x32_bf16 v[42:45], v[176:179], v[210:213], v[42:45]
	v_mfma_f32_16x16x32_bf16 v[30:33], v[168:171], v[218:221], v[30:33]
	v_mfma_f32_16x16x32_bf16 v[26:29], v[176:179], v[218:221], v[26:29]
	v_mfma_f32_16x16x32_bf16 v[4:7], v[168:171], v[226:229], v[4:7]
	v_mfma_f32_16x16x32_bf16 v[0:3], v[176:179], v[226:229], v[0:3]
	v_mfma_f32_16x16x32_bf16 v[18:21], v[168:171], v[184:187], v[62:65]
	v_mfma_f32_16x16x32_bf16 v[22:25], v[176:179], v[184:187], v[58:61]
	v_mfma_f32_16x16x32_bf16 v[46:49], v[172:175], v[214:217], v[46:49]
	v_mfma_f32_16x16x32_bf16 v[42:45], v[180:183], v[214:217], v[42:45]
	v_mfma_f32_16x16x32_bf16 v[30:33], v[172:175], v[222:225], v[30:33]
	v_mfma_f32_16x16x32_bf16 v[26:29], v[180:183], v[222:225], v[26:29]
	v_mfma_f32_16x16x32_bf16 v[4:7], v[172:175], v[230:233], v[4:7]
	v_mfma_f32_16x16x32_bf16 v[0:3], v[180:183], v[230:233], v[0:3]
	v_mfma_f32_16x16x32_bf16 v[18:21], v[172:175], v[188:191], v[18:21]
	v_mfma_f32_16x16x32_bf16 v[22:25], v[180:183], v[188:191], v[22:25]
	s_barrier
; #define PG8_STAGE(bufoff, gbase, voff) do { _Pragma("unroll") for (int _i = 0; _i < 2; ++_i) \
;         __builtin_amdgcn_global_load_lds((const unsigned*)((const char*)(gbase) + (voff)[_i]), (PG8_LAS unsigned*)(lds + (bufoff) + ldsw + _i * 8192), 16, 0, 0); } while (0)
; #define PG8_LDA(dst, b, h) do { _Pragma("unroll") for (int m = 0; m < 4; ++m) _Pragma("unroll") for (int k = 0; k < 2; ++k) dst[m][k] = *(const PG8_LAS bf16x8*)(lds + PG8_SA(b, h) + aoff + m * 2048 + k * 1024); } while (0)
; #define PG8_LDB(dst, b, h) do { _Pragma("unroll") for (int n = 0; n < 2; ++n) _Pragma("unroll") for (int k = 0; k < 2; ++k) dst[n][k] = *(const PG8_LAS bf16x8*)(lds + PG8_SB(b, h) + boff + n * 2048 + k * 1024); } while (0)
; #define PG8_MMA(ai, bj, At, Bt) do { __builtin_amdgcn_s_setprio(1); _Pragma("unroll") for (int m = 0; m < 4; ++m) _Pragma("unroll") for (int n = 0; n < 2; ++n) _Pragma("unroll") for (int k = 0; k < 2; ++k) \
;         acc[ai][bj][m][n] = __builtin_amdgcn_mfma_f32_16x16x32_bf16(Bt[n][k], At[m][k], acc[ai][bj][m][n], 0, 0, 0); __builtin_amdgcn_s_setprio(0); } while (0)
; #define PG8_WAIT_V(n) asm volatile("s_waitcnt vmcnt(" #n ")" ::: "memory")
; #define PG8_WAIT_L(n) asm volatile("s_waitcnt lgkmcnt(" #n ")" ::: "memory")
; #define PG8_BAR __builtin_amdgcn_s_barrier()
; #define PG8_SCHED __builtin_amdgcn_sched_barrier(0)
; template <class Epi>
; __device__ __forceinline__ void gemm_phase(PG8_LAS unsigned char* lds, PG8_LAS unsigned char* xl, const Gemm g, const Sched& S, const Epi& E, const int wid) {
;     ...
;             PG8_LDB(B0, 1, 0); PG8_LDB(B1, 1, 1); PG8_SCHED; PG8_LDA(At, 1, 0); PG8_STAGE(PG8_SA(0, 1), a2 + hstepA, voffA);
;             PG8_WAIT_V(8); PG8_WAIT_L(0); PG8_BAR; if (do0) { PG8_MMA(0, 0, At, B0); PG8_MMA(0, 1, At, B1); } PG8_BAR; PG8_SCHED;
;             PG8_LDA(At, 1, 1); PG8_STAGE(PG8_SB(1, 0), b3, voffB); PG8_STAGE(PG8_SB(1, 1), b3 + hstepB, voffB); PG8_STAGE(PG8_SA(1, 0), a3, voffA);
	s_setprio 0
	s_add_i32 s54, 0, 0x18000
	s_add_i32 s55, 0, 0x1c000
	v_add_u32_e32 v164, s54, v158
	v_add_u32_e32 v180, s55, v158
	ds_read_b128 v[58:61], v164
	ds_read_b128 v[62:65], v164 offset:1024
	ds_read_b128 v[160:163], v164 offset:2048
	ds_read_b128 v[164:167], v164 offset:3072
	ds_read_b128 v[168:171], v180
	ds_read_b128 v[172:175], v180 offset:1024
	ds_read_b128 v[176:179], v180 offset:2048
	ds_read_b128 v[180:183], v180 offset:3072
	s_add_u32 s20, s46, 0x80000
	s_addc_u32 s21, s47, 0
	s_mov_b32 m0, s87
	v_lshl_add_u64 v[240:241], s[20:21], 0, v[140:141]
	ds_read_b128 v[184:187], v159 offset:32768
	ds_read_b128 v[188:191], v159 offset:33792
	ds_read_b128 v[210:213], v159 offset:34816
	ds_read_b128 v[214:217], v159 offset:35840
	ds_read_b128 v[218:221], v159 offset:36864
	ds_read_b128 v[222:225], v159 offset:37888
	ds_read_b128 v[226:229], v159 offset:38912
	ds_read_b128 v[230:233], v159 offset:39936
	global_load_lds_dwordx4 v[240:241], off
	v_lshl_add_u64 v[240:241], s[20:21], 0, v[144:145]
	s_mov_b32 m0, s88
	s_nop 0
	global_load_lds_dwordx4 v[240:241], off
	s_waitcnt vmcnt(8)
	s_waitcnt lgkmcnt(0)
	s_setprio 1
	s_barrier
	v_mfma_f32_16x16x32_bf16 v[136:139], v[58:61], v[184:187], v[136:139]
	v_mfma_f32_16x16x32_bf16 v[132:135], v[160:163], v[184:187], v[132:135]
	v_mfma_f32_16x16x32_bf16 v[120:123], v[58:61], v[210:213], v[120:123]
	v_mfma_f32_16x16x32_bf16 v[116:119], v[160:163], v[210:213], v[116:119]
	v_mfma_f32_16x16x32_bf16 v[104:107], v[58:61], v[218:221], v[104:107]
	v_mfma_f32_16x16x32_bf16 v[100:103], v[160:163], v[218:221], v[100:103]
	v_mfma_f32_16x16x32_bf16 v[86:89], v[58:61], v[226:229], v[86:89]
	v_mfma_f32_16x16x32_bf16 v[82:85], v[160:163], v[226:229], v[82:85]
	v_mfma_f32_16x16x32_bf16 v[136:139], v[62:65], v[188:191], v[136:139]
	v_mfma_f32_16x16x32_bf16 v[132:135], v[164:167], v[188:191], v[132:135]
	v_mfma_f32_16x16x32_bf16 v[120:123], v[62:65], v[214:217], v[120:123]
	v_mfma_f32_16x16x32_bf16 v[116:119], v[164:167], v[214:217], v[116:119]
	v_mfma_f32_16x16x32_bf16 v[104:107], v[62:65], v[222:225], v[104:107]
	v_mfma_f32_16x16x32_bf16 v[100:103], v[164:167], v[222:225], v[100:103]
	v_mfma_f32_16x16x32_bf16 v[86:89], v[62:65], v[230:233], v[86:89]
	v_mfma_f32_16x16x32_bf16 v[82:85], v[164:167], v[230:233], v[82:85]
	s_setprio 0
	s_setprio 1
	v_mfma_f32_16x16x32_bf16 v[128:131], v[168:171], v[184:187], v[128:131]
	v_mfma_f32_16x16x32_bf16 v[124:127], v[176:179], v[184:187], v[124:127]
	v_mfma_f32_16x16x32_bf16 v[112:115], v[168:171], v[210:213], v[112:115]
	v_mfma_f32_16x16x32_bf16 v[108:111], v[176:179], v[210:213], v[108:111]
	v_mfma_f32_16x16x32_bf16 v[96:99], v[168:171], v[218:221], v[96:99]
	v_mfma_f32_16x16x32_bf16 v[92:95], v[176:179], v[218:221], v[92:95]
	v_mfma_f32_16x16x32_bf16 v[78:81], v[168:171], v[226:229], v[78:81]
	v_mfma_f32_16x16x32_bf16 v[74:77], v[176:179], v[226:229], v[74:77]
	v_mfma_f32_16x16x32_bf16 v[128:131], v[172:175], v[188:191], v[128:131]
	v_mfma_f32_16x16x32_bf16 v[124:127], v[180:183], v[188:191], v[124:127]
	v_mfma_f32_16x16x32_bf16 v[112:115], v[172:175], v[214:217], v[112:115]
	v_mfma_f32_16x16x32_bf16 v[108:111], v[180:183], v[214:217], v[108:111]
	v_mfma_f32_16x16x32_bf16 v[96:99], v[172:175], v[222:225], v[96:99]
	v_mfma_f32_16x16x32_bf16 v[92:95], v[180:183], v[222:225], v[92:95]
	v_mfma_f32_16x16x32_bf16 v[78:81], v[172:175], v[230:233], v[78:81]
	v_mfma_f32_16x16x32_bf16 v[74:77], v[180:183], v[230:233], v[74:77]
	s_barrier
; #define PG8_STAGE(bufoff, gbase, voff) do { _Pragma("unroll") for (int _i = 0; _i < 2; ++_i) \
;         __builtin_amdgcn_global_load_lds((const unsigned*)((const char*)(gbase) + (voff)[_i]), (PG8_LAS unsigned*)(lds + (bufoff) + ldsw + _i * 8192), 16, 0, 0); } while (0)
; #define PG8_LDA(dst, b, h) do { _Pragma("unroll") for (int m = 0; m < 4; ++m) _Pragma("unroll") for (int k = 0; k < 2; ++k) dst[m][k] = *(const PG8_LAS bf16x8*)(lds + PG8_SA(b, h) + aoff + m * 2048 + k * 1024); } while (0)
; #define PG8_MMA(ai, bj, At, Bt) do { __builtin_amdgcn_s_setprio(1); _Pragma("unroll") for (int m = 0; m < 4; ++m) _Pragma("unroll") for (int n = 0; n < 2; ++n) _Pragma("unroll") for (int k = 0; k < 2; ++k) \
;         acc[ai][bj][m][n] = __builtin_amdgcn_mfma_f32_16x16x32_bf16(Bt[n][k], At[m][k], acc[ai][bj][m][n], 0, 0, 0); __builtin_amdgcn_s_setprio(0); } while (0)
; #define PG8_WAIT_V(n) asm volatile("s_waitcnt vmcnt(" #n ")" ::: "memory")
; #define PG8_WAIT_L(n) asm volatile("s_waitcnt lgkmcnt(" #n ")" ::: "memory")
; #define PG8_BAR __builtin_amdgcn_s_barrier()
; #define PG8_SCHED __builtin_amdgcn_sched_barrier(0)
; template <class Epi>
; __device__ __forceinline__ void gemm_phase(PG8_LAS unsigned char* lds, PG8_LAS unsigned char* xl, const Gemm g, const Sched& S, const Epi& E, const int wid) {
;     ...
;             PG8_LDA(At, 1, 1); PG8_STAGE(PG8_SB(1, 0), b3, voffB); PG8_STAGE(PG8_SB(1, 1), b3 + hstepB, voffB); PG8_STAGE(PG8_SA(1, 0), a3, voffA);
;             PG8_WAIT_V(8); PG8_WAIT_L(0); PG8_BAR; if (do1) { PG8_MMA(1, 0, At, B0); PG8_MMA(1, 1, At, B1); } PG8_BAR; PG8_SCHED;
;         }
;         if (wr == 0) PG8_BAR;
	s_setprio 0
	s_add_i32 s20, s54, s29
	v_lshl_add_u64 v[156:157], v[156:157], 0, s[22:23]
	s_mov_b32 m0, s20
	ds_read_b128 v[184:187], v159 offset:49152
	ds_read_b128 v[188:191], v159 offset:50176
	ds_read_b128 v[210:213], v159 offset:51200
	ds_read_b128 v[214:217], v159 offset:52224
	ds_read_b128 v[218:221], v159 offset:53248
	ds_read_b128 v[222:225], v159 offset:54272
	ds_read_b128 v[226:229], v159 offset:55296
	ds_read_b128 v[230:233], v159 offset:56320
	global_load_lds_dwordx4 v[156:157], off
	s_add_i32 m0, s20, 0x2000
	s_add_u32 s20, s44, 0x80080
	v_lshl_add_u64 v[156:157], v[234:235], 0, s[22:23]
	s_addc_u32 s21, s45, 0
	s_add_i32 s44, s55, s29
	global_load_lds_dwordx4 v[156:157], off
	v_lshl_add_u64 v[156:157], s[20:21], 0, v[142:143]
	s_mov_b32 m0, s44
	s_nop 0
	global_load_lds_dwordx4 v[156:157], off
	v_lshl_add_u64 v[156:157], s[20:21], 0, v[146:147]
	s_add_i32 m0, s44, 0x2000
	s_nop 0
	global_load_lds_dwordx4 v[156:157], off
	v_lshl_add_u64 v[156:157], v[236:237], 0, s[22:23]
	s_mov_b32 m0, s91
	s_nop 0
	global_load_lds_dwordx4 v[156:157], off
	v_lshl_add_u64 v[156:157], v[238:239], 0, s[22:23]
	s_mov_b32 m0, s92
	s_nop 0
	global_load_lds_dwordx4 v[156:157], off
	s_waitcnt vmcnt(8)
	s_waitcnt lgkmcnt(0)
	s_setprio 1
	s_barrier
	v_mfma_f32_16x16x32_bf16 v[70:73], v[58:61], v[184:187], v[70:73]
	v_mfma_f32_16x16x32_bf16 v[66:69], v[160:163], v[184:187], v[66:69]
	v_mfma_f32_16x16x32_bf16 v[54:57], v[58:61], v[210:213], v[54:57]
	v_mfma_f32_16x16x32_bf16 v[50:53], v[160:163], v[210:213], v[50:53]
	v_mfma_f32_16x16x32_bf16 v[38:41], v[58:61], v[218:221], v[38:41]
	v_mfma_f32_16x16x32_bf16 v[34:37], v[160:163], v[218:221], v[34:37]
	v_mfma_f32_16x16x32_bf16 v[12:15], v[58:61], v[226:229], v[12:15]
	v_mfma_f32_16x16x32_bf16 v[8:11], v[160:163], v[226:229], v[8:11]
	v_mfma_f32_16x16x32_bf16 v[70:73], v[62:65], v[188:191], v[70:73]
	v_mfma_f32_16x16x32_bf16 v[66:69], v[164:167], v[188:191], v[66:69]
	v_mfma_f32_16x16x32_bf16 v[54:57], v[62:65], v[214:217], v[54:57]
	v_mfma_f32_16x16x32_bf16 v[50:53], v[164:167], v[214:217], v[50:53]
	v_mfma_f32_16x16x32_bf16 v[38:41], v[62:65], v[222:225], v[38:41]
	v_mfma_f32_16x16x32_bf16 v[34:37], v[164:167], v[222:225], v[34:37]
	v_mfma_f32_16x16x32_bf16 v[12:15], v[62:65], v[230:233], v[12:15]
	v_mfma_f32_16x16x32_bf16 v[8:11], v[164:167], v[230:233], v[8:11]
	s_setprio 0
	s_setprio 1
	v_mfma_f32_16x16x32_bf16 v[18:21], v[168:171], v[184:187], v[18:21]
	v_mfma_f32_16x16x32_bf16 v[62:65], v[172:175], v[188:191], v[18:21]
	v_mfma_f32_16x16x32_bf16 v[18:21], v[176:179], v[184:187], v[22:25]
	v_mfma_f32_16x16x32_bf16 v[58:61], v[180:183], v[188:191], v[18:21]
	v_mfma_f32_16x16x32_bf16 v[18:21], v[168:171], v[210:213], v[46:49]
	v_mfma_f32_16x16x32_bf16 v[46:49], v[172:175], v[214:217], v[18:21]
	v_mfma_f32_16x16x32_bf16 v[18:21], v[176:179], v[210:213], v[42:45]
	v_mfma_f32_16x16x32_bf16 v[42:45], v[180:183], v[214:217], v[18:21]
	v_mfma_f32_16x16x32_bf16 v[18:21], v[168:171], v[218:221], v[30:33]
	v_mfma_f32_16x16x32_bf16 v[30:33], v[172:175], v[222:225], v[18:21]
	v_mfma_f32_16x16x32_bf16 v[18:21], v[176:179], v[218:221], v[26:29]
	v_mfma_f32_16x16x32_bf16 v[4:7], v[168:171], v[226:229], v[4:7]
	v_mfma_f32_16x16x32_bf16 v[0:3], v[176:179], v[226:229], v[0:3]
	v_mfma_f32_16x16x32_bf16 v[26:29], v[180:183], v[222:225], v[18:21]
	v_mfma_f32_16x16x32_bf16 v[4:7], v[172:175], v[230:233], v[4:7]
	v_mfma_f32_16x16x32_bf16 v[0:3], v[180:183], v[230:233], v[0:3]
	s_barrier
	s_setprio 0
	s_add_i32 s62, s62, 2
	s_add_u32 s13, s13, 0x100
	s_addc_u32 s57, s57, 0
	s_cmp_gt_u32 s62, 29
	s_mov_b64 s[20:21], s[30:31]
	s_cbranch_scc0 .LBB0_238
	s_and_b64 vcc, exec, s[14:15]
	s_cbranch_vccz .LBB0_241
	s_barrier

; #define PG8_BAR __builtin_amdgcn_s_barrier()
; template <class Epi>
; __device__ __forceinline__ void gemm_phase(PG8_LAS unsigned char* lds, PG8_LAS unsigned char* xl, const Gemm g, const Sched& S, const Epi& E, const int wid) {
;     ...
;         if (!has_next) break;
; #pragma unroll
;         for (int a = 0; a < 2; ++a)
; #pragma unroll
;             for (int b = 0; b < 2; ++b)
; #pragma unroll
;                 for (int m = 0; m < 4; ++m)
; #pragma unroll
;                     for (int n = 0; n < 2; ++n) acc[a][b][m][n] = (f32x4){0.f, 0.f, 0.f, 0.f};
;         cur = nxt; cA = nA; cB = nB; ++ui;
;         if (wr == 1) PG8_BAR;
.LBB0_331:
	s_andn2_b64 vcc, exec, s[40:41]
	s_mov_b64 s[8:9], -1
	s_cbranch_vccnz .LBB0_234
	s_and_b64 vcc, exec, s[38:39]
	s_cbranch_vccnz .LBB0_233
	s_mov_b32 s100, 1
	s_branch .LBB0_233

; __device__ __forceinline__ const char* a_tile(const Gemm& g, const Unit& u) { return (const char*)(g.A + ((long)u.z1 * g.aS1 + (long)u.z2 * g.aS2 + (long)u.pm * BM * g.lda)); }
; __device__ __forceinline__ const char* b_tile(const Gemm& g, const Unit& u) { return (const char*)(g.Bt + ((long)u.z1 * g.bS1 + (long)u.z2 * g.bS2 + (long)u.pn * BM * g.ldb)); }
; __device__ __forceinline__ int lane_id_opq() { int l; asm volatile("v_mbcnt_lo_u32_b32 %0, -1, 0\n\tv_mbcnt_hi_u32_b32 %0, -1, %0" : "=v"(l)); return l; }
; #define PG8_WAIT_V(n) asm volatile("s_waitcnt vmcnt(" #n ")" ::: "memory")
; #define PG8_BAR __builtin_amdgcn_s_barrier()
; template <class Epi>
; __device__ __forceinline__ void gemm_phase(PG8_LAS unsigned char* lds, PG8_LAS unsigned char* xl, const Gemm g, const Sched& S, const Epi& E, const int wid) {
;     ...
;         const bool has_next = S.next(ui + 1, nxt);
;         const char* nA = has_next ? a_tile(g, nxt) : cA; const char* nB = has_next ? b_tile(g, nxt) : cB;
;         for (int t = 0; t < nt; t += 2) {
;             const bool last = (t == nt - 2);
;             const bool do0 = !blkdiag_v<Epi> || t == 0, do1 = !blkdiag_v<Epi> || t != 0;
;             long j1 = 0, ja2 = 0, jb2 = 0;
;             if constexpr (Epi::MID) {
;                 if (t == g.tj) { const int lnM = lane_id_opq(); E.mid(acc, cur, wr, wc, lnM & 15, lnM >> 4); }
;                 if (t >= g.tj) j1 = g.jA;
;                 if (t + 2 >= g.tj) { ja2 = g.jA; jb2 = g.jB; } }
;             const char* a1 = cA + (size_t)(t + 1) * kstep + j1;
;             const char* a2 = last ? nA : cA + (size_t)(t + 2) * kstep + ja2; const char* b2 = last ? nB : cB + (size_t)(t + 2) * kstep + jb2;
;             const char* a3 = a2 + kstep; const char* b3 = b2 + kstep;
;             PG8_LDB(B0, 0, 0); PG8_LDB(B1, 0, 1); PG8_SCHED; PG8_LDA(At, 0, 0); PG8_STAGE(PG8_SA(1, 1), a1 + hstepA, voffA);
;             PG8_WAIT_V(8); PG8_WAIT_L(0); PG8_BAR; if (do0) { PG8_MMA(0, 0, At, B0); PG8_MMA(0, 1, At, B1); } PG8_BAR; PG8_SCHED;
;     ...
; #pragma unroll
;         for (int a = 0; a < 2; ++a)
; #pragma unroll
;             for (int b = 0; b < 2; ++b)
; #pragma unroll
;                 for (int m = 0; m < 4; ++m)
; #pragma unroll
;                     for (int n = 0; n < 2; ++n) acc[a][b][m][n] = (f32x4){0.f, 0.f, 0.f, 0.f};
;         cur = nxt; cA = nA; cB = nB; ++ui;
;         if (wr == 1) PG8_BAR;
.LBB0_407:
	s_add_u32 s8, s76, 0x100
	v_mov_b32_e32 v0, 0
	s_addc_u32 s9, s77, 0
	s_mov_b32 s10, -2
	v_mov_b32_e32 v1, v0
	v_mov_b32_e32 v2, v0
	v_mov_b32_e32 v3, v0
	v_mov_b32_e32 v4, v0
	v_mov_b32_e32 v5, v0
	v_mov_b32_e32 v6, v0
	v_mov_b32_e32 v7, v0
	v_mov_b32_e32 v8, v0
	v_mov_b32_e32 v9, v0
	v_mov_b32_e32 v10, v0
	v_mov_b32_e32 v11, v0
	v_mov_b32_e32 v16, v0
	v_mov_b32_e32 v17, v0
	v_mov_b32_e32 v18, v0
	v_mov_b32_e32 v19, v0
	v_mov_b32_e32 v24, v0
	v_mov_b32_e32 v25, v0
	v_mov_b32_e32 v26, v0
	v_mov_b32_e32 v27, v0
	v_mov_b32_e32 v32, v0
	v_mov_b32_e32 v33, v0
	v_mov_b32_e32 v34, v0
	v_mov_b32_e32 v35, v0
	v_mov_b32_e32 v40, v0
	v_mov_b32_e32 v41, v0
	v_mov_b32_e32 v42, v0
	v_mov_b32_e32 v43, v0
	v_mov_b32_e32 v48, v0
	v_mov_b32_e32 v49, v0
	v_mov_b32_e32 v50, v0
	v_mov_b32_e32 v51, v0
	v_mov_b32_e32 v12, v0
	v_mov_b32_e32 v13, v0
	v_mov_b32_e32 v14, v0
	v_mov_b32_e32 v15, v0
	v_mov_b32_e32 v20, v0
	v_mov_b32_e32 v21, v0
	v_mov_b32_e32 v22, v0
	v_mov_b32_e32 v23, v0
	v_mov_b32_e32 v28, v0
	v_mov_b32_e32 v29, v0
	v_mov_b32_e32 v30, v0
	v_mov_b32_e32 v31, v0
	v_mov_b32_e32 v36, v0
	v_mov_b32_e32 v37, v0
	v_mov_b32_e32 v38, v0
	v_mov_b32_e32 v39, v0
	v_mov_b32_e32 v44, v0
	v_mov_b32_e32 v45, v0
	v_mov_b32_e32 v46, v0
	v_mov_b32_e32 v47, v0
	v_mov_b32_e32 v52, v0
	v_mov_b32_e32 v53, v0
	v_mov_b32_e32 v54, v0
	v_mov_b32_e32 v55, v0
	v_mov_b32_e32 v56, v0
	v_mov_b32_e32 v57, v0
	v_mov_b32_e32 v58, v0
	v_mov_b32_e32 v59, v0
	v_mov_b32_e32 v60, v0
	v_mov_b32_e32 v61, v0
	v_mov_b32_e32 v62, v0
	v_mov_b32_e32 v63, v0
	v_mov_b32_e32 v64, v0
	v_mov_b32_e32 v65, v0
	v_mov_b32_e32 v66, v0
	v_mov_b32_e32 v67, v0
	v_mov_b32_e32 v68, v0
	v_mov_b32_e32 v69, v0
	v_mov_b32_e32 v70, v0
	v_mov_b32_e32 v71, v0
	v_mov_b32_e32 v72, v0
	v_mov_b32_e32 v73, v0
	v_mov_b32_e32 v74, v0
	v_mov_b32_e32 v75, v0
	v_mov_b32_e32 v80, v0
	v_mov_b32_e32 v81, v0
	v_mov_b32_e32 v82, v0
	v_mov_b32_e32 v83, v0
	v_mov_b32_e32 v88, v0
	v_mov_b32_e32 v89, v0
	v_mov_b32_e32 v90, v0
	v_mov_b32_e32 v91, v0
	v_mov_b32_e32 v96, v0
	v_mov_b32_e32 v97, v0
	v_mov_b32_e32 v98, v0
	v_mov_b32_e32 v99, v0
	v_mov_b32_e32 v104, v0
	v_mov_b32_e32 v105, v0
	v_mov_b32_e32 v106, v0
	v_mov_b32_e32 v107, v0
	v_mov_b32_e32 v112, v0
	v_mov_b32_e32 v113, v0
	v_mov_b32_e32 v114, v0
	v_mov_b32_e32 v115, v0
	v_mov_b32_e32 v76, v0
	v_mov_b32_e32 v77, v0
	v_mov_b32_e32 v78, v0
	v_mov_b32_e32 v79, v0
	v_mov_b32_e32 v84, v0
	v_mov_b32_e32 v85, v0
	v_mov_b32_e32 v86, v0
	v_mov_b32_e32 v87, v0
	v_mov_b32_e32 v92, v0
	v_mov_b32_e32 v93, v0
	v_mov_b32_e32 v94, v0
	v_mov_b32_e32 v95, v0
	v_mov_b32_e32 v100, v0
	v_mov_b32_e32 v101, v0
	v_mov_b32_e32 v102, v0
	v_mov_b32_e32 v103, v0
	v_mov_b32_e32 v108, v0
	v_mov_b32_e32 v109, v0
	v_mov_b32_e32 v110, v0
	v_mov_b32_e32 v111, v0
	v_mov_b32_e32 v116, v0
	v_mov_b32_e32 v117, v0
	v_mov_b32_e32 v118, v0
	v_mov_b32_e32 v119, v0
	v_mov_b32_e32 v120, v0
	v_mov_b32_e32 v121, v0
	v_mov_b32_e32 v122, v0
	v_mov_b32_e32 v123, v0
	v_mov_b32_e32 v124, v0
	v_mov_b32_e32 v125, v0
	v_mov_b32_e32 v126, v0
	v_mov_b32_e32 v127, v0
	s_cmp_lg_u32 s100, 1
	s_cbranch_scc1 .Ldefbar_skip_2
	s_mov_b32 s100, 0
	s_barrier
.Ldefbar_skip_2:
.LBB0_408:
	s_add_u32 s76, s60, 0x100
	s_addc_u32 s77, s61, 0
	s_add_i32 s11, 0, 0x10000
	s_cmp_eq_u32 s10, 4
	s_cselect_b32 s41, s47, s77
	s_cselect_b32 s40, s46, s76
	s_cselect_b32 vcc_hi, s59, s9
	s_cselect_b32 vcc_lo, s58, s8
	s_add_i32 s21, 0, 0x14000
	v_add_u32_e32 v154, s11, v140
	v_add_u32_e32 v170, s21, v140
	ds_read_b128 v[142:145], v154
	ds_read_b128 v[146:149], v154 offset:1024
	ds_read_b128 v[150:153], v154 offset:2048
	ds_read_b128 v[154:157], v154 offset:3072
	ds_read_b128 v[158:161], v170
	ds_read_b128 v[162:165], v170 offset:1024
	ds_read_b128 v[166:169], v170 offset:2048
	ds_read_b128 v[170:173], v170 offset:3072
	v_lshl_add_u64 v[190:191], s[60:61], 0, v[136:137]
	s_add_i32 m0, s13, 0xc000
	ds_read_b128 v[174:177], v141
	ds_read_b128 v[178:181], v141 offset:1024
	ds_read_b128 v[182:185], v141 offset:2048
	ds_read_b128 v[186:189], v141 offset:3072
	ds_read_b128 v[210:213], v141 offset:4096
	ds_read_b128 v[214:217], v141 offset:5120
	ds_read_b128 v[218:221], v141 offset:6144
	ds_read_b128 v[222:225], v141 offset:7168
	global_load_lds_dwordx4 v[190:191], off
	v_lshl_add_u64 v[190:191], s[60:61], 0, v[138:139]
	s_add_i32 m0, s13, 0xe000
	s_nop 0
	global_load_lds_dwordx4 v[190:191], off
	s_waitcnt vmcnt(8)
	s_waitcnt lgkmcnt(0)
	s_setprio 1
	s_barrier
	v_mfma_f32_16x16x32_bf16 v[124:127], v[142:145], v[174:177], v[124:127]
	v_mfma_f32_16x16x32_bf16 v[120:123], v[150:153], v[174:177], v[120:123]
	v_mfma_f32_16x16x32_bf16 v[116:119], v[142:145], v[182:185], v[116:119]
	v_mfma_f32_16x16x32_bf16 v[108:111], v[150:153], v[182:185], v[108:111]
	v_mfma_f32_16x16x32_bf16 v[100:103], v[142:145], v[210:213], v[100:103]
	v_mfma_f32_16x16x32_bf16 v[92:95], v[150:153], v[210:213], v[92:95]
	v_mfma_f32_16x16x32_bf16 v[84:87], v[142:145], v[218:221], v[84:87]
	v_mfma_f32_16x16x32_bf16 v[76:79], v[150:153], v[218:221], v[76:79]
	v_mfma_f32_16x16x32_bf16 v[124:127], v[146:149], v[178:181], v[124:127]
	v_mfma_f32_16x16x32_bf16 v[120:123], v[154:157], v[178:181], v[120:123]
	v_mfma_f32_16x16x32_bf16 v[116:119], v[146:149], v[186:189], v[116:119]
	v_mfma_f32_16x16x32_bf16 v[108:111], v[154:157], v[186:189], v[108:111]
	v_mfma_f32_16x16x32_bf16 v[100:103], v[146:149], v[214:217], v[100:103]
	v_mfma_f32_16x16x32_bf16 v[92:95], v[154:157], v[214:217], v[92:95]
	v_mfma_f32_16x16x32_bf16 v[84:87], v[146:149], v[222:225], v[84:87]
	v_mfma_f32_16x16x32_bf16 v[76:79], v[154:157], v[222:225], v[76:79]
	s_setprio 0
	s_setprio 1
	v_mfma_f32_16x16x32_bf16 v[112:115], v[158:161], v[174:177], v[112:115]
	v_mfma_f32_16x16x32_bf16 v[104:107], v[166:169], v[174:177], v[104:107]
	v_mfma_f32_16x16x32_bf16 v[96:99], v[158:161], v[182:185], v[96:99]
	v_mfma_f32_16x16x32_bf16 v[88:91], v[166:169], v[182:185], v[88:91]
	v_mfma_f32_16x16x32_bf16 v[80:83], v[158:161], v[210:213], v[80:83]
	v_mfma_f32_16x16x32_bf16 v[72:75], v[166:169], v[210:213], v[72:75]
	v_mfma_f32_16x16x32_bf16 v[68:71], v[158:161], v[218:221], v[68:71]
	v_mfma_f32_16x16x32_bf16 v[64:67], v[166:169], v[218:221], v[64:67]
	v_mfma_f32_16x16x32_bf16 v[112:115], v[162:165], v[178:181], v[112:115]
	v_mfma_f32_16x16x32_bf16 v[104:107], v[170:173], v[178:181], v[104:107]
	v_mfma_f32_16x16x32_bf16 v[96:99], v[162:165], v[186:189], v[96:99]
	v_mfma_f32_16x16x32_bf16 v[88:91], v[170:173], v[186:189], v[88:91]
	v_mfma_f32_16x16x32_bf16 v[80:83], v[162:165], v[214:217], v[80:83]
	v_mfma_f32_16x16x32_bf16 v[72:75], v[170:173], v[214:217], v[72:75]
	v_mfma_f32_16x16x32_bf16 v[68:71], v[162:165], v[222:225], v[68:71]
	v_mfma_f32_16x16x32_bf16 v[64:67], v[170:173], v[222:225], v[64:67]
	s_barrier
; #define PG8_STAGE(bufoff, gbase, voff) do { _Pragma("unroll") for (int _i = 0; _i < 2; ++_i) \
;         __builtin_amdgcn_global_load_lds((const unsigned*)((const char*)(gbase) + (voff)[_i]), (PG8_LAS unsigned*)(lds + (bufoff) + ldsw + _i * 8192), 16, 0, 0); } while (0)
; #define PG8_LDA(dst, b, h) do { _Pragma("unroll") for (int m = 0; m < 4; ++m) _Pragma("unroll") for (int k = 0; k < 2; ++k) dst[m][k] = *(const PG8_LAS bf16x8*)(lds + PG8_SA(b, h) + aoff + m * 2048 + k * 1024); } while (0)
; #define PG8_LDB(dst, b, h) do { _Pragma("unroll") for (int n = 0; n < 2; ++n) _Pragma("unroll") for (int k = 0; k < 2; ++k) dst[n][k] = *(const PG8_LAS bf16x8*)(lds + PG8_SB(b, h) + boff + n * 2048 + k * 1024); } while (0)
; #define PG8_MMA(ai, bj, At, Bt) do { __builtin_amdgcn_s_setprio(1); _Pragma("unroll") for (int m = 0; m < 4; ++m) _Pragma("unroll") for (int n = 0; n < 2; ++n) _Pragma("unroll") for (int k = 0; k < 2; ++k) \
;         acc[ai][bj][m][n] = __builtin_amdgcn_mfma_f32_16x16x32_bf16(Bt[n][k], At[m][k], acc[ai][bj][m][n], 0, 0, 0); __builtin_amdgcn_s_setprio(0); } while (0)
; #define PG8_WAIT_V(n) asm volatile("s_waitcnt vmcnt(" #n ")" ::: "memory")
; #define PG8_WAIT_L(n) asm volatile("s_waitcnt lgkmcnt(" #n ")" ::: "memory")
; #define PG8_BAR __builtin_amdgcn_s_barrier()
; #define PG8_SCHED __builtin_amdgcn_sched_barrier(0)
; template <class Epi>
; __device__ __forceinline__ void gemm_phase(PG8_LAS unsigned char* lds, PG8_LAS unsigned char* xl, const Gemm g, const Sched& S, const Epi& E, const int wid) {
;     ...
;             PG8_WAIT_V(8); PG8_WAIT_L(0); PG8_BAR; if (do0) { PG8_MMA(0, 0, At, B0); PG8_MMA(0, 1, At, B1); } PG8_BAR; PG8_SCHED;
;             PG8_LDA(At, 0, 1); PG8_STAGE(PG8_SB(0, 0), b2, voffB); PG8_STAGE(PG8_SB(0, 1), b2 + hstepB, voffB); PG8_STAGE(PG8_SA(0, 0), a2, voffA);
;             PG8_WAIT_V(8); PG8_WAIT_L(0); PG8_BAR; if (do1) { PG8_MMA(1, 0, At, B0); PG8_MMA(1, 1, At, B1); } PG8_BAR; PG8_SCHED;
;             PG8_LDB(B0, 1, 0); PG8_LDB(B1, 1, 1); PG8_SCHED; PG8_LDA(At, 1, 0); PG8_STAGE(PG8_SA(0, 1), a2 + hstepA, voffA);
;             PG8_WAIT_V(8); PG8_WAIT_L(0); PG8_BAR; if (do0) { PG8_MMA(0, 0, At, B0); PG8_MMA(0, 1, At, B1); } PG8_BAR; PG8_SCHED;
	s_setprio 0
	s_add_i32 s11, s11, s29
	v_lshl_add_u64 v[190:191], vcc, 0, v[132:133]
	s_mov_b32 m0, s11
	ds_read_b128 v[174:177], v141 offset:16384
	ds_read_b128 v[178:181], v141 offset:17408
	ds_read_b128 v[182:185], v141 offset:18432
	ds_read_b128 v[186:189], v141 offset:19456
	ds_read_b128 v[210:213], v141 offset:20480
	ds_read_b128 v[214:217], v141 offset:21504
	ds_read_b128 v[218:221], v141 offset:22528
	ds_read_b128 v[222:225], v141 offset:23552
	global_load_lds_dwordx4 v[190:191], off
	s_add_i32 m0, s11, 0x2000
	s_add_u32 s54, vcc_lo, 0x80000
	v_lshl_add_u64 v[226:227], vcc, 0, v[128:129]
	s_addc_u32 s55, vcc_hi, 0
	s_add_i32 s11, s21, s29
	global_load_lds_dwordx4 v[226:227], off
	v_lshl_add_u64 v[228:229], s[54:55], 0, v[132:133]
	s_mov_b32 m0, s11
	v_lshl_add_u64 v[230:231], s[40:41], 0, v[130:131]
	global_load_lds_dwordx4 v[228:229], off
	v_lshl_add_u64 v[228:229], s[54:55], 0, v[128:129]
	s_add_i32 m0, s11, 0x2000
	s_nop 0
	global_load_lds_dwordx4 v[228:229], off
	v_lshl_add_u64 v[228:229], s[40:41], 0, v[134:135]
	s_mov_b32 m0, s13
	s_nop 0
	global_load_lds_dwordx4 v[228:229], off
	s_mov_b32 m0, s67
	s_nop 0
	global_load_lds_dwordx4 v[230:231], off
	s_waitcnt vmcnt(8)
	s_waitcnt lgkmcnt(0)
	s_setprio 1
	s_barrier
	v_mfma_f32_16x16x32_bf16 v[60:63], v[142:145], v[174:177], v[60:63]
	v_mfma_f32_16x16x32_bf16 v[56:59], v[150:153], v[174:177], v[56:59]
	v_mfma_f32_16x16x32_bf16 v[52:55], v[142:145], v[182:185], v[52:55]
	v_mfma_f32_16x16x32_bf16 v[44:47], v[150:153], v[182:185], v[44:47]
	v_mfma_f32_16x16x32_bf16 v[36:39], v[142:145], v[210:213], v[36:39]
	v_mfma_f32_16x16x32_bf16 v[28:31], v[150:153], v[210:213], v[28:31]
	v_mfma_f32_16x16x32_bf16 v[20:23], v[142:145], v[218:221], v[20:23]
	v_mfma_f32_16x16x32_bf16 v[12:15], v[150:153], v[218:221], v[12:15]
	v_mfma_f32_16x16x32_bf16 v[60:63], v[146:149], v[178:181], v[60:63]
	v_mfma_f32_16x16x32_bf16 v[56:59], v[154:157], v[178:181], v[56:59]
	v_mfma_f32_16x16x32_bf16 v[52:55], v[146:149], v[186:189], v[52:55]
	v_mfma_f32_16x16x32_bf16 v[44:47], v[154:157], v[186:189], v[44:47]
	v_mfma_f32_16x16x32_bf16 v[36:39], v[146:149], v[214:217], v[36:39]
	v_mfma_f32_16x16x32_bf16 v[28:31], v[154:157], v[214:217], v[28:31]
	v_mfma_f32_16x16x32_bf16 v[20:23], v[146:149], v[222:225], v[20:23]
	v_mfma_f32_16x16x32_bf16 v[12:15], v[154:157], v[222:225], v[12:15]
	s_setprio 0
	s_setprio 1
	v_mfma_f32_16x16x32_bf16 v[48:51], v[158:161], v[174:177], v[48:51]
	v_mfma_f32_16x16x32_bf16 v[40:43], v[166:169], v[174:177], v[40:43]
	v_mfma_f32_16x16x32_bf16 v[32:35], v[158:161], v[182:185], v[32:35]
	v_mfma_f32_16x16x32_bf16 v[24:27], v[166:169], v[182:185], v[24:27]
	v_mfma_f32_16x16x32_bf16 v[16:19], v[158:161], v[210:213], v[16:19]
	v_mfma_f32_16x16x32_bf16 v[8:11], v[166:169], v[210:213], v[8:11]
	v_mfma_f32_16x16x32_bf16 v[4:7], v[158:161], v[218:221], v[4:7]
	v_mfma_f32_16x16x32_bf16 v[0:3], v[166:169], v[218:221], v[0:3]
	v_mfma_f32_16x16x32_bf16 v[48:51], v[162:165], v[178:181], v[48:51]
	v_mfma_f32_16x16x32_bf16 v[40:43], v[170:173], v[178:181], v[40:43]
	v_mfma_f32_16x16x32_bf16 v[32:35], v[162:165], v[186:189], v[32:35]
	v_mfma_f32_16x16x32_bf16 v[24:27], v[170:173], v[186:189], v[24:27]
	v_mfma_f32_16x16x32_bf16 v[16:19], v[162:165], v[214:217], v[16:19]
	v_mfma_f32_16x16x32_bf16 v[8:11], v[170:173], v[214:217], v[8:11]
	v_mfma_f32_16x16x32_bf16 v[4:7], v[162:165], v[222:225], v[4:7]
	v_mfma_f32_16x16x32_bf16 v[0:3], v[170:173], v[222:225], v[0:3]
	s_barrier
	s_setprio 0
	s_add_i32 s11, 0, 0x18000
	s_add_i32 s21, 0, 0x1c000
	v_add_u32_e32 v154, s11, v140
	v_add_u32_e32 v170, s21, v140
	ds_read_b128 v[142:145], v154
	ds_read_b128 v[146:149], v154 offset:1024
	ds_read_b128 v[150:153], v154 offset:2048
	ds_read_b128 v[154:157], v154 offset:3072
	ds_read_b128 v[158:161], v170
	ds_read_b128 v[162:165], v170 offset:1024
	ds_read_b128 v[166:169], v170 offset:2048
	ds_read_b128 v[170:173], v170 offset:3072
	s_add_u32 s40, s40, 0x100000
	s_addc_u32 s41, s41, 0
	s_mov_b32 m0, s68
	v_lshl_add_u64 v[232:233], s[40:41], 0, v[134:135]
	ds_read_b128 v[174:177], v141 offset:32768
	ds_read_b128 v[178:181], v141 offset:33792
	ds_read_b128 v[182:185], v141 offset:34816
	ds_read_b128 v[186:189], v141 offset:35840
	ds_read_b128 v[210:213], v141 offset:36864
	ds_read_b128 v[214:217], v141 offset:37888
	ds_read_b128 v[218:221], v141 offset:38912
	ds_read_b128 v[222:225], v141 offset:39936
	global_load_lds_dwordx4 v[232:233], off
	v_lshl_add_u64 v[232:233], s[40:41], 0, v[130:131]
	s_mov_b32 m0, s69
	s_nop 0
	global_load_lds_dwordx4 v[232:233], off
	s_waitcnt vmcnt(8)
	s_waitcnt lgkmcnt(0)
	s_setprio 1
	s_barrier
; #define PG8_STAGE(bufoff, gbase, voff) do { _Pragma("unroll") for (int _i = 0; _i < 2; ++_i) \
;         __builtin_amdgcn_global_load_lds((const unsigned*)((const char*)(gbase) + (voff)[_i]), (PG8_LAS unsigned*)(lds + (bufoff) + ldsw + _i * 8192), 16, 0, 0); } while (0)
; #define PG8_LDA(dst, b, h) do { _Pragma("unroll") for (int m = 0; m < 4; ++m) _Pragma("unroll") for (int k = 0; k < 2; ++k) dst[m][k] = *(const PG8_LAS bf16x8*)(lds + PG8_SA(b, h) + aoff + m * 2048 + k * 1024); } while (0)
; #define PG8_MMA(ai, bj, At, Bt) do { __builtin_amdgcn_s_setprio(1); _Pragma("unroll") for (int m = 0; m < 4; ++m) _Pragma("unroll") for (int n = 0; n < 2; ++n) _Pragma("unroll") for (int k = 0; k < 2; ++k) \
;         acc[ai][bj][m][n] = __builtin_amdgcn_mfma_f32_16x16x32_bf16(Bt[n][k], At[m][k], acc[ai][bj][m][n], 0, 0, 0); __builtin_amdgcn_s_setprio(0); } while (0)
; #define PG8_WAIT_V(n) asm volatile("s_waitcnt vmcnt(" #n ")" ::: "memory")
; #define PG8_WAIT_L(n) asm volatile("s_waitcnt lgkmcnt(" #n ")" ::: "memory")
; #define PG8_BAR __builtin_amdgcn_s_barrier()
; #define PG8_SCHED __builtin_amdgcn_sched_barrier(0)
; template <class Epi>
; __device__ __forceinline__ void gemm_phase(PG8_LAS unsigned char* lds, PG8_LAS unsigned char* xl, const Gemm g, const Sched& S, const Epi& E, const int wid) {
;     ...
;             PG8_WAIT_V(8); PG8_WAIT_L(0); PG8_BAR; if (do0) { PG8_MMA(0, 0, At, B0); PG8_MMA(0, 1, At, B1); } PG8_BAR; PG8_SCHED;
;             PG8_LDA(At, 1, 1); PG8_STAGE(PG8_SB(1, 0), b3, voffB); PG8_STAGE(PG8_SB(1, 1), b3 + hstepB, voffB); PG8_STAGE(PG8_SA(1, 0), a3, voffA);
;             PG8_WAIT_V(8); PG8_WAIT_L(0); PG8_BAR; if (do1) { PG8_MMA(1, 0, At, B0); PG8_MMA(1, 1, At, B1); } PG8_BAR; PG8_SCHED;
;         }
;         if (wr == 0) PG8_BAR;
	v_mfma_f32_16x16x32_bf16 v[124:127], v[142:145], v[174:177], v[124:127]
	v_mfma_f32_16x16x32_bf16 v[120:123], v[150:153], v[174:177], v[120:123]
	v_mfma_f32_16x16x32_bf16 v[116:119], v[142:145], v[182:185], v[116:119]
	v_mfma_f32_16x16x32_bf16 v[108:111], v[150:153], v[182:185], v[108:111]
	v_mfma_f32_16x16x32_bf16 v[100:103], v[142:145], v[210:213], v[100:103]
	v_mfma_f32_16x16x32_bf16 v[92:95], v[150:153], v[210:213], v[92:95]
	v_mfma_f32_16x16x32_bf16 v[84:87], v[142:145], v[218:221], v[84:87]
	v_mfma_f32_16x16x32_bf16 v[76:79], v[150:153], v[218:221], v[76:79]
	v_mfma_f32_16x16x32_bf16 v[124:127], v[146:149], v[178:181], v[124:127]
	v_mfma_f32_16x16x32_bf16 v[120:123], v[154:157], v[178:181], v[120:123]
	v_mfma_f32_16x16x32_bf16 v[116:119], v[146:149], v[186:189], v[116:119]
	v_mfma_f32_16x16x32_bf16 v[108:111], v[154:157], v[186:189], v[108:111]
	v_mfma_f32_16x16x32_bf16 v[100:103], v[146:149], v[214:217], v[100:103]
	v_mfma_f32_16x16x32_bf16 v[92:95], v[154:157], v[214:217], v[92:95]
	v_mfma_f32_16x16x32_bf16 v[84:87], v[146:149], v[222:225], v[84:87]
	v_mfma_f32_16x16x32_bf16 v[76:79], v[154:157], v[222:225], v[76:79]
	s_setprio 0
	s_setprio 1
	v_mfma_f32_16x16x32_bf16 v[112:115], v[158:161], v[174:177], v[112:115]
	v_mfma_f32_16x16x32_bf16 v[104:107], v[166:169], v[174:177], v[104:107]
	v_mfma_f32_16x16x32_bf16 v[96:99], v[158:161], v[182:185], v[96:99]
	v_mfma_f32_16x16x32_bf16 v[88:91], v[166:169], v[182:185], v[88:91]
	v_mfma_f32_16x16x32_bf16 v[80:83], v[158:161], v[210:213], v[80:83]
	v_mfma_f32_16x16x32_bf16 v[72:75], v[166:169], v[210:213], v[72:75]
	v_mfma_f32_16x16x32_bf16 v[68:71], v[158:161], v[218:221], v[68:71]
	v_mfma_f32_16x16x32_bf16 v[64:67], v[166:169], v[218:221], v[64:67]
	v_mfma_f32_16x16x32_bf16 v[112:115], v[162:165], v[178:181], v[112:115]
	v_mfma_f32_16x16x32_bf16 v[104:107], v[170:173], v[178:181], v[104:107]
	v_mfma_f32_16x16x32_bf16 v[96:99], v[162:165], v[186:189], v[96:99]
	v_mfma_f32_16x16x32_bf16 v[88:91], v[170:173], v[186:189], v[88:91]
	v_mfma_f32_16x16x32_bf16 v[80:83], v[162:165], v[214:217], v[80:83]
	v_mfma_f32_16x16x32_bf16 v[72:75], v[170:173], v[214:217], v[72:75]
	v_mfma_f32_16x16x32_bf16 v[68:71], v[162:165], v[222:225], v[68:71]
	v_mfma_f32_16x16x32_bf16 v[64:67], v[170:173], v[222:225], v[64:67]
	s_barrier
	s_setprio 0
	s_add_i32 s11, s11, s29
	v_lshl_add_u64 v[190:191], v[190:191], 0, s[22:23]
	s_mov_b32 m0, s11
	ds_read_b128 v[174:177], v141 offset:49152
	ds_read_b128 v[178:181], v141 offset:50176
	ds_read_b128 v[182:185], v141 offset:51200
	ds_read_b128 v[186:189], v141 offset:52224
	ds_read_b128 v[210:213], v141 offset:53248
	ds_read_b128 v[214:217], v141 offset:54272
	ds_read_b128 v[218:221], v141 offset:55296
	ds_read_b128 v[222:225], v141 offset:56320
	global_load_lds_dwordx4 v[190:191], off
	s_add_i32 m0, s11, 0x2000
	s_add_u32 s40, vcc_lo, 0x80080
	v_lshl_add_u64 v[190:191], v[226:227], 0, s[22:23]
	s_addc_u32 s41, vcc_hi, 0
	s_add_i32 s11, s21, s29
	global_load_lds_dwordx4 v[190:191], off
	v_lshl_add_u64 v[190:191], s[40:41], 0, v[132:133]
	s_mov_b32 m0, s11
	s_nop 0
	global_load_lds_dwordx4 v[190:191], off
	v_lshl_add_u64 v[190:191], s[40:41], 0, v[128:129]
	s_add_i32 m0, s11, 0x2000
	s_nop 0
	global_load_lds_dwordx4 v[190:191], off
	v_lshl_add_u64 v[190:191], v[228:229], 0, s[22:23]
	s_mov_b32 m0, s88
	s_nop 0
	global_load_lds_dwordx4 v[190:191], off
	v_lshl_add_u64 v[190:191], v[230:231], 0, s[22:23]
	s_mov_b32 m0, s89
	s_nop 0
	global_load_lds_dwordx4 v[190:191], off
	s_waitcnt vmcnt(8)
	s_waitcnt lgkmcnt(0)
	s_setprio 1
	s_barrier
	v_mfma_f32_16x16x32_bf16 v[60:63], v[142:145], v[174:177], v[60:63]
	v_mfma_f32_16x16x32_bf16 v[56:59], v[150:153], v[174:177], v[56:59]
	v_mfma_f32_16x16x32_bf16 v[52:55], v[142:145], v[182:185], v[52:55]
	v_mfma_f32_16x16x32_bf16 v[44:47], v[150:153], v[182:185], v[44:47]
	v_mfma_f32_16x16x32_bf16 v[36:39], v[142:145], v[210:213], v[36:39]
	v_mfma_f32_16x16x32_bf16 v[28:31], v[150:153], v[210:213], v[28:31]
	v_mfma_f32_16x16x32_bf16 v[20:23], v[142:145], v[218:221], v[20:23]
	v_mfma_f32_16x16x32_bf16 v[12:15], v[150:153], v[218:221], v[12:15]
	v_mfma_f32_16x16x32_bf16 v[60:63], v[146:149], v[178:181], v[60:63]
	v_mfma_f32_16x16x32_bf16 v[56:59], v[154:157], v[178:181], v[56:59]
	v_mfma_f32_16x16x32_bf16 v[52:55], v[146:149], v[186:189], v[52:55]
	v_mfma_f32_16x16x32_bf16 v[44:47], v[154:157], v[186:189], v[44:47]
	v_mfma_f32_16x16x32_bf16 v[36:39], v[146:149], v[214:217], v[36:39]
	v_mfma_f32_16x16x32_bf16 v[28:31], v[154:157], v[214:217], v[28:31]
	v_mfma_f32_16x16x32_bf16 v[20:23], v[146:149], v[222:225], v[20:23]
	v_mfma_f32_16x16x32_bf16 v[12:15], v[154:157], v[222:225], v[12:15]
	s_setprio 0
	s_setprio 1
	v_mfma_f32_16x16x32_bf16 v[48:51], v[158:161], v[174:177], v[48:51]
	v_mfma_f32_16x16x32_bf16 v[40:43], v[166:169], v[174:177], v[40:43]
	v_mfma_f32_16x16x32_bf16 v[32:35], v[158:161], v[182:185], v[32:35]
	v_mfma_f32_16x16x32_bf16 v[24:27], v[166:169], v[182:185], v[24:27]
	v_mfma_f32_16x16x32_bf16 v[16:19], v[158:161], v[210:213], v[16:19]
	v_mfma_f32_16x16x32_bf16 v[8:11], v[166:169], v[210:213], v[8:11]
	v_mfma_f32_16x16x32_bf16 v[4:7], v[158:161], v[218:221], v[4:7]
	v_mfma_f32_16x16x32_bf16 v[0:3], v[166:169], v[218:221], v[0:3]
	v_mfma_f32_16x16x32_bf16 v[48:51], v[162:165], v[178:181], v[48:51]
	v_mfma_f32_16x16x32_bf16 v[40:43], v[170:173], v[178:181], v[40:43]
	v_mfma_f32_16x16x32_bf16 v[32:35], v[162:165], v[186:189], v[32:35]
	v_mfma_f32_16x16x32_bf16 v[24:27], v[170:173], v[186:189], v[24:27]
	v_mfma_f32_16x16x32_bf16 v[16:19], v[162:165], v[214:217], v[16:19]
	v_mfma_f32_16x16x32_bf16 v[8:11], v[170:173], v[214:217], v[8:11]
	v_mfma_f32_16x16x32_bf16 v[4:7], v[162:165], v[222:225], v[4:7]
	v_mfma_f32_16x16x32_bf16 v[0:3], v[170:173], v[222:225], v[0:3]
	s_barrier
	s_setprio 0
	s_add_i32 s10, s10, 2
	s_add_u32 s8, s8, 0x100
	s_addc_u32 s9, s9, 0
	s_cmp_gt_u32 s10, 5
	s_mov_b64 s[60:61], s[76:77]
	s_cbranch_scc0 .LBB0_408
	s_and_b64 vcc, exec, s[14:15]
	s_cbranch_vccz .LBB0_411
	s_barrier
; #define ACT4(v, F) do { const f32x2 _lo = F((f32x2){v[0], v[1]}), _hi = F((f32x2){v[2], v[3]}); v = (f32x4){_lo.x, _lo.y, _hi.x, _hi.y}; } while (0)
; #define PACK8(w, v0, v1) do { w.x = cvt_pk_bf16(v0[0], v0[1]); w.y = cvt_pk_bf16(v0[2], v0[3]); w.z = cvt_pk_bf16(v1[0], v1[1]); w.w = cvt_pk_bf16(v1[2], v1[3]); } while (0)
; #define PG8_BAR __builtin_amdgcn_s_barrier()
;     __device__ __forceinline__ void operator()(EPI_ARGS) const {
;     ...
; #pragma unroll
;         for (int ai = 0; ai < 2; ++ai)
; #pragma unroll
;             for (int m = 0; m < 4; ++m) { char* rb = ub + (size_t)(ai * HALF + m) * ldc * 2;
;                 float s1 = 0.f, s2 = 0.f;
; #pragma unroll
;                 for (int bj = 0; bj < 2; ++bj) { f32x4 v0 = acc[ai][bj][m][0] * rs[ai][m], v1 = acc[ai][bj][m][1] * rs[ai][m];
;                     if (act == 1) { ACT4(v0, gelu_t2); ACT4(v1, gelu_t2); }
;                     else if (act == 2) { ACT4(v0, sigm2); ACT4(v1, sigm2); }
;                     u32x4 w; PACK8(w, v0, v1);
;                     *(u32x4*)(rb + lo + bj * 256) = w;
; template <class Epi>
; __device__ __forceinline__ void gemm_phase(PG8_LAS unsigned char* lds, PG8_LAS unsigned char* xl, const Gemm g, const Sched& S, const Epi& E, const int wid) {
;     ...
;         if (!has_next) break;
; #pragma unroll
;         for (int a = 0; a < 2; ++a)
; #pragma unroll
;             for (int b = 0; b < 2; ++b)
; #pragma unroll
;                 for (int m = 0; m < 4; ++m)
; #pragma unroll
;                     for (int n = 0; n < 2; ++n) acc[a][b][m][n] = (f32x4){0.f, 0.f, 0.f, 0.f};
;         cur = nxt; cA = nA; cB = nB; ++ui;
;         if (wr == 1) PG8_BAR;
.LBB0_411:
	s_ashr_i32 s57, s56, 31
	s_lshl_b64 s[8:9], s[56:57], 22
	s_add_u32 s10, s70, s8
	s_addc_u32 s11, s71, s9
	s_ashr_i32 s53, s52, 31
	s_lshl_b64 s[8:9], s[52:53], 20
	s_add_u32 s10, s10, s8
	s_addc_u32 s11, s11, s9
	s_ashr_i32 s37, s36, 31
	s_lshl_b64 s[8:9], s[36:37], 20
	s_add_u32 s10, s10, s8
	s_addc_u32 s11, s11, s9
	s_lshl_b32 s8, s12, 8
	v_mbcnt_lo_u32_b32 v142, -1, 0
	v_mbcnt_hi_u32_b32 v142, -1, v142
	s_ashr_i32 s9, s8, 31
	v_lshlrev_b32_e32 v143, 2, v142
	v_and_or_b32 v143, v143, 60, s3
	s_lshl_b64 s[8:9], s[8:9], 1
	v_and_b32_e32 v142, -16, v142
	v_lshlrev_b32_e32 v143, 12, v143
	s_add_u32 s8, s10, s8
	v_add3_u32 v192, v142, s75, v143
	s_addc_u32 s9, s11, s9
	v_lshl_add_u64 v[142:143], s[8:9], 0, v[192:193]
	v_cvt_pk_bf16_f32 v124, v124, v125
	v_cvt_pk_bf16_f32 v125, v126, v127
	v_cvt_pk_bf16_f32 v126, v120, v121
	v_cvt_pk_bf16_f32 v127, v122, v123
	global_store_dwordx4 v192, v[124:127], s[8:9]
	v_cvt_pk_bf16_f32 v112, v112, v113
	v_cvt_pk_bf16_f32 v113, v114, v115
	v_cvt_pk_bf16_f32 v114, v104, v105
	v_cvt_pk_bf16_f32 v115, v106, v107
	global_store_dwordx4 v192, v[112:115], s[8:9] offset:256
	v_cvt_pk_bf16_f32 v104, v116, v117
	v_cvt_pk_bf16_f32 v105, v118, v119
	v_cvt_pk_bf16_f32 v106, v108, v109
	v_add_co_u32_e32 v108, vcc, s25, v142
	v_cvt_pk_bf16_f32 v107, v110, v111
	s_mov_b32 s4, 0x80000
	s_nop 0
	v_addc_co_u32_e32 v109, vcc, 0, v143, vcc
	v_add_co_u32_e32 v110, vcc, s78, v142
	s_mov_b64 s[8:9], -1
	s_nop 0
	v_addc_co_u32_e32 v111, vcc, 0, v143, vcc
	global_store_dwordx4 v[110:111], v[104:107], off offset:-4096
	v_cvt_pk_bf16_f32 v96, v96, v97
	v_cvt_pk_bf16_f32 v97, v98, v99
	v_cvt_pk_bf16_f32 v98, v88, v89
	v_cvt_pk_bf16_f32 v99, v90, v91
	global_store_dwordx4 v[108:109], v[96:99], off offset:256
	v_cvt_pk_bf16_f32 v88, v100, v101
	v_cvt_pk_bf16_f32 v89, v102, v103
	v_cvt_pk_bf16_f32 v90, v92, v93
	v_cvt_pk_bf16_f32 v91, v94, v95
	global_store_dwordx4 v[110:111], v[88:91], off
	v_cvt_pk_bf16_f32 v80, v80, v81
	v_cvt_pk_bf16_f32 v81, v82, v83
	v_cvt_pk_bf16_f32 v82, v72, v73
	v_cvt_pk_bf16_f32 v83, v74, v75
	global_store_dwordx4 v[110:111], v[80:83], off offset:256
	v_cvt_pk_bf16_f32 v72, v84, v85
	v_cvt_pk_bf16_f32 v73, v86, v87
	v_cvt_pk_bf16_f32 v74, v76, v77
	v_add_co_u32_e32 v76, vcc, s79, v142
	v_cvt_pk_bf16_f32 v75, v78, v79
	s_nop 1
	v_addc_co_u32_e32 v77, vcc, 0, v143, vcc
	global_store_dwordx4 v[76:77], v[72:75], off
	v_cvt_pk_bf16_f32 v68, v68, v69
	v_cvt_pk_bf16_f32 v69, v70, v71
	v_cvt_pk_bf16_f32 v70, v64, v65
	v_cvt_pk_bf16_f32 v71, v66, v67
	global_store_dwordx4 v[76:77], v[68:71], off offset:256
	v_cvt_pk_bf16_f32 v60, v60, v61
	v_cvt_pk_bf16_f32 v61, v62, v63
	v_cvt_pk_bf16_f32 v62, v56, v57
	v_add_co_u32_e32 v56, vcc, s4, v142
	v_cvt_pk_bf16_f32 v63, v58, v59
	s_mov_b32 s4, 0x82000
	s_nop 0
	v_addc_co_u32_e32 v57, vcc, 0, v143, vcc
	v_add_co_u32_e32 v58, vcc, s95, v142
	s_nop 1
	v_addc_co_u32_e32 v59, vcc, 0, v143, vcc
	global_store_dwordx4 v[58:59], v[60:63], off offset:-4096
	v_cvt_pk_bf16_f32 v48, v48, v49
	v_cvt_pk_bf16_f32 v49, v50, v51
	v_cvt_pk_bf16_f32 v50, v40, v41
	v_cvt_pk_bf16_f32 v51, v42, v43
	global_store_dwordx4 v[56:57], v[48:51], off offset:256
	v_cvt_pk_bf16_f32 v40, v52, v53
	v_cvt_pk_bf16_f32 v41, v54, v55
	v_cvt_pk_bf16_f32 v42, v44, v45
	v_cvt_pk_bf16_f32 v43, v46, v47
	global_store_dwordx4 v[58:59], v[40:43], off
	v_cvt_pk_bf16_f32 v32, v32, v33
	v_cvt_pk_bf16_f32 v33, v34, v35
	v_cvt_pk_bf16_f32 v34, v24, v25
	v_cvt_pk_bf16_f32 v35, v26, v27
	global_store_dwordx4 v[58:59], v[32:35], off offset:256
	v_cvt_pk_bf16_f32 v24, v36, v37
	v_cvt_pk_bf16_f32 v25, v38, v39
	v_cvt_pk_bf16_f32 v26, v28, v29
	v_add_co_u32_e32 v28, vcc, s4, v142
	s_mov_b32 s4, 0x83000
	s_nop 0
	v_addc_co_u32_e32 v29, vcc, 0, v143, vcc
	v_cvt_pk_bf16_f32 v27, v30, v31
	v_add_co_u32_e32 v30, vcc, s4, v142
	s_nop 1
	v_addc_co_u32_e32 v31, vcc, 0, v143, vcc
	s_and_b64 vcc, exec, s[42:43]
	global_store_dwordx4 v[30:31], v[24:27], off offset:-4096
	v_cvt_pk_bf16_f32 v16, v16, v17
	v_cvt_pk_bf16_f32 v17, v18, v19
	v_cvt_pk_bf16_f32 v18, v8, v9
	v_cvt_pk_bf16_f32 v19, v10, v11
	global_store_dwordx4 v[28:29], v[16:19], off offset:256
	v_cvt_pk_bf16_f32 v8, v20, v21
	v_cvt_pk_bf16_f32 v9, v22, v23
	v_cvt_pk_bf16_f32 v10, v12, v13
	v_cvt_pk_bf16_f32 v11, v14, v15
	global_store_dwordx4 v[30:31], v[8:11], off
	v_cvt_pk_bf16_f32 v4, v4, v5
	v_cvt_pk_bf16_f32 v5, v6, v7
	v_cvt_pk_bf16_f32 v6, v0, v1
	v_cvt_pk_bf16_f32 v7, v2, v3
	global_store_dwordx4 v[30:31], v[4:7], off offset:256
	s_cbranch_vccnz .LBB0_400
	s_and_b64 vcc, exec, s[38:39]
	s_cbranch_vccnz .LBB0_399
	s_mov_b32 s100, 1
	s_branch .LBB0_399

; __device__ __forceinline__ const char* a_tile(const Gemm& g, const Unit& u) { return (const char*)(g.A + ((long)u.z1 * g.aS1 + (long)u.z2 * g.aS2 + (long)u.pm * BM * g.lda)); }
; __device__ __forceinline__ const char* b_tile(const Gemm& g, const Unit& u) { return (const char*)(g.Bt + ((long)u.z1 * g.bS1 + (long)u.z2 * g.bS2 + (long)u.pn * BM * g.ldb)); }
; __device__ __forceinline__ int lane_id_opq() { int l; asm volatile("v_mbcnt_lo_u32_b32 %0, -1, 0\n\tv_mbcnt_hi_u32_b32 %0, -1, %0" : "=v"(l)); return l; }
; #define PG8_WAIT_V(n) asm volatile("s_waitcnt vmcnt(" #n ")" ::: "memory")
; #define PG8_BAR __builtin_amdgcn_s_barrier()
; template <class Epi>
; __device__ __forceinline__ void gemm_phase(PG8_LAS unsigned char* lds, PG8_LAS unsigned char* xl, const Gemm g, const Sched& S, const Epi& E, const int wid) {
;     ...
;         const bool has_next = S.next(ui + 1, nxt);
;         const char* nA = has_next ? a_tile(g, nxt) : cA; const char* nB = has_next ? b_tile(g, nxt) : cB;
;         for (int t = 0; t < nt; t += 2) {
;             const bool last = (t == nt - 2);
;             const bool do0 = !blkdiag_v<Epi> || t == 0, do1 = !blkdiag_v<Epi> || t != 0;
;             long j1 = 0, ja2 = 0, jb2 = 0;
;             if constexpr (Epi::MID) {
;                 if (t == g.tj) { const int lnM = lane_id_opq(); E.mid(acc, cur, wr, wc, lnM & 15, lnM >> 4); }
;                 if (t >= g.tj) j1 = g.jA;
;                 if (t + 2 >= g.tj) { ja2 = g.jA; jb2 = g.jB; } }
;             const char* a1 = cA + (size_t)(t + 1) * kstep + j1;
;             const char* a2 = last ? nA : cA + (size_t)(t + 2) * kstep + ja2; const char* b2 = last ? nB : cB + (size_t)(t + 2) * kstep + jb2;
;             const char* a3 = a2 + kstep; const char* b3 = b2 + kstep;
;             PG8_LDB(B0, 0, 0); PG8_LDB(B1, 0, 1); PG8_SCHED; PG8_LDA(At, 0, 0); PG8_STAGE(PG8_SA(1, 1), a1 + hstepA, voffA);
;             PG8_WAIT_V(8); PG8_WAIT_L(0); PG8_BAR; if (do0) { PG8_MMA(0, 0, At, B0); PG8_MMA(0, 1, At, B1); } PG8_BAR; PG8_SCHED;
;     ...
; #pragma unroll
;         for (int a = 0; a < 2; ++a)
; #pragma unroll
;             for (int b = 0; b < 2; ++b)
; #pragma unroll
;                 for (int m = 0; m < 4; ++m)
; #pragma unroll
;                     for (int n = 0; n < 2; ++n) acc[a][b][m][n] = (f32x4){0.f, 0.f, 0.f, 0.f};
;         cur = nxt; cA = nA; cB = nB; ++ui;
;         if (wr == 1) PG8_BAR;
.LBB0_427:
	s_add_u32 s8, s60, 0x100
	v_mov_b32_e32 v0, 0
	s_addc_u32 s9, s61, 0
	s_mov_b32 s10, -2
	v_mov_b32_e32 v1, v0
	v_mov_b32_e32 v2, v0
	v_mov_b32_e32 v3, v0
	v_mov_b32_e32 v4, v0
	v_mov_b32_e32 v5, v0
	v_mov_b32_e32 v6, v0
	v_mov_b32_e32 v7, v0
	v_mov_b32_e32 v8, v0
	v_mov_b32_e32 v9, v0
	v_mov_b32_e32 v10, v0
	v_mov_b32_e32 v11, v0
	v_mov_b32_e32 v16, v0
	v_mov_b32_e32 v17, v0
	v_mov_b32_e32 v18, v0
	v_mov_b32_e32 v19, v0
	v_mov_b32_e32 v24, v0
	v_mov_b32_e32 v25, v0
	v_mov_b32_e32 v26, v0
	v_mov_b32_e32 v27, v0
	v_mov_b32_e32 v32, v0
	v_mov_b32_e32 v33, v0
	v_mov_b32_e32 v34, v0
	v_mov_b32_e32 v35, v0
	v_mov_b32_e32 v40, v0
	v_mov_b32_e32 v41, v0
	v_mov_b32_e32 v42, v0
	v_mov_b32_e32 v43, v0
	v_mov_b32_e32 v48, v0
	v_mov_b32_e32 v49, v0
	v_mov_b32_e32 v50, v0
	v_mov_b32_e32 v51, v0
	v_mov_b32_e32 v12, v0
	v_mov_b32_e32 v13, v0
	v_mov_b32_e32 v14, v0
	v_mov_b32_e32 v15, v0
	v_mov_b32_e32 v20, v0
	v_mov_b32_e32 v21, v0
	v_mov_b32_e32 v22, v0
	v_mov_b32_e32 v23, v0
	v_mov_b32_e32 v28, v0
	v_mov_b32_e32 v29, v0
	v_mov_b32_e32 v30, v0
	v_mov_b32_e32 v31, v0
	v_mov_b32_e32 v36, v0
	v_mov_b32_e32 v37, v0
	v_mov_b32_e32 v38, v0
	v_mov_b32_e32 v39, v0
	v_mov_b32_e32 v44, v0
	v_mov_b32_e32 v45, v0
	v_mov_b32_e32 v46, v0
	v_mov_b32_e32 v47, v0
	v_mov_b32_e32 v52, v0
	v_mov_b32_e32 v53, v0
	v_mov_b32_e32 v54, v0
	v_mov_b32_e32 v55, v0
	v_mov_b32_e32 v56, v0
	v_mov_b32_e32 v57, v0
	v_mov_b32_e32 v58, v0
	v_mov_b32_e32 v59, v0
	v_mov_b32_e32 v60, v0
	v_mov_b32_e32 v61, v0
	v_mov_b32_e32 v62, v0
	v_mov_b32_e32 v63, v0
	v_mov_b32_e32 v64, v0
	v_mov_b32_e32 v65, v0
	v_mov_b32_e32 v66, v0
	v_mov_b32_e32 v67, v0
	v_mov_b32_e32 v68, v0
	v_mov_b32_e32 v69, v0
	v_mov_b32_e32 v70, v0
	v_mov_b32_e32 v71, v0
	v_mov_b32_e32 v72, v0
	v_mov_b32_e32 v73, v0
	v_mov_b32_e32 v74, v0
	v_mov_b32_e32 v75, v0
	v_mov_b32_e32 v80, v0
	v_mov_b32_e32 v81, v0
	v_mov_b32_e32 v82, v0
	v_mov_b32_e32 v83, v0
	v_mov_b32_e32 v88, v0
	v_mov_b32_e32 v89, v0
	v_mov_b32_e32 v90, v0
	v_mov_b32_e32 v91, v0
	v_mov_b32_e32 v96, v0
	v_mov_b32_e32 v97, v0
	v_mov_b32_e32 v98, v0
	v_mov_b32_e32 v99, v0
	v_mov_b32_e32 v104, v0
	v_mov_b32_e32 v105, v0
	v_mov_b32_e32 v106, v0
	v_mov_b32_e32 v107, v0
	v_mov_b32_e32 v112, v0
	v_mov_b32_e32 v113, v0
	v_mov_b32_e32 v114, v0
	v_mov_b32_e32 v115, v0
	v_mov_b32_e32 v76, v0
	v_mov_b32_e32 v77, v0
	v_mov_b32_e32 v78, v0
	v_mov_b32_e32 v79, v0
	v_mov_b32_e32 v84, v0
	v_mov_b32_e32 v85, v0
	v_mov_b32_e32 v86, v0
	v_mov_b32_e32 v87, v0
	v_mov_b32_e32 v92, v0
	v_mov_b32_e32 v93, v0
	v_mov_b32_e32 v94, v0
	v_mov_b32_e32 v95, v0
	v_mov_b32_e32 v100, v0
	v_mov_b32_e32 v101, v0
	v_mov_b32_e32 v102, v0
	v_mov_b32_e32 v103, v0
	v_mov_b32_e32 v108, v0
	v_mov_b32_e32 v109, v0
	v_mov_b32_e32 v110, v0
	v_mov_b32_e32 v111, v0
	v_mov_b32_e32 v116, v0
	v_mov_b32_e32 v117, v0
	v_mov_b32_e32 v118, v0
	v_mov_b32_e32 v119, v0
	v_mov_b32_e32 v120, v0
	v_mov_b32_e32 v121, v0
	v_mov_b32_e32 v122, v0
	v_mov_b32_e32 v123, v0
	v_mov_b32_e32 v124, v0
	v_mov_b32_e32 v125, v0
	v_mov_b32_e32 v126, v0
	v_mov_b32_e32 v127, v0
	s_cmp_lg_u32 s100, 1
	s_cbranch_scc1 .Ldefbar_skip_3
	s_mov_b32 s100, 0
	s_barrier
.Ldefbar_skip_3:
.LBB0_428:
	s_add_u32 s60, s58, 0x100
	s_addc_u32 s61, s59, 0
	s_add_i32 s11, 0, 0x10000
	s_cmp_eq_u32 s10, 4
	s_cselect_b32 s41, s47, s61
	s_cselect_b32 s40, s46, s60
	s_cselect_b32 s77, s57, s9
	s_cselect_b32 s76, s56, s8
	s_add_i32 s21, 0, 0x14000
	v_add_u32_e32 v154, s11, v140
	v_add_u32_e32 v170, s21, v140
	ds_read_b128 v[142:145], v154
	ds_read_b128 v[146:149], v154 offset:1024
	ds_read_b128 v[150:153], v154 offset:2048
	ds_read_b128 v[154:157], v154 offset:3072
	ds_read_b128 v[158:161], v170
	ds_read_b128 v[162:165], v170 offset:1024
	ds_read_b128 v[166:169], v170 offset:2048
	ds_read_b128 v[170:173], v170 offset:3072
	v_lshl_add_u64 v[190:191], s[58:59], 0, v[136:137]
	s_add_i32 m0, s13, 0xc000
	ds_read_b128 v[174:177], v141
	ds_read_b128 v[178:181], v141 offset:1024
	ds_read_b128 v[182:185], v141 offset:2048
	ds_read_b128 v[186:189], v141 offset:3072
	ds_read_b128 v[210:213], v141 offset:4096
	ds_read_b128 v[214:217], v141 offset:5120
	ds_read_b128 v[218:221], v141 offset:6144
	ds_read_b128 v[222:225], v141 offset:7168
	global_load_lds_dwordx4 v[190:191], off
	v_lshl_add_u64 v[190:191], s[58:59], 0, v[138:139]
	s_add_i32 m0, s13, 0xe000
	s_nop 0
	global_load_lds_dwordx4 v[190:191], off
	s_waitcnt vmcnt(8)
	s_waitcnt lgkmcnt(0)
	s_setprio 1
	s_barrier
	v_mfma_f32_16x16x32_bf16 v[124:127], v[142:145], v[174:177], v[124:127]
	v_mfma_f32_16x16x32_bf16 v[120:123], v[150:153], v[174:177], v[120:123]
	v_mfma_f32_16x16x32_bf16 v[116:119], v[142:145], v[182:185], v[116:119]
	v_mfma_f32_16x16x32_bf16 v[108:111], v[150:153], v[182:185], v[108:111]
	v_mfma_f32_16x16x32_bf16 v[100:103], v[142:145], v[210:213], v[100:103]
	v_mfma_f32_16x16x32_bf16 v[92:95], v[150:153], v[210:213], v[92:95]
	v_mfma_f32_16x16x32_bf16 v[84:87], v[142:145], v[218:221], v[84:87]
	v_mfma_f32_16x16x32_bf16 v[76:79], v[150:153], v[218:221], v[76:79]
	v_mfma_f32_16x16x32_bf16 v[124:127], v[146:149], v[178:181], v[124:127]
	v_mfma_f32_16x16x32_bf16 v[120:123], v[154:157], v[178:181], v[120:123]
	v_mfma_f32_16x16x32_bf16 v[116:119], v[146:149], v[186:189], v[116:119]
	v_mfma_f32_16x16x32_bf16 v[108:111], v[154:157], v[186:189], v[108:111]
	v_mfma_f32_16x16x32_bf16 v[100:103], v[146:149], v[214:217], v[100:103]
	v_mfma_f32_16x16x32_bf16 v[92:95], v[154:157], v[214:217], v[92:95]
	v_mfma_f32_16x16x32_bf16 v[84:87], v[146:149], v[222:225], v[84:87]
	v_mfma_f32_16x16x32_bf16 v[76:79], v[154:157], v[222:225], v[76:79]
	s_setprio 0
	s_setprio 1
	v_mfma_f32_16x16x32_bf16 v[112:115], v[158:161], v[174:177], v[112:115]
	v_mfma_f32_16x16x32_bf16 v[104:107], v[166:169], v[174:177], v[104:107]
	v_mfma_f32_16x16x32_bf16 v[96:99], v[158:161], v[182:185], v[96:99]
	v_mfma_f32_16x16x32_bf16 v[88:91], v[166:169], v[182:185], v[88:91]
	v_mfma_f32_16x16x32_bf16 v[80:83], v[158:161], v[210:213], v[80:83]
	v_mfma_f32_16x16x32_bf16 v[72:75], v[166:169], v[210:213], v[72:75]
	v_mfma_f32_16x16x32_bf16 v[68:71], v[158:161], v[218:221], v[68:71]
	v_mfma_f32_16x16x32_bf16 v[64:67], v[166:169], v[218:221], v[64:67]
	v_mfma_f32_16x16x32_bf16 v[112:115], v[162:165], v[178:181], v[112:115]
	v_mfma_f32_16x16x32_bf16 v[104:107], v[170:173], v[178:181], v[104:107]
	v_mfma_f32_16x16x32_bf16 v[96:99], v[162:165], v[186:189], v[96:99]
	v_mfma_f32_16x16x32_bf16 v[88:91], v[170:173], v[186:189], v[88:91]
	v_mfma_f32_16x16x32_bf16 v[80:83], v[162:165], v[214:217], v[80:83]
	v_mfma_f32_16x16x32_bf16 v[72:75], v[170:173], v[214:217], v[72:75]
	v_mfma_f32_16x16x32_bf16 v[68:71], v[162:165], v[222:225], v[68:71]
	v_mfma_f32_16x16x32_bf16 v[64:67], v[170:173], v[222:225], v[64:67]
	s_barrier
; #define PG8_STAGE(bufoff, gbase, voff) do { _Pragma("unroll") for (int _i = 0; _i < 2; ++_i) \
;         __builtin_amdgcn_global_load_lds((const unsigned*)((const char*)(gbase) + (voff)[_i]), (PG8_LAS unsigned*)(lds + (bufoff) + ldsw + _i * 8192), 16, 0, 0); } while (0)
; #define PG8_LDA(dst, b, h) do { _Pragma("unroll") for (int m = 0; m < 4; ++m) _Pragma("unroll") for (int k = 0; k < 2; ++k) dst[m][k] = *(const PG8_LAS bf16x8*)(lds + PG8_SA(b, h) + aoff + m * 2048 + k * 1024); } while (0)
; #define PG8_LDB(dst, b, h) do { _Pragma("unroll") for (int n = 0; n < 2; ++n) _Pragma("unroll") for (int k = 0; k < 2; ++k) dst[n][k] = *(const PG8_LAS bf16x8*)(lds + PG8_SB(b, h) + boff + n * 2048 + k * 1024); } while (0)
; #define PG8_MMA(ai, bj, At, Bt) do { __builtin_amdgcn_s_setprio(1); _Pragma("unroll") for (int m = 0; m < 4; ++m) _Pragma("unroll") for (int n = 0; n < 2; ++n) _Pragma("unroll") for (int k = 0; k < 2; ++k) \
;         acc[ai][bj][m][n] = __builtin_amdgcn_mfma_f32_16x16x32_bf16(Bt[n][k], At[m][k], acc[ai][bj][m][n], 0, 0, 0); __builtin_amdgcn_s_setprio(0); } while (0)
; #define PG8_WAIT_V(n) asm volatile("s_waitcnt vmcnt(" #n ")" ::: "memory")
; #define PG8_WAIT_L(n) asm volatile("s_waitcnt lgkmcnt(" #n ")" ::: "memory")
; #define PG8_BAR __builtin_amdgcn_s_barrier()
; #define PG8_SCHED __builtin_amdgcn_sched_barrier(0)
; template <class Epi>
; __device__ __forceinline__ void gemm_phase(PG8_LAS unsigned char* lds, PG8_LAS unsigned char* xl, const Gemm g, const Sched& S, const Epi& E, const int wid) {
;     ...
;             PG8_WAIT_V(8); PG8_WAIT_L(0); PG8_BAR; if (do0) { PG8_MMA(0, 0, At, B0); PG8_MMA(0, 1, At, B1); } PG8_BAR; PG8_SCHED;
;             PG8_LDA(At, 0, 1); PG8_STAGE(PG8_SB(0, 0), b2, voffB); PG8_STAGE(PG8_SB(0, 1), b2 + hstepB, voffB); PG8_STAGE(PG8_SA(0, 0), a2, voffA);
;             PG8_WAIT_V(8); PG8_WAIT_L(0); PG8_BAR; if (do1) { PG8_MMA(1, 0, At, B0); PG8_MMA(1, 1, At, B1); } PG8_BAR; PG8_SCHED;
;             PG8_LDB(B0, 1, 0); PG8_LDB(B1, 1, 1); PG8_SCHED; PG8_LDA(At, 1, 0); PG8_STAGE(PG8_SA(0, 1), a2 + hstepA, voffA);
;             PG8_WAIT_V(8); PG8_WAIT_L(0); PG8_BAR; if (do0) { PG8_MMA(0, 0, At, B0); PG8_MMA(0, 1, At, B1); } PG8_BAR; PG8_SCHED;
	s_setprio 0
	s_add_i32 s11, s11, s29
	v_lshl_add_u64 v[190:191], s[76:77], 0, v[132:133]
	s_mov_b32 m0, s11
	ds_read_b128 v[174:177], v141 offset:16384
	ds_read_b128 v[178:181], v141 offset:17408
	ds_read_b128 v[182:185], v141 offset:18432
	ds_read_b128 v[186:189], v141 offset:19456
	ds_read_b128 v[210:213], v141 offset:20480
	ds_read_b128 v[214:217], v141 offset:21504
	ds_read_b128 v[218:221], v141 offset:22528
	ds_read_b128 v[222:225], v141 offset:23552
	global_load_lds_dwordx4 v[190:191], off
	s_add_i32 m0, s11, 0x2000
	s_add_u32 s54, s76, 0x100000
	v_lshl_add_u64 v[226:227], s[76:77], 0, v[128:129]
	s_addc_u32 s55, s77, 0
	s_add_i32 s11, s21, s29
	global_load_lds_dwordx4 v[226:227], off
	v_lshl_add_u64 v[228:229], s[54:55], 0, v[132:133]
	s_mov_b32 m0, s11
	v_lshl_add_u64 v[230:231], s[40:41], 0, v[130:131]
	global_load_lds_dwordx4 v[228:229], off
	v_lshl_add_u64 v[228:229], s[54:55], 0, v[128:129]
	s_add_i32 m0, s11, 0x2000
	s_nop 0
	global_load_lds_dwordx4 v[228:229], off
	v_lshl_add_u64 v[228:229], s[40:41], 0, v[134:135]
	s_mov_b32 m0, s13
	s_nop 0
	global_load_lds_dwordx4 v[228:229], off
	s_mov_b32 m0, s69
	s_nop 0
	global_load_lds_dwordx4 v[230:231], off
	s_waitcnt vmcnt(8)
	s_waitcnt lgkmcnt(0)
	s_setprio 1
	s_barrier
	v_mfma_f32_16x16x32_bf16 v[60:63], v[142:145], v[174:177], v[60:63]
	v_mfma_f32_16x16x32_bf16 v[56:59], v[150:153], v[174:177], v[56:59]
	v_mfma_f32_16x16x32_bf16 v[52:55], v[142:145], v[182:185], v[52:55]
	v_mfma_f32_16x16x32_bf16 v[44:47], v[150:153], v[182:185], v[44:47]
	v_mfma_f32_16x16x32_bf16 v[36:39], v[142:145], v[210:213], v[36:39]
	v_mfma_f32_16x16x32_bf16 v[28:31], v[150:153], v[210:213], v[28:31]
	v_mfma_f32_16x16x32_bf16 v[20:23], v[142:145], v[218:221], v[20:23]
	v_mfma_f32_16x16x32_bf16 v[12:15], v[150:153], v[218:221], v[12:15]
	v_mfma_f32_16x16x32_bf16 v[60:63], v[146:149], v[178:181], v[60:63]
	v_mfma_f32_16x16x32_bf16 v[56:59], v[154:157], v[178:181], v[56:59]
	v_mfma_f32_16x16x32_bf16 v[52:55], v[146:149], v[186:189], v[52:55]
	v_mfma_f32_16x16x32_bf16 v[44:47], v[154:157], v[186:189], v[44:47]
	v_mfma_f32_16x16x32_bf16 v[36:39], v[146:149], v[214:217], v[36:39]
	v_mfma_f32_16x16x32_bf16 v[28:31], v[154:157], v[214:217], v[28:31]
	v_mfma_f32_16x16x32_bf16 v[20:23], v[146:149], v[222:225], v[20:23]
	v_mfma_f32_16x16x32_bf16 v[12:15], v[154:157], v[222:225], v[12:15]
	s_setprio 0
	s_setprio 1
	v_mfma_f32_16x16x32_bf16 v[48:51], v[158:161], v[174:177], v[48:51]
	v_mfma_f32_16x16x32_bf16 v[40:43], v[166:169], v[174:177], v[40:43]
	v_mfma_f32_16x16x32_bf16 v[32:35], v[158:161], v[182:185], v[32:35]
	v_mfma_f32_16x16x32_bf16 v[24:27], v[166:169], v[182:185], v[24:27]
	v_mfma_f32_16x16x32_bf16 v[16:19], v[158:161], v[210:213], v[16:19]
	v_mfma_f32_16x16x32_bf16 v[8:11], v[166:169], v[210:213], v[8:11]
	v_mfma_f32_16x16x32_bf16 v[4:7], v[158:161], v[218:221], v[4:7]
	v_mfma_f32_16x16x32_bf16 v[0:3], v[166:169], v[218:221], v[0:3]
	v_mfma_f32_16x16x32_bf16 v[48:51], v[162:165], v[178:181], v[48:51]
	v_mfma_f32_16x16x32_bf16 v[40:43], v[170:173], v[178:181], v[40:43]
	v_mfma_f32_16x16x32_bf16 v[32:35], v[162:165], v[186:189], v[32:35]
	v_mfma_f32_16x16x32_bf16 v[24:27], v[170:173], v[186:189], v[24:27]
	v_mfma_f32_16x16x32_bf16 v[16:19], v[162:165], v[214:217], v[16:19]
	v_mfma_f32_16x16x32_bf16 v[8:11], v[170:173], v[214:217], v[8:11]
	v_mfma_f32_16x16x32_bf16 v[4:7], v[162:165], v[222:225], v[4:7]
	v_mfma_f32_16x16x32_bf16 v[0:3], v[170:173], v[222:225], v[0:3]
	s_barrier
	s_setprio 0
	s_add_i32 s11, 0, 0x18000
	s_add_i32 s21, 0, 0x1c000
	v_add_u32_e32 v154, s11, v140
	v_add_u32_e32 v170, s21, v140
	ds_read_b128 v[142:145], v154
	ds_read_b128 v[146:149], v154 offset:1024
	ds_read_b128 v[150:153], v154 offset:2048
	ds_read_b128 v[154:157], v154 offset:3072
	ds_read_b128 v[158:161], v170
	ds_read_b128 v[162:165], v170 offset:1024
	ds_read_b128 v[166:169], v170 offset:2048
	ds_read_b128 v[170:173], v170 offset:3072
	s_add_u32 s40, s40, 0x80000
	s_addc_u32 s41, s41, 0
	s_mov_b32 m0, s70
	v_lshl_add_u64 v[232:233], s[40:41], 0, v[134:135]
	ds_read_b128 v[174:177], v141 offset:32768
	ds_read_b128 v[178:181], v141 offset:33792
	ds_read_b128 v[182:185], v141 offset:34816
	ds_read_b128 v[186:189], v141 offset:35840
	ds_read_b128 v[210:213], v141 offset:36864
	ds_read_b128 v[214:217], v141 offset:37888
	ds_read_b128 v[218:221], v141 offset:38912
	ds_read_b128 v[222:225], v141 offset:39936
	global_load_lds_dwordx4 v[232:233], off
	v_lshl_add_u64 v[232:233], s[40:41], 0, v[130:131]
	s_mov_b32 m0, s71
	s_nop 0
	global_load_lds_dwordx4 v[232:233], off
	s_waitcnt vmcnt(8)
	s_waitcnt lgkmcnt(0)
	s_setprio 1
	s_barrier
; #define PG8_STAGE(bufoff, gbase, voff) do { _Pragma("unroll") for (int _i = 0; _i < 2; ++_i) \
;         __builtin_amdgcn_global_load_lds((const unsigned*)((const char*)(gbase) + (voff)[_i]), (PG8_LAS unsigned*)(lds + (bufoff) + ldsw + _i * 8192), 16, 0, 0); } while (0)
; #define PG8_LDA(dst, b, h) do { _Pragma("unroll") for (int m = 0; m < 4; ++m) _Pragma("unroll") for (int k = 0; k < 2; ++k) dst[m][k] = *(const PG8_LAS bf16x8*)(lds + PG8_SA(b, h) + aoff + m * 2048 + k * 1024); } while (0)
; #define PG8_MMA(ai, bj, At, Bt) do { __builtin_amdgcn_s_setprio(1); _Pragma("unroll") for (int m = 0; m < 4; ++m) _Pragma("unroll") for (int n = 0; n < 2; ++n) _Pragma("unroll") for (int k = 0; k < 2; ++k) \
;         acc[ai][bj][m][n] = __builtin_amdgcn_mfma_f32_16x16x32_bf16(Bt[n][k], At[m][k], acc[ai][bj][m][n], 0, 0, 0); __builtin_amdgcn_s_setprio(0); } while (0)
; #define PG8_WAIT_V(n) asm volatile("s_waitcnt vmcnt(" #n ")" ::: "memory")
; #define PG8_WAIT_L(n) asm volatile("s_waitcnt lgkmcnt(" #n ")" ::: "memory")
; #define PG8_BAR __builtin_amdgcn_s_barrier()
; #define PG8_SCHED __builtin_amdgcn_sched_barrier(0)
; template <class Epi>
; __device__ __forceinline__ void gemm_phase(PG8_LAS unsigned char* lds, PG8_LAS unsigned char* xl, const Gemm g, const Sched& S, const Epi& E, const int wid) {
;     ...
;             PG8_WAIT_V(8); PG8_WAIT_L(0); PG8_BAR; if (do0) { PG8_MMA(0, 0, At, B0); PG8_MMA(0, 1, At, B1); } PG8_BAR; PG8_SCHED;
;             PG8_LDA(At, 1, 1); PG8_STAGE(PG8_SB(1, 0), b3, voffB); PG8_STAGE(PG8_SB(1, 1), b3 + hstepB, voffB); PG8_STAGE(PG8_SA(1, 0), a3, voffA);
;             PG8_WAIT_V(8); PG8_WAIT_L(0); PG8_BAR; if (do1) { PG8_MMA(1, 0, At, B0); PG8_MMA(1, 1, At, B1); } PG8_BAR; PG8_SCHED;
;         }
;         if (wr == 0) PG8_BAR;
	v_mfma_f32_16x16x32_bf16 v[124:127], v[142:145], v[174:177], v[124:127]
	v_mfma_f32_16x16x32_bf16 v[120:123], v[150:153], v[174:177], v[120:123]
	v_mfma_f32_16x16x32_bf16 v[116:119], v[142:145], v[182:185], v[116:119]
	v_mfma_f32_16x16x32_bf16 v[108:111], v[150:153], v[182:185], v[108:111]
	v_mfma_f32_16x16x32_bf16 v[100:103], v[142:145], v[210:213], v[100:103]
	v_mfma_f32_16x16x32_bf16 v[92:95], v[150:153], v[210:213], v[92:95]
	v_mfma_f32_16x16x32_bf16 v[84:87], v[142:145], v[218:221], v[84:87]
	v_mfma_f32_16x16x32_bf16 v[76:79], v[150:153], v[218:221], v[76:79]
	v_mfma_f32_16x16x32_bf16 v[124:127], v[146:149], v[178:181], v[124:127]
	v_mfma_f32_16x16x32_bf16 v[120:123], v[154:157], v[178:181], v[120:123]
	v_mfma_f32_16x16x32_bf16 v[116:119], v[146:149], v[186:189], v[116:119]
	v_mfma_f32_16x16x32_bf16 v[108:111], v[154:157], v[186:189], v[108:111]
	v_mfma_f32_16x16x32_bf16 v[100:103], v[146:149], v[214:217], v[100:103]
	v_mfma_f32_16x16x32_bf16 v[92:95], v[154:157], v[214:217], v[92:95]
	v_mfma_f32_16x16x32_bf16 v[84:87], v[146:149], v[222:225], v[84:87]
	v_mfma_f32_16x16x32_bf16 v[76:79], v[154:157], v[222:225], v[76:79]
	s_setprio 0
	s_setprio 1
	v_mfma_f32_16x16x32_bf16 v[112:115], v[158:161], v[174:177], v[112:115]
	v_mfma_f32_16x16x32_bf16 v[104:107], v[166:169], v[174:177], v[104:107]
	v_mfma_f32_16x16x32_bf16 v[96:99], v[158:161], v[182:185], v[96:99]
	v_mfma_f32_16x16x32_bf16 v[88:91], v[166:169], v[182:185], v[88:91]
	v_mfma_f32_16x16x32_bf16 v[80:83], v[158:161], v[210:213], v[80:83]
	v_mfma_f32_16x16x32_bf16 v[72:75], v[166:169], v[210:213], v[72:75]
	v_mfma_f32_16x16x32_bf16 v[68:71], v[158:161], v[218:221], v[68:71]
	v_mfma_f32_16x16x32_bf16 v[64:67], v[166:169], v[218:221], v[64:67]
	v_mfma_f32_16x16x32_bf16 v[112:115], v[162:165], v[178:181], v[112:115]
	v_mfma_f32_16x16x32_bf16 v[104:107], v[170:173], v[178:181], v[104:107]
	v_mfma_f32_16x16x32_bf16 v[96:99], v[162:165], v[186:189], v[96:99]
	v_mfma_f32_16x16x32_bf16 v[88:91], v[170:173], v[186:189], v[88:91]
	v_mfma_f32_16x16x32_bf16 v[80:83], v[162:165], v[214:217], v[80:83]
	v_mfma_f32_16x16x32_bf16 v[72:75], v[170:173], v[214:217], v[72:75]
	v_mfma_f32_16x16x32_bf16 v[68:71], v[162:165], v[222:225], v[68:71]
	v_mfma_f32_16x16x32_bf16 v[64:67], v[170:173], v[222:225], v[64:67]
	s_barrier
	s_setprio 0
	s_add_i32 s11, s11, s29
	v_lshl_add_u64 v[190:191], v[190:191], 0, s[22:23]
	s_mov_b32 m0, s11
	ds_read_b128 v[174:177], v141 offset:49152
	ds_read_b128 v[178:181], v141 offset:50176
	ds_read_b128 v[182:185], v141 offset:51200
	ds_read_b128 v[186:189], v141 offset:52224
	ds_read_b128 v[210:213], v141 offset:53248
	ds_read_b128 v[214:217], v141 offset:54272
	ds_read_b128 v[218:221], v141 offset:55296
	ds_read_b128 v[222:225], v141 offset:56320
	global_load_lds_dwordx4 v[190:191], off
	s_add_i32 m0, s11, 0x2000
	s_add_u32 s40, s76, 0x100080
	v_lshl_add_u64 v[190:191], v[226:227], 0, s[22:23]
	s_addc_u32 s41, s77, 0
	s_add_i32 s11, s21, s29
	global_load_lds_dwordx4 v[190:191], off
	v_lshl_add_u64 v[190:191], s[40:41], 0, v[132:133]
	s_mov_b32 m0, s11
	s_nop 0
	global_load_lds_dwordx4 v[190:191], off
	v_lshl_add_u64 v[190:191], s[40:41], 0, v[128:129]
	s_add_i32 m0, s11, 0x2000
	s_nop 0
	global_load_lds_dwordx4 v[190:191], off
	v_lshl_add_u64 v[190:191], v[228:229], 0, s[22:23]
	s_mov_b32 m0, s90
	s_nop 0
	global_load_lds_dwordx4 v[190:191], off
	v_lshl_add_u64 v[190:191], v[230:231], 0, s[22:23]
	s_mov_b32 m0, s91
	s_nop 0
	global_load_lds_dwordx4 v[190:191], off
	s_waitcnt vmcnt(8)
	s_waitcnt lgkmcnt(0)
	s_setprio 1
	s_barrier
	v_mfma_f32_16x16x32_bf16 v[60:63], v[142:145], v[174:177], v[60:63]
	v_mfma_f32_16x16x32_bf16 v[56:59], v[150:153], v[174:177], v[56:59]
	v_mfma_f32_16x16x32_bf16 v[52:55], v[142:145], v[182:185], v[52:55]
	v_mfma_f32_16x16x32_bf16 v[44:47], v[150:153], v[182:185], v[44:47]
	v_mfma_f32_16x16x32_bf16 v[36:39], v[142:145], v[210:213], v[36:39]
	v_mfma_f32_16x16x32_bf16 v[28:31], v[150:153], v[210:213], v[28:31]
	v_mfma_f32_16x16x32_bf16 v[20:23], v[142:145], v[218:221], v[20:23]
	v_mfma_f32_16x16x32_bf16 v[12:15], v[150:153], v[218:221], v[12:15]
	v_mfma_f32_16x16x32_bf16 v[60:63], v[146:149], v[178:181], v[60:63]
	v_mfma_f32_16x16x32_bf16 v[56:59], v[154:157], v[178:181], v[56:59]
	v_mfma_f32_16x16x32_bf16 v[52:55], v[146:149], v[186:189], v[52:55]
	v_mfma_f32_16x16x32_bf16 v[44:47], v[154:157], v[186:189], v[44:47]
	v_mfma_f32_16x16x32_bf16 v[36:39], v[146:149], v[214:217], v[36:39]
	v_mfma_f32_16x16x32_bf16 v[28:31], v[154:157], v[214:217], v[28:31]
	v_mfma_f32_16x16x32_bf16 v[20:23], v[146:149], v[222:225], v[20:23]
	v_mfma_f32_16x16x32_bf16 v[12:15], v[154:157], v[222:225], v[12:15]
	s_setprio 0
	s_setprio 1
	v_mfma_f32_16x16x32_bf16 v[48:51], v[158:161], v[174:177], v[48:51]
	v_mfma_f32_16x16x32_bf16 v[40:43], v[166:169], v[174:177], v[40:43]
	v_mfma_f32_16x16x32_bf16 v[32:35], v[158:161], v[182:185], v[32:35]
	v_mfma_f32_16x16x32_bf16 v[24:27], v[166:169], v[182:185], v[24:27]
	v_mfma_f32_16x16x32_bf16 v[16:19], v[158:161], v[210:213], v[16:19]
	v_mfma_f32_16x16x32_bf16 v[8:11], v[166:169], v[210:213], v[8:11]
	v_mfma_f32_16x16x32_bf16 v[4:7], v[158:161], v[218:221], v[4:7]
	v_mfma_f32_16x16x32_bf16 v[0:3], v[166:169], v[218:221], v[0:3]
	v_mfma_f32_16x16x32_bf16 v[48:51], v[162:165], v[178:181], v[48:51]
	v_mfma_f32_16x16x32_bf16 v[40:43], v[170:173], v[178:181], v[40:43]
	v_mfma_f32_16x16x32_bf16 v[32:35], v[162:165], v[186:189], v[32:35]
	v_mfma_f32_16x16x32_bf16 v[24:27], v[170:173], v[186:189], v[24:27]
	v_mfma_f32_16x16x32_bf16 v[16:19], v[162:165], v[214:217], v[16:19]
	v_mfma_f32_16x16x32_bf16 v[8:11], v[170:173], v[214:217], v[8:11]
	v_mfma_f32_16x16x32_bf16 v[4:7], v[162:165], v[222:225], v[4:7]
	v_mfma_f32_16x16x32_bf16 v[0:3], v[170:173], v[222:225], v[0:3]
	s_barrier
	s_setprio 0
	s_add_i32 s10, s10, 2
	s_add_u32 s8, s8, 0x100
	s_addc_u32 s9, s9, 0
	s_cmp_gt_u32 s10, 5
	s_mov_b64 s[58:59], s[60:61]
	s_cbranch_scc0 .LBB0_428
	s_and_b64 vcc, exec, s[14:15]
	s_cbranch_vccz .LBB0_431
	s_barrier
; #define ACT4(v, F) do { const f32x2 _lo = F((f32x2){v[0], v[1]}), _hi = F((f32x2){v[2], v[3]}); v = (f32x4){_lo.x, _lo.y, _hi.x, _hi.y}; } while (0)
; #define PACK8(w, v0, v1) do { w.x = cvt_pk_bf16(v0[0], v0[1]); w.y = cvt_pk_bf16(v0[2], v0[3]); w.z = cvt_pk_bf16(v1[0], v1[1]); w.w = cvt_pk_bf16(v1[2], v1[3]); } while (0)
; #define PG8_BAR __builtin_amdgcn_s_barrier()
;     __device__ __forceinline__ void operator()(EPI_ARGS) const {
;     ...
; #pragma unroll
;         for (int ai = 0; ai < 2; ++ai)
; #pragma unroll
;             for (int m = 0; m < 4; ++m) { char* rb = ub + (size_t)(ai * HALF + m) * ldc * 2;
;                 float s1 = 0.f, s2 = 0.f;
; #pragma unroll
;                 for (int bj = 0; bj < 2; ++bj) { f32x4 v0 = acc[ai][bj][m][0] * rs[ai][m], v1 = acc[ai][bj][m][1] * rs[ai][m];
;                     if (act == 1) { ACT4(v0, gelu_t2); ACT4(v1, gelu_t2); }
;                     else if (act == 2) { ACT4(v0, sigm2); ACT4(v1, sigm2); }
;                     u32x4 w; PACK8(w, v0, v1);
;                     *(u32x4*)(rb + lo + bj * 256) = w;
; template <class Epi>
; __device__ __forceinline__ void gemm_phase(PG8_LAS unsigned char* lds, PG8_LAS unsigned char* xl, const Gemm g, const Sched& S, const Epi& E, const int wid) {
;     ...
;         if (!has_next) break;
; #pragma unroll
;         for (int a = 0; a < 2; ++a)
; #pragma unroll
;             for (int b = 0; b < 2; ++b)
; #pragma unroll
;                 for (int m = 0; m < 4; ++m)
; #pragma unroll
;                     for (int n = 0; n < 2; ++n) acc[a][b][m][n] = (f32x4){0.f, 0.f, 0.f, 0.f};
;         cur = nxt; cA = nA; cB = nB; ++ui;
;         if (wr == 1) PG8_BAR;
.LBB0_431:
	s_ashr_i32 s49, s48, 31
	s_lshl_b64 s[8:9], s[48:49], 22
	s_add_u32 s10, s88, s8
	s_addc_u32 s11, s89, s9
	s_ashr_i32 s45, s44, 31
	s_lshl_b64 s[8:9], s[44:45], 9
	s_add_u32 s10, s10, s8
	s_addc_u32 s11, s11, s9
	s_ashr_i32 s21, s20, 31
	s_lshl_b64 s[8:9], s[20:21], 19
	s_add_u32 s10, s10, s8
	s_addc_u32 s11, s11, s9
	s_lshl_b32 s8, s12, 8
	v_mbcnt_lo_u32_b32 v142, -1, 0
	v_mbcnt_hi_u32_b32 v142, -1, v142
	s_ashr_i32 s9, s8, 31
	v_lshlrev_b32_e32 v143, 2, v142
	v_and_or_b32 v143, v143, 60, s3
	s_lshl_b64 s[8:9], s[8:9], 1
	v_and_b32_e32 v142, -16, v142
	v_lshlrev_b32_e32 v143, 11, v143
	s_add_u32 s8, s10, s8
	v_add3_u32 v192, v142, s75, v143
	s_addc_u32 s9, s11, s9
	v_lshl_add_u64 v[142:143], s[8:9], 0, v[192:193]
	v_cvt_pk_bf16_f32 v124, v124, v125
	v_cvt_pk_bf16_f32 v125, v126, v127
	v_cvt_pk_bf16_f32 v126, v120, v121
	v_cvt_pk_bf16_f32 v127, v122, v123
	global_store_dwordx4 v192, v[124:127], s[8:9]
	v_cvt_pk_bf16_f32 v112, v112, v113
	v_cvt_pk_bf16_f32 v113, v114, v115
	v_cvt_pk_bf16_f32 v114, v104, v105
	v_cvt_pk_bf16_f32 v115, v106, v107
	global_store_dwordx4 v192, v[112:115], s[8:9] offset:256
	v_cvt_pk_bf16_f32 v104, v116, v117
	v_cvt_pk_bf16_f32 v105, v118, v119
	v_cvt_pk_bf16_f32 v106, v108, v109
	v_cvt_pk_bf16_f32 v107, v110, v111
	global_store_dwordx4 v192, v[104:107], s[8:9] offset:2048
	v_cvt_pk_bf16_f32 v96, v96, v97
	v_cvt_pk_bf16_f32 v97, v98, v99
	v_cvt_pk_bf16_f32 v98, v88, v89
	v_cvt_pk_bf16_f32 v99, v90, v91
	global_store_dwordx4 v192, v[96:99], s[8:9] offset:2304
	v_cvt_pk_bf16_f32 v88, v100, v101
	v_cvt_pk_bf16_f32 v89, v102, v103
	v_cvt_pk_bf16_f32 v90, v92, v93
	v_add_co_u32_e32 v92, vcc, s25, v142
	v_cvt_pk_bf16_f32 v91, v94, v95
	s_mov_b64 s[8:9], -1
	s_nop 0
	v_addc_co_u32_e32 v93, vcc, 0, v143, vcc
	global_store_dwordx4 v[92:93], v[88:91], off
	v_cvt_pk_bf16_f32 v80, v80, v81
	v_cvt_pk_bf16_f32 v81, v82, v83
	v_cvt_pk_bf16_f32 v82, v72, v73
	v_cvt_pk_bf16_f32 v83, v74, v75
	global_store_dwordx4 v[92:93], v[80:83], off offset:256
	v_cvt_pk_bf16_f32 v72, v84, v85
	v_cvt_pk_bf16_f32 v73, v86, v87
	v_cvt_pk_bf16_f32 v74, v76, v77
	v_cvt_pk_bf16_f32 v75, v78, v79
	global_store_dwordx4 v[92:93], v[72:75], off offset:2048
	v_cvt_pk_bf16_f32 v68, v68, v69
	v_cvt_pk_bf16_f32 v69, v70, v71
	v_cvt_pk_bf16_f32 v70, v64, v65
	v_cvt_pk_bf16_f32 v71, v66, v67
	global_store_dwordx4 v[92:93], v[68:71], off offset:2304
	v_cvt_pk_bf16_f32 v60, v60, v61
	v_cvt_pk_bf16_f32 v61, v62, v63
	v_cvt_pk_bf16_f32 v62, v56, v57
	v_add_co_u32_e32 v56, vcc, s5, v142
	v_cvt_pk_bf16_f32 v63, v58, v59
	s_nop 1
	v_addc_co_u32_e32 v57, vcc, 0, v143, vcc
	v_add_co_u32_e32 v58, vcc, s72, v142
	s_nop 1
	v_addc_co_u32_e32 v59, vcc, 0, v143, vcc
	s_and_b64 vcc, exec, s[42:43]
	global_store_dwordx4 v[58:59], v[60:63], off offset:-4096
	v_cvt_pk_bf16_f32 v48, v48, v49
	v_cvt_pk_bf16_f32 v49, v50, v51
	v_cvt_pk_bf16_f32 v50, v40, v41
	v_cvt_pk_bf16_f32 v51, v42, v43
	global_store_dwordx4 v[56:57], v[48:51], off offset:256
	v_cvt_pk_bf16_f32 v40, v52, v53
	v_cvt_pk_bf16_f32 v41, v54, v55
	v_cvt_pk_bf16_f32 v42, v44, v45
	v_cvt_pk_bf16_f32 v43, v46, v47
	global_store_dwordx4 v[56:57], v[40:43], off offset:2048
	v_cvt_pk_bf16_f32 v32, v32, v33
	v_cvt_pk_bf16_f32 v33, v34, v35
	v_cvt_pk_bf16_f32 v34, v24, v25
	v_cvt_pk_bf16_f32 v35, v26, v27
	global_store_dwordx4 v[56:57], v[32:35], off offset:2304
	v_cvt_pk_bf16_f32 v24, v36, v37
	v_cvt_pk_bf16_f32 v25, v38, v39
	v_cvt_pk_bf16_f32 v26, v28, v29
	v_cvt_pk_bf16_f32 v27, v30, v31
	global_store_dwordx4 v[58:59], v[24:27], off
	v_cvt_pk_bf16_f32 v16, v16, v17
	v_cvt_pk_bf16_f32 v17, v18, v19
	v_cvt_pk_bf16_f32 v18, v8, v9
	v_cvt_pk_bf16_f32 v19, v10, v11
	global_store_dwordx4 v[58:59], v[16:19], off offset:256
	v_cvt_pk_bf16_f32 v8, v20, v21
	v_cvt_pk_bf16_f32 v9, v22, v23
	v_cvt_pk_bf16_f32 v10, v12, v13
	v_cvt_pk_bf16_f32 v11, v14, v15
	global_store_dwordx4 v[58:59], v[8:11], off offset:2048
	v_cvt_pk_bf16_f32 v4, v4, v5
	v_cvt_pk_bf16_f32 v5, v6, v7
	v_cvt_pk_bf16_f32 v6, v0, v1
	v_cvt_pk_bf16_f32 v7, v2, v3
	global_store_dwordx4 v[58:59], v[4:7], off offset:2304
	s_cbranch_vccnz .LBB0_420
	s_and_b64 vcc, exec, s[38:39]
	s_cbranch_vccnz .LBB0_419
	s_mov_b32 s100, 1
	s_branch .LBB0_419

; __device__ __forceinline__ int lane_id_opq() { int l; asm volatile("v_mbcnt_lo_u32_b32 %0, -1, 0\n\tv_mbcnt_hi_u32_b32 %0, -1, %0" : "=v"(l)); return l; }
; #define PG8_STAGE(bufoff, gbase, voff) do { _Pragma("unroll") for (int _i = 0; _i < 2; ++_i) \
;         __builtin_amdgcn_global_load_lds((const unsigned*)((const char*)(gbase) + (voff)[_i]), (PG8_LAS unsigned*)(lds + (bufoff) + ldsw + _i * 8192), 16, 0, 0); } while (0)
; #define PG8_LDA(dst, b, h) do { _Pragma("unroll") for (int m = 0; m < 4; ++m) _Pragma("unroll") for (int k = 0; k < 2; ++k) dst[m][k] = *(const PG8_LAS bf16x8*)(lds + PG8_SA(b, h) + aoff + m * 2048 + k * 1024); } while (0)
; #define PG8_WAIT_V(n) asm volatile("s_waitcnt vmcnt(" #n ")" ::: "memory")
; template <class Epi>
; __device__ __forceinline__ void gemm_phase(PG8_LAS unsigned char* lds, PG8_LAS unsigned char* xl, const Gemm g, const Sched& S, const Epi& E, const int wid) {
;     ...
;         for (int t = 0; t < nt; t += 2) {
;             const bool last = (t == nt - 2);
;             const bool do0 = !blkdiag_v<Epi> || t == 0, do1 = !blkdiag_v<Epi> || t != 0;
;             long j1 = 0, ja2 = 0, jb2 = 0;
;             if constexpr (Epi::MID) {
;                 if (t == g.tj) { const int lnM = lane_id_opq(); E.mid(acc, cur, wr, wc, lnM & 15, lnM >> 4); }
;                 if (t >= g.tj) j1 = g.jA;
;                 if (t + 2 >= g.tj) { ja2 = g.jA; jb2 = g.jB; } }
;             const char* a1 = cA + (size_t)(t + 1) * kstep + j1;
;             const char* a2 = last ? nA : cA + (size_t)(t + 2) * kstep + ja2; const char* b2 = last ? nB : cB + (size_t)(t + 2) * kstep + jb2;
;             const char* a3 = a2 + kstep; const char* b3 = b2 + kstep;
;             PG8_LDB(B0, 0, 0); PG8_LDB(B1, 0, 1); PG8_SCHED; PG8_LDA(At, 0, 0); PG8_STAGE(PG8_SA(1, 1), a1 + hstepA, voffA);
;             PG8_WAIT_V(8); PG8_WAIT_L(0); PG8_BAR; if (do0) { PG8_MMA(0, 0, At, B0); PG8_MMA(0, 1, At, B1); } PG8_BAR; PG8_SCHED;
;             PG8_LDA(At, 0, 1); PG8_STAGE(PG8_SB(0, 0), b2, voffB); PG8_STAGE(PG8_SB(0, 1), b2 + hstepB, voffB); PG8_STAGE(PG8_SA(0, 0), a2, voffA);
;             PG8_WAIT_V(8); PG8_WAIT_L(0); PG8_BAR; if (do1) { PG8_MMA(1, 0, At, B0); PG8_MMA(1, 1, At, B1); } PG8_BAR; PG8_SCHED;
;             PG8_LDB(B0, 1, 0); PG8_LDB(B1, 1, 1); PG8_SCHED; PG8_LDA(At, 1, 0); PG8_STAGE(PG8_SA(0, 1), a2 + hstepA, voffA);
.LBB0_510:
	s_add_i32 s31, 0, 0x10000
	s_add_i32 s37, 0, 0x14000
	v_add_u32_e32 v188, s31, v195
	v_add_u32_e32 v189, s37, v195
	ds_read_b128 v[0:3], v188
	ds_read_b128 v[4:7], v188 offset:1024
	ds_read_b128 v[8:11], v188 offset:2048
	ds_read_b128 v[12:15], v188 offset:3072
	ds_read_b128 v[16:19], v189
	ds_read_b128 v[20:23], v189 offset:1024
	ds_read_b128 v[24:27], v189 offset:2048
	ds_read_b128 v[28:31], v189 offset:3072
	s_add_u32 s10, s60, 0x10080
	s_addc_u32 s11, s61, 0
	s_add_i32 s41, s51, 0xc000
	v_lshl_add_u64 v[64:65], s[10:11], 0, v[216:217]
	s_mov_b32 m0, s41
	ds_read_b128 v[32:35], v248
	ds_read_b128 v[36:39], v248 offset:1024
	ds_read_b128 v[40:43], v248 offset:2048
	ds_read_b128 v[44:47], v248 offset:3072
	ds_read_b128 v[48:51], v248 offset:4096
	ds_read_b128 v[52:55], v248 offset:5120
	ds_read_b128 v[56:59], v248 offset:6144
	ds_read_b128 v[60:63], v248 offset:7168
	global_load_lds_dwordx4 v[64:65], off
	v_lshl_add_u64 v[64:65], s[10:11], 0, v[212:213]
	s_add_i32 s10, s51, 0xe000
	s_mov_b32 m0, s10
	s_nop 0
	global_load_lds_dwordx4 v[64:65], off
	s_waitcnt vmcnt(8)
	s_waitcnt lgkmcnt(0)
	s_setprio 1
	s_barrier
	v_mfma_f32_16x16x32_bf16 v[64:67], v[0:3], v[32:35], 0
	v_mfma_f32_16x16x32_bf16 v[72:75], v[0:3], v[40:43], 0
	v_mfma_f32_16x16x32_bf16 v[80:83], v[0:3], v[48:51], 0
	v_mfma_f32_16x16x32_bf16 v[0:3], v[0:3], v[56:59], 0
	v_mfma_f32_16x16x32_bf16 v[64:67], v[4:7], v[36:39], v[64:67]
	v_mfma_f32_16x16x32_bf16 v[72:75], v[4:7], v[44:47], v[72:75]
	v_mfma_f32_16x16x32_bf16 v[76:79], v[8:11], v[40:43], 0
	v_mfma_f32_16x16x32_bf16 v[80:83], v[4:7], v[52:55], v[80:83]
	v_mfma_f32_16x16x32_bf16 v[84:87], v[8:11], v[48:51], 0
	v_mfma_f32_16x16x32_bf16 v[0:3], v[4:7], v[60:63], v[0:3]
	v_mfma_f32_16x16x32_bf16 v[4:7], v[8:11], v[56:59], 0
	v_mfma_f32_16x16x32_bf16 v[68:71], v[8:11], v[32:35], 0
	v_mfma_f32_16x16x32_bf16 v[76:79], v[12:15], v[44:47], v[76:79]
	v_mfma_f32_16x16x32_bf16 v[84:87], v[12:15], v[52:55], v[84:87]
	v_mfma_f32_16x16x32_bf16 v[4:7], v[12:15], v[60:63], v[4:7]
	v_mfma_f32_16x16x32_bf16 v[68:71], v[12:15], v[36:39], v[68:71]
	s_setprio 0
	s_setprio 1
	v_mfma_f32_16x16x32_bf16 v[8:11], v[16:19], v[32:35], 0
	v_mfma_f32_16x16x32_bf16 v[12:15], v[24:27], v[32:35], 0
	v_mfma_f32_16x16x32_bf16 v[8:11], v[20:23], v[36:39], v[8:11]
	v_mfma_f32_16x16x32_bf16 v[12:15], v[28:31], v[36:39], v[12:15]
	v_mfma_f32_16x16x32_bf16 v[32:35], v[16:19], v[40:43], 0
	v_mfma_f32_16x16x32_bf16 v[36:39], v[24:27], v[40:43], 0
	v_mfma_f32_16x16x32_bf16 v[40:43], v[16:19], v[48:51], 0
	v_mfma_f32_16x16x32_bf16 v[16:19], v[16:19], v[56:59], 0
	v_mfma_f32_16x16x32_bf16 v[32:35], v[20:23], v[44:47], v[32:35]
	v_mfma_f32_16x16x32_bf16 v[40:43], v[20:23], v[52:55], v[40:43]
	v_mfma_f32_16x16x32_bf16 v[16:19], v[20:23], v[60:63], v[16:19]
	v_mfma_f32_16x16x32_bf16 v[20:23], v[24:27], v[56:59], 0
	v_mfma_f32_16x16x32_bf16 v[36:39], v[28:31], v[44:47], v[36:39]
	v_mfma_f32_16x16x32_bf16 v[44:47], v[24:27], v[48:51], 0
	v_mfma_f32_16x16x32_bf16 v[20:23], v[28:31], v[60:63], v[20:23]
	v_mfma_f32_16x16x32_bf16 v[44:47], v[28:31], v[52:55], v[44:47]
	s_barrier
	s_setprio 0
	s_add_i32 s11, s31, s29
	v_lshl_add_u64 v[172:173], s[76:77], 0, v[214:215]
	s_add_i32 s31, s11, 0x2000
	v_lshl_add_u64 v[24:25], v[172:173], 0, s[70:71]
	s_mov_b32 m0, s11
	v_lshl_add_u64 v[174:175], s[76:77], 0, v[210:211]
	s_add_u32 s48, s76, 0x10100
	global_load_lds_dwordx4 v[24:25], off
	v_lshl_add_u64 v[24:25], v[174:175], 0, s[70:71]
	s_mov_b32 m0, s31
	s_addc_u32 s49, s77, 0
	s_add_i32 s37, s37, s29
	global_load_lds_dwordx4 v[24:25], off
	v_lshl_add_u64 v[24:25], s[48:49], 0, v[214:215]
	s_mov_b32 m0, s37
	s_add_i32 s43, s37, 0x2000
	global_load_lds_dwordx4 v[24:25], off
	v_lshl_add_u64 v[24:25], s[48:49], 0, v[210:211]
	s_mov_b32 m0, s43
	v_lshl_add_u64 v[184:185], s[60:61], 0, v[216:217]
	global_load_lds_dwordx4 v[24:25], off
	v_lshl_add_u64 v[24:25], v[184:185], 0, s[70:71]
	s_mov_b32 m0, s51
	v_lshl_add_u64 v[186:187], s[60:61], 0, v[212:213]
	global_load_lds_dwordx4 v[24:25], off
	v_lshl_add_u64 v[24:25], v[186:187], 0, s[70:71]
	s_mov_b32 m0, s53
	s_nop 0
	global_load_lds_dwordx4 v[24:25], off
	s_waitcnt vmcnt(8)
	s_waitcnt lgkmcnt(0)
	s_barrier
	s_barrier
	s_add_i32 s54, 0, 0x18000
	s_add_i32 s55, 0, 0x1c000
	v_add_u32_e32 v190, s54, v195
	v_add_u32_e32 v191, s55, v195
	ds_read_b128 v[24:27], v190
	ds_read_b128 v[28:31], v190 offset:1024
	ds_read_b128 v[48:51], v190 offset:2048
	ds_read_b128 v[52:55], v190 offset:3072
	ds_read_b128 v[56:59], v191
	ds_read_b128 v[60:63], v191 offset:1024
	ds_read_b128 v[92:95], v191 offset:2048
	ds_read_b128 v[96:99], v191 offset:3072
	s_add_u32 s48, s60, 0x10100
	s_addc_u32 s49, s61, 0
	s_mov_b32 m0, s62
	v_lshl_add_u64 v[104:105], s[48:49], 0, v[216:217]
	ds_read_b128 v[88:91], v248 offset:32768
	ds_read_b128 v[100:103], v248 offset:33792
	ds_read_b128 v[112:115], v248 offset:34816
	ds_read_b128 v[116:119], v248 offset:35840
	ds_read_b128 v[124:127], v248 offset:36864
	ds_read_b128 v[136:139], v248 offset:37888
	ds_read_b128 v[148:151], v248 offset:38912
	ds_read_b128 v[160:163], v248 offset:39936
	global_load_lds_dwordx4 v[104:105], off
	v_lshl_add_u64 v[104:105], s[48:49], 0, v[212:213]
	s_mov_b32 m0, s68
	s_nop 0
	global_load_lds_dwordx4 v[104:105], off
	s_waitcnt vmcnt(8)
	s_waitcnt lgkmcnt(0)
	s_setprio 1
	s_barrier
; #define PG8_STAGE(bufoff, gbase, voff) do { _Pragma("unroll") for (int _i = 0; _i < 2; ++_i) \
;         __builtin_amdgcn_global_load_lds((const unsigned*)((const char*)(gbase) + (voff)[_i]), (PG8_LAS unsigned*)(lds + (bufoff) + ldsw + _i * 8192), 16, 0, 0); } while (0)
; #define PG8_LDA(dst, b, h) do { _Pragma("unroll") for (int m = 0; m < 4; ++m) _Pragma("unroll") for (int k = 0; k < 2; ++k) dst[m][k] = *(const PG8_LAS bf16x8*)(lds + PG8_SA(b, h) + aoff + m * 2048 + k * 1024); } while (0)
; #define PG8_LDB(dst, b, h) do { _Pragma("unroll") for (int n = 0; n < 2; ++n) _Pragma("unroll") for (int k = 0; k < 2; ++k) dst[n][k] = *(const PG8_LAS bf16x8*)(lds + PG8_SB(b, h) + boff + n * 2048 + k * 1024); } while (0)
; #define PG8_MMA(ai, bj, At, Bt) do { __builtin_amdgcn_s_setprio(1); _Pragma("unroll") for (int m = 0; m < 4; ++m) _Pragma("unroll") for (int n = 0; n < 2; ++n) _Pragma("unroll") for (int k = 0; k < 2; ++k) \
;         acc[ai][bj][m][n] = __builtin_amdgcn_mfma_f32_16x16x32_bf16(Bt[n][k], At[m][k], acc[ai][bj][m][n], 0, 0, 0); __builtin_amdgcn_s_setprio(0); } while (0)
; #define PG8_WAIT_V(n) asm volatile("s_waitcnt vmcnt(" #n ")" ::: "memory")
; #define PG8_WAIT_L(n) asm volatile("s_waitcnt lgkmcnt(" #n ")" ::: "memory")
; #define PG8_BAR __builtin_amdgcn_s_barrier()
; #define PG8_SCHED __builtin_amdgcn_sched_barrier(0)
; template <class Epi>
; __device__ __forceinline__ void gemm_phase(PG8_LAS unsigned char* lds, PG8_LAS unsigned char* xl, const Gemm g, const Sched& S, const Epi& E, const int wid) {
;     ...
;             PG8_LDB(B0, 1, 0); PG8_LDB(B1, 1, 1); PG8_SCHED; PG8_LDA(At, 1, 0); PG8_STAGE(PG8_SA(0, 1), a2 + hstepA, voffA);
;             PG8_WAIT_V(8); PG8_WAIT_L(0); PG8_BAR; if (do0) { PG8_MMA(0, 0, At, B0); PG8_MMA(0, 1, At, B1); } PG8_BAR; PG8_SCHED;
;             PG8_LDA(At, 1, 1); PG8_STAGE(PG8_SB(1, 0), b3, voffB); PG8_STAGE(PG8_SB(1, 1), b3 + hstepB, voffB); PG8_STAGE(PG8_SA(1, 0), a3, voffA);
;             PG8_WAIT_V(8); PG8_WAIT_L(0); PG8_BAR; if (do1) { PG8_MMA(1, 0, At, B0); PG8_MMA(1, 1, At, B1); } PG8_BAR; PG8_SCHED;
	v_mfma_f32_16x16x32_bf16 v[64:67], v[24:27], v[88:91], v[64:67]
	v_mfma_f32_16x16x32_bf16 v[180:183], v[28:31], v[100:103], v[64:67]
	v_mfma_f32_16x16x32_bf16 v[64:67], v[48:51], v[88:91], v[68:71]
	v_mfma_f32_16x16x32_bf16 v[176:179], v[52:55], v[100:103], v[64:67]
	v_mfma_f32_16x16x32_bf16 v[64:67], v[24:27], v[112:115], v[72:75]
	v_mfma_f32_16x16x32_bf16 v[156:159], v[28:31], v[116:119], v[64:67]
	v_mfma_f32_16x16x32_bf16 v[64:67], v[48:51], v[112:115], v[76:79]
	v_mfma_f32_16x16x32_bf16 v[152:155], v[52:55], v[116:119], v[64:67]
	v_mfma_f32_16x16x32_bf16 v[64:67], v[24:27], v[124:127], v[80:83]
	v_mfma_f32_16x16x32_bf16 v[0:3], v[24:27], v[148:151], v[0:3]
	v_mfma_f32_16x16x32_bf16 v[132:135], v[28:31], v[136:139], v[64:67]
	v_mfma_f32_16x16x32_bf16 v[64:67], v[48:51], v[124:127], v[84:87]
	v_mfma_f32_16x16x32_bf16 v[108:111], v[28:31], v[160:163], v[0:3]
	v_mfma_f32_16x16x32_bf16 v[0:3], v[48:51], v[148:151], v[4:7]
	v_mfma_f32_16x16x32_bf16 v[128:131], v[52:55], v[136:139], v[64:67]
	v_mfma_f32_16x16x32_bf16 v[104:107], v[52:55], v[160:163], v[0:3]
	s_setprio 0
	s_setprio 1
	v_mfma_f32_16x16x32_bf16 v[0:3], v[56:59], v[88:91], v[8:11]
	v_mfma_f32_16x16x32_bf16 v[168:171], v[60:63], v[100:103], v[0:3]
	v_mfma_f32_16x16x32_bf16 v[0:3], v[92:95], v[88:91], v[12:15]
	v_mfma_f32_16x16x32_bf16 v[164:167], v[96:99], v[100:103], v[0:3]
	v_mfma_f32_16x16x32_bf16 v[0:3], v[56:59], v[112:115], v[32:35]
	v_mfma_f32_16x16x32_bf16 v[144:147], v[60:63], v[116:119], v[0:3]
	v_mfma_f32_16x16x32_bf16 v[0:3], v[92:95], v[112:115], v[36:39]
	v_mfma_f32_16x16x32_bf16 v[140:143], v[96:99], v[116:119], v[0:3]
	v_mfma_f32_16x16x32_bf16 v[0:3], v[56:59], v[124:127], v[40:43]
	v_mfma_f32_16x16x32_bf16 v[120:123], v[60:63], v[136:139], v[0:3]
	v_mfma_f32_16x16x32_bf16 v[0:3], v[92:95], v[124:127], v[44:47]
	v_mfma_f32_16x16x32_bf16 v[116:119], v[96:99], v[136:139], v[0:3]
	v_mfma_f32_16x16x32_bf16 v[0:3], v[56:59], v[148:151], v[16:19]
	v_mfma_f32_16x16x32_bf16 v[88:91], v[60:63], v[160:163], v[0:3]
	v_mfma_f32_16x16x32_bf16 v[0:3], v[92:95], v[148:151], v[20:23]
	v_mfma_f32_16x16x32_bf16 v[84:87], v[96:99], v[160:163], v[0:3]
	s_barrier
	s_setprio 0
	s_add_i32 s54, s54, s29
	s_add_i32 s66, s54, 0x2000
	s_nop 2
	v_lshl_add_u64 v[0:1], v[172:173], 0, s[72:73]
	s_mov_b32 m0, s54
	s_add_u32 s48, s76, 0x10180
	global_load_lds_dwordx4 v[0:1], off
	v_lshl_add_u64 v[0:1], v[174:175], 0, s[72:73]
	s_mov_b32 m0, s66
	s_addc_u32 s49, s77, 0
	s_add_i32 s55, s55, s29
	global_load_lds_dwordx4 v[0:1], off
	v_lshl_add_u64 v[0:1], s[48:49], 0, v[214:215]
	s_mov_b32 m0, s55
	s_add_i32 s67, s55, 0x2000
	global_load_lds_dwordx4 v[0:1], off
	v_lshl_add_u64 v[0:1], s[48:49], 0, v[210:211]
	s_mov_b32 m0, s67
	s_nop 0
	global_load_lds_dwordx4 v[0:1], off
	v_lshl_add_u64 v[0:1], v[184:185], 0, s[72:73]
	s_mov_b32 m0, s89
	s_nop 0
	global_load_lds_dwordx4 v[0:1], off
	v_lshl_add_u64 v[0:1], v[186:187], 0, s[72:73]
	s_mov_b32 m0, s90
	s_nop 0
	global_load_lds_dwordx4 v[0:1], off
	s_waitcnt vmcnt(8)
	s_waitcnt lgkmcnt(0)
	s_barrier
	s_barrier
	ds_read_b128 v[0:3], v188
	ds_read_b128 v[4:7], v188 offset:1024
	ds_read_b128 v[8:11], v188 offset:2048
	ds_read_b128 v[12:15], v188 offset:3072
	ds_read_b128 v[16:19], v189
	ds_read_b128 v[20:23], v189 offset:1024
	ds_read_b128 v[24:27], v189 offset:2048
	ds_read_b128 v[28:31], v189 offset:3072
	s_add_u32 s48, s60, 0x10180
	s_addc_u32 s49, s61, 0
	s_mov_b32 m0, s41
	v_lshl_add_u64 v[32:33], s[48:49], 0, v[216:217]
	global_load_lds_dwordx4 v[32:33], off
	v_lshl_add_u64 v[32:33], s[48:49], 0, v[212:213]
	s_mov_b32 m0, s10
	s_nop 0
	global_load_lds_dwordx4 v[32:33], off
	s_waitcnt vmcnt(8)
	s_waitcnt lgkmcnt(0)
	s_barrier
	s_barrier
	s_mov_b32 m0, s11
	v_lshl_add_u64 v[96:97], s[12:13], 0, v[214:215]
	s_add_u32 s10, s12, 0x10000
	ds_read_b128 v[32:35], v248 offset:16384
	ds_read_b128 v[36:39], v248 offset:17408
	ds_read_b128 v[40:43], v248 offset:18432
	ds_read_b128 v[44:47], v248 offset:19456
	ds_read_b128 v[48:51], v248 offset:20480
	ds_read_b128 v[52:55], v248 offset:21504
	ds_read_b128 v[56:59], v248 offset:22528
	ds_read_b128 v[60:63], v248 offset:23552
	global_load_lds_dwordx4 v[96:97], off
	v_lshl_add_u64 v[98:99], s[12:13], 0, v[210:211]
	s_mov_b32 m0, s31
	s_addc_u32 s11, s13, 0
	global_load_lds_dwordx4 v[98:99], off
	v_lshl_add_u64 v[64:65], s[10:11], 0, v[214:215]
	s_mov_b32 m0, s37
	v_lshl_add_u64 v[238:239], s[44:45], 0, v[216:217]
	global_load_lds_dwordx4 v[64:65], off
	v_lshl_add_u64 v[64:65], s[10:11], 0, v[210:211]
	s_mov_b32 m0, s43
	v_lshl_add_u64 v[240:241], s[44:45], 0, v[212:213]
	global_load_lds_dwordx4 v[64:65], off
	s_mov_b32 m0, s51
	s_nop 0
	global_load_lds_dwordx4 v[238:239], off
	s_mov_b32 m0, s53
	s_nop 0
	global_load_lds_dwordx4 v[240:241], off
	s_waitcnt vmcnt(8)
	s_waitcnt lgkmcnt(0)
	s_setprio 1
	s_barrier
; #define PG8_MMA(ai, bj, At, Bt) do { __builtin_amdgcn_s_setprio(1); _Pragma("unroll") for (int m = 0; m < 4; ++m) _Pragma("unroll") for (int n = 0; n < 2; ++n) _Pragma("unroll") for (int k = 0; k < 2; ++k) \
;         acc[ai][bj][m][n] = __builtin_amdgcn_mfma_f32_16x16x32_bf16(Bt[n][k], At[m][k], acc[ai][bj][m][n], 0, 0, 0); __builtin_amdgcn_s_setprio(0); } while (0)
; #define PG8_WAIT_V(n) asm volatile("s_waitcnt vmcnt(" #n ")" ::: "memory")
; #define PG8_WAIT_L(n) asm volatile("s_waitcnt lgkmcnt(" #n ")" ::: "memory")
; #define PG8_BAR __builtin_amdgcn_s_barrier()
; #define PG8_SCHED __builtin_amdgcn_sched_barrier(0)
; template <class Epi>
; __device__ __forceinline__ void gemm_phase(PG8_LAS unsigned char* lds, PG8_LAS unsigned char* xl, const Gemm g, const Sched& S, const Epi& E, const int wid) {
;     ...
;             PG8_WAIT_V(8); PG8_WAIT_L(0); PG8_BAR; if (do1) { PG8_MMA(1, 0, At, B0); PG8_MMA(1, 1, At, B1); } PG8_BAR; PG8_SCHED;
;         }
;         if (wr == 0) PG8_BAR;
	v_mfma_f32_16x16x32_bf16 v[64:67], v[0:3], v[32:35], 0
	v_mfma_f32_16x16x32_bf16 v[72:75], v[0:3], v[40:43], 0
	v_mfma_f32_16x16x32_bf16 v[80:83], v[0:3], v[48:51], 0
	v_mfma_f32_16x16x32_bf16 v[0:3], v[0:3], v[56:59], 0
	v_mfma_f32_16x16x32_bf16 v[64:67], v[4:7], v[36:39], v[64:67]
	v_mfma_f32_16x16x32_bf16 v[72:75], v[4:7], v[44:47], v[72:75]
	v_mfma_f32_16x16x32_bf16 v[76:79], v[8:11], v[40:43], 0
	v_mfma_f32_16x16x32_bf16 v[80:83], v[4:7], v[52:55], v[80:83]
	v_mfma_f32_16x16x32_bf16 v[0:3], v[4:7], v[60:63], v[0:3]
	v_mfma_f32_16x16x32_bf16 v[4:7], v[8:11], v[56:59], 0
	v_mfma_f32_16x16x32_bf16 v[68:71], v[8:11], v[32:35], 0
	v_mfma_f32_16x16x32_bf16 v[76:79], v[12:15], v[44:47], v[76:79]
	v_mfma_f32_16x16x32_bf16 v[92:95], v[8:11], v[48:51], 0
	v_mfma_f32_16x16x32_bf16 v[4:7], v[12:15], v[60:63], v[4:7]
	v_mfma_f32_16x16x32_bf16 v[68:71], v[12:15], v[36:39], v[68:71]
	v_mfma_f32_16x16x32_bf16 v[100:103], v[12:15], v[52:55], v[92:95]
	s_setprio 0
	s_setprio 1
	v_mfma_f32_16x16x32_bf16 v[8:11], v[16:19], v[32:35], 0
	v_mfma_f32_16x16x32_bf16 v[112:115], v[20:23], v[36:39], v[8:11]
	v_mfma_f32_16x16x32_bf16 v[8:11], v[24:27], v[32:35], 0
	v_mfma_f32_16x16x32_bf16 v[32:35], v[28:31], v[36:39], v[8:11]
	v_mfma_f32_16x16x32_bf16 v[8:11], v[16:19], v[40:43], 0
	v_mfma_f32_16x16x32_bf16 v[124:127], v[20:23], v[44:47], v[8:11]
	v_mfma_f32_16x16x32_bf16 v[8:11], v[24:27], v[40:43], 0
	v_mfma_f32_16x16x32_bf16 v[44:47], v[28:31], v[44:47], v[8:11]
	v_mfma_f32_16x16x32_bf16 v[8:11], v[16:19], v[48:51], 0
	v_mfma_f32_16x16x32_bf16 v[136:139], v[20:23], v[52:55], v[8:11]
	v_mfma_f32_16x16x32_bf16 v[8:11], v[24:27], v[48:51], 0
	v_mfma_f32_16x16x32_bf16 v[148:151], v[28:31], v[52:55], v[8:11]
	v_mfma_f32_16x16x32_bf16 v[8:11], v[16:19], v[56:59], 0
	v_mfma_f32_16x16x32_bf16 v[16:19], v[20:23], v[60:63], v[8:11]
	v_mfma_f32_16x16x32_bf16 v[8:11], v[24:27], v[56:59], 0
	v_mfma_f32_16x16x32_bf16 v[28:31], v[28:31], v[60:63], v[8:11]
	s_barrier
	s_setprio 0
	s_nop 4
	ds_read_b128 v[8:11], v190
	ds_read_b128 v[12:15], v190 offset:1024
	ds_read_b128 v[20:23], v190 offset:2048
	ds_read_b128 v[24:27], v190 offset:3072
	ds_read_b128 v[56:59], v191
	ds_read_b128 v[160:163], v191 offset:1024
	ds_read_b128 v[172:175], v191 offset:2048
	ds_read_b128 v[184:187], v191 offset:3072
	s_add_u32 s10, s44, 0x10000
	s_addc_u32 s11, s45, 0
	s_mov_b32 m0, s62
	v_lshl_add_u64 v[36:37], s[10:11], 0, v[216:217]
	global_load_lds_dwordx4 v[36:37], off
	v_lshl_add_u64 v[36:37], s[10:11], 0, v[212:213]
	s_mov_b32 m0, s68
	s_nop 0
	global_load_lds_dwordx4 v[36:37], off
	s_waitcnt vmcnt(8)
	s_waitcnt lgkmcnt(0)
	s_barrier
	s_barrier
	s_mov_b32 m0, s54
	v_lshl_add_u64 v[36:37], v[96:97], 0, s[22:23]
	s_add_u32 s10, s12, 0x10080
	ds_read_b128 v[48:51], v248 offset:49152
	ds_read_b128 v[52:55], v248 offset:50176
	ds_read_b128 v[188:191], v248 offset:51200
	ds_read_b128 v[218:221], v248 offset:52224
	ds_read_b128 v[222:225], v248 offset:53248
	ds_read_b128 v[226:229], v248 offset:54272
	ds_read_b128 v[230:233], v248 offset:55296
	ds_read_b128 v[234:237], v248 offset:56320
	global_load_lds_dwordx4 v[36:37], off
	v_lshl_add_u64 v[36:37], v[98:99], 0, s[22:23]
	s_mov_b32 m0, s66
	s_addc_u32 s11, s13, 0
	global_load_lds_dwordx4 v[36:37], off
	v_lshl_add_u64 v[36:37], s[10:11], 0, v[214:215]
	s_mov_b32 m0, s55
	s_nop 0
	global_load_lds_dwordx4 v[36:37], off
	v_lshl_add_u64 v[36:37], s[10:11], 0, v[210:211]
	s_mov_b32 m0, s67
	s_nop 0
	global_load_lds_dwordx4 v[36:37], off
	v_lshl_add_u64 v[36:37], v[238:239], 0, s[22:23]
	s_mov_b32 m0, s89
	s_nop 0
	global_load_lds_dwordx4 v[36:37], off
	v_lshl_add_u64 v[36:37], v[240:241], 0, s[22:23]
	s_mov_b32 m0, s90
	s_nop 0
	global_load_lds_dwordx4 v[36:37], off
	s_waitcnt vmcnt(8)
	s_waitcnt lgkmcnt(0)
	s_setprio 1
	s_barrier
	v_mfma_f32_16x16x32_bf16 v[36:39], v[8:11], v[48:51], v[64:67]
	v_mfma_f32_16x16x32_bf16 v[96:99], v[12:15], v[52:55], v[36:39]
	v_mfma_f32_16x16x32_bf16 v[36:39], v[20:23], v[48:51], v[68:71]
	v_mfma_f32_16x16x32_bf16 v[92:95], v[24:27], v[52:55], v[36:39]
	v_mfma_f32_16x16x32_bf16 v[36:39], v[8:11], v[188:191], v[72:75]
	v_mfma_f32_16x16x32_bf16 v[64:67], v[12:15], v[218:221], v[36:39]
	v_mfma_f32_16x16x32_bf16 v[36:39], v[20:23], v[188:191], v[76:79]
	v_mfma_f32_16x16x32_bf16 v[60:63], v[24:27], v[218:221], v[36:39]
	v_mfma_f32_16x16x32_bf16 v[36:39], v[8:11], v[222:225], v[80:83]
	v_mfma_f32_16x16x32_bf16 v[0:3], v[8:11], v[230:233], v[0:3]
	v_mfma_f32_16x16x32_bf16 v[40:43], v[12:15], v[226:229], v[36:39]
	v_mfma_f32_16x16x32_bf16 v[36:39], v[20:23], v[222:225], v[100:103]
	v_mfma_f32_16x16x32_bf16 v[12:15], v[12:15], v[234:237], v[0:3]
	v_mfma_f32_16x16x32_bf16 v[0:3], v[20:23], v[230:233], v[4:7]
	v_mfma_f32_16x16x32_bf16 v[36:39], v[24:27], v[226:229], v[36:39]
	v_mfma_f32_16x16x32_bf16 v[8:11], v[24:27], v[234:237], v[0:3]
	s_setprio 0
	s_setprio 1
	v_mfma_f32_16x16x32_bf16 v[0:3], v[56:59], v[48:51], v[112:115]
	v_mfma_f32_16x16x32_bf16 v[76:79], v[160:163], v[52:55], v[0:3]
	v_mfma_f32_16x16x32_bf16 v[0:3], v[172:175], v[48:51], v[32:35]
	v_mfma_f32_16x16x32_bf16 v[72:75], v[184:187], v[52:55], v[0:3]
	v_mfma_f32_16x16x32_bf16 v[0:3], v[56:59], v[188:191], v[124:127]
	v_mfma_f32_16x16x32_bf16 v[52:55], v[160:163], v[218:221], v[0:3]
	v_mfma_f32_16x16x32_bf16 v[0:3], v[172:175], v[188:191], v[44:47]
	v_mfma_f32_16x16x32_bf16 v[48:51], v[184:187], v[218:221], v[0:3]
	v_mfma_f32_16x16x32_bf16 v[0:3], v[56:59], v[222:225], v[136:139]
	v_mfma_f32_16x16x32_bf16 v[24:27], v[160:163], v[226:229], v[0:3]
	v_mfma_f32_16x16x32_bf16 v[0:3], v[172:175], v[222:225], v[148:151]
	v_mfma_f32_16x16x32_bf16 v[20:23], v[184:187], v[226:229], v[0:3]
	v_mfma_f32_16x16x32_bf16 v[0:3], v[56:59], v[230:233], v[16:19]
	v_mfma_f32_16x16x32_bf16 v[4:7], v[160:163], v[234:237], v[0:3]
	v_mfma_f32_16x16x32_bf16 v[0:3], v[172:175], v[230:233], v[28:31]
	v_mfma_f32_16x16x32_bf16 v[0:3], v[184:187], v[234:237], v[0:3]
	s_barrier
	s_setprio 0
	s_andn2_b64 vcc, exec, s[14:15]
	s_cbranch_vccnz .LBB0_512
	s_barrier

; __device__ __forceinline__ const char* a_tile(const Gemm& g, const Unit& u) { return (const char*)(g.A + ((long)u.z1 * g.aS1 + (long)u.z2 * g.aS2 + (long)u.pm * BM * g.lda)); }
; __device__ __forceinline__ const char* b_tile(const Gemm& g, const Unit& u) { return (const char*)(g.Bt + ((long)u.z1 * g.bS1 + (long)u.z2 * g.bS2 + (long)u.pn * BM * g.ldb)); }
; __device__ __forceinline__ int lane_id_opq() { int l; asm volatile("v_mbcnt_lo_u32_b32 %0, -1, 0\n\tv_mbcnt_hi_u32_b32 %0, -1, %0" : "=v"(l)); return l; }
; #define PG8_WAIT_V(n) asm volatile("s_waitcnt vmcnt(" #n ")" ::: "memory")
; #define PG8_BAR __builtin_amdgcn_s_barrier()
; template <class Epi>
; __device__ __forceinline__ void gemm_phase(PG8_LAS unsigned char* lds, PG8_LAS unsigned char* xl, const Gemm g, const Sched& S, const Epi& E, const int wid) {
;     ...
;         const bool has_next = S.next(ui + 1, nxt);
;         const char* nA = has_next ? a_tile(g, nxt) : cA; const char* nB = has_next ? b_tile(g, nxt) : cB;
;         for (int t = 0; t < nt; t += 2) {
;             const bool last = (t == nt - 2);
;             const bool do0 = !blkdiag_v<Epi> || t == 0, do1 = !blkdiag_v<Epi> || t != 0;
;             long j1 = 0, ja2 = 0, jb2 = 0;
;             if constexpr (Epi::MID) {
;                 if (t == g.tj) { const int lnM = lane_id_opq(); E.mid(acc, cur, wr, wc, lnM & 15, lnM >> 4); }
;                 if (t >= g.tj) j1 = g.jA;
;                 if (t + 2 >= g.tj) { ja2 = g.jA; jb2 = g.jB; } }
;             const char* a1 = cA + (size_t)(t + 1) * kstep + j1;
;             const char* a2 = last ? nA : cA + (size_t)(t + 2) * kstep + ja2; const char* b2 = last ? nB : cB + (size_t)(t + 2) * kstep + jb2;
;             const char* a3 = a2 + kstep; const char* b3 = b2 + kstep;
;             PG8_LDB(B0, 0, 0); PG8_LDB(B1, 0, 1); PG8_SCHED; PG8_LDA(At, 0, 0); PG8_STAGE(PG8_SA(1, 1), a1 + hstepA, voffA);
;             PG8_WAIT_V(8); PG8_WAIT_L(0); PG8_BAR; if (do0) { PG8_MMA(0, 0, At, B0); PG8_MMA(0, 1, At, B1); } PG8_BAR; PG8_SCHED;
;     ...
; #pragma unroll
;         for (int a = 0; a < 2; ++a)
; #pragma unroll
;             for (int b = 0; b < 2; ++b)
; #pragma unroll
;                 for (int m = 0; m < 4; ++m)
; #pragma unroll
;                     for (int n = 0; n < 2; ++n) acc[a][b][m][n] = (f32x4){0.f, 0.f, 0.f, 0.f};
;         cur = nxt; cA = nA; cB = nB; ++ui;
;         if (wr == 1) PG8_BAR;
.LBB0_526:
	s_ashr_i32 s37, s36, 31
	s_lshl_b64 s[8:9], s[36:37], 20
	s_add_u32 s42, s76, s8
	s_addc_u32 s43, s77, s9
	s_and_b64 s[8:9], s[46:47], exec
	s_cselect_b32 s8, s43, s13
	s_cselect_b32 s9, s42, s12
	s_ashr_i32 s59, s58, 31
	s_lshl_b64 s[10:11], s[58:59], 20
	s_add_u32 s30, s60, s10
	s_addc_u32 s31, s61, s11
	s_and_b64 s[10:11], s[46:47], exec
	s_cselect_b32 s10, s31, s21
	s_cselect_b32 s11, s30, s20
	s_add_u32 s59, s20, 0x100
	v_mov_b32_e32 v0, 0
	s_addc_u32 s62, s21, 0
	s_mov_b32 s66, -2
	v_mov_b32_e32 v1, v0
	s_waitcnt lgkmcnt(0)
	v_mov_b32_e32 v2, v0
	v_mov_b32_e32 v3, v0
	v_mov_b32_e32 v4, v0
	v_mov_b32_e32 v5, v0
	v_mov_b32_e32 v6, v0
	v_mov_b32_e32 v7, v0
	v_mov_b32_e32 v18, v0
	v_mov_b32_e32 v19, v0
	v_mov_b32_e32 v20, v0
	v_mov_b32_e32 v21, v0
	v_mov_b32_e32 v30, v0
	v_mov_b32_e32 v31, v0
	v_mov_b32_e32 v32, v0
	v_mov_b32_e32 v33, v0
	v_mov_b32_e32 v42, v0
	v_mov_b32_e32 v43, v0
	v_mov_b32_e32 v44, v0
	v_mov_b32_e32 v45, v0
	v_mov_b32_e32 v46, v0
	v_mov_b32_e32 v47, v0
	v_mov_b32_e32 v48, v0
	v_mov_b32_e32 v49, v0
	v_mov_b32_e32 v58, v0
	v_mov_b32_e32 v59, v0
	v_mov_b32_e32 v60, v0
	v_mov_b32_e32 v61, v0
	v_mov_b32_e32 v62, v0
	v_mov_b32_e32 v63, v0
	v_mov_b32_e32 v64, v0
	v_mov_b32_e32 v65, v0
	v_mov_b32_e32 v8, v0
	v_mov_b32_e32 v9, v0
	v_mov_b32_e32 v10, v0
	v_mov_b32_e32 v11, v0
	v_mov_b32_e32 v12, v0
	v_mov_b32_e32 v13, v0
	v_mov_b32_e32 v14, v0
	v_mov_b32_e32 v15, v0
	v_mov_b32_e32 v34, v0
	v_mov_b32_e32 v35, v0
	v_mov_b32_e32 v36, v0
	v_mov_b32_e32 v37, v0
	v_mov_b32_e32 v38, v0
	v_mov_b32_e32 v39, v0
	v_mov_b32_e32 v40, v0
	v_mov_b32_e32 v41, v0
	v_mov_b32_e32 v50, v0
	v_mov_b32_e32 v51, v0
	v_mov_b32_e32 v52, v0
	v_mov_b32_e32 v53, v0
	v_mov_b32_e32 v54, v0
	v_mov_b32_e32 v55, v0
	v_mov_b32_e32 v56, v0
	v_mov_b32_e32 v57, v0
	v_mov_b32_e32 v66, v0
	v_mov_b32_e32 v67, v0
	v_mov_b32_e32 v68, v0
	v_mov_b32_e32 v69, v0
	v_mov_b32_e32 v70, v0
	v_mov_b32_e32 v71, v0
	v_mov_b32_e32 v72, v0
	v_mov_b32_e32 v73, v0
	v_mov_b32_e32 v74, v0
	v_mov_b32_e32 v75, v0
	v_mov_b32_e32 v76, v0
	v_mov_b32_e32 v77, v0
	v_mov_b32_e32 v78, v0
	v_mov_b32_e32 v79, v0
	v_mov_b32_e32 v80, v0
	v_mov_b32_e32 v81, v0
	v_mov_b32_e32 v92, v0
	v_mov_b32_e32 v93, v0
	v_mov_b32_e32 v94, v0
	v_mov_b32_e32 v95, v0
	v_mov_b32_e32 v96, v0
	v_mov_b32_e32 v97, v0
	v_mov_b32_e32 v98, v0
	v_mov_b32_e32 v99, v0
	v_mov_b32_e32 v108, v0
	v_mov_b32_e32 v109, v0
	v_mov_b32_e32 v110, v0
	v_mov_b32_e32 v111, v0
	v_mov_b32_e32 v112, v0
	v_mov_b32_e32 v113, v0
	v_mov_b32_e32 v114, v0
	v_mov_b32_e32 v115, v0
	v_mov_b32_e32 v124, v0
	v_mov_b32_e32 v125, v0
	v_mov_b32_e32 v126, v0
	v_mov_b32_e32 v127, v0
	v_mov_b32_e32 v128, v0
	v_mov_b32_e32 v129, v0
	v_mov_b32_e32 v130, v0
	v_mov_b32_e32 v131, v0
	v_mov_b32_e32 v82, v0
	v_mov_b32_e32 v83, v0
	v_mov_b32_e32 v84, v0
	v_mov_b32_e32 v85, v0
	v_mov_b32_e32 v86, v0
	v_mov_b32_e32 v87, v0
	v_mov_b32_e32 v88, v0
	v_mov_b32_e32 v89, v0
	v_mov_b32_e32 v100, v0
	v_mov_b32_e32 v101, v0
	v_mov_b32_e32 v102, v0
	v_mov_b32_e32 v103, v0
	v_mov_b32_e32 v104, v0
	v_mov_b32_e32 v105, v0
	v_mov_b32_e32 v106, v0
	v_mov_b32_e32 v107, v0
	v_mov_b32_e32 v116, v0
	v_mov_b32_e32 v117, v0
	v_mov_b32_e32 v118, v0
	v_mov_b32_e32 v119, v0
	v_mov_b32_e32 v120, v0
	v_mov_b32_e32 v121, v0
	v_mov_b32_e32 v122, v0
	v_mov_b32_e32 v123, v0
	v_mov_b32_e32 v132, v0
	v_mov_b32_e32 v133, v0
	v_mov_b32_e32 v134, v0
	v_mov_b32_e32 v135, v0
	v_mov_b32_e32 v136, v0
	v_mov_b32_e32 v137, v0
	v_mov_b32_e32 v138, v0
	v_mov_b32_e32 v139, v0
	s_cmp_lg_u32 s100, 1
	s_cbranch_scc1 .Ldefbar_skip_4
	s_mov_b32 s100, 0
	s_barrier
.Ldefbar_skip_4:
.LBB0_527:
	s_add_u32 s20, s12, 0x100
	s_addc_u32 s21, s13, 0
	s_add_i32 s54, 0, 0x10000
	s_cmp_eq_u32 s66, 28
	s_cselect_b32 s53, s8, s21
	s_cselect_b32 s52, s9, s20
	v_add_u32_e32 v156, s54, v158
	s_cselect_b32 s51, s10, s62
	s_cselect_b32 s50, s11, s59
	s_add_i32 s55, 0, 0x14000
	ds_read_b128 v[22:25], v156
	ds_read_b128 v[26:29], v156 offset:1024
	ds_read_b128 v[160:163], v156 offset:2048
	ds_read_b128 v[164:167], v156 offset:3072
	v_add_u32_e32 v156, s55, v158
	ds_read_b128 v[168:171], v156
	ds_read_b128 v[172:175], v156 offset:1024
	ds_read_b128 v[176:179], v156 offset:2048
	ds_read_b128 v[180:183], v156 offset:3072
	v_lshl_add_u64 v[156:157], s[12:13], 0, v[148:149]
	s_add_i32 m0, s45, 0xc000
	ds_read_b128 v[184:187], v159
	ds_read_b128 v[188:191], v159 offset:1024
	ds_read_b128 v[210:213], v159 offset:2048
	ds_read_b128 v[214:217], v159 offset:3072
	ds_read_b128 v[218:221], v159 offset:4096
	ds_read_b128 v[222:225], v159 offset:5120
	ds_read_b128 v[226:229], v159 offset:6144
	ds_read_b128 v[230:233], v159 offset:7168
	global_load_lds_dwordx4 v[156:157], off
	v_lshl_add_u64 v[156:157], s[12:13], 0, v[150:151]
	s_add_i32 m0, s45, 0xe000
	s_nop 0
	global_load_lds_dwordx4 v[156:157], off
	s_waitcnt vmcnt(8)
	s_waitcnt lgkmcnt(0)
	s_setprio 1
	s_barrier
; #define PG8_STAGE(bufoff, gbase, voff) do { _Pragma("unroll") for (int _i = 0; _i < 2; ++_i) \
;         __builtin_amdgcn_global_load_lds((const unsigned*)((const char*)(gbase) + (voff)[_i]), (PG8_LAS unsigned*)(lds + (bufoff) + ldsw + _i * 8192), 16, 0, 0); } while (0)
; #define PG8_LDA(dst, b, h) do { _Pragma("unroll") for (int m = 0; m < 4; ++m) _Pragma("unroll") for (int k = 0; k < 2; ++k) dst[m][k] = *(const PG8_LAS bf16x8*)(lds + PG8_SA(b, h) + aoff + m * 2048 + k * 1024); } while (0)
; #define PG8_LDB(dst, b, h) do { _Pragma("unroll") for (int n = 0; n < 2; ++n) _Pragma("unroll") for (int k = 0; k < 2; ++k) dst[n][k] = *(const PG8_LAS bf16x8*)(lds + PG8_SB(b, h) + boff + n * 2048 + k * 1024); } while (0)
; #define PG8_MMA(ai, bj, At, Bt) do { __builtin_amdgcn_s_setprio(1); _Pragma("unroll") for (int m = 0; m < 4; ++m) _Pragma("unroll") for (int n = 0; n < 2; ++n) _Pragma("unroll") for (int k = 0; k < 2; ++k) \
;         acc[ai][bj][m][n] = __builtin_amdgcn_mfma_f32_16x16x32_bf16(Bt[n][k], At[m][k], acc[ai][bj][m][n], 0, 0, 0); __builtin_amdgcn_s_setprio(0); } while (0)
; #define PG8_WAIT_V(n) asm volatile("s_waitcnt vmcnt(" #n ")" ::: "memory")
; #define PG8_WAIT_L(n) asm volatile("s_waitcnt lgkmcnt(" #n ")" ::: "memory")
; #define PG8_BAR __builtin_amdgcn_s_barrier()
; #define PG8_SCHED __builtin_amdgcn_sched_barrier(0)
; template <class Epi>
; __device__ __forceinline__ void gemm_phase(PG8_LAS unsigned char* lds, PG8_LAS unsigned char* xl, const Gemm g, const Sched& S, const Epi& E, const int wid) {
;     ...
;             PG8_WAIT_V(8); PG8_WAIT_L(0); PG8_BAR; if (do0) { PG8_MMA(0, 0, At, B0); PG8_MMA(0, 1, At, B1); } PG8_BAR; PG8_SCHED;
;             PG8_LDA(At, 0, 1); PG8_STAGE(PG8_SB(0, 0), b2, voffB); PG8_STAGE(PG8_SB(0, 1), b2 + hstepB, voffB); PG8_STAGE(PG8_SA(0, 0), a2, voffA);
;             PG8_WAIT_V(8); PG8_WAIT_L(0); PG8_BAR; if (do1) { PG8_MMA(1, 0, At, B0); PG8_MMA(1, 1, At, B1); } PG8_BAR; PG8_SCHED;
;             PG8_LDB(B0, 1, 0); PG8_LDB(B1, 1, 1); PG8_SCHED; PG8_LDA(At, 1, 0); PG8_STAGE(PG8_SA(0, 1), a2 + hstepA, voffA);
	v_mfma_f32_16x16x32_bf16 v[136:139], v[22:25], v[184:187], v[136:139]
	v_mfma_f32_16x16x32_bf16 v[132:135], v[160:163], v[184:187], v[132:135]
	v_mfma_f32_16x16x32_bf16 v[120:123], v[22:25], v[210:213], v[120:123]
	v_mfma_f32_16x16x32_bf16 v[116:119], v[160:163], v[210:213], v[116:119]
	v_mfma_f32_16x16x32_bf16 v[104:107], v[22:25], v[218:221], v[104:107]
	v_mfma_f32_16x16x32_bf16 v[100:103], v[160:163], v[218:221], v[100:103]
	v_mfma_f32_16x16x32_bf16 v[86:89], v[22:25], v[226:229], v[86:89]
	v_mfma_f32_16x16x32_bf16 v[82:85], v[160:163], v[226:229], v[82:85]
	v_mfma_f32_16x16x32_bf16 v[136:139], v[26:29], v[188:191], v[136:139]
	v_mfma_f32_16x16x32_bf16 v[132:135], v[164:167], v[188:191], v[132:135]
	v_mfma_f32_16x16x32_bf16 v[120:123], v[26:29], v[214:217], v[120:123]
	v_mfma_f32_16x16x32_bf16 v[116:119], v[164:167], v[214:217], v[116:119]
	v_mfma_f32_16x16x32_bf16 v[104:107], v[26:29], v[222:225], v[104:107]
	v_mfma_f32_16x16x32_bf16 v[100:103], v[164:167], v[222:225], v[100:103]
	v_mfma_f32_16x16x32_bf16 v[86:89], v[26:29], v[230:233], v[86:89]
	v_mfma_f32_16x16x32_bf16 v[82:85], v[164:167], v[230:233], v[82:85]
	s_setprio 0
	s_setprio 1
	v_mfma_f32_16x16x32_bf16 v[128:131], v[168:171], v[184:187], v[128:131]
	v_mfma_f32_16x16x32_bf16 v[124:127], v[176:179], v[184:187], v[124:127]
	v_mfma_f32_16x16x32_bf16 v[112:115], v[168:171], v[210:213], v[112:115]
	v_mfma_f32_16x16x32_bf16 v[108:111], v[176:179], v[210:213], v[108:111]
	v_mfma_f32_16x16x32_bf16 v[96:99], v[168:171], v[218:221], v[96:99]
	v_mfma_f32_16x16x32_bf16 v[92:95], v[176:179], v[218:221], v[92:95]
	v_mfma_f32_16x16x32_bf16 v[78:81], v[168:171], v[226:229], v[78:81]
	v_mfma_f32_16x16x32_bf16 v[74:77], v[176:179], v[226:229], v[74:77]
	v_mfma_f32_16x16x32_bf16 v[128:131], v[172:175], v[188:191], v[128:131]
	v_mfma_f32_16x16x32_bf16 v[124:127], v[180:183], v[188:191], v[124:127]
	v_mfma_f32_16x16x32_bf16 v[112:115], v[172:175], v[214:217], v[112:115]
	v_mfma_f32_16x16x32_bf16 v[108:111], v[180:183], v[214:217], v[108:111]
	v_mfma_f32_16x16x32_bf16 v[96:99], v[172:175], v[222:225], v[96:99]
	v_mfma_f32_16x16x32_bf16 v[92:95], v[180:183], v[222:225], v[92:95]
	v_mfma_f32_16x16x32_bf16 v[78:81], v[172:175], v[230:233], v[78:81]
	v_mfma_f32_16x16x32_bf16 v[74:77], v[180:183], v[230:233], v[74:77]
	s_barrier
	s_setprio 0
	s_add_i32 s12, s54, s29
	v_lshl_add_u64 v[156:157], s[50:51], 0, v[142:143]
	s_mov_b32 m0, s12
	ds_read_b128 v[184:187], v159 offset:16384
	ds_read_b128 v[188:191], v159 offset:17408
	ds_read_b128 v[210:213], v159 offset:18432
	ds_read_b128 v[214:217], v159 offset:19456
	ds_read_b128 v[218:221], v159 offset:20480
	ds_read_b128 v[222:225], v159 offset:21504
	ds_read_b128 v[226:229], v159 offset:22528
	ds_read_b128 v[230:233], v159 offset:23552
	global_load_lds_dwordx4 v[156:157], off
	s_add_i32 m0, s12, 0x2000
	s_add_u32 s12, s50, 0x80000
	v_lshl_add_u64 v[204:205], s[50:51], 0, v[146:147]
	s_addc_u32 s13, s51, 0
	s_add_i32 s54, s55, s29
	global_load_lds_dwordx4 v[204:205], off
	v_lshl_add_u64 v[234:235], s[12:13], 0, v[142:143]
	s_mov_b32 m0, s54
	v_lshl_add_u64 v[236:237], s[52:53], 0, v[144:145]
	global_load_lds_dwordx4 v[234:235], off
	v_lshl_add_u64 v[234:235], s[12:13], 0, v[146:147]
	s_add_i32 m0, s54, 0x2000
	s_nop 0
	global_load_lds_dwordx4 v[234:235], off
	v_lshl_add_u64 v[234:235], s[52:53], 0, v[140:141]
	s_mov_b32 m0, s45
	s_nop 0
	global_load_lds_dwordx4 v[234:235], off
	s_mov_b32 m0, s41
	s_nop 0
	global_load_lds_dwordx4 v[236:237], off
	s_waitcnt vmcnt(8)
	s_waitcnt lgkmcnt(0)
	s_setprio 1
	s_barrier
	v_mfma_f32_16x16x32_bf16 v[70:73], v[22:25], v[184:187], v[70:73]
	v_mfma_f32_16x16x32_bf16 v[66:69], v[160:163], v[184:187], v[66:69]
	v_mfma_f32_16x16x32_bf16 v[54:57], v[22:25], v[210:213], v[54:57]
	v_mfma_f32_16x16x32_bf16 v[50:53], v[160:163], v[210:213], v[50:53]
	v_mfma_f32_16x16x32_bf16 v[38:41], v[22:25], v[218:221], v[38:41]
	v_mfma_f32_16x16x32_bf16 v[34:37], v[160:163], v[218:221], v[34:37]
	v_mfma_f32_16x16x32_bf16 v[12:15], v[22:25], v[226:229], v[12:15]
	v_mfma_f32_16x16x32_bf16 v[8:11], v[160:163], v[226:229], v[8:11]
	v_mfma_f32_16x16x32_bf16 v[70:73], v[26:29], v[188:191], v[70:73]
	v_mfma_f32_16x16x32_bf16 v[66:69], v[164:167], v[188:191], v[66:69]
	v_mfma_f32_16x16x32_bf16 v[54:57], v[26:29], v[214:217], v[54:57]
	v_mfma_f32_16x16x32_bf16 v[50:53], v[164:167], v[214:217], v[50:53]
	v_mfma_f32_16x16x32_bf16 v[38:41], v[26:29], v[222:225], v[38:41]
	v_mfma_f32_16x16x32_bf16 v[34:37], v[164:167], v[222:225], v[34:37]
	v_mfma_f32_16x16x32_bf16 v[12:15], v[26:29], v[230:233], v[12:15]
	v_mfma_f32_16x16x32_bf16 v[8:11], v[164:167], v[230:233], v[8:11]
	s_setprio 0
	s_setprio 1
	v_mfma_f32_16x16x32_bf16 v[46:49], v[168:171], v[210:213], v[46:49]
	v_mfma_f32_16x16x32_bf16 v[42:45], v[176:179], v[210:213], v[42:45]
	v_mfma_f32_16x16x32_bf16 v[30:33], v[168:171], v[218:221], v[30:33]
	v_mfma_f32_16x16x32_bf16 v[18:21], v[176:179], v[218:221], v[18:21]
	v_mfma_f32_16x16x32_bf16 v[4:7], v[168:171], v[226:229], v[4:7]
	v_mfma_f32_16x16x32_bf16 v[0:3], v[176:179], v[226:229], v[0:3]
	v_mfma_f32_16x16x32_bf16 v[22:25], v[168:171], v[184:187], v[62:65]
	v_mfma_f32_16x16x32_bf16 v[26:29], v[176:179], v[184:187], v[58:61]
	v_mfma_f32_16x16x32_bf16 v[46:49], v[172:175], v[214:217], v[46:49]
	v_mfma_f32_16x16x32_bf16 v[42:45], v[180:183], v[214:217], v[42:45]
	v_mfma_f32_16x16x32_bf16 v[30:33], v[172:175], v[222:225], v[30:33]
	v_mfma_f32_16x16x32_bf16 v[18:21], v[180:183], v[222:225], v[18:21]
	v_mfma_f32_16x16x32_bf16 v[4:7], v[172:175], v[230:233], v[4:7]
	v_mfma_f32_16x16x32_bf16 v[0:3], v[180:183], v[230:233], v[0:3]
	v_mfma_f32_16x16x32_bf16 v[22:25], v[172:175], v[188:191], v[22:25]
	v_mfma_f32_16x16x32_bf16 v[26:29], v[180:183], v[188:191], v[26:29]
	s_barrier
; #define PG8_STAGE(bufoff, gbase, voff) do { _Pragma("unroll") for (int _i = 0; _i < 2; ++_i) \
;         __builtin_amdgcn_global_load_lds((const unsigned*)((const char*)(gbase) + (voff)[_i]), (PG8_LAS unsigned*)(lds + (bufoff) + ldsw + _i * 8192), 16, 0, 0); } while (0)
; #define PG8_LDA(dst, b, h) do { _Pragma("unroll") for (int m = 0; m < 4; ++m) _Pragma("unroll") for (int k = 0; k < 2; ++k) dst[m][k] = *(const PG8_LAS bf16x8*)(lds + PG8_SA(b, h) + aoff + m * 2048 + k * 1024); } while (0)
; #define PG8_LDB(dst, b, h) do { _Pragma("unroll") for (int n = 0; n < 2; ++n) _Pragma("unroll") for (int k = 0; k < 2; ++k) dst[n][k] = *(const PG8_LAS bf16x8*)(lds + PG8_SB(b, h) + boff + n * 2048 + k * 1024); } while (0)
; #define PG8_MMA(ai, bj, At, Bt) do { __builtin_amdgcn_s_setprio(1); _Pragma("unroll") for (int m = 0; m < 4; ++m) _Pragma("unroll") for (int n = 0; n < 2; ++n) _Pragma("unroll") for (int k = 0; k < 2; ++k) \
;         acc[ai][bj][m][n] = __builtin_amdgcn_mfma_f32_16x16x32_bf16(Bt[n][k], At[m][k], acc[ai][bj][m][n], 0, 0, 0); __builtin_amdgcn_s_setprio(0); } while (0)
; #define PG8_WAIT_V(n) asm volatile("s_waitcnt vmcnt(" #n ")" ::: "memory")
; #define PG8_WAIT_L(n) asm volatile("s_waitcnt lgkmcnt(" #n ")" ::: "memory")
; #define PG8_BAR __builtin_amdgcn_s_barrier()
; #define PG8_SCHED __builtin_amdgcn_sched_barrier(0)
; template <class Epi>
; __device__ __forceinline__ void gemm_phase(PG8_LAS unsigned char* lds, PG8_LAS unsigned char* xl, const Gemm g, const Sched& S, const Epi& E, const int wid) {
;     ...
;             PG8_LDB(B0, 1, 0); PG8_LDB(B1, 1, 1); PG8_SCHED; PG8_LDA(At, 1, 0); PG8_STAGE(PG8_SA(0, 1), a2 + hstepA, voffA);
;             PG8_WAIT_V(8); PG8_WAIT_L(0); PG8_BAR; if (do0) { PG8_MMA(0, 0, At, B0); PG8_MMA(0, 1, At, B1); } PG8_BAR; PG8_SCHED;
;             PG8_LDA(At, 1, 1); PG8_STAGE(PG8_SB(1, 0), b3, voffB); PG8_STAGE(PG8_SB(1, 1), b3 + hstepB, voffB); PG8_STAGE(PG8_SA(1, 0), a3, voffA);
	s_setprio 0
	s_add_i32 s54, 0, 0x18000
	s_add_i32 s55, 0, 0x1c000
	v_add_u32_e32 v164, s54, v158
	v_add_u32_e32 v180, s55, v158
	ds_read_b128 v[58:61], v164
	ds_read_b128 v[62:65], v164 offset:1024
	ds_read_b128 v[160:163], v164 offset:2048
	ds_read_b128 v[164:167], v164 offset:3072
	ds_read_b128 v[168:171], v180
	ds_read_b128 v[172:175], v180 offset:1024
	ds_read_b128 v[176:179], v180 offset:2048
	ds_read_b128 v[180:183], v180 offset:3072
	s_add_u32 s12, s52, 0x80000
	s_addc_u32 s13, s53, 0
	s_mov_b32 m0, s88
	v_lshl_add_u64 v[238:239], s[12:13], 0, v[140:141]
	ds_read_b128 v[184:187], v159 offset:32768
	ds_read_b128 v[188:191], v159 offset:33792
	ds_read_b128 v[210:213], v159 offset:34816
	ds_read_b128 v[214:217], v159 offset:35840
	ds_read_b128 v[218:221], v159 offset:36864
	ds_read_b128 v[222:225], v159 offset:37888
	ds_read_b128 v[226:229], v159 offset:38912
	ds_read_b128 v[230:233], v159 offset:39936
	global_load_lds_dwordx4 v[238:239], off
	v_lshl_add_u64 v[238:239], s[12:13], 0, v[144:145]
	s_mov_b32 m0, s89
	s_nop 0
	global_load_lds_dwordx4 v[238:239], off
	s_waitcnt vmcnt(8)
	s_waitcnt lgkmcnt(0)
	s_setprio 1
	s_barrier
	v_mfma_f32_16x16x32_bf16 v[136:139], v[58:61], v[184:187], v[136:139]
	v_mfma_f32_16x16x32_bf16 v[132:135], v[160:163], v[184:187], v[132:135]
	v_mfma_f32_16x16x32_bf16 v[120:123], v[58:61], v[210:213], v[120:123]
	v_mfma_f32_16x16x32_bf16 v[116:119], v[160:163], v[210:213], v[116:119]
	v_mfma_f32_16x16x32_bf16 v[104:107], v[58:61], v[218:221], v[104:107]
	v_mfma_f32_16x16x32_bf16 v[100:103], v[160:163], v[218:221], v[100:103]
	v_mfma_f32_16x16x32_bf16 v[86:89], v[58:61], v[226:229], v[86:89]
	v_mfma_f32_16x16x32_bf16 v[82:85], v[160:163], v[226:229], v[82:85]
	v_mfma_f32_16x16x32_bf16 v[136:139], v[62:65], v[188:191], v[136:139]
	v_mfma_f32_16x16x32_bf16 v[132:135], v[164:167], v[188:191], v[132:135]
	v_mfma_f32_16x16x32_bf16 v[120:123], v[62:65], v[214:217], v[120:123]
	v_mfma_f32_16x16x32_bf16 v[116:119], v[164:167], v[214:217], v[116:119]
	v_mfma_f32_16x16x32_bf16 v[104:107], v[62:65], v[222:225], v[104:107]
	v_mfma_f32_16x16x32_bf16 v[100:103], v[164:167], v[222:225], v[100:103]
	v_mfma_f32_16x16x32_bf16 v[86:89], v[62:65], v[230:233], v[86:89]
	v_mfma_f32_16x16x32_bf16 v[82:85], v[164:167], v[230:233], v[82:85]
	s_setprio 0
	s_setprio 1
	v_mfma_f32_16x16x32_bf16 v[128:131], v[168:171], v[184:187], v[128:131]
	v_mfma_f32_16x16x32_bf16 v[124:127], v[176:179], v[184:187], v[124:127]
	v_mfma_f32_16x16x32_bf16 v[112:115], v[168:171], v[210:213], v[112:115]
	v_mfma_f32_16x16x32_bf16 v[108:111], v[176:179], v[210:213], v[108:111]
	v_mfma_f32_16x16x32_bf16 v[96:99], v[168:171], v[218:221], v[96:99]
	v_mfma_f32_16x16x32_bf16 v[92:95], v[176:179], v[218:221], v[92:95]
	v_mfma_f32_16x16x32_bf16 v[78:81], v[168:171], v[226:229], v[78:81]
	v_mfma_f32_16x16x32_bf16 v[74:77], v[176:179], v[226:229], v[74:77]
	v_mfma_f32_16x16x32_bf16 v[128:131], v[172:175], v[188:191], v[128:131]
	v_mfma_f32_16x16x32_bf16 v[124:127], v[180:183], v[188:191], v[124:127]
	v_mfma_f32_16x16x32_bf16 v[112:115], v[172:175], v[214:217], v[112:115]
	v_mfma_f32_16x16x32_bf16 v[108:111], v[180:183], v[214:217], v[108:111]
	v_mfma_f32_16x16x32_bf16 v[96:99], v[172:175], v[222:225], v[96:99]
	v_mfma_f32_16x16x32_bf16 v[92:95], v[180:183], v[222:225], v[92:95]
	v_mfma_f32_16x16x32_bf16 v[78:81], v[172:175], v[230:233], v[78:81]
	v_mfma_f32_16x16x32_bf16 v[74:77], v[180:183], v[230:233], v[74:77]
	s_barrier
; #define PG8_STAGE(bufoff, gbase, voff) do { _Pragma("unroll") for (int _i = 0; _i < 2; ++_i) \
;         __builtin_amdgcn_global_load_lds((const unsigned*)((const char*)(gbase) + (voff)[_i]), (PG8_LAS unsigned*)(lds + (bufoff) + ldsw + _i * 8192), 16, 0, 0); } while (0)
; #define PG8_LDA(dst, b, h) do { _Pragma("unroll") for (int m = 0; m < 4; ++m) _Pragma("unroll") for (int k = 0; k < 2; ++k) dst[m][k] = *(const PG8_LAS bf16x8*)(lds + PG8_SA(b, h) + aoff + m * 2048 + k * 1024); } while (0)
; #define PG8_MMA(ai, bj, At, Bt) do { __builtin_amdgcn_s_setprio(1); _Pragma("unroll") for (int m = 0; m < 4; ++m) _Pragma("unroll") for (int n = 0; n < 2; ++n) _Pragma("unroll") for (int k = 0; k < 2; ++k) \
;         acc[ai][bj][m][n] = __builtin_amdgcn_mfma_f32_16x16x32_bf16(Bt[n][k], At[m][k], acc[ai][bj][m][n], 0, 0, 0); __builtin_amdgcn_s_setprio(0); } while (0)
; #define PG8_WAIT_V(n) asm volatile("s_waitcnt vmcnt(" #n ")" ::: "memory")
; #define PG8_WAIT_L(n) asm volatile("s_waitcnt lgkmcnt(" #n ")" ::: "memory")
; #define PG8_BAR __builtin_amdgcn_s_barrier()
; #define PG8_SCHED __builtin_amdgcn_sched_barrier(0)
; template <class Epi>
; __device__ __forceinline__ void gemm_phase(PG8_LAS unsigned char* lds, PG8_LAS unsigned char* xl, const Gemm g, const Sched& S, const Epi& E, const int wid) {
;     ...
;             PG8_LDA(At, 1, 1); PG8_STAGE(PG8_SB(1, 0), b3, voffB); PG8_STAGE(PG8_SB(1, 1), b3 + hstepB, voffB); PG8_STAGE(PG8_SA(1, 0), a3, voffA);
;             PG8_WAIT_V(8); PG8_WAIT_L(0); PG8_BAR; if (do1) { PG8_MMA(1, 0, At, B0); PG8_MMA(1, 1, At, B1); } PG8_BAR; PG8_SCHED;
;         }
;         if (wr == 0) PG8_BAR;
	s_setprio 0
	s_add_i32 s12, s54, s29
	v_lshl_add_u64 v[156:157], v[156:157], 0, s[22:23]
	s_mov_b32 m0, s12
	ds_read_b128 v[184:187], v159 offset:49152
	ds_read_b128 v[188:191], v159 offset:50176
	ds_read_b128 v[210:213], v159 offset:51200
	ds_read_b128 v[214:217], v159 offset:52224
	ds_read_b128 v[218:221], v159 offset:53248
	ds_read_b128 v[222:225], v159 offset:54272
	ds_read_b128 v[226:229], v159 offset:55296
	ds_read_b128 v[230:233], v159 offset:56320
	global_load_lds_dwordx4 v[156:157], off
	s_add_i32 m0, s12, 0x2000
	s_add_u32 s12, s50, 0x80080
	v_lshl_add_u64 v[156:157], v[204:205], 0, s[22:23]
	s_addc_u32 s13, s51, 0
	s_add_i32 s50, s55, s29
	global_load_lds_dwordx4 v[156:157], off
	v_lshl_add_u64 v[156:157], s[12:13], 0, v[142:143]
	s_mov_b32 m0, s50
	s_nop 0
	global_load_lds_dwordx4 v[156:157], off
	v_lshl_add_u64 v[156:157], s[12:13], 0, v[146:147]
	s_add_i32 m0, s50, 0x2000
	s_nop 0
	global_load_lds_dwordx4 v[156:157], off
	v_lshl_add_u64 v[156:157], v[234:235], 0, s[22:23]
	s_mov_b32 m0, s90
	s_nop 0
	global_load_lds_dwordx4 v[156:157], off
	v_lshl_add_u64 v[156:157], v[236:237], 0, s[22:23]
	s_mov_b32 m0, s91
	s_nop 0
	global_load_lds_dwordx4 v[156:157], off
	s_waitcnt vmcnt(8)
	s_waitcnt lgkmcnt(0)
	s_setprio 1
	s_barrier
	v_mfma_f32_16x16x32_bf16 v[70:73], v[58:61], v[184:187], v[70:73]
	v_mfma_f32_16x16x32_bf16 v[66:69], v[160:163], v[184:187], v[66:69]
	v_mfma_f32_16x16x32_bf16 v[54:57], v[58:61], v[210:213], v[54:57]
	v_mfma_f32_16x16x32_bf16 v[50:53], v[160:163], v[210:213], v[50:53]
	v_mfma_f32_16x16x32_bf16 v[38:41], v[58:61], v[218:221], v[38:41]
	v_mfma_f32_16x16x32_bf16 v[34:37], v[160:163], v[218:221], v[34:37]
	v_mfma_f32_16x16x32_bf16 v[12:15], v[58:61], v[226:229], v[12:15]
	v_mfma_f32_16x16x32_bf16 v[8:11], v[160:163], v[226:229], v[8:11]
	v_mfma_f32_16x16x32_bf16 v[70:73], v[62:65], v[188:191], v[70:73]
	v_mfma_f32_16x16x32_bf16 v[66:69], v[164:167], v[188:191], v[66:69]
	v_mfma_f32_16x16x32_bf16 v[54:57], v[62:65], v[214:217], v[54:57]
	v_mfma_f32_16x16x32_bf16 v[50:53], v[164:167], v[214:217], v[50:53]
	v_mfma_f32_16x16x32_bf16 v[38:41], v[62:65], v[222:225], v[38:41]
	v_mfma_f32_16x16x32_bf16 v[34:37], v[164:167], v[222:225], v[34:37]
	v_mfma_f32_16x16x32_bf16 v[12:15], v[62:65], v[230:233], v[12:15]
	v_mfma_f32_16x16x32_bf16 v[8:11], v[164:167], v[230:233], v[8:11]
	s_setprio 0
	s_setprio 1
	v_mfma_f32_16x16x32_bf16 v[22:25], v[168:171], v[184:187], v[22:25]
	v_mfma_f32_16x16x32_bf16 v[62:65], v[172:175], v[188:191], v[22:25]
	v_mfma_f32_16x16x32_bf16 v[22:25], v[176:179], v[184:187], v[26:29]
	v_mfma_f32_16x16x32_bf16 v[58:61], v[180:183], v[188:191], v[22:25]
	v_mfma_f32_16x16x32_bf16 v[22:25], v[168:171], v[210:213], v[46:49]
	v_mfma_f32_16x16x32_bf16 v[46:49], v[172:175], v[214:217], v[22:25]
	v_mfma_f32_16x16x32_bf16 v[22:25], v[176:179], v[210:213], v[42:45]
	v_mfma_f32_16x16x32_bf16 v[42:45], v[180:183], v[214:217], v[22:25]
	v_mfma_f32_16x16x32_bf16 v[22:25], v[168:171], v[218:221], v[30:33]
	v_mfma_f32_16x16x32_bf16 v[18:21], v[176:179], v[218:221], v[18:21]
	v_mfma_f32_16x16x32_bf16 v[4:7], v[168:171], v[226:229], v[4:7]
	v_mfma_f32_16x16x32_bf16 v[0:3], v[176:179], v[226:229], v[0:3]
	v_mfma_f32_16x16x32_bf16 v[30:33], v[172:175], v[222:225], v[22:25]
	v_mfma_f32_16x16x32_bf16 v[18:21], v[180:183], v[222:225], v[18:21]
	v_mfma_f32_16x16x32_bf16 v[4:7], v[172:175], v[230:233], v[4:7]
	v_mfma_f32_16x16x32_bf16 v[0:3], v[180:183], v[230:233], v[0:3]
	s_barrier
	s_setprio 0
	s_add_i32 s66, s66, 2
	s_add_u32 s59, s59, 0x100
	s_addc_u32 s62, s62, 0
	s_cmp_gt_u32 s66, 29
	s_mov_b64 s[12:13], s[20:21]
	s_cbranch_scc0 .LBB0_527
	s_and_b64 vcc, exec, s[14:15]
	s_cbranch_vccz .LBB0_530
	s_barrier

; #define PG8_BAR __builtin_amdgcn_s_barrier()
; template <class Epi>
; __device__ __forceinline__ void gemm_phase(PG8_LAS unsigned char* lds, PG8_LAS unsigned char* xl, const Gemm g, const Sched& S, const Epi& E, const int wid) {
;     ...
;         if (!has_next) break;
; #pragma unroll
;         for (int a = 0; a < 2; ++a)
; #pragma unroll
;             for (int b = 0; b < 2; ++b)
; #pragma unroll
;                 for (int m = 0; m < 4; ++m)
; #pragma unroll
;                     for (int n = 0; n < 2; ++n) acc[a][b][m][n] = (f32x4){0.f, 0.f, 0.f, 0.f};
;         cur = nxt; cA = nA; cB = nB; ++ui;
;         if (wr == 1) PG8_BAR;
.LBB0_620:
	s_andn2_b64 vcc, exec, s[46:47]
	s_mov_b64 s[8:9], -1
	s_cbranch_vccnz .LBB0_523
	s_and_b64 vcc, exec, s[38:39]
	s_cbranch_vccnz .LBB0_522
	s_mov_b32 s100, 1
	s_branch .LBB0_522

; __device__ __forceinline__ const char* a_tile(const Gemm& g, const Unit& u) { return (const char*)(g.A + ((long)u.z1 * g.aS1 + (long)u.z2 * g.aS2 + (long)u.pm * BM * g.lda)); }
; __device__ __forceinline__ const char* b_tile(const Gemm& g, const Unit& u) { return (const char*)(g.Bt + ((long)u.z1 * g.bS1 + (long)u.z2 * g.bS2 + (long)u.pn * BM * g.ldb)); }
; __device__ __forceinline__ int lane_id_opq() { int l; asm volatile("v_mbcnt_lo_u32_b32 %0, -1, 0\n\tv_mbcnt_hi_u32_b32 %0, -1, %0" : "=v"(l)); return l; }
; #define PG8_BAR __builtin_amdgcn_s_barrier()
; template <class Epi>
; __device__ __forceinline__ void gemm_phase(PG8_LAS unsigned char* lds, PG8_LAS unsigned char* xl, const Gemm g, const Sched& S, const Epi& E, const int wid) {
;     ...
;         const bool has_next = S.next(ui + 1, nxt);
;         const char* nA = has_next ? a_tile(g, nxt) : cA; const char* nB = has_next ? b_tile(g, nxt) : cB;
;         for (int t = 0; t < nt; t += 2) {
;             const bool last = (t == nt - 2);
;             const bool do0 = !blkdiag_v<Epi> || t == 0, do1 = !blkdiag_v<Epi> || t != 0;
;             long j1 = 0, ja2 = 0, jb2 = 0;
;             if constexpr (Epi::MID) {
;                 if (t == g.tj) { const int lnM = lane_id_opq(); E.mid(acc, cur, wr, wc, lnM & 15, lnM >> 4); }
;                 if (t >= g.tj) j1 = g.jA;
;                 if (t + 2 >= g.tj) { ja2 = g.jA; jb2 = g.jB; } }
;             const char* a1 = cA + (size_t)(t + 1) * kstep + j1;
;             const char* a2 = last ? nA : cA + (size_t)(t + 2) * kstep + ja2; const char* b2 = last ? nB : cB + (size_t)(t + 2) * kstep + jb2;
;     ...
; #pragma unroll
;         for (int a = 0; a < 2; ++a)
; #pragma unroll
;             for (int b = 0; b < 2; ++b)
; #pragma unroll
;                 for (int m = 0; m < 4; ++m)
; #pragma unroll
;                     for (int n = 0; n < 2; ++n) acc[a][b][m][n] = (f32x4){0.f, 0.f, 0.f, 0.f};
;         cur = nxt; cA = nA; cB = nB; ++ui;
;         if (wr == 1) PG8_BAR;
.LBB0_688:
	s_ashr_i32 s13, s12, 31
	s_lshl_b64 s[10:11], s[12:13], 20
	s_add_u32 s30, s9, s10
	s_addc_u32 s31, s52, s11
	s_and_b64 s[10:11], s[48:49], exec
	s_cselect_b32 s10, s31, s45
	s_cselect_b32 s11, s30, s44
	s_lshl_b32 s40, s40, 8
	s_ashr_i32 s41, s40, 31
	s_lshl_b64 s[42:43], s[40:41], 1
	s_add_u32 s13, s59, s42
	s_addc_u32 s43, s60, s43
	s_mul_i32 s42, s66, 0x580000
	s_mul_hi_i32 s48, s66, 0x580000
	s_add_u32 s42, s13, s42
	s_addc_u32 s43, s43, s48
	s_add_u32 s48, s36, 0x2c0080
	s_addc_u32 s49, s37, 0
	s_add_u32 s13, s44, 0x100
	v_mov_b32_e32 v0, 0
	v_lshl_add_u64 v[136:137], s[48:49], 0, v[160:161]
	v_lshl_add_u64 v[138:139], s[48:49], 0, v[162:163]
	s_addc_u32 s67, s45, 0
	s_mov_b32 s70, -2
	s_mov_b64 s[44:45], 0
	v_mov_b32_e32 v1, v0
	v_mov_b32_e32 v2, v0
	v_mov_b32_e32 v3, v0
	v_mov_b32_e32 v4, v0
	v_mov_b32_e32 v5, v0
	v_mov_b32_e32 v6, v0
	v_mov_b32_e32 v7, v0
	v_mov_b32_e32 v12, v0
	v_mov_b32_e32 v13, v0
	v_mov_b32_e32 v14, v0
	v_mov_b32_e32 v15, v0
	v_mov_b32_e32 v20, v0
	v_mov_b32_e32 v21, v0
	v_mov_b32_e32 v22, v0
	v_mov_b32_e32 v23, v0
	v_mov_b32_e32 v28, v0
	v_mov_b32_e32 v29, v0
	v_mov_b32_e32 v30, v0
	v_mov_b32_e32 v31, v0
	v_mov_b32_e32 v36, v0
	v_mov_b32_e32 v37, v0
	v_mov_b32_e32 v38, v0
	v_mov_b32_e32 v39, v0
	v_mov_b32_e32 v44, v0
	v_mov_b32_e32 v45, v0
	v_mov_b32_e32 v46, v0
	v_mov_b32_e32 v47, v0
	v_mov_b32_e32 v52, v0
	v_mov_b32_e32 v53, v0
	v_mov_b32_e32 v54, v0
	v_mov_b32_e32 v55, v0
	v_mov_b32_e32 v8, v0
	v_mov_b32_e32 v9, v0
	v_mov_b32_e32 v10, v0
	v_mov_b32_e32 v11, v0
	v_mov_b32_e32 v16, v0
	v_mov_b32_e32 v17, v0
	v_mov_b32_e32 v18, v0
	v_mov_b32_e32 v19, v0
	v_mov_b32_e32 v24, v0
	v_mov_b32_e32 v25, v0
	v_mov_b32_e32 v26, v0
	v_mov_b32_e32 v27, v0
	v_mov_b32_e32 v32, v0
	v_mov_b32_e32 v33, v0
	v_mov_b32_e32 v34, v0
	v_mov_b32_e32 v35, v0
	v_mov_b32_e32 v40, v0
	v_mov_b32_e32 v41, v0
	v_mov_b32_e32 v42, v0
	v_mov_b32_e32 v43, v0
	v_mov_b32_e32 v48, v0
	v_mov_b32_e32 v49, v0
	v_mov_b32_e32 v50, v0
	v_mov_b32_e32 v51, v0
	v_mov_b32_e32 v56, v0
	v_mov_b32_e32 v57, v0
	v_mov_b32_e32 v58, v0
	v_mov_b32_e32 v59, v0
	v_mov_b32_e32 v60, v0
	v_mov_b32_e32 v61, v0
	v_mov_b32_e32 v62, v0
	v_mov_b32_e32 v63, v0
	v_mov_b32_e32 v64, v0
	v_mov_b32_e32 v65, v0
	v_mov_b32_e32 v66, v0
	v_mov_b32_e32 v67, v0
	v_mov_b32_e32 v68, v0
	v_mov_b32_e32 v69, v0
	v_mov_b32_e32 v70, v0
	v_mov_b32_e32 v71, v0
	v_mov_b32_e32 v76, v0
	v_mov_b32_e32 v77, v0
	v_mov_b32_e32 v78, v0
	v_mov_b32_e32 v79, v0
	v_mov_b32_e32 v84, v0
	v_mov_b32_e32 v85, v0
	v_mov_b32_e32 v86, v0
	v_mov_b32_e32 v87, v0
	v_mov_b32_e32 v92, v0
	v_mov_b32_e32 v93, v0
	v_mov_b32_e32 v94, v0
	v_mov_b32_e32 v95, v0
	v_mov_b32_e32 v100, v0
	v_mov_b32_e32 v101, v0
	v_mov_b32_e32 v102, v0
	v_mov_b32_e32 v103, v0
	v_mov_b32_e32 v112, v0
	v_mov_b32_e32 v113, v0
	v_mov_b32_e32 v114, v0
	v_mov_b32_e32 v115, v0
	v_mov_b32_e32 v116, v0
	v_mov_b32_e32 v117, v0
	v_mov_b32_e32 v118, v0
	v_mov_b32_e32 v119, v0
	v_mov_b32_e32 v72, v0
	v_mov_b32_e32 v73, v0
	v_mov_b32_e32 v74, v0
	v_mov_b32_e32 v75, v0
	v_mov_b32_e32 v80, v0
	v_mov_b32_e32 v81, v0
	v_mov_b32_e32 v82, v0
	v_mov_b32_e32 v83, v0
	v_mov_b32_e32 v88, v0
	v_mov_b32_e32 v89, v0
	v_mov_b32_e32 v90, v0
	v_mov_b32_e32 v91, v0
	v_mov_b32_e32 v96, v0
	v_mov_b32_e32 v97, v0
	v_mov_b32_e32 v98, v0
	v_mov_b32_e32 v99, v0
	v_mov_b32_e32 v104, v0
	v_mov_b32_e32 v105, v0
	v_mov_b32_e32 v106, v0
	v_mov_b32_e32 v107, v0
	v_mov_b32_e32 v108, v0
	v_mov_b32_e32 v109, v0
	v_mov_b32_e32 v110, v0
	v_mov_b32_e32 v111, v0
	v_mov_b32_e32 v120, v0
	v_mov_b32_e32 v121, v0
	v_mov_b32_e32 v122, v0
	v_mov_b32_e32 v123, v0
	v_mov_b32_e32 v124, v0
	v_mov_b32_e32 v125, v0
	v_mov_b32_e32 v126, v0
	v_mov_b32_e32 v127, v0
	s_cmp_lg_u32 s100, 1
	s_cbranch_scc1 .Ldefbar_skip_5
	s_mov_b32 s100, 0
	s_barrier

; __device__ __forceinline__ int lane_id_opq() { int l; asm volatile("v_mbcnt_lo_u32_b32 %0, -1, 0\n\tv_mbcnt_hi_u32_b32 %0, -1, %0" : "=v"(l)); return l; }
; #define PG8_STAGE(bufoff, gbase, voff) do { _Pragma("unroll") for (int _i = 0; _i < 2; ++_i) \
;         __builtin_amdgcn_global_load_lds((const unsigned*)((const char*)(gbase) + (voff)[_i]), (PG8_LAS unsigned*)(lds + (bufoff) + ldsw + _i * 8192), 16, 0, 0); } while (0)
; #define PG8_LDA(dst, b, h) do { _Pragma("unroll") for (int m = 0; m < 4; ++m) _Pragma("unroll") for (int k = 0; k < 2; ++k) dst[m][k] = *(const PG8_LAS bf16x8*)(lds + PG8_SA(b, h) + aoff + m * 2048 + k * 1024); } while (0)
; #define PG8_LDB(dst, b, h) do { _Pragma("unroll") for (int n = 0; n < 2; ++n) _Pragma("unroll") for (int k = 0; k < 2; ++k) dst[n][k] = *(const PG8_LAS bf16x8*)(lds + PG8_SB(b, h) + boff + n * 2048 + k * 1024); } while (0)
; #define PG8_BAR __builtin_amdgcn_s_barrier()
; template <class Epi>
; __device__ __forceinline__ void gemm_phase(PG8_LAS unsigned char* lds, PG8_LAS unsigned char* xl, const Gemm g, const Sched& S, const Epi& E, const int wid) {
;     ...
;             const bool last = (t == nt - 2);
;             const bool do0 = !blkdiag_v<Epi> || t == 0, do1 = !blkdiag_v<Epi> || t != 0;
;             long j1 = 0, ja2 = 0, jb2 = 0;
;             if constexpr (Epi::MID) {
;                 if (t == g.tj) { const int lnM = lane_id_opq(); E.mid(acc, cur, wr, wc, lnM & 15, lnM >> 4); }
;                 if (t >= g.tj) j1 = g.jA;
;                 if (t + 2 >= g.tj) { ja2 = g.jA; jb2 = g.jB; } }
;             const char* a1 = cA + (size_t)(t + 1) * kstep + j1;
;             const char* a2 = last ? nA : cA + (size_t)(t + 2) * kstep + ja2; const char* b2 = last ? nB : cB + (size_t)(t + 2) * kstep + jb2;
;             const char* a3 = a2 + kstep; const char* b3 = b2 + kstep;
;             PG8_LDB(B0, 0, 0); PG8_LDB(B1, 0, 1); PG8_SCHED; PG8_LDA(At, 0, 0); PG8_STAGE(PG8_SA(1, 1), a1 + hstepA, voffA);
;             PG8_WAIT_V(8); PG8_WAIT_L(0); PG8_BAR; if (do0) { PG8_MMA(0, 0, At, B0); PG8_MMA(0, 1, At, B1); } PG8_BAR; PG8_SCHED;
;             PG8_LDA(At, 0, 1); PG8_STAGE(PG8_SB(0, 0), b2, voffB); PG8_STAGE(PG8_SB(0, 1), b2 + hstepB, voffB); PG8_STAGE(PG8_SA(0, 0), a2, voffA);
;             PG8_WAIT_V(8); PG8_WAIT_L(0); PG8_BAR; if (do1) { PG8_MMA(1, 0, At, B0); PG8_MMA(1, 1, At, B1); } PG8_BAR; PG8_SCHED;
.LBB0_689:
	s_add_i32 s70, s70, 2
	s_cmp_lt_u32 s70, 30
	s_cselect_b32 s48, 0, 0x800
	s_cselect_b32 s49, 0, 0x7ff000
	s_add_u32 s48, s48, s44
	s_addc_u32 s50, 0, s45
	s_add_u32 s48, s36, s48
	s_addc_u32 s50, s37, s50
	s_add_u32 s48, s48, 0x100
	s_addc_u32 s50, s50, 0
	s_add_u32 s49, s49, s44
	s_addc_u32 s51, 0, s45
	s_add_u32 s54, s13, s49
	s_addc_u32 s49, s67, s51
	s_add_i32 s71, 0, 0x10000
	s_cmp_lt_u32 s70, 32
	s_cselect_b32 s55, 0, 0x800
	s_cmpk_eq_i32 s44, 0x1f00
	s_cselect_b32 s51, s21, s50
	s_cselect_b32 s50, s20, s48
	s_cselect_b32 s49, s10, s49
	s_cselect_b32 s48, s11, s54
	s_add_i32 s72, 0, 0x14000
	v_add_u32_e32 v144, s71, v168
	v_add_u32_e32 v174, s72, v168
	ds_read_b128 v[128:131], v144
	ds_read_b128 v[132:135], v144 offset:1024
	ds_read_b128 v[140:143], v144 offset:2048
	ds_read_b128 v[144:147], v144 offset:3072
	ds_read_b128 v[148:151], v174
	ds_read_b128 v[164:167], v174 offset:1024
	ds_read_b128 v[170:173], v174 offset:2048
	ds_read_b128 v[174:177], v174 offset:3072
	s_add_u32 s54, s55, s44
	s_addc_u32 s55, 0, s45
	v_lshl_add_u64 v[190:191], v[136:137], 0, s[54:55]
	s_add_i32 m0, s53, 0xc000
	ds_read_b128 v[178:181], v169
	ds_read_b128 v[182:185], v169 offset:1024
	ds_read_b128 v[186:189], v169 offset:2048
	ds_read_b128 v[210:213], v169 offset:3072
	ds_read_b128 v[214:217], v169 offset:4096
	ds_read_b128 v[218:221], v169 offset:5120
	ds_read_b128 v[222:225], v169 offset:6144
	ds_read_b128 v[226:229], v169 offset:7168
	global_load_lds_dwordx4 v[190:191], off
	v_lshl_add_u64 v[190:191], v[138:139], 0, s[54:55]
	s_add_i32 m0, s53, 0xe000
	s_nop 0
	global_load_lds_dwordx4 v[190:191], off
	s_waitcnt vmcnt(8)
	s_waitcnt lgkmcnt(0)
	s_setprio 1
	s_barrier
	v_mfma_f32_16x16x32_bf16 v[124:127], v[128:131], v[178:181], v[124:127]
	v_mfma_f32_16x16x32_bf16 v[120:123], v[140:143], v[178:181], v[120:123]
	v_mfma_f32_16x16x32_bf16 v[108:111], v[128:131], v[186:189], v[108:111]
	v_mfma_f32_16x16x32_bf16 v[104:107], v[140:143], v[186:189], v[104:107]
	v_mfma_f32_16x16x32_bf16 v[96:99], v[128:131], v[214:217], v[96:99]
	v_mfma_f32_16x16x32_bf16 v[88:91], v[140:143], v[214:217], v[88:91]
	v_mfma_f32_16x16x32_bf16 v[80:83], v[128:131], v[222:225], v[80:83]
	v_mfma_f32_16x16x32_bf16 v[72:75], v[140:143], v[222:225], v[72:75]
	v_mfma_f32_16x16x32_bf16 v[124:127], v[132:135], v[182:185], v[124:127]
	v_mfma_f32_16x16x32_bf16 v[120:123], v[144:147], v[182:185], v[120:123]
	v_mfma_f32_16x16x32_bf16 v[108:111], v[132:135], v[210:213], v[108:111]
	v_mfma_f32_16x16x32_bf16 v[104:107], v[144:147], v[210:213], v[104:107]
	v_mfma_f32_16x16x32_bf16 v[96:99], v[132:135], v[218:221], v[96:99]
	v_mfma_f32_16x16x32_bf16 v[88:91], v[144:147], v[218:221], v[88:91]
	v_mfma_f32_16x16x32_bf16 v[80:83], v[132:135], v[226:229], v[80:83]
	v_mfma_f32_16x16x32_bf16 v[72:75], v[144:147], v[226:229], v[72:75]
	s_setprio 0
	s_setprio 1
	v_mfma_f32_16x16x32_bf16 v[116:119], v[148:151], v[178:181], v[116:119]
	v_mfma_f32_16x16x32_bf16 v[112:115], v[170:173], v[178:181], v[112:115]
	v_mfma_f32_16x16x32_bf16 v[100:103], v[148:151], v[186:189], v[100:103]
	v_mfma_f32_16x16x32_bf16 v[92:95], v[170:173], v[186:189], v[92:95]
	v_mfma_f32_16x16x32_bf16 v[84:87], v[148:151], v[214:217], v[84:87]
	v_mfma_f32_16x16x32_bf16 v[76:79], v[170:173], v[214:217], v[76:79]
	v_mfma_f32_16x16x32_bf16 v[68:71], v[148:151], v[222:225], v[68:71]
	v_mfma_f32_16x16x32_bf16 v[64:67], v[170:173], v[222:225], v[64:67]
	v_mfma_f32_16x16x32_bf16 v[116:119], v[164:167], v[182:185], v[116:119]
	v_mfma_f32_16x16x32_bf16 v[112:115], v[174:177], v[182:185], v[112:115]
	v_mfma_f32_16x16x32_bf16 v[100:103], v[164:167], v[210:213], v[100:103]
	v_mfma_f32_16x16x32_bf16 v[92:95], v[174:177], v[210:213], v[92:95]
	v_mfma_f32_16x16x32_bf16 v[84:87], v[164:167], v[218:221], v[84:87]
	v_mfma_f32_16x16x32_bf16 v[76:79], v[174:177], v[218:221], v[76:79]
	v_mfma_f32_16x16x32_bf16 v[68:71], v[164:167], v[226:229], v[68:71]
	v_mfma_f32_16x16x32_bf16 v[64:67], v[174:177], v[226:229], v[64:67]
	s_barrier
	s_setprio 0
	s_add_i32 s54, s71, s29
	v_lshl_add_u64 v[190:191], s[48:49], 0, v[156:157]
	s_mov_b32 m0, s54
	ds_read_b128 v[178:181], v169 offset:16384
	ds_read_b128 v[182:185], v169 offset:17408
	ds_read_b128 v[186:189], v169 offset:18432
	ds_read_b128 v[210:213], v169 offset:19456
	ds_read_b128 v[214:217], v169 offset:20480
	ds_read_b128 v[218:221], v169 offset:21504
	ds_read_b128 v[222:225], v169 offset:22528
	ds_read_b128 v[226:229], v169 offset:23552
	global_load_lds_dwordx4 v[190:191], off
	s_add_i32 m0, s54, 0x2000
	s_add_u32 s54, s48, 0x80000
	v_lshl_add_u64 v[204:205], s[48:49], 0, v[152:153]
	s_addc_u32 s55, s49, 0
	s_add_i32 s71, s72, s29
	global_load_lds_dwordx4 v[204:205], off
	v_lshl_add_u64 v[230:231], s[54:55], 0, v[156:157]
	s_mov_b32 m0, s71
	v_lshl_add_u64 v[232:233], s[50:51], 0, v[154:155]
	global_load_lds_dwordx4 v[230:231], off
	v_lshl_add_u64 v[230:231], s[54:55], 0, v[152:153]
	s_add_i32 m0, s71, 0x2000
	s_nop 0
	global_load_lds_dwordx4 v[230:231], off
	v_lshl_add_u64 v[230:231], s[50:51], 0, v[158:159]
	s_mov_b32 m0, s53
	s_nop 0
	global_load_lds_dwordx4 v[230:231], off
	s_mov_b32 m0, s56
	s_nop 0
	global_load_lds_dwordx4 v[232:233], off
	s_waitcnt vmcnt(8)
	s_waitcnt lgkmcnt(0)
	s_setprio 1
	s_barrier
; #define PG8_STAGE(bufoff, gbase, voff) do { _Pragma("unroll") for (int _i = 0; _i < 2; ++_i) \
;         __builtin_amdgcn_global_load_lds((const unsigned*)((const char*)(gbase) + (voff)[_i]), (PG8_LAS unsigned*)(lds + (bufoff) + ldsw + _i * 8192), 16, 0, 0); } while (0)
; #define PG8_LDA(dst, b, h) do { _Pragma("unroll") for (int m = 0; m < 4; ++m) _Pragma("unroll") for (int k = 0; k < 2; ++k) dst[m][k] = *(const PG8_LAS bf16x8*)(lds + PG8_SA(b, h) + aoff + m * 2048 + k * 1024); } while (0)
; #define PG8_LDB(dst, b, h) do { _Pragma("unroll") for (int n = 0; n < 2; ++n) _Pragma("unroll") for (int k = 0; k < 2; ++k) dst[n][k] = *(const PG8_LAS bf16x8*)(lds + PG8_SB(b, h) + boff + n * 2048 + k * 1024); } while (0)
; #define PG8_MMA(ai, bj, At, Bt) do { __builtin_amdgcn_s_setprio(1); _Pragma("unroll") for (int m = 0; m < 4; ++m) _Pragma("unroll") for (int n = 0; n < 2; ++n) _Pragma("unroll") for (int k = 0; k < 2; ++k) \
;         acc[ai][bj][m][n] = __builtin_amdgcn_mfma_f32_16x16x32_bf16(Bt[n][k], At[m][k], acc[ai][bj][m][n], 0, 0, 0); __builtin_amdgcn_s_setprio(0); } while (0)
; #define PG8_WAIT_V(n) asm volatile("s_waitcnt vmcnt(" #n ")" ::: "memory")
; #define PG8_WAIT_L(n) asm volatile("s_waitcnt lgkmcnt(" #n ")" ::: "memory")
; #define PG8_BAR __builtin_amdgcn_s_barrier()
; #define PG8_SCHED __builtin_amdgcn_sched_barrier(0)
; template <class Epi>
; __device__ __forceinline__ void gemm_phase(PG8_LAS unsigned char* lds, PG8_LAS unsigned char* xl, const Gemm g, const Sched& S, const Epi& E, const int wid) {
;     ...
;             PG8_WAIT_V(8); PG8_WAIT_L(0); PG8_BAR; if (do1) { PG8_MMA(1, 0, At, B0); PG8_MMA(1, 1, At, B1); } PG8_BAR; PG8_SCHED;
;             PG8_LDB(B0, 1, 0); PG8_LDB(B1, 1, 1); PG8_SCHED; PG8_LDA(At, 1, 0); PG8_STAGE(PG8_SA(0, 1), a2 + hstepA, voffA);
;             PG8_WAIT_V(8); PG8_WAIT_L(0); PG8_BAR; if (do0) { PG8_MMA(0, 0, At, B0); PG8_MMA(0, 1, At, B1); } PG8_BAR; PG8_SCHED;
;             PG8_LDA(At, 1, 1); PG8_STAGE(PG8_SB(1, 0), b3, voffB); PG8_STAGE(PG8_SB(1, 1), b3 + hstepB, voffB); PG8_STAGE(PG8_SA(1, 0), a3, voffA);
;             PG8_WAIT_V(8); PG8_WAIT_L(0); PG8_BAR; if (do1) { PG8_MMA(1, 0, At, B0); PG8_MMA(1, 1, At, B1); } PG8_BAR; PG8_SCHED;
	v_mfma_f32_16x16x32_bf16 v[60:63], v[128:131], v[178:181], v[60:63]
	v_mfma_f32_16x16x32_bf16 v[56:59], v[140:143], v[178:181], v[56:59]
	v_mfma_f32_16x16x32_bf16 v[48:51], v[128:131], v[186:189], v[48:51]
	v_mfma_f32_16x16x32_bf16 v[40:43], v[140:143], v[186:189], v[40:43]
	v_mfma_f32_16x16x32_bf16 v[32:35], v[128:131], v[214:217], v[32:35]
	v_mfma_f32_16x16x32_bf16 v[24:27], v[140:143], v[214:217], v[24:27]
	v_mfma_f32_16x16x32_bf16 v[16:19], v[128:131], v[222:225], v[16:19]
	v_mfma_f32_16x16x32_bf16 v[8:11], v[140:143], v[222:225], v[8:11]
	v_mfma_f32_16x16x32_bf16 v[60:63], v[132:135], v[182:185], v[60:63]
	v_mfma_f32_16x16x32_bf16 v[56:59], v[144:147], v[182:185], v[56:59]
	v_mfma_f32_16x16x32_bf16 v[48:51], v[132:135], v[210:213], v[48:51]
	v_mfma_f32_16x16x32_bf16 v[40:43], v[144:147], v[210:213], v[40:43]
	v_mfma_f32_16x16x32_bf16 v[32:35], v[132:135], v[218:221], v[32:35]
	v_mfma_f32_16x16x32_bf16 v[24:27], v[144:147], v[218:221], v[24:27]
	v_mfma_f32_16x16x32_bf16 v[16:19], v[132:135], v[226:229], v[16:19]
	v_mfma_f32_16x16x32_bf16 v[8:11], v[144:147], v[226:229], v[8:11]
	s_setprio 0
	s_setprio 1
	v_mfma_f32_16x16x32_bf16 v[52:55], v[148:151], v[178:181], v[52:55]
	v_mfma_f32_16x16x32_bf16 v[44:47], v[170:173], v[178:181], v[44:47]
	v_mfma_f32_16x16x32_bf16 v[36:39], v[148:151], v[186:189], v[36:39]
	v_mfma_f32_16x16x32_bf16 v[28:31], v[170:173], v[186:189], v[28:31]
	v_mfma_f32_16x16x32_bf16 v[20:23], v[148:151], v[214:217], v[20:23]
	v_mfma_f32_16x16x32_bf16 v[12:15], v[170:173], v[214:217], v[12:15]
	v_mfma_f32_16x16x32_bf16 v[4:7], v[148:151], v[222:225], v[4:7]
	v_mfma_f32_16x16x32_bf16 v[0:3], v[170:173], v[222:225], v[0:3]
	v_mfma_f32_16x16x32_bf16 v[52:55], v[164:167], v[182:185], v[52:55]
	v_mfma_f32_16x16x32_bf16 v[44:47], v[174:177], v[182:185], v[44:47]
	v_mfma_f32_16x16x32_bf16 v[36:39], v[164:167], v[210:213], v[36:39]
	v_mfma_f32_16x16x32_bf16 v[28:31], v[174:177], v[210:213], v[28:31]
	v_mfma_f32_16x16x32_bf16 v[20:23], v[164:167], v[218:221], v[20:23]
	v_mfma_f32_16x16x32_bf16 v[12:15], v[174:177], v[218:221], v[12:15]
	v_mfma_f32_16x16x32_bf16 v[4:7], v[164:167], v[226:229], v[4:7]
	v_mfma_f32_16x16x32_bf16 v[0:3], v[174:177], v[226:229], v[0:3]
	s_barrier
	s_setprio 0
	s_add_i32 s54, 0, 0x18000
	s_add_i32 s55, 0, 0x1c000
	v_add_u32_e32 v144, s54, v168
	v_add_u32_e32 v174, s55, v168
	ds_read_b128 v[128:131], v144
	ds_read_b128 v[132:135], v144 offset:1024
	ds_read_b128 v[140:143], v144 offset:2048
	ds_read_b128 v[144:147], v144 offset:3072
	ds_read_b128 v[148:151], v174
	ds_read_b128 v[164:167], v174 offset:1024
	ds_read_b128 v[170:173], v174 offset:2048
	ds_read_b128 v[174:177], v174 offset:3072
	s_add_u32 s50, s50, 0x2c0000
	s_addc_u32 s51, s51, 0
	s_mov_b32 m0, s57
	v_lshl_add_u64 v[234:235], s[50:51], 0, v[158:159]
	ds_read_b128 v[178:181], v169 offset:32768
	ds_read_b128 v[182:185], v169 offset:33792
	ds_read_b128 v[186:189], v169 offset:34816
	ds_read_b128 v[210:213], v169 offset:35840
	ds_read_b128 v[214:217], v169 offset:36864
	ds_read_b128 v[218:221], v169 offset:37888
	ds_read_b128 v[222:225], v169 offset:38912
	ds_read_b128 v[226:229], v169 offset:39936
	global_load_lds_dwordx4 v[234:235], off
	v_lshl_add_u64 v[234:235], s[50:51], 0, v[154:155]
	s_mov_b32 m0, s58
	s_nop 0
	global_load_lds_dwordx4 v[234:235], off
	s_waitcnt vmcnt(8)
	s_waitcnt lgkmcnt(0)
	s_setprio 1
	s_barrier
	v_mfma_f32_16x16x32_bf16 v[124:127], v[128:131], v[178:181], v[124:127]
	v_mfma_f32_16x16x32_bf16 v[120:123], v[140:143], v[178:181], v[120:123]
	v_mfma_f32_16x16x32_bf16 v[108:111], v[128:131], v[186:189], v[108:111]
	v_mfma_f32_16x16x32_bf16 v[104:107], v[140:143], v[186:189], v[104:107]
	v_mfma_f32_16x16x32_bf16 v[96:99], v[128:131], v[214:217], v[96:99]
	v_mfma_f32_16x16x32_bf16 v[88:91], v[140:143], v[214:217], v[88:91]
	v_mfma_f32_16x16x32_bf16 v[80:83], v[128:131], v[222:225], v[80:83]
	v_mfma_f32_16x16x32_bf16 v[72:75], v[140:143], v[222:225], v[72:75]
	v_mfma_f32_16x16x32_bf16 v[124:127], v[132:135], v[182:185], v[124:127]
	v_mfma_f32_16x16x32_bf16 v[120:123], v[144:147], v[182:185], v[120:123]
	v_mfma_f32_16x16x32_bf16 v[108:111], v[132:135], v[210:213], v[108:111]
	v_mfma_f32_16x16x32_bf16 v[104:107], v[144:147], v[210:213], v[104:107]
	v_mfma_f32_16x16x32_bf16 v[96:99], v[132:135], v[218:221], v[96:99]
	v_mfma_f32_16x16x32_bf16 v[88:91], v[144:147], v[218:221], v[88:91]
	v_mfma_f32_16x16x32_bf16 v[80:83], v[132:135], v[226:229], v[80:83]
	v_mfma_f32_16x16x32_bf16 v[72:75], v[144:147], v[226:229], v[72:75]
	s_setprio 0
	s_setprio 1
	v_mfma_f32_16x16x32_bf16 v[116:119], v[148:151], v[178:181], v[116:119]
	v_mfma_f32_16x16x32_bf16 v[112:115], v[170:173], v[178:181], v[112:115]
	v_mfma_f32_16x16x32_bf16 v[100:103], v[148:151], v[186:189], v[100:103]
	v_mfma_f32_16x16x32_bf16 v[92:95], v[170:173], v[186:189], v[92:95]
	v_mfma_f32_16x16x32_bf16 v[84:87], v[148:151], v[214:217], v[84:87]
	v_mfma_f32_16x16x32_bf16 v[76:79], v[170:173], v[214:217], v[76:79]
	v_mfma_f32_16x16x32_bf16 v[68:71], v[148:151], v[222:225], v[68:71]
	v_mfma_f32_16x16x32_bf16 v[64:67], v[170:173], v[222:225], v[64:67]
	v_mfma_f32_16x16x32_bf16 v[116:119], v[164:167], v[182:185], v[116:119]
	v_mfma_f32_16x16x32_bf16 v[112:115], v[174:177], v[182:185], v[112:115]
	v_mfma_f32_16x16x32_bf16 v[100:103], v[164:167], v[210:213], v[100:103]
	v_mfma_f32_16x16x32_bf16 v[92:95], v[174:177], v[210:213], v[92:95]
	v_mfma_f32_16x16x32_bf16 v[84:87], v[164:167], v[218:221], v[84:87]
	v_mfma_f32_16x16x32_bf16 v[76:79], v[174:177], v[218:221], v[76:79]
	v_mfma_f32_16x16x32_bf16 v[68:71], v[164:167], v[226:229], v[68:71]
	v_mfma_f32_16x16x32_bf16 v[64:67], v[174:177], v[226:229], v[64:67]
	s_barrier
; #define PG8_STAGE(bufoff, gbase, voff) do { _Pragma("unroll") for (int _i = 0; _i < 2; ++_i) \
;         __builtin_amdgcn_global_load_lds((const unsigned*)((const char*)(gbase) + (voff)[_i]), (PG8_LAS unsigned*)(lds + (bufoff) + ldsw + _i * 8192), 16, 0, 0); } while (0)
; #define PG8_LDA(dst, b, h) do { _Pragma("unroll") for (int m = 0; m < 4; ++m) _Pragma("unroll") for (int k = 0; k < 2; ++k) dst[m][k] = *(const PG8_LAS bf16x8*)(lds + PG8_SA(b, h) + aoff + m * 2048 + k * 1024); } while (0)
; #define PG8_MMA(ai, bj, At, Bt) do { __builtin_amdgcn_s_setprio(1); _Pragma("unroll") for (int m = 0; m < 4; ++m) _Pragma("unroll") for (int n = 0; n < 2; ++n) _Pragma("unroll") for (int k = 0; k < 2; ++k) \
;         acc[ai][bj][m][n] = __builtin_amdgcn_mfma_f32_16x16x32_bf16(Bt[n][k], At[m][k], acc[ai][bj][m][n], 0, 0, 0); __builtin_amdgcn_s_setprio(0); } while (0)
; #define PG8_WAIT_V(n) asm volatile("s_waitcnt vmcnt(" #n ")" ::: "memory")
; #define PG8_WAIT_L(n) asm volatile("s_waitcnt lgkmcnt(" #n ")" ::: "memory")
; #define PG8_BAR __builtin_amdgcn_s_barrier()
; #define PG8_SCHED __builtin_amdgcn_sched_barrier(0)
; template <class Epi>
; __device__ __forceinline__ void gemm_phase(PG8_LAS unsigned char* lds, PG8_LAS unsigned char* xl, const Gemm g, const Sched& S, const Epi& E, const int wid) {
;     ...
;             PG8_LDA(At, 1, 1); PG8_STAGE(PG8_SB(1, 0), b3, voffB); PG8_STAGE(PG8_SB(1, 1), b3 + hstepB, voffB); PG8_STAGE(PG8_SA(1, 0), a3, voffA);
;             PG8_WAIT_V(8); PG8_WAIT_L(0); PG8_BAR; if (do1) { PG8_MMA(1, 0, At, B0); PG8_MMA(1, 1, At, B1); } PG8_BAR; PG8_SCHED;
;         }
	s_setprio 0
	s_add_i32 s50, s54, s29
	v_lshl_add_u64 v[190:191], v[190:191], 0, s[22:23]
	s_mov_b32 m0, s50
	ds_read_b128 v[178:181], v169 offset:49152
	ds_read_b128 v[182:185], v169 offset:50176
	ds_read_b128 v[186:189], v169 offset:51200
	ds_read_b128 v[210:213], v169 offset:52224
	ds_read_b128 v[214:217], v169 offset:53248
	ds_read_b128 v[218:221], v169 offset:54272
	ds_read_b128 v[222:225], v169 offset:55296
	ds_read_b128 v[226:229], v169 offset:56320
	global_load_lds_dwordx4 v[190:191], off
	s_add_i32 m0, s50, 0x2000
	s_add_u32 s48, s48, 0x80080
	v_lshl_add_u64 v[190:191], v[204:205], 0, s[22:23]
	s_addc_u32 s49, s49, 0
	s_add_i32 s50, s55, s29
	global_load_lds_dwordx4 v[190:191], off
	v_lshl_add_u64 v[190:191], s[48:49], 0, v[156:157]
	s_mov_b32 m0, s50
	s_nop 0
	global_load_lds_dwordx4 v[190:191], off
	v_lshl_add_u64 v[190:191], s[48:49], 0, v[152:153]
	s_add_i32 m0, s50, 0x2000
	s_nop 0
	global_load_lds_dwordx4 v[190:191], off
	v_lshl_add_u64 v[190:191], v[230:231], 0, s[22:23]
	s_mov_b32 m0, s76
	s_nop 0
	global_load_lds_dwordx4 v[190:191], off
	v_lshl_add_u64 v[190:191], v[232:233], 0, s[22:23]
	s_mov_b32 m0, s77
	s_nop 0
	global_load_lds_dwordx4 v[190:191], off
	s_waitcnt vmcnt(8)
	s_waitcnt lgkmcnt(0)
	s_setprio 1
	s_barrier
	v_mfma_f32_16x16x32_bf16 v[60:63], v[128:131], v[178:181], v[60:63]
	v_mfma_f32_16x16x32_bf16 v[56:59], v[140:143], v[178:181], v[56:59]
	v_mfma_f32_16x16x32_bf16 v[48:51], v[128:131], v[186:189], v[48:51]
	v_mfma_f32_16x16x32_bf16 v[40:43], v[140:143], v[186:189], v[40:43]
	v_mfma_f32_16x16x32_bf16 v[32:35], v[128:131], v[214:217], v[32:35]
	v_mfma_f32_16x16x32_bf16 v[24:27], v[140:143], v[214:217], v[24:27]
	v_mfma_f32_16x16x32_bf16 v[16:19], v[128:131], v[222:225], v[16:19]
	v_mfma_f32_16x16x32_bf16 v[8:11], v[140:143], v[222:225], v[8:11]
	v_mfma_f32_16x16x32_bf16 v[60:63], v[132:135], v[182:185], v[60:63]
	v_mfma_f32_16x16x32_bf16 v[56:59], v[144:147], v[182:185], v[56:59]
	v_mfma_f32_16x16x32_bf16 v[48:51], v[132:135], v[210:213], v[48:51]
	v_mfma_f32_16x16x32_bf16 v[40:43], v[144:147], v[210:213], v[40:43]
	v_mfma_f32_16x16x32_bf16 v[32:35], v[132:135], v[218:221], v[32:35]
	v_mfma_f32_16x16x32_bf16 v[24:27], v[144:147], v[218:221], v[24:27]
	v_mfma_f32_16x16x32_bf16 v[16:19], v[132:135], v[226:229], v[16:19]
	v_mfma_f32_16x16x32_bf16 v[8:11], v[144:147], v[226:229], v[8:11]
	s_setprio 0
	s_setprio 1
	v_mfma_f32_16x16x32_bf16 v[52:55], v[148:151], v[178:181], v[52:55]
	v_mfma_f32_16x16x32_bf16 v[44:47], v[170:173], v[178:181], v[44:47]
	v_mfma_f32_16x16x32_bf16 v[36:39], v[148:151], v[186:189], v[36:39]
	v_mfma_f32_16x16x32_bf16 v[28:31], v[170:173], v[186:189], v[28:31]
	v_mfma_f32_16x16x32_bf16 v[20:23], v[148:151], v[214:217], v[20:23]
	v_mfma_f32_16x16x32_bf16 v[12:15], v[170:173], v[214:217], v[12:15]
	v_mfma_f32_16x16x32_bf16 v[4:7], v[148:151], v[222:225], v[4:7]
	v_mfma_f32_16x16x32_bf16 v[0:3], v[170:173], v[222:225], v[0:3]
	v_mfma_f32_16x16x32_bf16 v[52:55], v[164:167], v[182:185], v[52:55]
	v_mfma_f32_16x16x32_bf16 v[44:47], v[174:177], v[182:185], v[44:47]
	v_mfma_f32_16x16x32_bf16 v[36:39], v[164:167], v[210:213], v[36:39]
	v_mfma_f32_16x16x32_bf16 v[28:31], v[174:177], v[210:213], v[28:31]
	v_mfma_f32_16x16x32_bf16 v[20:23], v[164:167], v[218:221], v[20:23]
	v_mfma_f32_16x16x32_bf16 v[12:15], v[174:177], v[218:221], v[12:15]
	v_mfma_f32_16x16x32_bf16 v[4:7], v[164:167], v[226:229], v[4:7]
	v_mfma_f32_16x16x32_bf16 v[0:3], v[174:177], v[226:229], v[0:3]
	s_barrier
	s_setprio 0
	s_add_u32 s44, s44, 0x100
	s_addc_u32 s45, 0, s45
	s_cmp_gt_u32 s70, 61
	s_cbranch_scc1 .LBB0_692

; #define PACK8(w, v0, v1) do { w.x = cvt_pk_bf16(v0[0], v0[1]); w.y = cvt_pk_bf16(v0[2], v0[3]); w.z = cvt_pk_bf16(v1[0], v1[1]); w.w = cvt_pk_bf16(v1[2], v1[3]); } while (0)
; #define MUL8(v0, v1, g) do { v0[0] *= bf_lo(g.x); v0[1] *= bf_hi(g.x); v0[2] *= bf_lo(g.y); v0[3] *= bf_hi(g.y); v1[0] *= bf_lo(g.z); v1[1] *= bf_hi(g.z); v1[2] *= bf_lo(g.w); v1[3] *= bf_hi(g.w); } while (0)
;     __device__ __forceinline__ void operator()(EPI_ARGS) const {
;         const long uo = (long)u.pm * BM * ld + u.pn * BM;
;         const char* gb = (const char*)(GS + uo); char* ob = (char*)(O + uo);
;         const unsigned lo = (unsigned)((wr * 64 + 4 * fr) * ld + wc * 32 + 8 * fq) * 2u;
; #pragma unroll
;         for (int ai = 0; ai < 2; ++ai) {
;             u32x4 gq[4][2];
; #pragma unroll
;             for (int m = 0; m < 4; ++m)
; #pragma unroll
;                 for (int bj = 0; bj < 2; ++bj) { const size_t ro = (size_t)(ai * HALF + m) * ld * 2; gq[m][bj] = *(const u32x4*)(gb + ro + lo + bj * 256); }
;             asm volatile("" ::: "memory");
; #pragma unroll
;             for (int m = 0; m < 4; ++m)
; #pragma unroll
;                 for (int bj = 0; bj < 2; ++bj) { const size_t ro = (size_t)(ai * HALF + m) * ld * 2;
;                     f32x4 v0 = acc[ai][bj][m][0], v1 = acc[ai][bj][m][1];
;                     MUL8(v0, v1, gq[m][bj]);
;                     u32x4 w; PACK8(w, v0, v1);
;                     *(u32x4*)(ob + ro + lo + bj * 256) = w; }
.LBB0_694:
	s_mul_i32 s10, s66, 0x2c0000
	v_mbcnt_lo_u32_b32 v128, -1, 0
	v_mbcnt_hi_u32_b32 v128, -1, v128
	s_mul_hi_i32 s11, s66, 0x2c0000
	s_add_u32 s10, s10, s40
	v_lshlrev_b32_e32 v129, 3, v128
	s_addc_u32 s11, s11, s41
	v_and_b32_e32 v129, 0x78, v129
	s_lshl_b64 s[10:11], s[10:11], 1
	v_or_b32_e32 v129, s65, v129
	s_add_u32 s40, s61, s10
	v_and_b32_e32 v128, -16, v128
	v_mul_lo_u32 v129, v129, s17
	s_addc_u32 s41, s62, s11
	v_add3_u32 v192, v128, s75, v129
	global_load_dwordx4 v[170:173], v192, s[40:41]
	global_load_dwordx4 v[174:177], v192, s[40:41] offset:256
	v_lshl_add_u64 v[166:167], s[40:41], 0, v[192:193]
	v_add_co_u32_e32 v128, vcc, s19, v166
	s_add_u32 s36, s68, s10
	s_nop 0
	v_addc_co_u32_e32 v129, vcc, 0, v167, vcc
	global_load_dwordx4 v[148:151], v[128:129], off offset:2048
	global_load_dwordx4 v[144:147], v[128:129], off offset:2304
	v_add_co_u32_e32 v128, vcc, s27, v166
	s_addc_u32 s37, s69, s11
	s_nop 0
	v_addc_co_u32_e32 v129, vcc, 0, v167, vcc
	global_load_dwordx4 v[140:143], v[128:129], off
	global_load_dwordx4 v[132:135], v[128:129], off offset:256
	v_add_co_u32_e32 v128, vcc, s34, v166
	v_lshl_add_u64 v[164:165], s[36:37], 0, v[192:193]
	s_nop 0
	v_addc_co_u32_e32 v129, vcc, 0, v167, vcc
	global_load_dwordx4 v[136:139], v[128:129], off offset:2048
	s_nop 0
	global_load_dwordx4 v[128:131], v[128:129], off offset:2304
	s_mov_b64 s[10:11], -1
	s_waitcnt vmcnt(0)
	v_lshlrev_b32_e32 v178, 16, v170
	v_and_b32_e32 v170, 0xffff0000, v170
	v_mul_f32_e32 v125, v125, v170
	v_lshlrev_b32_e32 v170, 16, v171
	v_mul_f32_e32 v126, v126, v170
	v_and_b32_e32 v170, 0xffff0000, v171
	v_mul_f32_e32 v127, v127, v170
	v_lshlrev_b32_e32 v170, 16, v172
	v_mul_f32_e32 v170, v120, v170
	v_and_b32_e32 v120, 0xffff0000, v172
	v_mul_f32_e32 v171, v121, v120
	v_lshlrev_b32_e32 v120, 16, v173
	v_mul_f32_e32 v172, v122, v120
	v_and_b32_e32 v120, 0xffff0000, v173
	v_mul_f32_e32 v124, v124, v178
	v_mul_f32_e32 v123, v123, v120
	v_cvt_pk_bf16_f32 v120, v124, v125
	v_cvt_pk_bf16_f32 v121, v126, v127
	v_cvt_pk_bf16_f32 v122, v170, v171
	v_cvt_pk_bf16_f32 v123, v172, v123
	global_store_dwordx4 v192, v[120:123], s[36:37]
	s_nop 1
	v_lshlrev_b32_e32 v120, 16, v174
	v_mul_f32_e32 v116, v116, v120
	v_and_b32_e32 v120, 0xffff0000, v174
	v_mul_f32_e32 v117, v117, v120
	v_lshlrev_b32_e32 v120, 16, v175
	v_mul_f32_e32 v118, v118, v120
	v_and_b32_e32 v120, 0xffff0000, v175
	v_mul_f32_e32 v119, v119, v120
	v_lshlrev_b32_e32 v120, 16, v176
	v_mul_f32_e32 v120, v112, v120
	v_and_b32_e32 v112, 0xffff0000, v176
	v_mul_f32_e32 v121, v113, v112
	v_lshlrev_b32_e32 v112, 16, v177
	v_mul_f32_e32 v122, v114, v112
	v_and_b32_e32 v112, 0xffff0000, v177
	v_mul_f32_e32 v115, v115, v112
	v_cvt_pk_bf16_f32 v112, v116, v117
	v_cvt_pk_bf16_f32 v113, v118, v119
	v_cvt_pk_bf16_f32 v114, v120, v121
	v_cvt_pk_bf16_f32 v115, v122, v115
	global_store_dwordx4 v192, v[112:115], s[36:37] offset:256
	s_nop 1
	v_lshlrev_b32_e32 v112, 16, v148
	v_mul_f32_e32 v108, v108, v112
	v_and_b32_e32 v112, 0xffff0000, v148
	v_mul_f32_e32 v109, v109, v112
	v_lshlrev_b32_e32 v112, 16, v149
	v_mul_f32_e32 v110, v110, v112
	v_and_b32_e32 v112, 0xffff0000, v149
	v_mul_f32_e32 v111, v111, v112
	v_lshlrev_b32_e32 v112, 16, v150
	v_mul_f32_e32 v112, v104, v112
	v_and_b32_e32 v104, 0xffff0000, v150
	v_mul_f32_e32 v113, v105, v104
	v_lshlrev_b32_e32 v104, 16, v151
	v_mul_f32_e32 v114, v106, v104
	v_and_b32_e32 v104, 0xffff0000, v151
	v_mul_f32_e32 v107, v107, v104
	v_cvt_pk_bf16_f32 v104, v108, v109
	v_add_co_u32_e32 v108, vcc, s19, v164
	v_cvt_pk_bf16_f32 v105, v110, v111
	v_cvt_pk_bf16_f32 v106, v112, v113
	v_cvt_pk_bf16_f32 v107, v114, v107
	s_nop 1
	v_addc_co_u32_e32 v109, vcc, 0, v165, vcc
	global_store_dwordx4 v[108:109], v[104:107], off offset:2048
	s_nop 1
	v_lshlrev_b32_e32 v104, 16, v144
	v_mul_f32_e32 v100, v100, v104
	v_and_b32_e32 v104, 0xffff0000, v144
	v_mul_f32_e32 v101, v101, v104
	v_lshlrev_b32_e32 v104, 16, v145
	v_mul_f32_e32 v102, v102, v104
	v_and_b32_e32 v104, 0xffff0000, v145
	v_mul_f32_e32 v103, v103, v104
	v_lshlrev_b32_e32 v104, 16, v146
	v_mul_f32_e32 v104, v92, v104
	v_and_b32_e32 v92, 0xffff0000, v146
	v_mul_f32_e32 v105, v93, v92
	v_lshlrev_b32_e32 v92, 16, v147
	v_mul_f32_e32 v106, v94, v92
	v_and_b32_e32 v92, 0xffff0000, v147
	v_mul_f32_e32 v95, v95, v92
	v_cvt_pk_bf16_f32 v92, v100, v101
	v_cvt_pk_bf16_f32 v93, v102, v103
	v_cvt_pk_bf16_f32 v94, v104, v105
	v_cvt_pk_bf16_f32 v95, v106, v95
	global_store_dwordx4 v[108:109], v[92:95], off offset:2304
	s_nop 1
	v_lshlrev_b32_e32 v92, 16, v140
	v_mul_f32_e32 v92, v96, v92
	v_lshlrev_b32_e32 v96, 16, v142
	v_and_b32_e32 v93, 0xffff0000, v140
	v_mul_f32_e32 v96, v88, v96
	v_and_b32_e32 v88, 0xffff0000, v142
	v_mul_f32_e32 v93, v97, v93
	v_lshlrev_b32_e32 v94, 16, v141
	v_mul_f32_e32 v97, v89, v88
	v_lshlrev_b32_e32 v88, 16, v143
	v_mul_f32_e32 v94, v98, v94
	v_mul_f32_e32 v98, v90, v88
	v_and_b32_e32 v88, 0xffff0000, v143
	v_mul_f32_e32 v91, v91, v88
	v_cvt_pk_bf16_f32 v88, v92, v93
	v_add_co_u32_e32 v92, vcc, s27, v164
	v_and_b32_e32 v95, 0xffff0000, v141
	s_nop 0
	v_addc_co_u32_e32 v93, vcc, 0, v165, vcc
	v_mul_f32_e32 v95, v99, v95
	v_cvt_pk_bf16_f32 v89, v94, v95
	v_cvt_pk_bf16_f32 v90, v96, v97
	v_cvt_pk_bf16_f32 v91, v98, v91
	global_store_dwordx4 v[92:93], v[88:91], off
	s_nop 1
	v_lshlrev_b32_e32 v88, 16, v132
	v_mul_f32_e32 v84, v84, v88
	v_and_b32_e32 v88, 0xffff0000, v132
	v_mul_f32_e32 v85, v85, v88
	v_lshlrev_b32_e32 v88, 16, v133
	v_mul_f32_e32 v86, v86, v88
	v_and_b32_e32 v88, 0xffff0000, v133
	v_mul_f32_e32 v87, v87, v88
	v_lshlrev_b32_e32 v88, 16, v134
	v_mul_f32_e32 v88, v76, v88
	v_and_b32_e32 v76, 0xffff0000, v134
; #define PACK8(w, v0, v1) do { w.x = cvt_pk_bf16(v0[0], v0[1]); w.y = cvt_pk_bf16(v0[2], v0[3]); w.z = cvt_pk_bf16(v1[0], v1[1]); w.w = cvt_pk_bf16(v1[2], v1[3]); } while (0)
; #define MUL8(v0, v1, g) do { v0[0] *= bf_lo(g.x); v0[1] *= bf_hi(g.x); v0[2] *= bf_lo(g.y); v0[3] *= bf_hi(g.y); v1[0] *= bf_lo(g.z); v1[1] *= bf_hi(g.z); v1[2] *= bf_lo(g.w); v1[3] *= bf_hi(g.w); } while (0)
;     __device__ __forceinline__ void operator()(EPI_ARGS) const {
;     ...
; #pragma unroll
;         for (int ai = 0; ai < 2; ++ai) {
;             u32x4 gq[4][2];
; #pragma unroll
;             for (int m = 0; m < 4; ++m)
; #pragma unroll
;                 for (int bj = 0; bj < 2; ++bj) { const size_t ro = (size_t)(ai * HALF + m) * ld * 2; gq[m][bj] = *(const u32x4*)(gb + ro + lo + bj * 256); }
;             asm volatile("" ::: "memory");
; #pragma unroll
;             for (int m = 0; m < 4; ++m)
; #pragma unroll
;                 for (int bj = 0; bj < 2; ++bj) { const size_t ro = (size_t)(ai * HALF + m) * ld * 2;
;                     f32x4 v0 = acc[ai][bj][m][0], v1 = acc[ai][bj][m][1];
;                     MUL8(v0, v1, gq[m][bj]);
;                     u32x4 w; PACK8(w, v0, v1);
;                     *(u32x4*)(ob + ro + lo + bj * 256) = w; }
	v_mul_f32_e32 v89, v77, v76
	v_lshlrev_b32_e32 v76, 16, v135
	v_mul_f32_e32 v90, v78, v76
	v_and_b32_e32 v76, 0xffff0000, v135
	v_mul_f32_e32 v79, v79, v76
	v_cvt_pk_bf16_f32 v76, v84, v85
	v_cvt_pk_bf16_f32 v77, v86, v87
	v_cvt_pk_bf16_f32 v78, v88, v89
	v_cvt_pk_bf16_f32 v79, v90, v79
	global_store_dwordx4 v[92:93], v[76:79], off offset:256
	s_nop 1
	v_lshlrev_b32_e32 v76, 16, v136
	v_mul_f32_e32 v76, v80, v76
	v_lshlrev_b32_e32 v80, 16, v138
	v_and_b32_e32 v77, 0xffff0000, v136
	v_mul_f32_e32 v80, v72, v80
	v_and_b32_e32 v72, 0xffff0000, v138
	v_mul_f32_e32 v77, v81, v77
	v_lshlrev_b32_e32 v78, 16, v137
	v_mul_f32_e32 v81, v73, v72
	v_lshlrev_b32_e32 v72, 16, v139
	v_mul_f32_e32 v78, v82, v78
	v_mul_f32_e32 v82, v74, v72
	v_and_b32_e32 v72, 0xffff0000, v139
	v_mul_f32_e32 v75, v75, v72
	v_cvt_pk_bf16_f32 v72, v76, v77
	v_add_co_u32_e32 v76, vcc, s34, v164
	v_and_b32_e32 v79, 0xffff0000, v137
	s_nop 0
	v_addc_co_u32_e32 v77, vcc, 0, v165, vcc
	v_mul_f32_e32 v79, v83, v79
	v_cvt_pk_bf16_f32 v73, v78, v79
	v_cvt_pk_bf16_f32 v74, v80, v81
	v_cvt_pk_bf16_f32 v75, v82, v75
	global_store_dwordx4 v[76:77], v[72:75], off offset:2048
	s_nop 1
	v_lshlrev_b32_e32 v72, 16, v128
	v_mul_f32_e32 v68, v68, v72
	v_and_b32_e32 v72, 0xffff0000, v128
	v_mul_f32_e32 v69, v69, v72
	v_lshlrev_b32_e32 v72, 16, v129
	v_mul_f32_e32 v70, v70, v72
	v_and_b32_e32 v72, 0xffff0000, v129
	v_mul_f32_e32 v71, v71, v72
	v_lshlrev_b32_e32 v72, 16, v130
	v_mul_f32_e32 v72, v64, v72
	v_and_b32_e32 v64, 0xffff0000, v130
	v_mul_f32_e32 v73, v65, v64
	v_lshlrev_b32_e32 v64, 16, v131
	v_mul_f32_e32 v74, v66, v64
	v_and_b32_e32 v64, 0xffff0000, v131
	v_mul_f32_e32 v67, v67, v64
	v_cvt_pk_bf16_f32 v64, v68, v69
	v_cvt_pk_bf16_f32 v65, v70, v71
	v_cvt_pk_bf16_f32 v66, v72, v73
	v_cvt_pk_bf16_f32 v67, v74, v67
	global_store_dwordx4 v[76:77], v[64:67], off offset:2304
	v_add_co_u32_e32 v68, vcc, s80, v166
	s_nop 1
	v_addc_co_u32_e32 v69, vcc, 0, v167, vcc
	global_load_dwordx4 v[64:67], v[68:69], off
	s_nop 0
	global_load_dwordx4 v[68:71], v[68:69], off offset:256
	v_add_co_u32_e32 v76, vcc, s81, v166
	s_waitcnt vmcnt(1)
	v_lshlrev_b32_e32 v96, 16, v64
	v_addc_co_u32_e32 v77, vcc, 0, v167, vcc
	global_load_dwordx4 v[72:75], v[76:77], off offset:2048
	s_nop 0
	global_load_dwordx4 v[76:79], v[76:77], off offset:2304
	v_add_co_u32_e32 v84, vcc, s82, v166
	v_and_b32_e32 v64, 0xffff0000, v64
	s_nop 0
	v_addc_co_u32_e32 v85, vcc, 0, v167, vcc
	global_load_dwordx4 v[80:83], v[84:85], off
	s_nop 0
	global_load_dwordx4 v[84:87], v[84:85], off offset:256
	v_add_co_u32_e32 v92, vcc, s83, v166
	v_mul_f32_e32 v61, v61, v64
	s_nop 0
	v_addc_co_u32_e32 v93, vcc, 0, v167, vcc
	global_load_dwordx4 v[88:91], v[92:93], off offset:2048
	s_nop 0
	global_load_dwordx4 v[92:95], v[92:93], off offset:2304
	v_lshlrev_b32_e32 v64, 16, v65
	v_mul_f32_e32 v62, v62, v64
	v_and_b32_e32 v64, 0xffff0000, v65
	v_mul_f32_e32 v63, v63, v64
	v_lshlrev_b32_e32 v64, 16, v66
	v_mul_f32_e32 v64, v56, v64
	v_and_b32_e32 v56, 0xffff0000, v66
	v_mul_f32_e32 v65, v57, v56
	v_lshlrev_b32_e32 v56, 16, v67
	v_mul_f32_e32 v60, v60, v96
	v_mul_f32_e32 v66, v58, v56
	v_and_b32_e32 v56, 0xffff0000, v67
	v_mul_f32_e32 v59, v59, v56
	v_cvt_pk_bf16_f32 v56, v60, v61
	v_add_co_u32_e32 v60, vcc, s80, v164
	v_cvt_pk_bf16_f32 v57, v62, v63
	v_cvt_pk_bf16_f32 v58, v64, v65
	v_cvt_pk_bf16_f32 v59, v66, v59
	s_nop 1
	v_addc_co_u32_e32 v61, vcc, 0, v165, vcc
	global_store_dwordx4 v[60:61], v[56:59], off
	s_waitcnt vmcnt(7)
	s_nop 0
	v_lshlrev_b32_e32 v56, 16, v68
	v_mul_f32_e32 v52, v52, v56
	v_and_b32_e32 v56, 0xffff0000, v68
	v_mul_f32_e32 v53, v53, v56
	v_lshlrev_b32_e32 v56, 16, v69
	v_mul_f32_e32 v54, v54, v56
	v_and_b32_e32 v56, 0xffff0000, v69
	v_mul_f32_e32 v55, v55, v56
	v_lshlrev_b32_e32 v56, 16, v70
	v_mul_f32_e32 v56, v44, v56
	v_and_b32_e32 v44, 0xffff0000, v70
	v_mul_f32_e32 v57, v45, v44
	v_lshlrev_b32_e32 v44, 16, v71
	v_mul_f32_e32 v58, v46, v44
	v_and_b32_e32 v44, 0xffff0000, v71
	v_mul_f32_e32 v47, v47, v44
	v_cvt_pk_bf16_f32 v44, v52, v53
	v_cvt_pk_bf16_f32 v45, v54, v55
	v_cvt_pk_bf16_f32 v46, v56, v57
	v_cvt_pk_bf16_f32 v47, v58, v47
	global_store_dwordx4 v[60:61], v[44:47], off offset:256
	s_waitcnt vmcnt(7)
; #define PACK8(w, v0, v1) do { w.x = cvt_pk_bf16(v0[0], v0[1]); w.y = cvt_pk_bf16(v0[2], v0[3]); w.z = cvt_pk_bf16(v1[0], v1[1]); w.w = cvt_pk_bf16(v1[2], v1[3]); } while (0)
; #define MUL8(v0, v1, g) do { v0[0] *= bf_lo(g.x); v0[1] *= bf_hi(g.x); v0[2] *= bf_lo(g.y); v0[3] *= bf_hi(g.y); v1[0] *= bf_lo(g.z); v1[1] *= bf_hi(g.z); v1[2] *= bf_lo(g.w); v1[3] *= bf_hi(g.w); } while (0)
; #define PG8_BAR __builtin_amdgcn_s_barrier()
;     __device__ __forceinline__ void operator()(EPI_ARGS) const {
;     ...
;             for (int m = 0; m < 4; ++m)
; #pragma unroll
;                 for (int bj = 0; bj < 2; ++bj) { const size_t ro = (size_t)(ai * HALF + m) * ld * 2;
;                     f32x4 v0 = acc[ai][bj][m][0], v1 = acc[ai][bj][m][1];
;                     MUL8(v0, v1, gq[m][bj]);
;                     u32x4 w; PACK8(w, v0, v1);
;                     *(u32x4*)(ob + ro + lo + bj * 256) = w; }
;             asm volatile("" ::: "memory"); }
; template <class Epi>
; __device__ __forceinline__ void gemm_phase(PG8_LAS unsigned char* lds, PG8_LAS unsigned char* xl, const Gemm g, const Sched& S, const Epi& E, const int wid) {
;     ...
;         if (!has_next) break;
; #pragma unroll
;         for (int a = 0; a < 2; ++a)
; #pragma unroll
;             for (int b = 0; b < 2; ++b)
; #pragma unroll
;                 for (int m = 0; m < 4; ++m)
; #pragma unroll
;                     for (int n = 0; n < 2; ++n) acc[a][b][m][n] = (f32x4){0.f, 0.f, 0.f, 0.f};
;         cur = nxt; cA = nA; cB = nB; ++ui;
;         if (wr == 1) PG8_BAR;
	s_nop 0
	v_lshlrev_b32_e32 v44, 16, v72
	v_mul_f32_e32 v44, v48, v44
	v_lshlrev_b32_e32 v48, 16, v74
	v_and_b32_e32 v45, 0xffff0000, v72
	v_mul_f32_e32 v48, v40, v48
	v_and_b32_e32 v40, 0xffff0000, v74
	v_mul_f32_e32 v45, v49, v45
	v_lshlrev_b32_e32 v46, 16, v73
	v_mul_f32_e32 v49, v41, v40
	v_lshlrev_b32_e32 v40, 16, v75
	v_mul_f32_e32 v46, v50, v46
	v_mul_f32_e32 v50, v42, v40
	v_and_b32_e32 v40, 0xffff0000, v75
	v_mul_f32_e32 v43, v43, v40
	v_cvt_pk_bf16_f32 v40, v44, v45
	v_add_co_u32_e32 v44, vcc, s81, v164
	v_and_b32_e32 v47, 0xffff0000, v73
	s_nop 0
	v_addc_co_u32_e32 v45, vcc, 0, v165, vcc
	v_mul_f32_e32 v47, v51, v47
	v_cvt_pk_bf16_f32 v41, v46, v47
	v_cvt_pk_bf16_f32 v42, v48, v49
	v_cvt_pk_bf16_f32 v43, v50, v43
	global_store_dwordx4 v[44:45], v[40:43], off offset:2048
	s_waitcnt vmcnt(7)
	s_nop 0
	v_lshlrev_b32_e32 v40, 16, v76
	v_mul_f32_e32 v36, v36, v40
	v_and_b32_e32 v40, 0xffff0000, v76
	v_mul_f32_e32 v37, v37, v40
	v_lshlrev_b32_e32 v40, 16, v77
	v_mul_f32_e32 v38, v38, v40
	v_and_b32_e32 v40, 0xffff0000, v77
	v_mul_f32_e32 v39, v39, v40
	v_lshlrev_b32_e32 v40, 16, v78
	v_mul_f32_e32 v40, v28, v40
	v_and_b32_e32 v28, 0xffff0000, v78
	v_mul_f32_e32 v41, v29, v28
	v_lshlrev_b32_e32 v28, 16, v79
	v_mul_f32_e32 v42, v30, v28
	v_and_b32_e32 v28, 0xffff0000, v79
	v_mul_f32_e32 v31, v31, v28
	v_cvt_pk_bf16_f32 v28, v36, v37
	v_cvt_pk_bf16_f32 v29, v38, v39
	v_cvt_pk_bf16_f32 v30, v40, v41
	v_cvt_pk_bf16_f32 v31, v42, v31
	global_store_dwordx4 v[44:45], v[28:31], off offset:2304
	s_waitcnt vmcnt(7)
	s_nop 0
	v_lshlrev_b32_e32 v28, 16, v80
	v_mul_f32_e32 v28, v32, v28
	v_lshlrev_b32_e32 v32, 16, v82
	v_and_b32_e32 v29, 0xffff0000, v80
	v_mul_f32_e32 v32, v24, v32
	v_and_b32_e32 v24, 0xffff0000, v82
	v_mul_f32_e32 v29, v33, v29
	v_lshlrev_b32_e32 v30, 16, v81
	v_mul_f32_e32 v33, v25, v24
	v_lshlrev_b32_e32 v24, 16, v83
	v_mul_f32_e32 v30, v34, v30
	v_mul_f32_e32 v34, v26, v24
	v_and_b32_e32 v24, 0xffff0000, v83
	v_mul_f32_e32 v27, v27, v24
	v_cvt_pk_bf16_f32 v24, v28, v29
	v_add_co_u32_e32 v28, vcc, s82, v164
	v_and_b32_e32 v31, 0xffff0000, v81
	s_nop 0
	v_addc_co_u32_e32 v29, vcc, 0, v165, vcc
	v_mul_f32_e32 v31, v35, v31
	v_cvt_pk_bf16_f32 v25, v30, v31
	v_cvt_pk_bf16_f32 v26, v32, v33
	v_cvt_pk_bf16_f32 v27, v34, v27
	global_store_dwordx4 v[28:29], v[24:27], off
	s_waitcnt vmcnt(7)
	s_nop 0
	v_lshlrev_b32_e32 v24, 16, v84
	v_mul_f32_e32 v20, v20, v24
	v_and_b32_e32 v24, 0xffff0000, v84
	v_mul_f32_e32 v21, v21, v24
	v_lshlrev_b32_e32 v24, 16, v85
	v_mul_f32_e32 v22, v22, v24
	v_and_b32_e32 v24, 0xffff0000, v85
	v_mul_f32_e32 v23, v23, v24
	v_lshlrev_b32_e32 v24, 16, v86
	v_mul_f32_e32 v24, v12, v24
	v_and_b32_e32 v12, 0xffff0000, v86
	v_mul_f32_e32 v25, v13, v12
	v_lshlrev_b32_e32 v12, 16, v87
	v_mul_f32_e32 v26, v14, v12
	v_and_b32_e32 v12, 0xffff0000, v87
	v_mul_f32_e32 v15, v15, v12
	v_cvt_pk_bf16_f32 v12, v20, v21
	v_cvt_pk_bf16_f32 v13, v22, v23
	v_cvt_pk_bf16_f32 v14, v24, v25
	v_cvt_pk_bf16_f32 v15, v26, v15
	global_store_dwordx4 v[28:29], v[12:15], off offset:256
	s_waitcnt vmcnt(7)
	s_nop 0
	v_lshlrev_b32_e32 v12, 16, v88
	v_mul_f32_e32 v12, v16, v12
	v_lshlrev_b32_e32 v16, 16, v90
	v_and_b32_e32 v13, 0xffff0000, v88
	v_mul_f32_e32 v16, v8, v16
	v_and_b32_e32 v8, 0xffff0000, v90
	v_mul_f32_e32 v13, v17, v13
	v_lshlrev_b32_e32 v14, 16, v89
	v_mul_f32_e32 v17, v9, v8
	v_lshlrev_b32_e32 v8, 16, v91
	v_mul_f32_e32 v14, v18, v14
	v_mul_f32_e32 v18, v10, v8
	v_and_b32_e32 v8, 0xffff0000, v91
	v_mul_f32_e32 v11, v11, v8
	v_cvt_pk_bf16_f32 v8, v12, v13
	v_add_co_u32_e32 v12, vcc, s83, v164
	v_and_b32_e32 v15, 0xffff0000, v89
	s_nop 0
	v_addc_co_u32_e32 v13, vcc, 0, v165, vcc
	v_mul_f32_e32 v15, v19, v15
	v_cvt_pk_bf16_f32 v9, v14, v15
	v_cvt_pk_bf16_f32 v10, v16, v17
	v_cvt_pk_bf16_f32 v11, v18, v11
	global_store_dwordx4 v[12:13], v[8:11], off offset:2048
	s_and_b64 vcc, exec, s[46:47]
	s_waitcnt vmcnt(7)
	v_lshlrev_b32_e32 v8, 16, v92
	v_mul_f32_e32 v4, v4, v8
	v_and_b32_e32 v8, 0xffff0000, v92
	v_mul_f32_e32 v5, v5, v8
	v_lshlrev_b32_e32 v8, 16, v93
	v_mul_f32_e32 v6, v6, v8
	v_and_b32_e32 v8, 0xffff0000, v93
	v_mul_f32_e32 v7, v7, v8
	v_lshlrev_b32_e32 v8, 16, v94
	v_mul_f32_e32 v8, v0, v8
	v_and_b32_e32 v0, 0xffff0000, v94
	v_mul_f32_e32 v9, v1, v0
	v_lshlrev_b32_e32 v0, 16, v95
	v_mul_f32_e32 v10, v2, v0
	v_and_b32_e32 v0, 0xffff0000, v95
	v_mul_f32_e32 v3, v3, v0
	v_cvt_pk_bf16_f32 v0, v4, v5
	v_cvt_pk_bf16_f32 v1, v6, v7
	v_cvt_pk_bf16_f32 v2, v8, v9
	v_cvt_pk_bf16_f32 v3, v10, v3
	global_store_dwordx4 v[12:13], v[0:3], off offset:2304
	s_cbranch_vccnz .LBB0_683
	s_and_b64 vcc, exec, s[38:39]
	s_cbranch_vccnz .LBB0_682
	s_mov_b32 s100, 1
	s_branch .LBB0_682

; #define PG8_STAGE(bufoff, gbase, voff) do { _Pragma("unroll") for (int _i = 0; _i < 2; ++_i) \
;         __builtin_amdgcn_global_load_lds((const unsigned*)((const char*)(gbase) + (voff)[_i]), (PG8_LAS unsigned*)(lds + (bufoff) + ldsw + _i * 8192), 16, 0, 0); } while (0)
; #define PG8_LDA(dst, b, h) do { _Pragma("unroll") for (int m = 0; m < 4; ++m) _Pragma("unroll") for (int k = 0; k < 2; ++k) dst[m][k] = *(const PG8_LAS bf16x8*)(lds + PG8_SA(b, h) + aoff + m * 2048 + k * 1024); } while (0)
; #define PG8_LDB(dst, b, h) do { _Pragma("unroll") for (int n = 0; n < 2; ++n) _Pragma("unroll") for (int k = 0; k < 2; ++k) dst[n][k] = *(const PG8_LAS bf16x8*)(lds + PG8_SB(b, h) + boff + n * 2048 + k * 1024); } while (0)
; #define PG8_MMA(ai, bj, At, Bt) do { __builtin_amdgcn_s_setprio(1); _Pragma("unroll") for (int m = 0; m < 4; ++m) _Pragma("unroll") for (int n = 0; n < 2; ++n) _Pragma("unroll") for (int k = 0; k < 2; ++k) \
;         acc[ai][bj][m][n] = __builtin_amdgcn_mfma_f32_16x16x32_bf16(Bt[n][k], At[m][k], acc[ai][bj][m][n], 0, 0, 0); __builtin_amdgcn_s_setprio(0); } while (0)
; #define PG8_WAIT_V(n) asm volatile("s_waitcnt vmcnt(" #n ")" ::: "memory")
; #define PG8_WAIT_L(n) asm volatile("s_waitcnt lgkmcnt(" #n ")" ::: "memory")
; #define PG8_BAR __builtin_amdgcn_s_barrier()
; template <class Epi>
; __device__ __forceinline__ void gemm_phase(PG8_LAS unsigned char* lds, PG8_LAS unsigned char* xl, const Gemm g, const Sched& S, const Epi& E, const int wid) {
;     ...
;             const char* a1 = cA + (size_t)(t + 1) * kstep + j1;
;             const char* a2 = last ? nA : cA + (size_t)(t + 2) * kstep + ja2; const char* b2 = last ? nB : cB + (size_t)(t + 2) * kstep + jb2;
;             const char* a3 = a2 + kstep; const char* b3 = b2 + kstep;
;             PG8_LDB(B0, 0, 0); PG8_LDB(B1, 0, 1); PG8_SCHED; PG8_LDA(At, 0, 0); PG8_STAGE(PG8_SA(1, 1), a1 + hstepA, voffA);
;             PG8_WAIT_V(8); PG8_WAIT_L(0); PG8_BAR; if (do0) { PG8_MMA(0, 0, At, B0); PG8_MMA(0, 1, At, B1); } PG8_BAR; PG8_SCHED;
;     ...
;         for (int a = 0; a < 2; ++a)
; #pragma unroll
;             for (int b = 0; b < 2; ++b)
; #pragma unroll
;                 for (int m = 0; m < 4; ++m)
; #pragma unroll
;                     for (int n = 0; n < 2; ++n) acc[a][b][m][n] = (f32x4){0.f, 0.f, 0.f, 0.f};
;         cur = nxt; cA = nA; cB = nB; ++ui;
;         if (wr == 1) PG8_BAR;
.LBB0_764:
	s_ashr_i32 s31, s30, 31
	s_lshl_b64 s[8:9], s[30:31], 20
	s_add_u32 s40, s51, s8
	s_addc_u32 s41, s52, s9
	s_and_b64 s[8:9], s[48:49], exec
	s_cselect_b32 s8, s41, s45
	s_cselect_b32 s9, s40, s44
	s_add_u32 s42, s42, 0x2c0080
	s_addc_u32 s43, s43, 0
	s_add_u32 s10, s44, 0x100
	v_mov_b32_e32 v0, 0
	s_addc_u32 s11, s45, 0
	s_mov_b32 s13, -2
	s_waitcnt lgkmcnt(0)
	v_mov_b32_e32 v1, v0
	v_mov_b32_e32 v2, v0
	v_mov_b32_e32 v3, v0
	v_mov_b32_e32 v4, v0
	v_mov_b32_e32 v5, v0
	v_mov_b32_e32 v6, v0
	v_mov_b32_e32 v7, v0
	v_mov_b32_e32 v16, v0
	v_mov_b32_e32 v17, v0
	v_mov_b32_e32 v18, v0
	v_mov_b32_e32 v19, v0
	v_mov_b32_e32 v20, v0
	v_mov_b32_e32 v21, v0
	v_mov_b32_e32 v22, v0
	v_mov_b32_e32 v23, v0
	v_mov_b32_e32 v32, v0
	v_mov_b32_e32 v33, v0
	v_mov_b32_e32 v34, v0
	v_mov_b32_e32 v35, v0
	v_mov_b32_e32 v36, v0
	v_mov_b32_e32 v37, v0
	v_mov_b32_e32 v38, v0
	v_mov_b32_e32 v39, v0
	v_mov_b32_e32 v48, v0
	v_mov_b32_e32 v49, v0
	v_mov_b32_e32 v50, v0
	v_mov_b32_e32 v51, v0
	v_mov_b32_e32 v52, v0
	v_mov_b32_e32 v53, v0
	v_mov_b32_e32 v54, v0
	v_mov_b32_e32 v55, v0
	v_mov_b32_e32 v8, v0
	v_mov_b32_e32 v9, v0
	v_mov_b32_e32 v10, v0
	v_mov_b32_e32 v11, v0
	v_mov_b32_e32 v12, v0
	v_mov_b32_e32 v13, v0
	v_mov_b32_e32 v14, v0
	v_mov_b32_e32 v15, v0
	v_mov_b32_e32 v24, v0
	v_mov_b32_e32 v25, v0
	v_mov_b32_e32 v26, v0
	v_mov_b32_e32 v27, v0
	v_mov_b32_e32 v28, v0
	v_mov_b32_e32 v29, v0
	v_mov_b32_e32 v30, v0
	v_mov_b32_e32 v31, v0
	v_mov_b32_e32 v40, v0
	v_mov_b32_e32 v41, v0
	v_mov_b32_e32 v42, v0
	v_mov_b32_e32 v43, v0
	v_mov_b32_e32 v44, v0
	v_mov_b32_e32 v45, v0
	v_mov_b32_e32 v46, v0
	v_mov_b32_e32 v47, v0
	v_mov_b32_e32 v56, v0
	v_mov_b32_e32 v57, v0
	v_mov_b32_e32 v58, v0
	v_mov_b32_e32 v59, v0
	v_mov_b32_e32 v60, v0
	v_mov_b32_e32 v61, v0
	v_mov_b32_e32 v62, v0
	v_mov_b32_e32 v63, v0
	v_mov_b32_e32 v64, v0
	v_mov_b32_e32 v65, v0
	v_mov_b32_e32 v66, v0
	v_mov_b32_e32 v67, v0
	v_mov_b32_e32 v68, v0
	v_mov_b32_e32 v69, v0
	v_mov_b32_e32 v70, v0
	v_mov_b32_e32 v71, v0
	v_mov_b32_e32 v80, v0
	v_mov_b32_e32 v81, v0
	v_mov_b32_e32 v82, v0
	v_mov_b32_e32 v83, v0
	v_mov_b32_e32 v84, v0
	v_mov_b32_e32 v85, v0
	v_mov_b32_e32 v86, v0
	v_mov_b32_e32 v87, v0
	v_mov_b32_e32 v96, v0
	v_mov_b32_e32 v97, v0
	v_mov_b32_e32 v98, v0
	v_mov_b32_e32 v99, v0
	v_mov_b32_e32 v100, v0
	v_mov_b32_e32 v101, v0
	v_mov_b32_e32 v102, v0
	v_mov_b32_e32 v103, v0
	v_mov_b32_e32 v112, v0
	v_mov_b32_e32 v113, v0
	v_mov_b32_e32 v114, v0
	v_mov_b32_e32 v115, v0
	v_mov_b32_e32 v116, v0
	v_mov_b32_e32 v117, v0
	v_mov_b32_e32 v118, v0
	v_mov_b32_e32 v119, v0
	v_mov_b32_e32 v72, v0
	v_mov_b32_e32 v73, v0
	v_mov_b32_e32 v74, v0
	v_mov_b32_e32 v75, v0
	v_mov_b32_e32 v76, v0
	v_mov_b32_e32 v77, v0
	v_mov_b32_e32 v78, v0
	v_mov_b32_e32 v79, v0
	v_mov_b32_e32 v88, v0
	v_mov_b32_e32 v89, v0
	v_mov_b32_e32 v90, v0
	v_mov_b32_e32 v91, v0
	v_mov_b32_e32 v92, v0
	v_mov_b32_e32 v93, v0
	v_mov_b32_e32 v94, v0
	v_mov_b32_e32 v95, v0
	v_mov_b32_e32 v104, v0
	v_mov_b32_e32 v105, v0
	v_mov_b32_e32 v106, v0
	v_mov_b32_e32 v107, v0
	v_mov_b32_e32 v108, v0
	v_mov_b32_e32 v109, v0
	v_mov_b32_e32 v110, v0
	v_mov_b32_e32 v111, v0
	v_mov_b32_e32 v132, v0
	v_mov_b32_e32 v133, v0
	v_mov_b32_e32 v134, v0
	v_mov_b32_e32 v135, v0
	v_mov_b32_e32 v140, v0
	v_mov_b32_e32 v141, v0
	v_mov_b32_e32 v142, v0
	v_mov_b32_e32 v143, v0
	s_cmp_lg_u32 s100, 1
	s_cbranch_scc1 .Ldefbar_skip_6
	s_mov_b32 s100, 0
	s_barrier
.Ldefbar_skip_6:
.LBB0_765:
	s_add_u32 s21, s42, 0xffd40080
	s_addc_u32 s31, s43, -1
	s_add_i32 s54, 0, 0x10000
	s_cmp_eq_u32 s13, 28
	s_cselect_b32 s49, s37, s31
	s_cselect_b32 s48, s36, s21
	s_cselect_b32 s45, s8, s11
	s_cselect_b32 s44, s9, s10
	s_add_i32 s21, 0, 0x14000
	v_add_u32_e32 v136, s54, v195
	v_add_u32_e32 v156, s21, v195
	ds_read_b128 v[120:123], v136
	ds_read_b128 v[124:127], v136 offset:1024
	ds_read_b128 v[128:131], v136 offset:2048
	ds_read_b128 v[136:139], v136 offset:3072
	ds_read_b128 v[144:147], v156
	ds_read_b128 v[148:151], v156 offset:1024
	ds_read_b128 v[152:155], v156 offset:2048
	ds_read_b128 v[156:159], v156 offset:3072
	v_lshl_add_u64 v[204:205], s[42:43], 0, v[214:215]
	s_add_i32 m0, s53, 0xc000
	ds_read_b128 v[160:163], v220
	ds_read_b128 v[164:167], v220 offset:1024
	ds_read_b128 v[168:171], v220 offset:2048
	ds_read_b128 v[172:175], v220 offset:3072
	ds_read_b128 v[176:179], v220 offset:4096
	ds_read_b128 v[180:183], v220 offset:5120
	ds_read_b128 v[184:187], v220 offset:6144
	ds_read_b128 v[222:225], v220 offset:7168
	global_load_lds_dwordx4 v[204:205], off
	v_lshl_add_u64 v[204:205], s[42:43], 0, v[216:217]
	s_add_i32 m0, s53, 0xe000
	s_nop 0
	global_load_lds_dwordx4 v[204:205], off
	s_waitcnt vmcnt(8)
	s_waitcnt lgkmcnt(0)
	s_setprio 1
	s_barrier
; #define PG8_STAGE(bufoff, gbase, voff) do { _Pragma("unroll") for (int _i = 0; _i < 2; ++_i) \
;         __builtin_amdgcn_global_load_lds((const unsigned*)((const char*)(gbase) + (voff)[_i]), (PG8_LAS unsigned*)(lds + (bufoff) + ldsw + _i * 8192), 16, 0, 0); } while (0)
; #define PG8_LDA(dst, b, h) do { _Pragma("unroll") for (int m = 0; m < 4; ++m) _Pragma("unroll") for (int k = 0; k < 2; ++k) dst[m][k] = *(const PG8_LAS bf16x8*)(lds + PG8_SA(b, h) + aoff + m * 2048 + k * 1024); } while (0)
; #define PG8_LDB(dst, b, h) do { _Pragma("unroll") for (int n = 0; n < 2; ++n) _Pragma("unroll") for (int k = 0; k < 2; ++k) dst[n][k] = *(const PG8_LAS bf16x8*)(lds + PG8_SB(b, h) + boff + n * 2048 + k * 1024); } while (0)
; #define PG8_MMA(ai, bj, At, Bt) do { __builtin_amdgcn_s_setprio(1); _Pragma("unroll") for (int m = 0; m < 4; ++m) _Pragma("unroll") for (int n = 0; n < 2; ++n) _Pragma("unroll") for (int k = 0; k < 2; ++k) \
;         acc[ai][bj][m][n] = __builtin_amdgcn_mfma_f32_16x16x32_bf16(Bt[n][k], At[m][k], acc[ai][bj][m][n], 0, 0, 0); __builtin_amdgcn_s_setprio(0); } while (0)
; #define PG8_WAIT_V(n) asm volatile("s_waitcnt vmcnt(" #n ")" ::: "memory")
; #define PG8_WAIT_L(n) asm volatile("s_waitcnt lgkmcnt(" #n ")" ::: "memory")
; #define PG8_BAR __builtin_amdgcn_s_barrier()
; #define PG8_SCHED __builtin_amdgcn_sched_barrier(0)
; template <class Epi>
; __device__ __forceinline__ void gemm_phase(PG8_LAS unsigned char* lds, PG8_LAS unsigned char* xl, const Gemm g, const Sched& S, const Epi& E, const int wid) {
;     ...
;             PG8_WAIT_V(8); PG8_WAIT_L(0); PG8_BAR; if (do0) { PG8_MMA(0, 0, At, B0); PG8_MMA(0, 1, At, B1); } PG8_BAR; PG8_SCHED;
;             PG8_LDA(At, 0, 1); PG8_STAGE(PG8_SB(0, 0), b2, voffB); PG8_STAGE(PG8_SB(0, 1), b2 + hstepB, voffB); PG8_STAGE(PG8_SA(0, 0), a2, voffA);
;             PG8_WAIT_V(8); PG8_WAIT_L(0); PG8_BAR; if (do1) { PG8_MMA(1, 0, At, B0); PG8_MMA(1, 1, At, B1); } PG8_BAR; PG8_SCHED;
;             PG8_LDB(B0, 1, 0); PG8_LDB(B1, 1, 1); PG8_SCHED; PG8_LDA(At, 1, 0); PG8_STAGE(PG8_SA(0, 1), a2 + hstepA, voffA);
;             PG8_WAIT_V(8); PG8_WAIT_L(0); PG8_BAR; if (do0) { PG8_MMA(0, 0, At, B0); PG8_MMA(0, 1, At, B1); } PG8_BAR; PG8_SCHED;
	v_mfma_f32_16x16x32_bf16 v[140:143], v[120:123], v[160:163], v[140:143]
	v_mfma_f32_16x16x32_bf16 v[132:135], v[128:131], v[160:163], v[132:135]
	v_mfma_f32_16x16x32_bf16 v[108:111], v[120:123], v[168:171], v[108:111]
	v_mfma_f32_16x16x32_bf16 v[104:107], v[128:131], v[168:171], v[104:107]
	v_mfma_f32_16x16x32_bf16 v[92:95], v[120:123], v[176:179], v[92:95]
	v_mfma_f32_16x16x32_bf16 v[88:91], v[128:131], v[176:179], v[88:91]
	v_mfma_f32_16x16x32_bf16 v[76:79], v[120:123], v[184:187], v[76:79]
	v_mfma_f32_16x16x32_bf16 v[72:75], v[128:131], v[184:187], v[72:75]
	v_mfma_f32_16x16x32_bf16 v[140:143], v[124:127], v[164:167], v[140:143]
	v_mfma_f32_16x16x32_bf16 v[132:135], v[136:139], v[164:167], v[132:135]
	v_mfma_f32_16x16x32_bf16 v[108:111], v[124:127], v[172:175], v[108:111]
	v_mfma_f32_16x16x32_bf16 v[104:107], v[136:139], v[172:175], v[104:107]
	v_mfma_f32_16x16x32_bf16 v[92:95], v[124:127], v[180:183], v[92:95]
	v_mfma_f32_16x16x32_bf16 v[88:91], v[136:139], v[180:183], v[88:91]
	v_mfma_f32_16x16x32_bf16 v[76:79], v[124:127], v[222:225], v[76:79]
	v_mfma_f32_16x16x32_bf16 v[72:75], v[136:139], v[222:225], v[72:75]
	s_setprio 0
	s_setprio 1
	v_mfma_f32_16x16x32_bf16 v[116:119], v[144:147], v[160:163], v[116:119]
	v_mfma_f32_16x16x32_bf16 v[112:115], v[152:155], v[160:163], v[112:115]
	v_mfma_f32_16x16x32_bf16 v[100:103], v[144:147], v[168:171], v[100:103]
	v_mfma_f32_16x16x32_bf16 v[96:99], v[152:155], v[168:171], v[96:99]
	v_mfma_f32_16x16x32_bf16 v[84:87], v[144:147], v[176:179], v[84:87]
	v_mfma_f32_16x16x32_bf16 v[80:83], v[152:155], v[176:179], v[80:83]
	v_mfma_f32_16x16x32_bf16 v[68:71], v[144:147], v[184:187], v[68:71]
	v_mfma_f32_16x16x32_bf16 v[64:67], v[152:155], v[184:187], v[64:67]
	v_mfma_f32_16x16x32_bf16 v[116:119], v[148:151], v[164:167], v[116:119]
	v_mfma_f32_16x16x32_bf16 v[112:115], v[156:159], v[164:167], v[112:115]
	v_mfma_f32_16x16x32_bf16 v[100:103], v[148:151], v[172:175], v[100:103]
	v_mfma_f32_16x16x32_bf16 v[96:99], v[156:159], v[172:175], v[96:99]
	v_mfma_f32_16x16x32_bf16 v[84:87], v[148:151], v[180:183], v[84:87]
	v_mfma_f32_16x16x32_bf16 v[80:83], v[156:159], v[180:183], v[80:83]
	v_mfma_f32_16x16x32_bf16 v[68:71], v[148:151], v[222:225], v[68:71]
	v_mfma_f32_16x16x32_bf16 v[64:67], v[156:159], v[222:225], v[64:67]
	s_barrier
	s_setprio 0
	s_add_i32 s31, s54, s29
	v_lshl_add_u64 v[204:205], s[44:45], 0, v[190:191]
	s_mov_b32 m0, s31
	ds_read_b128 v[160:163], v220 offset:16384
	ds_read_b128 v[164:167], v220 offset:17408
	ds_read_b128 v[168:171], v220 offset:18432
	ds_read_b128 v[172:175], v220 offset:19456
	ds_read_b128 v[176:179], v220 offset:20480
	ds_read_b128 v[180:183], v220 offset:21504
	ds_read_b128 v[184:187], v220 offset:22528
	ds_read_b128 v[222:225], v220 offset:23552
	global_load_lds_dwordx4 v[204:205], off
	s_add_i32 m0, s31, 0x2000
	s_add_u32 s54, s44, 0x80000
	v_lshl_add_u64 v[218:219], s[44:45], 0, v[212:213]
	s_addc_u32 s55, s45, 0
	s_add_i32 s21, s21, s29
	global_load_lds_dwordx4 v[218:219], off
	v_lshl_add_u64 v[226:227], s[54:55], 0, v[190:191]
	s_mov_b32 m0, s21
	v_lshl_add_u64 v[228:229], s[48:49], 0, v[210:211]
	global_load_lds_dwordx4 v[226:227], off
	v_lshl_add_u64 v[226:227], s[54:55], 0, v[212:213]
	s_add_i32 m0, s21, 0x2000
	s_nop 0
	global_load_lds_dwordx4 v[226:227], off
	v_lshl_add_u64 v[226:227], s[48:49], 0, v[188:189]
	s_mov_b32 m0, s53
	s_nop 0
	global_load_lds_dwordx4 v[226:227], off
	s_mov_b32 m0, s56
	s_nop 0
	global_load_lds_dwordx4 v[228:229], off
	s_waitcnt vmcnt(8)
	s_waitcnt lgkmcnt(0)
	s_setprio 1
	s_barrier
	v_mfma_f32_16x16x32_bf16 v[60:63], v[120:123], v[160:163], v[60:63]
	v_mfma_f32_16x16x32_bf16 v[56:59], v[128:131], v[160:163], v[56:59]
	v_mfma_f32_16x16x32_bf16 v[44:47], v[120:123], v[168:171], v[44:47]
	v_mfma_f32_16x16x32_bf16 v[40:43], v[128:131], v[168:171], v[40:43]
	v_mfma_f32_16x16x32_bf16 v[28:31], v[120:123], v[176:179], v[28:31]
	v_mfma_f32_16x16x32_bf16 v[24:27], v[128:131], v[176:179], v[24:27]
	v_mfma_f32_16x16x32_bf16 v[12:15], v[120:123], v[184:187], v[12:15]
	v_mfma_f32_16x16x32_bf16 v[8:11], v[128:131], v[184:187], v[8:11]
	v_mfma_f32_16x16x32_bf16 v[60:63], v[124:127], v[164:167], v[60:63]
	v_mfma_f32_16x16x32_bf16 v[56:59], v[136:139], v[164:167], v[56:59]
	v_mfma_f32_16x16x32_bf16 v[44:47], v[124:127], v[172:175], v[44:47]
	v_mfma_f32_16x16x32_bf16 v[40:43], v[136:139], v[172:175], v[40:43]
	v_mfma_f32_16x16x32_bf16 v[28:31], v[124:127], v[180:183], v[28:31]
	v_mfma_f32_16x16x32_bf16 v[24:27], v[136:139], v[180:183], v[24:27]
	v_mfma_f32_16x16x32_bf16 v[12:15], v[124:127], v[222:225], v[12:15]
	v_mfma_f32_16x16x32_bf16 v[8:11], v[136:139], v[222:225], v[8:11]
	s_setprio 0
	s_setprio 1
	v_mfma_f32_16x16x32_bf16 v[52:55], v[144:147], v[160:163], v[52:55]
	v_mfma_f32_16x16x32_bf16 v[48:51], v[152:155], v[160:163], v[48:51]
	v_mfma_f32_16x16x32_bf16 v[36:39], v[144:147], v[168:171], v[36:39]
	v_mfma_f32_16x16x32_bf16 v[32:35], v[152:155], v[168:171], v[32:35]
	v_mfma_f32_16x16x32_bf16 v[20:23], v[144:147], v[176:179], v[20:23]
	v_mfma_f32_16x16x32_bf16 v[16:19], v[152:155], v[176:179], v[16:19]
	v_mfma_f32_16x16x32_bf16 v[4:7], v[144:147], v[184:187], v[4:7]
	v_mfma_f32_16x16x32_bf16 v[0:3], v[152:155], v[184:187], v[0:3]
	v_mfma_f32_16x16x32_bf16 v[52:55], v[148:151], v[164:167], v[52:55]
	v_mfma_f32_16x16x32_bf16 v[48:51], v[156:159], v[164:167], v[48:51]
	v_mfma_f32_16x16x32_bf16 v[36:39], v[148:151], v[172:175], v[36:39]
	v_mfma_f32_16x16x32_bf16 v[32:35], v[156:159], v[172:175], v[32:35]
	v_mfma_f32_16x16x32_bf16 v[20:23], v[148:151], v[180:183], v[20:23]
	v_mfma_f32_16x16x32_bf16 v[16:19], v[156:159], v[180:183], v[16:19]
	v_mfma_f32_16x16x32_bf16 v[4:7], v[148:151], v[222:225], v[4:7]
	v_mfma_f32_16x16x32_bf16 v[0:3], v[156:159], v[222:225], v[0:3]
	s_barrier
; #define PG8_STAGE(bufoff, gbase, voff) do { _Pragma("unroll") for (int _i = 0; _i < 2; ++_i) \
;         __builtin_amdgcn_global_load_lds((const unsigned*)((const char*)(gbase) + (voff)[_i]), (PG8_LAS unsigned*)(lds + (bufoff) + ldsw + _i * 8192), 16, 0, 0); } while (0)
; #define PG8_LDA(dst, b, h) do { _Pragma("unroll") for (int m = 0; m < 4; ++m) _Pragma("unroll") for (int k = 0; k < 2; ++k) dst[m][k] = *(const PG8_LAS bf16x8*)(lds + PG8_SA(b, h) + aoff + m * 2048 + k * 1024); } while (0)
; #define PG8_LDB(dst, b, h) do { _Pragma("unroll") for (int n = 0; n < 2; ++n) _Pragma("unroll") for (int k = 0; k < 2; ++k) dst[n][k] = *(const PG8_LAS bf16x8*)(lds + PG8_SB(b, h) + boff + n * 2048 + k * 1024); } while (0)
; #define PG8_MMA(ai, bj, At, Bt) do { __builtin_amdgcn_s_setprio(1); _Pragma("unroll") for (int m = 0; m < 4; ++m) _Pragma("unroll") for (int n = 0; n < 2; ++n) _Pragma("unroll") for (int k = 0; k < 2; ++k) \
;         acc[ai][bj][m][n] = __builtin_amdgcn_mfma_f32_16x16x32_bf16(Bt[n][k], At[m][k], acc[ai][bj][m][n], 0, 0, 0); __builtin_amdgcn_s_setprio(0); } while (0)
; #define PG8_WAIT_V(n) asm volatile("s_waitcnt vmcnt(" #n ")" ::: "memory")
; #define PG8_WAIT_L(n) asm volatile("s_waitcnt lgkmcnt(" #n ")" ::: "memory")
; #define PG8_BAR __builtin_amdgcn_s_barrier()
; #define PG8_SCHED __builtin_amdgcn_sched_barrier(0)
; template <class Epi>
; __device__ __forceinline__ void gemm_phase(PG8_LAS unsigned char* lds, PG8_LAS unsigned char* xl, const Gemm g, const Sched& S, const Epi& E, const int wid) {
;     ...
;             PG8_LDB(B0, 1, 0); PG8_LDB(B1, 1, 1); PG8_SCHED; PG8_LDA(At, 1, 0); PG8_STAGE(PG8_SA(0, 1), a2 + hstepA, voffA);
;             PG8_WAIT_V(8); PG8_WAIT_L(0); PG8_BAR; if (do0) { PG8_MMA(0, 0, At, B0); PG8_MMA(0, 1, At, B1); } PG8_BAR; PG8_SCHED;
;             PG8_LDA(At, 1, 1); PG8_STAGE(PG8_SB(1, 0), b3, voffB); PG8_STAGE(PG8_SB(1, 1), b3 + hstepB, voffB); PG8_STAGE(PG8_SA(1, 0), a3, voffA);
;             PG8_WAIT_V(8); PG8_WAIT_L(0); PG8_BAR; if (do1) { PG8_MMA(1, 0, At, B0); PG8_MMA(1, 1, At, B1); } PG8_BAR; PG8_SCHED;
	s_setprio 0
	s_add_i32 s21, 0, 0x18000
	s_add_i32 s31, 0, 0x1c000
	v_add_u32_e32 v136, s21, v195
	v_add_u32_e32 v156, s31, v195
	ds_read_b128 v[120:123], v136
	ds_read_b128 v[124:127], v136 offset:1024
	ds_read_b128 v[128:131], v136 offset:2048
	ds_read_b128 v[136:139], v136 offset:3072
	ds_read_b128 v[144:147], v156
	ds_read_b128 v[148:151], v156 offset:1024
	ds_read_b128 v[152:155], v156 offset:2048
	ds_read_b128 v[156:159], v156 offset:3072
	s_add_u32 s48, s48, 0x2c0000
	s_addc_u32 s49, s49, 0
	s_mov_b32 m0, s57
	v_lshl_add_u64 v[230:231], s[48:49], 0, v[188:189]
	ds_read_b128 v[160:163], v220 offset:32768
	ds_read_b128 v[164:167], v220 offset:33792
	ds_read_b128 v[168:171], v220 offset:34816
	ds_read_b128 v[172:175], v220 offset:35840
	ds_read_b128 v[176:179], v220 offset:36864
	ds_read_b128 v[180:183], v220 offset:37888
	ds_read_b128 v[184:187], v220 offset:38912
	ds_read_b128 v[222:225], v220 offset:39936
	global_load_lds_dwordx4 v[230:231], off
	v_lshl_add_u64 v[230:231], s[48:49], 0, v[210:211]
	s_mov_b32 m0, s58
	s_nop 0
	global_load_lds_dwordx4 v[230:231], off
	s_waitcnt vmcnt(8)
	s_waitcnt lgkmcnt(0)
	s_setprio 1
	s_barrier
	v_mfma_f32_16x16x32_bf16 v[140:143], v[120:123], v[160:163], v[140:143]
	v_mfma_f32_16x16x32_bf16 v[132:135], v[128:131], v[160:163], v[132:135]
	v_mfma_f32_16x16x32_bf16 v[108:111], v[120:123], v[168:171], v[108:111]
	v_mfma_f32_16x16x32_bf16 v[104:107], v[128:131], v[168:171], v[104:107]
	v_mfma_f32_16x16x32_bf16 v[92:95], v[120:123], v[176:179], v[92:95]
	v_mfma_f32_16x16x32_bf16 v[88:91], v[128:131], v[176:179], v[88:91]
	v_mfma_f32_16x16x32_bf16 v[76:79], v[120:123], v[184:187], v[76:79]
	v_mfma_f32_16x16x32_bf16 v[72:75], v[128:131], v[184:187], v[72:75]
	v_mfma_f32_16x16x32_bf16 v[140:143], v[124:127], v[164:167], v[140:143]
	v_mfma_f32_16x16x32_bf16 v[132:135], v[136:139], v[164:167], v[132:135]
	v_mfma_f32_16x16x32_bf16 v[108:111], v[124:127], v[172:175], v[108:111]
	v_mfma_f32_16x16x32_bf16 v[104:107], v[136:139], v[172:175], v[104:107]
	v_mfma_f32_16x16x32_bf16 v[92:95], v[124:127], v[180:183], v[92:95]
	v_mfma_f32_16x16x32_bf16 v[88:91], v[136:139], v[180:183], v[88:91]
	v_mfma_f32_16x16x32_bf16 v[76:79], v[124:127], v[222:225], v[76:79]
	v_mfma_f32_16x16x32_bf16 v[72:75], v[136:139], v[222:225], v[72:75]
	s_setprio 0
	s_setprio 1
	v_mfma_f32_16x16x32_bf16 v[116:119], v[144:147], v[160:163], v[116:119]
	v_mfma_f32_16x16x32_bf16 v[112:115], v[152:155], v[160:163], v[112:115]
	v_mfma_f32_16x16x32_bf16 v[100:103], v[144:147], v[168:171], v[100:103]
	v_mfma_f32_16x16x32_bf16 v[96:99], v[152:155], v[168:171], v[96:99]
	v_mfma_f32_16x16x32_bf16 v[84:87], v[144:147], v[176:179], v[84:87]
	v_mfma_f32_16x16x32_bf16 v[80:83], v[152:155], v[176:179], v[80:83]
	v_mfma_f32_16x16x32_bf16 v[68:71], v[144:147], v[184:187], v[68:71]
	v_mfma_f32_16x16x32_bf16 v[64:67], v[152:155], v[184:187], v[64:67]
	v_mfma_f32_16x16x32_bf16 v[116:119], v[148:151], v[164:167], v[116:119]
	v_mfma_f32_16x16x32_bf16 v[112:115], v[156:159], v[164:167], v[112:115]
	v_mfma_f32_16x16x32_bf16 v[100:103], v[148:151], v[172:175], v[100:103]
	v_mfma_f32_16x16x32_bf16 v[96:99], v[156:159], v[172:175], v[96:99]
	v_mfma_f32_16x16x32_bf16 v[84:87], v[148:151], v[180:183], v[84:87]
	v_mfma_f32_16x16x32_bf16 v[80:83], v[156:159], v[180:183], v[80:83]
	v_mfma_f32_16x16x32_bf16 v[68:71], v[148:151], v[222:225], v[68:71]
	v_mfma_f32_16x16x32_bf16 v[64:67], v[156:159], v[222:225], v[64:67]
	s_barrier
	s_setprio 0
	s_add_i32 s21, s21, s29
	v_lshl_add_u64 v[204:205], v[204:205], 0, s[22:23]
	s_mov_b32 m0, s21
	ds_read_b128 v[160:163], v220 offset:49152
	ds_read_b128 v[164:167], v220 offset:50176
	ds_read_b128 v[168:171], v220 offset:51200
	ds_read_b128 v[172:175], v220 offset:52224
	ds_read_b128 v[176:179], v220 offset:53248
	ds_read_b128 v[180:183], v220 offset:54272
	ds_read_b128 v[184:187], v220 offset:55296
	ds_read_b128 v[222:225], v220 offset:56320
	global_load_lds_dwordx4 v[204:205], off
	s_add_i32 m0, s21, 0x2000
	s_add_u32 s44, s44, 0x80080
	v_lshl_add_u64 v[204:205], v[218:219], 0, s[22:23]
	s_addc_u32 s45, s45, 0
	s_add_i32 s21, s31, s29
	global_load_lds_dwordx4 v[204:205], off
	v_lshl_add_u64 v[204:205], s[44:45], 0, v[190:191]
	s_mov_b32 m0, s21
	s_nop 0
	global_load_lds_dwordx4 v[204:205], off
	v_lshl_add_u64 v[204:205], s[44:45], 0, v[212:213]
	s_add_i32 m0, s21, 0x2000
	s_nop 0
	global_load_lds_dwordx4 v[204:205], off
	v_lshl_add_u64 v[204:205], v[226:227], 0, s[22:23]
	s_mov_b32 m0, s66
	s_nop 0
	global_load_lds_dwordx4 v[204:205], off
	v_lshl_add_u64 v[204:205], v[228:229], 0, s[22:23]
	s_mov_b32 m0, s67
	s_nop 0
	global_load_lds_dwordx4 v[204:205], off
	s_waitcnt vmcnt(8)
	s_waitcnt lgkmcnt(0)
	s_setprio 1
	s_barrier
; #define PG8_MMA(ai, bj, At, Bt) do { __builtin_amdgcn_s_setprio(1); _Pragma("unroll") for (int m = 0; m < 4; ++m) _Pragma("unroll") for (int n = 0; n < 2; ++n) _Pragma("unroll") for (int k = 0; k < 2; ++k) \
;         acc[ai][bj][m][n] = __builtin_amdgcn_mfma_f32_16x16x32_bf16(Bt[n][k], At[m][k], acc[ai][bj][m][n], 0, 0, 0); __builtin_amdgcn_s_setprio(0); } while (0)
; #define PG8_WAIT_V(n) asm volatile("s_waitcnt vmcnt(" #n ")" ::: "memory")
; #define PG8_WAIT_L(n) asm volatile("s_waitcnt lgkmcnt(" #n ")" ::: "memory")
; #define PG8_BAR __builtin_amdgcn_s_barrier()
; #define PG8_SCHED __builtin_amdgcn_sched_barrier(0)
; template <class Epi>
; __device__ __forceinline__ void gemm_phase(PG8_LAS unsigned char* lds, PG8_LAS unsigned char* xl, const Gemm g, const Sched& S, const Epi& E, const int wid) {
;     ...
;             PG8_WAIT_V(8); PG8_WAIT_L(0); PG8_BAR; if (do1) { PG8_MMA(1, 0, At, B0); PG8_MMA(1, 1, At, B1); } PG8_BAR; PG8_SCHED;
;         }
;         if (wr == 0) PG8_BAR;
	v_mfma_f32_16x16x32_bf16 v[60:63], v[120:123], v[160:163], v[60:63]
	v_mfma_f32_16x16x32_bf16 v[56:59], v[128:131], v[160:163], v[56:59]
	v_mfma_f32_16x16x32_bf16 v[44:47], v[120:123], v[168:171], v[44:47]
	v_mfma_f32_16x16x32_bf16 v[40:43], v[128:131], v[168:171], v[40:43]
	v_mfma_f32_16x16x32_bf16 v[28:31], v[120:123], v[176:179], v[28:31]
	v_mfma_f32_16x16x32_bf16 v[24:27], v[128:131], v[176:179], v[24:27]
	v_mfma_f32_16x16x32_bf16 v[12:15], v[120:123], v[184:187], v[12:15]
	v_mfma_f32_16x16x32_bf16 v[8:11], v[128:131], v[184:187], v[8:11]
	v_mfma_f32_16x16x32_bf16 v[60:63], v[124:127], v[164:167], v[60:63]
	v_mfma_f32_16x16x32_bf16 v[56:59], v[136:139], v[164:167], v[56:59]
	v_mfma_f32_16x16x32_bf16 v[44:47], v[124:127], v[172:175], v[44:47]
	v_mfma_f32_16x16x32_bf16 v[40:43], v[136:139], v[172:175], v[40:43]
	v_mfma_f32_16x16x32_bf16 v[28:31], v[124:127], v[180:183], v[28:31]
	v_mfma_f32_16x16x32_bf16 v[24:27], v[136:139], v[180:183], v[24:27]
	v_mfma_f32_16x16x32_bf16 v[12:15], v[124:127], v[222:225], v[12:15]
	v_mfma_f32_16x16x32_bf16 v[8:11], v[136:139], v[222:225], v[8:11]
	s_setprio 0
	s_setprio 1
	v_mfma_f32_16x16x32_bf16 v[52:55], v[144:147], v[160:163], v[52:55]
	v_mfma_f32_16x16x32_bf16 v[48:51], v[152:155], v[160:163], v[48:51]
	v_mfma_f32_16x16x32_bf16 v[36:39], v[144:147], v[168:171], v[36:39]
	v_mfma_f32_16x16x32_bf16 v[32:35], v[152:155], v[168:171], v[32:35]
	v_mfma_f32_16x16x32_bf16 v[20:23], v[144:147], v[176:179], v[20:23]
	v_mfma_f32_16x16x32_bf16 v[16:19], v[152:155], v[176:179], v[16:19]
	v_mfma_f32_16x16x32_bf16 v[4:7], v[144:147], v[184:187], v[4:7]
	v_mfma_f32_16x16x32_bf16 v[0:3], v[152:155], v[184:187], v[0:3]
	v_mfma_f32_16x16x32_bf16 v[52:55], v[148:151], v[164:167], v[52:55]
	v_mfma_f32_16x16x32_bf16 v[48:51], v[156:159], v[164:167], v[48:51]
	v_mfma_f32_16x16x32_bf16 v[36:39], v[148:151], v[172:175], v[36:39]
	v_mfma_f32_16x16x32_bf16 v[32:35], v[156:159], v[172:175], v[32:35]
	v_mfma_f32_16x16x32_bf16 v[20:23], v[148:151], v[180:183], v[20:23]
	v_mfma_f32_16x16x32_bf16 v[16:19], v[156:159], v[180:183], v[16:19]
	v_mfma_f32_16x16x32_bf16 v[4:7], v[148:151], v[222:225], v[4:7]
	v_mfma_f32_16x16x32_bf16 v[0:3], v[156:159], v[222:225], v[0:3]
	s_barrier
	s_setprio 0
	s_add_i32 s13, s13, 2
	s_add_u32 s42, s42, 0x100
	s_addc_u32 s43, s43, 0
	s_add_u32 s10, s10, 0x100
	s_addc_u32 s11, s11, 0
	s_cmp_gt_u32 s13, 29
	s_cbranch_scc0 .LBB0_765
	s_and_b64 vcc, exec, s[14:15]
	s_cbranch_vccz .LBB0_768
	s_barrier
; #define PG8_LAS __attribute__((address_space(3)))
; #define PACK8(w, v0, v1) do { w.x = cvt_pk_bf16(v0[0], v0[1]); w.y = cvt_pk_bf16(v0[2], v0[3]); w.z = cvt_pk_bf16(v1[0], v1[1]); w.w = cvt_pk_bf16(v1[2], v1[3]); } while (0)
; #define ADD8(v0, v1, g) do { v0[0] += bf_lo(g.x); v0[1] += bf_hi(g.x); v0[2] += bf_lo(g.y); v0[3] += bf_hi(g.y); v1[0] += bf_lo(g.z); v1[1] += bf_hi(g.z); v1[2] += bf_lo(g.w); v1[3] += bf_hi(g.w); } while (0)
;     __device__ __forceinline__ void operator()(EPI_ARGS) const {
;         char* ub = (char*)(XB + (long)u.z1 * cS1 + (long)u.pm * BM * ldc + u.pn * BM);
;         const unsigned lo = (unsigned)((wr * 64 + 4 * fr) * ldc + wc * 32 + 8 * fq) * 2u;
;         PG8_LAS float* XS = (PG8_LAS float*)xl;
;         const int ln = fq * 16 + fr;
;         u32x4 xq[2][4][2];
; #pragma unroll
;         for (int ai = 0; ai < 2; ++ai)
; #pragma unroll
;             for (int m = 0; m < 4; ++m)
; #pragma unroll
;                 for (int bj = 0; bj < 2; ++bj) xq[ai][m][bj] = *(const u32x4*)(ub + (size_t)(ai * HALF + m) * ldc * 2 + lo + bj * 256);
;         asm volatile("" ::: "memory");
; #pragma unroll
;         for (int ai = 0; ai < 2; ++ai)
; #pragma unroll
;             for (int m = 0; m < 4; ++m) { float ss = 0.f;
; #pragma unroll
;                 for (int bj = 0; bj < 2; ++bj) { f32x4 v0 = acc[ai][bj][m][0], v1 = acc[ai][bj][m][1];
;                     ADD8(v0, v1, xq[ai][m][bj]);
;                     u32x4 w; PACK8(w, v0, v1); *(u32x4*)(ub + (size_t)(ai * HALF + m) * ldc * 2 + lo + bj * 256) = w;
;                     ss += (v0[0] * v0[0] + v0[1] * v0[1]) + (v0[2] * v0[2] + v0[3] * v0[3]) + (v1[0] * v1[0] + v1[1] * v1[1]) + (v1[2] * v1[2] + v1[3] * v1[3]); }
.LBB0_768:
	s_ashr_i32 s21, s20, 31
	s_lshl_b64 s[8:9], s[20:21], 20
	s_add_u32 s10, s59, s8
	s_addc_u32 s11, s60, s9
	s_lshl_b32 s8, s12, 8
	v_mbcnt_lo_u32_b32 v221, -1, 0
	v_mbcnt_hi_u32_b32 v221, -1, v221
	s_ashr_i32 s9, s8, 31
	v_lshlrev_b32_e32 v204, 2, v221
	s_lshl_b64 s[8:9], s[8:9], 1
	v_and_or_b32 v205, v204, 60, s3
	s_add_u32 s42, s10, s8
	v_and_b32_e32 v120, -16, v221
	v_lshlrev_b32_e32 v121, 12, v205
	s_addc_u32 s43, s11, s9
	v_add3_u32 v192, v120, s75, v121
	global_load_dwordx4 v[224:227], v192, s[42:43]
	global_load_dwordx4 v[184:187], v192, s[42:43] offset:256
	v_lshl_add_u64 v[218:219], s[42:43], 0, v[192:193]
	v_add_co_u32_e32 v120, vcc, s25, v218
	s_mov_b32 s4, 0x80000
	s_nop 0
	v_addc_co_u32_e32 v121, vcc, 0, v219, vcc
	v_add_co_u32_e32 v122, vcc, s78, v218
	v_xor_b32_e32 v223, 64, v204
	s_nop 0
	v_addc_co_u32_e32 v123, vcc, 0, v219, vcc
	global_load_dwordx4 v[180:183], v[122:123], off offset:-4096
	global_load_dwordx4 v[176:179], v[120:121], off offset:256
	global_load_dwordx4 v[172:175], v[122:123], off
	global_load_dwordx4 v[168:171], v[122:123], off offset:256
	v_add_co_u32_e32 v120, vcc, s79, v218
	v_xor_b32_e32 v222, 0x80, v204
	s_nop 0
	v_addc_co_u32_e32 v121, vcc, 0, v219, vcc
	global_load_dwordx4 v[164:167], v[120:121], off
	global_load_dwordx4 v[160:163], v[120:121], off offset:256
	v_add_co_u32_e32 v120, vcc, s4, v218
	s_mov_b32 s4, 0x82000
	s_nop 0
	v_addc_co_u32_e32 v121, vcc, 0, v219, vcc
	v_add_co_u32_e32 v122, vcc, s95, v218
	s_nop 1
	v_addc_co_u32_e32 v123, vcc, 0, v219, vcc
	global_load_dwordx4 v[156:159], v[122:123], off offset:-4096
	global_load_dwordx4 v[152:155], v[120:121], off offset:256
	global_load_dwordx4 v[148:151], v[122:123], off
	global_load_dwordx4 v[136:139], v[122:123], off offset:256
	v_add_co_u32_e32 v120, vcc, s4, v218
	s_mov_b32 s4, 0x83000
	s_nop 0
	v_addc_co_u32_e32 v121, vcc, 0, v219, vcc
	v_add_co_u32_e32 v122, vcc, s4, v218
	s_nop 0
	s_nop 0
	v_addc_co_u32_e32 v123, vcc, 0, v219, vcc
	global_load_dwordx4 v[144:147], v[122:123], off offset:-4096
	global_load_dwordx4 v[128:131], v[120:121], off offset:256
	global_load_dwordx4 v[124:127], v[122:123], off
	s_nop 0
	global_load_dwordx4 v[120:123], v[122:123], off offset:256
	s_waitcnt vmcnt(8)
	v_lshlrev_b32_e32 v204, 16, v224
	v_add_f32_e32 v140, v140, v204
	v_and_b32_e32 v204, 0xffff0000, v224
	v_add_f32_e32 v141, v141, v204
	v_lshlrev_b32_e32 v204, 16, v225
	v_add_f32_e32 v142, v142, v204
	v_and_b32_e32 v204, 0xffff0000, v225
	v_add_f32_e32 v143, v143, v204
	v_lshlrev_b32_e32 v204, 16, v226
	v_add_f32_e32 v204, v132, v204
	v_and_b32_e32 v132, 0xffff0000, v226
	v_add_f32_e32 v224, v133, v132
	v_lshlrev_b32_e32 v132, 16, v227
	v_add_f32_e32 v225, v134, v132
	v_and_b32_e32 v132, 0xffff0000, v227
	v_add_f32_e32 v226, v135, v132
	v_cvt_pk_bf16_f32 v132, v140, v141
	v_cvt_pk_bf16_f32 v133, v142, v143
	v_cvt_pk_bf16_f32 v134, v204, v224
	v_cvt_pk_bf16_f32 v135, v225, v226
	global_store_dwordx4 v192, v[132:135], s[42:43]
	v_cmp_gt_u32_e32 vcc, 16, v221
	s_nop 0
	v_mul_f32_e32 v132, v141, v141
	v_mul_f32_e32 v133, v143, v143
	v_fmac_f32_e32 v132, v140, v140
	v_fmac_f32_e32 v133, v142, v142
	v_add_f32_e32 v132, v132, v133
	v_mul_f32_e32 v133, v224, v224
	v_fmac_f32_e32 v133, v204, v204
	v_add_f32_e32 v132, v133, v132
	v_mul_f32_e32 v133, v226, v226
	v_fmac_f32_e32 v133, v225, v225
	v_add_f32_e32 v132, v133, v132
	v_lshlrev_b32_e32 v133, 16, v184
	v_add_f32_e32 v116, v116, v133
	v_and_b32_e32 v133, 0xffff0000, v184
	v_add_f32_e32 v117, v117, v133
	v_lshlrev_b32_e32 v133, 16, v185
	v_add_f32_e32 v118, v118, v133
	v_and_b32_e32 v133, 0xffff0000, v185
	v_add_f32_e32 v119, v119, v133
	v_lshlrev_b32_e32 v133, 16, v186
	v_add_f32_e32 v133, v112, v133
	v_and_b32_e32 v112, 0xffff0000, v186
	v_add_f32_e32 v134, v113, v112
	v_lshlrev_b32_e32 v112, 16, v187
	v_add_f32_e32 v135, v114, v112
	v_and_b32_e32 v112, 0xffff0000, v187
	v_add_f32_e32 v140, v115, v112
	v_cvt_pk_bf16_f32 v112, v116, v117
	v_cvt_pk_bf16_f32 v113, v118, v119
	v_cvt_pk_bf16_f32 v114, v133, v134
	v_cvt_pk_bf16_f32 v115, v135, v140
	global_store_dwordx4 v192, v[112:115], s[42:43] offset:256
	s_nop 1
	v_mul_f32_e32 v112, v117, v117
	v_mul_f32_e32 v113, v119, v119
	v_fmac_f32_e32 v112, v116, v116
	v_fmac_f32_e32 v113, v118, v118
	v_add_f32_e32 v112, v112, v113
	v_mul_f32_e32 v113, v134, v134
	v_fmac_f32_e32 v113, v133, v133
	v_add_f32_e32 v112, v113, v112
	v_mul_f32_e32 v113, v140, v140
	v_fmac_f32_e32 v113, v135, v135
	v_add_f32_e32 v112, v113, v112
	v_add_f32_e32 v112, v132, v112
	ds_bpermute_b32 v113, v223, v112
	s_waitcnt lgkmcnt(0)
	v_add_f32_e32 v113, v112, v113
	ds_bpermute_b32 v114, v222, v113
	v_lshl_add_u32 v112, v205, 4, s64
	s_and_saveexec_b64 s[8:9], vcc
	s_cbranch_execz .LBB0_770
	s_waitcnt lgkmcnt(0)
	v_add_f32_e32 v113, v113, v114
	ds_write_b32 v112, v113

; #define PG8_BAR __builtin_amdgcn_s_barrier()
; template <class Epi>
; __device__ __forceinline__ void gemm_phase(PG8_LAS unsigned char* lds, PG8_LAS unsigned char* xl, const Gemm g, const Sched& S, const Epi& E, const int wid) {
;     ...
;         if (!has_next) break;
; #pragma unroll
;         for (int a = 0; a < 2; ++a)
; #pragma unroll
;             for (int b = 0; b < 2; ++b)
; #pragma unroll
;                 for (int m = 0; m < 4; ++m)
; #pragma unroll
;                     for (int n = 0; n < 2; ++n) acc[a][b][m][n] = (f32x4){0.f, 0.f, 0.f, 0.f};
;         cur = nxt; cA = nA; cB = nB; ++ui;
;         if (wr == 1) PG8_BAR;
.LBB0_786:
	s_or_b64 exec, exec, s[10:11]
	s_and_b64 vcc, exec, s[46:47]
	s_mov_b64 s[8:9], -1
	s_cbranch_vccnz .LBB0_759
	s_and_b64 vcc, exec, s[38:39]
	s_cbranch_vccnz .LBB0_758
	s_mov_b32 s100, 1
	s_branch .LBB0_758

; #define PG8_STAGE(bufoff, gbase, voff) do { _Pragma("unroll") for (int _i = 0; _i < 2; ++_i) \
;         __builtin_amdgcn_global_load_lds((const unsigned*)((const char*)(gbase) + (voff)[_i]), (PG8_LAS unsigned*)(lds + (bufoff) + ldsw + _i * 8192), 16, 0, 0); } while (0)
; #define PG8_LDA(dst, b, h) do { _Pragma("unroll") for (int m = 0; m < 4; ++m) _Pragma("unroll") for (int k = 0; k < 2; ++k) dst[m][k] = *(const PG8_LAS bf16x8*)(lds + PG8_SA(b, h) + aoff + m * 2048 + k * 1024); } while (0)
; #define PG8_LDB(dst, b, h) do { _Pragma("unroll") for (int n = 0; n < 2; ++n) _Pragma("unroll") for (int k = 0; k < 2; ++k) dst[n][k] = *(const PG8_LAS bf16x8*)(lds + PG8_SB(b, h) + boff + n * 2048 + k * 1024); } while (0)
; #define PG8_MMA(ai, bj, At, Bt) do { __builtin_amdgcn_s_setprio(1); _Pragma("unroll") for (int m = 0; m < 4; ++m) _Pragma("unroll") for (int n = 0; n < 2; ++n) _Pragma("unroll") for (int k = 0; k < 2; ++k) \
;         acc[ai][bj][m][n] = __builtin_amdgcn_mfma_f32_16x16x32_bf16(Bt[n][k], At[m][k], acc[ai][bj][m][n], 0, 0, 0); __builtin_amdgcn_s_setprio(0); } while (0)
; #define PG8_WAIT_V(n) asm volatile("s_waitcnt vmcnt(" #n ")" ::: "memory")
; #define PG8_WAIT_L(n) asm volatile("s_waitcnt lgkmcnt(" #n ")" ::: "memory")
; #define PG8_BAR __builtin_amdgcn_s_barrier()
; template <class Epi>
; __device__ __forceinline__ void gemm_phase(PG8_LAS unsigned char* lds, PG8_LAS unsigned char* xl, const Gemm g, const Sched& S, const Epi& E, const int wid) {
;     ...
;             const char* a1 = cA + (size_t)(t + 1) * kstep + j1;
;             const char* a2 = last ? nA : cA + (size_t)(t + 2) * kstep + ja2; const char* b2 = last ? nB : cB + (size_t)(t + 2) * kstep + jb2;
;             const char* a3 = a2 + kstep; const char* b3 = b2 + kstep;
;             PG8_LDB(B0, 0, 0); PG8_LDB(B1, 0, 1); PG8_SCHED; PG8_LDA(At, 0, 0); PG8_STAGE(PG8_SA(1, 1), a1 + hstepA, voffA);
;             PG8_WAIT_V(8); PG8_WAIT_L(0); PG8_BAR; if (do0) { PG8_MMA(0, 0, At, B0); PG8_MMA(0, 1, At, B1); } PG8_BAR; PG8_SCHED;
;     ...
;         for (int a = 0; a < 2; ++a)
; #pragma unroll
;             for (int b = 0; b < 2; ++b)
; #pragma unroll
;                 for (int m = 0; m < 4; ++m)
; #pragma unroll
;                     for (int n = 0; n < 2; ++n) acc[a][b][m][n] = (f32x4){0.f, 0.f, 0.f, 0.f};
;         cur = nxt; cA = nA; cB = nB; ++ui;
;         if (wr == 1) PG8_BAR;
.LBB0_858:
	s_add_u32 s8, s50, 0x100
	v_mov_b32_e32 v0, 0
	s_addc_u32 s9, s51, 0
	s_mov_b32 s10, -2
	v_mov_b32_e32 v1, v0
	v_mov_b32_e32 v2, v0
	v_mov_b32_e32 v3, v0
	v_mov_b32_e32 v4, v0
	v_mov_b32_e32 v5, v0
	v_mov_b32_e32 v6, v0
	v_mov_b32_e32 v7, v0
	v_mov_b32_e32 v16, v0
	v_mov_b32_e32 v17, v0
	v_mov_b32_e32 v18, v0
	v_mov_b32_e32 v19, v0
	v_mov_b32_e32 v20, v0
	v_mov_b32_e32 v21, v0
	v_mov_b32_e32 v22, v0
	v_mov_b32_e32 v23, v0
	v_mov_b32_e32 v32, v0
	v_mov_b32_e32 v33, v0
	v_mov_b32_e32 v34, v0
	v_mov_b32_e32 v35, v0
	v_mov_b32_e32 v36, v0
	v_mov_b32_e32 v37, v0
	v_mov_b32_e32 v38, v0
	v_mov_b32_e32 v39, v0
	v_mov_b32_e32 v48, v0
	v_mov_b32_e32 v49, v0
	v_mov_b32_e32 v50, v0
	v_mov_b32_e32 v51, v0
	v_mov_b32_e32 v52, v0
	v_mov_b32_e32 v53, v0
	v_mov_b32_e32 v54, v0
	v_mov_b32_e32 v55, v0
	v_mov_b32_e32 v8, v0
	v_mov_b32_e32 v9, v0
	v_mov_b32_e32 v10, v0
	v_mov_b32_e32 v11, v0
	v_mov_b32_e32 v12, v0
	v_mov_b32_e32 v13, v0
	v_mov_b32_e32 v14, v0
	v_mov_b32_e32 v15, v0
	v_mov_b32_e32 v24, v0
	v_mov_b32_e32 v25, v0
	v_mov_b32_e32 v26, v0
	v_mov_b32_e32 v27, v0
	v_mov_b32_e32 v28, v0
	v_mov_b32_e32 v29, v0
	v_mov_b32_e32 v30, v0
	v_mov_b32_e32 v31, v0
	v_mov_b32_e32 v40, v0
	v_mov_b32_e32 v41, v0
	v_mov_b32_e32 v42, v0
	v_mov_b32_e32 v43, v0
	v_mov_b32_e32 v44, v0
	v_mov_b32_e32 v45, v0
	v_mov_b32_e32 v46, v0
	v_mov_b32_e32 v47, v0
	v_mov_b32_e32 v56, v0
	v_mov_b32_e32 v57, v0
	v_mov_b32_e32 v58, v0
	v_mov_b32_e32 v59, v0
	v_mov_b32_e32 v60, v0
	v_mov_b32_e32 v61, v0
	v_mov_b32_e32 v62, v0
	v_mov_b32_e32 v63, v0
	v_mov_b32_e32 v64, v0
	v_mov_b32_e32 v65, v0
	v_mov_b32_e32 v66, v0
	v_mov_b32_e32 v67, v0
	v_mov_b32_e32 v68, v0
	v_mov_b32_e32 v69, v0
	v_mov_b32_e32 v70, v0
	v_mov_b32_e32 v71, v0
	v_mov_b32_e32 v80, v0
	v_mov_b32_e32 v81, v0
	v_mov_b32_e32 v82, v0
	v_mov_b32_e32 v83, v0
	v_mov_b32_e32 v84, v0
	v_mov_b32_e32 v85, v0
	v_mov_b32_e32 v86, v0
	v_mov_b32_e32 v87, v0
	v_mov_b32_e32 v96, v0
	v_mov_b32_e32 v97, v0
	v_mov_b32_e32 v98, v0
	v_mov_b32_e32 v99, v0
	v_mov_b32_e32 v100, v0
	v_mov_b32_e32 v101, v0
	v_mov_b32_e32 v102, v0
	v_mov_b32_e32 v103, v0
	v_mov_b32_e32 v112, v0
	v_mov_b32_e32 v113, v0
	v_mov_b32_e32 v114, v0
	v_mov_b32_e32 v115, v0
	v_mov_b32_e32 v116, v0
	v_mov_b32_e32 v117, v0
	v_mov_b32_e32 v118, v0
	v_mov_b32_e32 v119, v0
	v_mov_b32_e32 v72, v0
	v_mov_b32_e32 v73, v0
	v_mov_b32_e32 v74, v0
	v_mov_b32_e32 v75, v0
	v_mov_b32_e32 v76, v0
	v_mov_b32_e32 v77, v0
	v_mov_b32_e32 v78, v0
	v_mov_b32_e32 v79, v0
	v_mov_b32_e32 v88, v0
	v_mov_b32_e32 v89, v0
	v_mov_b32_e32 v90, v0
	v_mov_b32_e32 v91, v0
	v_mov_b32_e32 v92, v0
	v_mov_b32_e32 v93, v0
	v_mov_b32_e32 v94, v0
	v_mov_b32_e32 v95, v0
	v_mov_b32_e32 v104, v0
	v_mov_b32_e32 v105, v0
	v_mov_b32_e32 v106, v0
	v_mov_b32_e32 v107, v0
	v_mov_b32_e32 v108, v0
	v_mov_b32_e32 v109, v0
	v_mov_b32_e32 v110, v0
	v_mov_b32_e32 v111, v0
	v_mov_b32_e32 v128, v0
	v_mov_b32_e32 v129, v0
	v_mov_b32_e32 v130, v0
	v_mov_b32_e32 v131, v0
	v_mov_b32_e32 v132, v0
	v_mov_b32_e32 v133, v0
	v_mov_b32_e32 v134, v0
	v_mov_b32_e32 v135, v0
	s_cmp_lg_u32 s100, 1
	s_cbranch_scc1 .Ldefbar_skip_7
	s_mov_b32 s100, 0
	s_barrier
.Ldefbar_skip_7:
.LBB0_859:
	s_add_u32 s46, s48, 0x100
	s_addc_u32 s47, s49, 0
	s_add_i32 s11, 0, 0x10000
	s_cmp_eq_u32 s10, 28
	s_cselect_b32 vcc_hi, s59, s47
	s_cselect_b32 vcc_lo, s58, s46
	s_cselect_b32 s51, s21, s9
	s_cselect_b32 s50, s20, s8
	s_add_i32 s13, 0, 0x14000
	v_add_u32_e32 v140, s11, v195
	v_add_u32_e32 v156, s13, v195
	ds_read_b128 v[120:123], v140
	ds_read_b128 v[124:127], v140 offset:1024
	ds_read_b128 v[136:139], v140 offset:2048
	ds_read_b128 v[140:143], v140 offset:3072
	ds_read_b128 v[144:147], v156
	ds_read_b128 v[148:151], v156 offset:1024
	ds_read_b128 v[152:155], v156 offset:2048
	ds_read_b128 v[156:159], v156 offset:3072
	v_lshl_add_u64 v[204:205], s[48:49], 0, v[210:211]
	s_add_i32 m0, s89, 0xc000
	ds_read_b128 v[160:163], v216
	ds_read_b128 v[164:167], v216 offset:1024
	ds_read_b128 v[168:171], v216 offset:2048
	ds_read_b128 v[172:175], v216 offset:3072
	ds_read_b128 v[176:179], v216 offset:4096
	ds_read_b128 v[180:183], v216 offset:5120
	ds_read_b128 v[218:221], v216 offset:6144
	ds_read_b128 v[222:225], v216 offset:7168
	global_load_lds_dwordx4 v[204:205], off
	v_lshl_add_u64 v[204:205], s[48:49], 0, v[212:213]
	s_add_i32 m0, s89, 0xe000
	s_nop 0
	global_load_lds_dwordx4 v[204:205], off
	s_waitcnt vmcnt(8)
	s_waitcnt lgkmcnt(0)
	s_setprio 1
	s_barrier
	v_mfma_f32_16x16x32_bf16 v[132:135], v[120:123], v[160:163], v[132:135]
	v_mfma_f32_16x16x32_bf16 v[128:131], v[136:139], v[160:163], v[128:131]
	v_mfma_f32_16x16x32_bf16 v[108:111], v[120:123], v[168:171], v[108:111]
	v_mfma_f32_16x16x32_bf16 v[104:107], v[136:139], v[168:171], v[104:107]
	v_mfma_f32_16x16x32_bf16 v[92:95], v[120:123], v[176:179], v[92:95]
	v_mfma_f32_16x16x32_bf16 v[88:91], v[136:139], v[176:179], v[88:91]
	v_mfma_f32_16x16x32_bf16 v[76:79], v[120:123], v[218:221], v[76:79]
	v_mfma_f32_16x16x32_bf16 v[72:75], v[136:139], v[218:221], v[72:75]
	v_mfma_f32_16x16x32_bf16 v[132:135], v[124:127], v[164:167], v[132:135]
	v_mfma_f32_16x16x32_bf16 v[128:131], v[140:143], v[164:167], v[128:131]
	v_mfma_f32_16x16x32_bf16 v[108:111], v[124:127], v[172:175], v[108:111]
	v_mfma_f32_16x16x32_bf16 v[104:107], v[140:143], v[172:175], v[104:107]
	v_mfma_f32_16x16x32_bf16 v[92:95], v[124:127], v[180:183], v[92:95]
	v_mfma_f32_16x16x32_bf16 v[88:91], v[140:143], v[180:183], v[88:91]
	v_mfma_f32_16x16x32_bf16 v[76:79], v[124:127], v[222:225], v[76:79]
	v_mfma_f32_16x16x32_bf16 v[72:75], v[140:143], v[222:225], v[72:75]
	s_setprio 0
	s_setprio 1
	v_mfma_f32_16x16x32_bf16 v[116:119], v[144:147], v[160:163], v[116:119]
	v_mfma_f32_16x16x32_bf16 v[112:115], v[152:155], v[160:163], v[112:115]
	v_mfma_f32_16x16x32_bf16 v[100:103], v[144:147], v[168:171], v[100:103]
	v_mfma_f32_16x16x32_bf16 v[96:99], v[152:155], v[168:171], v[96:99]
	v_mfma_f32_16x16x32_bf16 v[84:87], v[144:147], v[176:179], v[84:87]
	v_mfma_f32_16x16x32_bf16 v[80:83], v[152:155], v[176:179], v[80:83]
	v_mfma_f32_16x16x32_bf16 v[68:71], v[144:147], v[218:221], v[68:71]
	v_mfma_f32_16x16x32_bf16 v[64:67], v[152:155], v[218:221], v[64:67]
	v_mfma_f32_16x16x32_bf16 v[116:119], v[148:151], v[164:167], v[116:119]
	v_mfma_f32_16x16x32_bf16 v[112:115], v[156:159], v[164:167], v[112:115]
	v_mfma_f32_16x16x32_bf16 v[100:103], v[148:151], v[172:175], v[100:103]
	v_mfma_f32_16x16x32_bf16 v[96:99], v[156:159], v[172:175], v[96:99]
	v_mfma_f32_16x16x32_bf16 v[84:87], v[148:151], v[180:183], v[84:87]
	v_mfma_f32_16x16x32_bf16 v[80:83], v[156:159], v[180:183], v[80:83]
	v_mfma_f32_16x16x32_bf16 v[68:71], v[148:151], v[222:225], v[68:71]
	v_mfma_f32_16x16x32_bf16 v[64:67], v[156:159], v[222:225], v[64:67]
	s_barrier
; #define PG8_STAGE(bufoff, gbase, voff) do { _Pragma("unroll") for (int _i = 0; _i < 2; ++_i) \
;         __builtin_amdgcn_global_load_lds((const unsigned*)((const char*)(gbase) + (voff)[_i]), (PG8_LAS unsigned*)(lds + (bufoff) + ldsw + _i * 8192), 16, 0, 0); } while (0)
; #define PG8_LDA(dst, b, h) do { _Pragma("unroll") for (int m = 0; m < 4; ++m) _Pragma("unroll") for (int k = 0; k < 2; ++k) dst[m][k] = *(const PG8_LAS bf16x8*)(lds + PG8_SA(b, h) + aoff + m * 2048 + k * 1024); } while (0)
; #define PG8_LDB(dst, b, h) do { _Pragma("unroll") for (int n = 0; n < 2; ++n) _Pragma("unroll") for (int k = 0; k < 2; ++k) dst[n][k] = *(const PG8_LAS bf16x8*)(lds + PG8_SB(b, h) + boff + n * 2048 + k * 1024); } while (0)
; #define PG8_MMA(ai, bj, At, Bt) do { __builtin_amdgcn_s_setprio(1); _Pragma("unroll") for (int m = 0; m < 4; ++m) _Pragma("unroll") for (int n = 0; n < 2; ++n) _Pragma("unroll") for (int k = 0; k < 2; ++k) \
;         acc[ai][bj][m][n] = __builtin_amdgcn_mfma_f32_16x16x32_bf16(Bt[n][k], At[m][k], acc[ai][bj][m][n], 0, 0, 0); __builtin_amdgcn_s_setprio(0); } while (0)
; #define PG8_WAIT_V(n) asm volatile("s_waitcnt vmcnt(" #n ")" ::: "memory")
; #define PG8_WAIT_L(n) asm volatile("s_waitcnt lgkmcnt(" #n ")" ::: "memory")
; #define PG8_BAR __builtin_amdgcn_s_barrier()
; #define PG8_SCHED __builtin_amdgcn_sched_barrier(0)
; template <class Epi>
; __device__ __forceinline__ void gemm_phase(PG8_LAS unsigned char* lds, PG8_LAS unsigned char* xl, const Gemm g, const Sched& S, const Epi& E, const int wid) {
;     ...
;             PG8_WAIT_V(8); PG8_WAIT_L(0); PG8_BAR; if (do0) { PG8_MMA(0, 0, At, B0); PG8_MMA(0, 1, At, B1); } PG8_BAR; PG8_SCHED;
;             PG8_LDA(At, 0, 1); PG8_STAGE(PG8_SB(0, 0), b2, voffB); PG8_STAGE(PG8_SB(0, 1), b2 + hstepB, voffB); PG8_STAGE(PG8_SA(0, 0), a2, voffA);
;             PG8_WAIT_V(8); PG8_WAIT_L(0); PG8_BAR; if (do1) { PG8_MMA(1, 0, At, B0); PG8_MMA(1, 1, At, B1); } PG8_BAR; PG8_SCHED;
;             PG8_LDB(B0, 1, 0); PG8_LDB(B1, 1, 1); PG8_SCHED; PG8_LDA(At, 1, 0); PG8_STAGE(PG8_SA(0, 1), a2 + hstepA, voffA);
;             PG8_WAIT_V(8); PG8_WAIT_L(0); PG8_BAR; if (do0) { PG8_MMA(0, 0, At, B0); PG8_MMA(0, 1, At, B1); } PG8_BAR; PG8_SCHED;
	s_setprio 0
	s_add_i32 s11, s11, s29
	v_lshl_add_u64 v[204:205], s[50:51], 0, v[186:187]
	s_mov_b32 m0, s11
	ds_read_b128 v[160:163], v216 offset:16384
	ds_read_b128 v[164:167], v216 offset:17408
	ds_read_b128 v[168:171], v216 offset:18432
	ds_read_b128 v[172:175], v216 offset:19456
	ds_read_b128 v[176:179], v216 offset:20480
	ds_read_b128 v[180:183], v216 offset:21504
	ds_read_b128 v[218:221], v216 offset:22528
	ds_read_b128 v[222:225], v216 offset:23552
	global_load_lds_dwordx4 v[204:205], off
	s_add_i32 m0, s11, 0x2000
	s_add_u32 s48, s50, 0x80000
	v_lshl_add_u64 v[214:215], s[50:51], 0, v[190:191]
	s_addc_u32 s49, s51, 0
	s_add_i32 s11, s13, s29
	global_load_lds_dwordx4 v[214:215], off
	v_lshl_add_u64 v[226:227], s[48:49], 0, v[186:187]
	s_mov_b32 m0, s11
	v_lshl_add_u64 v[228:229], vcc, 0, v[188:189]
	global_load_lds_dwordx4 v[226:227], off
	v_lshl_add_u64 v[226:227], s[48:49], 0, v[190:191]
	s_add_i32 m0, s11, 0x2000
	s_nop 0
	global_load_lds_dwordx4 v[226:227], off
	v_lshl_add_u64 v[226:227], vcc, 0, v[184:185]
	s_mov_b32 m0, s89
	s_nop 0
	global_load_lds_dwordx4 v[226:227], off
	s_mov_b32 m0, s90
	s_nop 0
	global_load_lds_dwordx4 v[228:229], off
	s_waitcnt vmcnt(8)
	s_waitcnt lgkmcnt(0)
	s_setprio 1
	s_barrier
	v_mfma_f32_16x16x32_bf16 v[60:63], v[120:123], v[160:163], v[60:63]
	v_mfma_f32_16x16x32_bf16 v[56:59], v[136:139], v[160:163], v[56:59]
	v_mfma_f32_16x16x32_bf16 v[44:47], v[120:123], v[168:171], v[44:47]
	v_mfma_f32_16x16x32_bf16 v[40:43], v[136:139], v[168:171], v[40:43]
	v_mfma_f32_16x16x32_bf16 v[28:31], v[120:123], v[176:179], v[28:31]
	v_mfma_f32_16x16x32_bf16 v[24:27], v[136:139], v[176:179], v[24:27]
	v_mfma_f32_16x16x32_bf16 v[12:15], v[120:123], v[218:221], v[12:15]
	v_mfma_f32_16x16x32_bf16 v[8:11], v[136:139], v[218:221], v[8:11]
	v_mfma_f32_16x16x32_bf16 v[60:63], v[124:127], v[164:167], v[60:63]
	v_mfma_f32_16x16x32_bf16 v[56:59], v[140:143], v[164:167], v[56:59]
	v_mfma_f32_16x16x32_bf16 v[44:47], v[124:127], v[172:175], v[44:47]
	v_mfma_f32_16x16x32_bf16 v[40:43], v[140:143], v[172:175], v[40:43]
	v_mfma_f32_16x16x32_bf16 v[28:31], v[124:127], v[180:183], v[28:31]
	v_mfma_f32_16x16x32_bf16 v[24:27], v[140:143], v[180:183], v[24:27]
	v_mfma_f32_16x16x32_bf16 v[12:15], v[124:127], v[222:225], v[12:15]
	v_mfma_f32_16x16x32_bf16 v[8:11], v[140:143], v[222:225], v[8:11]
	s_setprio 0
	s_setprio 1
	v_mfma_f32_16x16x32_bf16 v[52:55], v[144:147], v[160:163], v[52:55]
	v_mfma_f32_16x16x32_bf16 v[48:51], v[152:155], v[160:163], v[48:51]
	v_mfma_f32_16x16x32_bf16 v[36:39], v[144:147], v[168:171], v[36:39]
	v_mfma_f32_16x16x32_bf16 v[32:35], v[152:155], v[168:171], v[32:35]
	v_mfma_f32_16x16x32_bf16 v[20:23], v[144:147], v[176:179], v[20:23]
	v_mfma_f32_16x16x32_bf16 v[16:19], v[152:155], v[176:179], v[16:19]
	v_mfma_f32_16x16x32_bf16 v[4:7], v[144:147], v[218:221], v[4:7]
	v_mfma_f32_16x16x32_bf16 v[0:3], v[152:155], v[218:221], v[0:3]
	v_mfma_f32_16x16x32_bf16 v[52:55], v[148:151], v[164:167], v[52:55]
	v_mfma_f32_16x16x32_bf16 v[48:51], v[156:159], v[164:167], v[48:51]
	v_mfma_f32_16x16x32_bf16 v[36:39], v[148:151], v[172:175], v[36:39]
	v_mfma_f32_16x16x32_bf16 v[32:35], v[156:159], v[172:175], v[32:35]
	v_mfma_f32_16x16x32_bf16 v[20:23], v[148:151], v[180:183], v[20:23]
	v_mfma_f32_16x16x32_bf16 v[16:19], v[156:159], v[180:183], v[16:19]
	v_mfma_f32_16x16x32_bf16 v[4:7], v[148:151], v[222:225], v[4:7]
	v_mfma_f32_16x16x32_bf16 v[0:3], v[156:159], v[222:225], v[0:3]
	s_barrier
	s_setprio 0
	s_add_i32 s11, 0, 0x18000
	s_add_i32 s13, 0, 0x1c000
	v_add_u32_e32 v140, s11, v195
	v_add_u32_e32 v156, s13, v195
	ds_read_b128 v[120:123], v140
	ds_read_b128 v[124:127], v140 offset:1024
	ds_read_b128 v[136:139], v140 offset:2048
	ds_read_b128 v[140:143], v140 offset:3072
	ds_read_b128 v[144:147], v156
	ds_read_b128 v[148:151], v156 offset:1024
	ds_read_b128 v[152:155], v156 offset:2048
	ds_read_b128 v[156:159], v156 offset:3072
	s_add_u32 s48, vcc_lo, 0x80000
	s_addc_u32 s49, vcc_hi, 0
	s_mov_b32 m0, s91
	v_lshl_add_u64 v[230:231], s[48:49], 0, v[184:185]
	ds_read_b128 v[160:163], v216 offset:32768
	ds_read_b128 v[164:167], v216 offset:33792
	ds_read_b128 v[168:171], v216 offset:34816
	ds_read_b128 v[172:175], v216 offset:35840
	ds_read_b128 v[176:179], v216 offset:36864
	ds_read_b128 v[180:183], v216 offset:37888
	ds_read_b128 v[218:221], v216 offset:38912
	ds_read_b128 v[222:225], v216 offset:39936
	global_load_lds_dwordx4 v[230:231], off
	v_lshl_add_u64 v[230:231], s[48:49], 0, v[188:189]
	s_mov_b32 m0, s92
	s_nop 0
	global_load_lds_dwordx4 v[230:231], off
	s_waitcnt vmcnt(8)
	s_waitcnt lgkmcnt(0)
	s_setprio 1
	s_barrier
; #define PG8_STAGE(bufoff, gbase, voff) do { _Pragma("unroll") for (int _i = 0; _i < 2; ++_i) \
;         __builtin_amdgcn_global_load_lds((const unsigned*)((const char*)(gbase) + (voff)[_i]), (PG8_LAS unsigned*)(lds + (bufoff) + ldsw + _i * 8192), 16, 0, 0); } while (0)
; #define PG8_LDA(dst, b, h) do { _Pragma("unroll") for (int m = 0; m < 4; ++m) _Pragma("unroll") for (int k = 0; k < 2; ++k) dst[m][k] = *(const PG8_LAS bf16x8*)(lds + PG8_SA(b, h) + aoff + m * 2048 + k * 1024); } while (0)
; #define PG8_MMA(ai, bj, At, Bt) do { __builtin_amdgcn_s_setprio(1); _Pragma("unroll") for (int m = 0; m < 4; ++m) _Pragma("unroll") for (int n = 0; n < 2; ++n) _Pragma("unroll") for (int k = 0; k < 2; ++k) \
;         acc[ai][bj][m][n] = __builtin_amdgcn_mfma_f32_16x16x32_bf16(Bt[n][k], At[m][k], acc[ai][bj][m][n], 0, 0, 0); __builtin_amdgcn_s_setprio(0); } while (0)
; #define PG8_WAIT_V(n) asm volatile("s_waitcnt vmcnt(" #n ")" ::: "memory")
; #define PG8_WAIT_L(n) asm volatile("s_waitcnt lgkmcnt(" #n ")" ::: "memory")
; #define PG8_BAR __builtin_amdgcn_s_barrier()
; #define PG8_SCHED __builtin_amdgcn_sched_barrier(0)
; template <class Epi>
; __device__ __forceinline__ void gemm_phase(PG8_LAS unsigned char* lds, PG8_LAS unsigned char* xl, const Gemm g, const Sched& S, const Epi& E, const int wid) {
;     ...
;             PG8_WAIT_V(8); PG8_WAIT_L(0); PG8_BAR; if (do0) { PG8_MMA(0, 0, At, B0); PG8_MMA(0, 1, At, B1); } PG8_BAR; PG8_SCHED;
;             PG8_LDA(At, 1, 1); PG8_STAGE(PG8_SB(1, 0), b3, voffB); PG8_STAGE(PG8_SB(1, 1), b3 + hstepB, voffB); PG8_STAGE(PG8_SA(1, 0), a3, voffA);
;             PG8_WAIT_V(8); PG8_WAIT_L(0); PG8_BAR; if (do1) { PG8_MMA(1, 0, At, B0); PG8_MMA(1, 1, At, B1); } PG8_BAR; PG8_SCHED;
;         }
;         if (wr == 0) PG8_BAR;
	v_mfma_f32_16x16x32_bf16 v[132:135], v[120:123], v[160:163], v[132:135]
	v_mfma_f32_16x16x32_bf16 v[128:131], v[136:139], v[160:163], v[128:131]
	v_mfma_f32_16x16x32_bf16 v[108:111], v[120:123], v[168:171], v[108:111]
	v_mfma_f32_16x16x32_bf16 v[104:107], v[136:139], v[168:171], v[104:107]
	v_mfma_f32_16x16x32_bf16 v[92:95], v[120:123], v[176:179], v[92:95]
	v_mfma_f32_16x16x32_bf16 v[88:91], v[136:139], v[176:179], v[88:91]
	v_mfma_f32_16x16x32_bf16 v[76:79], v[120:123], v[218:221], v[76:79]
	v_mfma_f32_16x16x32_bf16 v[72:75], v[136:139], v[218:221], v[72:75]
	v_mfma_f32_16x16x32_bf16 v[132:135], v[124:127], v[164:167], v[132:135]
	v_mfma_f32_16x16x32_bf16 v[128:131], v[140:143], v[164:167], v[128:131]
	v_mfma_f32_16x16x32_bf16 v[108:111], v[124:127], v[172:175], v[108:111]
	v_mfma_f32_16x16x32_bf16 v[104:107], v[140:143], v[172:175], v[104:107]
	v_mfma_f32_16x16x32_bf16 v[92:95], v[124:127], v[180:183], v[92:95]
	v_mfma_f32_16x16x32_bf16 v[88:91], v[140:143], v[180:183], v[88:91]
	v_mfma_f32_16x16x32_bf16 v[76:79], v[124:127], v[222:225], v[76:79]
	v_mfma_f32_16x16x32_bf16 v[72:75], v[140:143], v[222:225], v[72:75]
	s_setprio 0
	s_setprio 1
	v_mfma_f32_16x16x32_bf16 v[116:119], v[144:147], v[160:163], v[116:119]
	v_mfma_f32_16x16x32_bf16 v[112:115], v[152:155], v[160:163], v[112:115]
	v_mfma_f32_16x16x32_bf16 v[100:103], v[144:147], v[168:171], v[100:103]
	v_mfma_f32_16x16x32_bf16 v[96:99], v[152:155], v[168:171], v[96:99]
	v_mfma_f32_16x16x32_bf16 v[84:87], v[144:147], v[176:179], v[84:87]
	v_mfma_f32_16x16x32_bf16 v[80:83], v[152:155], v[176:179], v[80:83]
	v_mfma_f32_16x16x32_bf16 v[68:71], v[144:147], v[218:221], v[68:71]
	v_mfma_f32_16x16x32_bf16 v[64:67], v[152:155], v[218:221], v[64:67]
	v_mfma_f32_16x16x32_bf16 v[116:119], v[148:151], v[164:167], v[116:119]
	v_mfma_f32_16x16x32_bf16 v[112:115], v[156:159], v[164:167], v[112:115]
	v_mfma_f32_16x16x32_bf16 v[100:103], v[148:151], v[172:175], v[100:103]
	v_mfma_f32_16x16x32_bf16 v[96:99], v[156:159], v[172:175], v[96:99]
	v_mfma_f32_16x16x32_bf16 v[84:87], v[148:151], v[180:183], v[84:87]
	v_mfma_f32_16x16x32_bf16 v[80:83], v[156:159], v[180:183], v[80:83]
	v_mfma_f32_16x16x32_bf16 v[68:71], v[148:151], v[222:225], v[68:71]
	v_mfma_f32_16x16x32_bf16 v[64:67], v[156:159], v[222:225], v[64:67]
	s_barrier
	s_setprio 0
	s_add_i32 s11, s11, s29
	v_lshl_add_u64 v[204:205], v[204:205], 0, s[22:23]
	s_mov_b32 m0, s11
	ds_read_b128 v[160:163], v216 offset:49152
	ds_read_b128 v[164:167], v216 offset:50176
	ds_read_b128 v[168:171], v216 offset:51200
	ds_read_b128 v[172:175], v216 offset:52224
	ds_read_b128 v[176:179], v216 offset:53248
	ds_read_b128 v[180:183], v216 offset:54272
	ds_read_b128 v[218:221], v216 offset:55296
	ds_read_b128 v[222:225], v216 offset:56320
	global_load_lds_dwordx4 v[204:205], off
	s_add_i32 m0, s11, 0x2000
	s_add_u32 s48, s50, 0x80080
	v_lshl_add_u64 v[204:205], v[214:215], 0, s[22:23]
	s_addc_u32 s49, s51, 0
	s_add_i32 s11, s13, s29
	global_load_lds_dwordx4 v[204:205], off
	v_lshl_add_u64 v[204:205], s[48:49], 0, v[186:187]
	s_mov_b32 m0, s11
	s_nop 0
	global_load_lds_dwordx4 v[204:205], off
	v_lshl_add_u64 v[204:205], s[48:49], 0, v[190:191]
	s_add_i32 m0, s11, 0x2000
	s_nop 0
	global_load_lds_dwordx4 v[204:205], off
	v_lshl_add_u64 v[204:205], v[226:227], 0, s[22:23]
	s_mov_b32 m0, s95
	s_nop 0
	global_load_lds_dwordx4 v[204:205], off
	v_lshl_add_u64 v[204:205], v[228:229], 0, s[22:23]
	s_mov_b32 m0, s96
	s_nop 0
	global_load_lds_dwordx4 v[204:205], off
	s_waitcnt vmcnt(8)
	s_waitcnt lgkmcnt(0)
	s_setprio 1
	s_barrier
	v_mfma_f32_16x16x32_bf16 v[60:63], v[120:123], v[160:163], v[60:63]
	v_mfma_f32_16x16x32_bf16 v[56:59], v[136:139], v[160:163], v[56:59]
	v_mfma_f32_16x16x32_bf16 v[44:47], v[120:123], v[168:171], v[44:47]
	v_mfma_f32_16x16x32_bf16 v[40:43], v[136:139], v[168:171], v[40:43]
	v_mfma_f32_16x16x32_bf16 v[28:31], v[120:123], v[176:179], v[28:31]
	v_mfma_f32_16x16x32_bf16 v[24:27], v[136:139], v[176:179], v[24:27]
	v_mfma_f32_16x16x32_bf16 v[12:15], v[120:123], v[218:221], v[12:15]
	v_mfma_f32_16x16x32_bf16 v[8:11], v[136:139], v[218:221], v[8:11]
	v_mfma_f32_16x16x32_bf16 v[60:63], v[124:127], v[164:167], v[60:63]
	v_mfma_f32_16x16x32_bf16 v[56:59], v[140:143], v[164:167], v[56:59]
	v_mfma_f32_16x16x32_bf16 v[44:47], v[124:127], v[172:175], v[44:47]
	v_mfma_f32_16x16x32_bf16 v[40:43], v[140:143], v[172:175], v[40:43]
	v_mfma_f32_16x16x32_bf16 v[28:31], v[124:127], v[180:183], v[28:31]
	v_mfma_f32_16x16x32_bf16 v[24:27], v[140:143], v[180:183], v[24:27]
	v_mfma_f32_16x16x32_bf16 v[12:15], v[124:127], v[222:225], v[12:15]
	v_mfma_f32_16x16x32_bf16 v[8:11], v[140:143], v[222:225], v[8:11]
	s_setprio 0
	s_setprio 1
	v_mfma_f32_16x16x32_bf16 v[52:55], v[144:147], v[160:163], v[52:55]
	v_mfma_f32_16x16x32_bf16 v[48:51], v[152:155], v[160:163], v[48:51]
	v_mfma_f32_16x16x32_bf16 v[36:39], v[144:147], v[168:171], v[36:39]
	v_mfma_f32_16x16x32_bf16 v[32:35], v[152:155], v[168:171], v[32:35]
	v_mfma_f32_16x16x32_bf16 v[20:23], v[144:147], v[176:179], v[20:23]
	v_mfma_f32_16x16x32_bf16 v[16:19], v[152:155], v[176:179], v[16:19]
	v_mfma_f32_16x16x32_bf16 v[4:7], v[144:147], v[218:221], v[4:7]
	v_mfma_f32_16x16x32_bf16 v[0:3], v[152:155], v[218:221], v[0:3]
	v_mfma_f32_16x16x32_bf16 v[52:55], v[148:151], v[164:167], v[52:55]
	v_mfma_f32_16x16x32_bf16 v[48:51], v[156:159], v[164:167], v[48:51]
	v_mfma_f32_16x16x32_bf16 v[36:39], v[148:151], v[172:175], v[36:39]
	v_mfma_f32_16x16x32_bf16 v[32:35], v[156:159], v[172:175], v[32:35]
	v_mfma_f32_16x16x32_bf16 v[20:23], v[148:151], v[180:183], v[20:23]
	v_mfma_f32_16x16x32_bf16 v[16:19], v[156:159], v[180:183], v[16:19]
	v_mfma_f32_16x16x32_bf16 v[4:7], v[148:151], v[222:225], v[4:7]
	v_mfma_f32_16x16x32_bf16 v[0:3], v[156:159], v[222:225], v[0:3]
	s_barrier
	s_setprio 0
	s_add_i32 s10, s10, 2
	s_add_u32 s8, s8, 0x100
	s_addc_u32 s9, s9, 0
	s_cmp_gt_u32 s10, 29
	s_mov_b64 s[48:49], s[46:47]
	s_cbranch_scc0 .LBB0_859
	s_and_b64 vcc, exec, s[14:15]
	s_cbranch_vccz .LBB0_862
	s_barrier

; #define PACK8(w, v0, v1) do { w.x = cvt_pk_bf16(v0[0], v0[1]); w.y = cvt_pk_bf16(v0[2], v0[3]); w.z = cvt_pk_bf16(v1[0], v1[1]); w.w = cvt_pk_bf16(v1[2], v1[3]); } while (0)
;     __device__ __forceinline__ void operator()(EPI_ARGS) const {
;     ...
;         asm volatile("s_waitcnt lgkmcnt(0)" ::: "memory"); __builtin_amdgcn_s_barrier(); asm volatile("" ::: "memory");
;         char* ub = (char*)(P + (long)u.z1 * cS1 + (long)u.pm * BM * ldc + u.pn * BM);
;         const unsigned lo = (unsigned)((wr * 64 + 4 * fr) * ldc + wc * 32 + 8 * fq) * 2u;
; #pragma unroll
;         for (int ai = 0; ai < 2; ++ai)
; #pragma unroll
;             for (int m = 0; m < 4; ++m) { const int r = ai * HALF + wr * 64 + 4 * fr + m;
;                 const f32x2 a = X[r * 4 + 0], b = X[r * 4 + 1], c = X[r * 4 + 2], d = X[r * 4 + 3];
;                 const float mt = fmaxf(fmaxf(a.x, b.x), fmaxf(c.x, d.x));
;                 const float l = a.y * __builtin_amdgcn_exp2f(a.x - mt) + b.y * __builtin_amdgcn_exp2f(b.x - mt) + c.y * __builtin_amdgcn_exp2f(c.x - mt) + d.y * __builtin_amdgcn_exp2f(d.x - mt);
;                 const float f = __builtin_amdgcn_exp2f(mw[ai][m] - mt) / l;
;                 char* rb = ub + (size_t)(ai * HALF + m) * ldc * 2;
; #pragma unroll
;                 for (int bj = 0; bj < 2; ++bj) { const f32x4 v0 = acc[ai][bj][m][0] * f, v1 = acc[ai][bj][m][1] * f; u32x4 w; PACK8(w, v0, v1);
;                     *(u32x4*)(rb + lo + bj * 256) = w; } }
.LBB0_880:
	s_or_b64 exec, exec, s[10:11]
	s_waitcnt lgkmcnt(0)
	s_barrier
	v_add_u32_e32 v121, s6, v123
	s_waitcnt lgkmcnt(0)
	ds_read_b128 v[124:127], v121
	ds_read_b128 v[138:141], v121 offset:16
	s_ashr_i32 s57, s56, 31
	s_lshl_b64 s[8:9], s[56:57], 22
	s_add_u32 s10, s93, s8
	s_addc_u32 s11, s94, s9
	s_waitcnt lgkmcnt(0)
	v_max_f32_e32 v123, v140, v140
	v_max_f32_e32 v142, v138, v138
	v_max_f32_e32 v123, v142, v123
	v_max3_f32 v123, v124, v126, v123
	v_sub_f32_e32 v124, v124, v123
	v_exp_f32_e32 v142, v124
	v_sub_f32_e32 v124, v126, v123
	v_exp_f32_e32 v143, v124
	v_sub_f32_e32 v124, v138, v123
	v_exp_f32_e32 v147, v124
	v_sub_f32_e32 v124, v140, v123
	v_exp_f32_e32 v146, v124
	s_ashr_i32 s53, s52, 31
	s_lshl_b64 s[8:9], s[52:53], 19
	v_mov_b32_e32 v126, v125
	v_sub_f32_e32 v123, v214, v123
	s_add_u32 s10, s10, s8
	v_pk_mul_f32 v[124:125], v[126:127], v[142:143]
	v_mov_b32_e32 v138, v141
	v_exp_f32_e32 v123, v123
	s_addc_u32 s13, s11, s9
	s_lshl_b32 s8, s42, 8
	v_pk_mul_f32 v[126:127], v[138:139], v[146:147]
	v_add_f32_e32 v124, v124, v125
	s_ashr_i32 s9, s8, 31
	v_add_f32_e32 v124, v127, v124
	s_lshl_b64 s[8:9], s[8:9], 1
	v_add_f32_e32 v124, v126, v124
	s_add_u32 s42, s10, s8
	v_div_scale_f32 v125, s[10:11], v124, v124, v123
	v_rcp_f32_e32 v126, v125
	v_and_b32_e32 v137, -16, v217
	v_lshlrev_b32_e32 v127, 11, v192
	v_add3_u32 v192, v137, s75, v127
	v_fma_f32 v127, -v125, v126, 1.0
	v_fmac_f32_e32 v126, v127, v126
	v_div_scale_f32 v127, vcc, v123, v124, v123
	v_mul_f32_e32 v137, v127, v126
	v_fma_f32 v138, -v125, v137, v127
	v_fmac_f32_e32 v137, v138, v126
	v_fma_f32 v125, -v125, v137, v127
	v_div_fmas_f32 v125, v125, v126, v137
	v_div_fixup_f32 v138, v125, v124, v123
	v_pk_mul_f32 v[124:125], v[130:131], v[138:139] op_sel_hi:[1,0]
	s_addc_u32 s43, s13, s9
	v_pk_mul_f32 v[126:127], v[134:135], v[138:139] op_sel_hi:[1,0]
	v_cvt_pk_bf16_f32 v124, v124, v125
	v_pk_mul_f32 v[130:131], v[132:133], v[138:139] op_sel_hi:[1,0]
	v_cvt_pk_bf16_f32 v125, v126, v127
	v_pk_mul_f32 v[128:129], v[128:129], v[138:139] op_sel_hi:[1,0]
	v_pk_mul_f32 v[118:119], v[118:119], v[138:139] op_sel_hi:[1,0]
	v_cvt_pk_bf16_f32 v126, v128, v129
	v_cvt_pk_bf16_f32 v127, v130, v131
	global_store_dwordx4 v192, v[124:127], s[42:43]
	v_pk_mul_f32 v[114:115], v[114:115], v[138:139] op_sel_hi:[1,0]
	v_pk_mul_f32 v[116:117], v[116:117], v[138:139] op_sel_hi:[1,0]
	v_pk_mul_f32 v[124:125], v[112:113], v[138:139] op_sel_hi:[1,0]
	v_cvt_pk_bf16_f32 v112, v114, v115
	v_cvt_pk_bf16_f32 v113, v118, v119
	s_nop 0
	v_cvt_pk_bf16_f32 v114, v124, v125
	v_cvt_pk_bf16_f32 v115, v116, v117
	ds_read_b128 v[116:119], v121 offset:48
	ds_read_b128 v[124:127], v121 offset:32
	global_store_dwordx4 v192, v[112:115], s[42:43] offset:256
	s_waitcnt lgkmcnt(1)
	v_max_f32_e32 v123, v118, v118
	v_max_f32_e32 v128, v116, v116
	v_max_f32_e32 v123, v128, v123
	s_waitcnt lgkmcnt(0)
	v_max3_f32 v123, v124, v126, v123
	v_sub_f32_e32 v124, v124, v123
	v_exp_f32_e32 v128, v124
	v_sub_f32_e32 v124, v126, v123
	v_sub_f32_e32 v116, v116, v123
	v_exp_f32_e32 v129, v124
	v_exp_f32_e32 v131, v116
	v_sub_f32_e32 v116, v118, v123
	v_exp_f32_e32 v130, v116
	v_mov_b32_e32 v126, v125
	v_mov_b32_e32 v116, v119
	v_sub_f32_e32 v119, v176, v123
	v_pk_mul_f32 v[124:125], v[126:127], v[128:129]
	v_exp_f32_e32 v119, v119
	v_pk_mul_f32 v[116:117], v[116:117], v[130:131]
	v_add_f32_e32 v118, v124, v125
	v_add_f32_e32 v117, v117, v118
	v_add_f32_e32 v116, v116, v117
	v_div_scale_f32 v117, s[8:9], v116, v116, v119
	v_rcp_f32_e32 v118, v117
	s_nop 0
	v_fma_f32 v112, -v117, v118, 1.0
	v_fmac_f32_e32 v118, v112, v118
	v_div_scale_f32 v112, vcc, v119, v116, v119
	v_mul_f32_e32 v113, v112, v118
	v_fma_f32 v114, -v117, v113, v112
	v_fmac_f32_e32 v113, v114, v118
	v_fma_f32 v112, -v117, v113, v112
	v_div_fmas_f32 v112, v112, v118, v113
	v_div_fixup_f32 v112, v112, v116, v119
	v_pk_mul_f32 v[110:111], v[110:111], v[112:113] op_sel_hi:[1,0]
	v_pk_mul_f32 v[108:109], v[108:109], v[112:113] op_sel_hi:[1,0]
	v_pk_mul_f32 v[114:115], v[106:107], v[112:113] op_sel_hi:[1,0]
	v_pk_mul_f32 v[106:107], v[104:105], v[112:113] op_sel_hi:[1,0]
	v_cvt_pk_bf16_f32 v104, v108, v109
	v_cvt_pk_bf16_f32 v105, v110, v111
	v_pk_mul_f32 v[102:103], v[102:103], v[112:113] op_sel_hi:[1,0]
	v_cvt_pk_bf16_f32 v106, v106, v107
	v_cvt_pk_bf16_f32 v107, v114, v115
	global_store_dwordx4 v192, v[104:107], s[42:43] offset:2048
	v_pk_mul_f32 v[100:101], v[100:101], v[112:113] op_sel_hi:[1,0]
	v_pk_mul_f32 v[96:97], v[96:97], v[112:113] op_sel_hi:[1,0]
	v_pk_mul_f32 v[104:105], v[98:99], v[112:113] op_sel_hi:[1,0]
	v_cvt_pk_bf16_f32 v98, v100, v101
	v_cvt_pk_bf16_f32 v99, v102, v103
	v_cvt_pk_bf16_f32 v100, v96, v97
	s_nop 0
	v_cvt_pk_bf16_f32 v101, v104, v105
	ds_read_b128 v[102:105], v121 offset:80
	ds_read_b128 v[106:109], v121 offset:64
	global_store_dwordx4 v192, v[98:101], s[42:43] offset:2304
	s_waitcnt lgkmcnt(1)
	v_max_f32_e32 v96, v104, v104
	v_max_f32_e32 v97, v102, v102
	v_max_f32_e32 v96, v97, v96
	s_waitcnt lgkmcnt(0)
; #define PACK8(w, v0, v1) do { w.x = cvt_pk_bf16(v0[0], v0[1]); w.y = cvt_pk_bf16(v0[2], v0[3]); w.z = cvt_pk_bf16(v1[0], v1[1]); w.w = cvt_pk_bf16(v1[2], v1[3]); } while (0)
;     __device__ __forceinline__ void operator()(EPI_ARGS) const {
;     ...
;             for (int m = 0; m < 4; ++m) { const int r = ai * HALF + wr * 64 + 4 * fr + m;
;                 const f32x2 a = X[r * 4 + 0], b = X[r * 4 + 1], c = X[r * 4 + 2], d = X[r * 4 + 3];
;                 const float mt = fmaxf(fmaxf(a.x, b.x), fmaxf(c.x, d.x));
;                 const float l = a.y * __builtin_amdgcn_exp2f(a.x - mt) + b.y * __builtin_amdgcn_exp2f(b.x - mt) + c.y * __builtin_amdgcn_exp2f(c.x - mt) + d.y * __builtin_amdgcn_exp2f(d.x - mt);
;                 const float f = __builtin_amdgcn_exp2f(mw[ai][m] - mt) / l;
;                 char* rb = ub + (size_t)(ai * HALF + m) * ldc * 2;
; #pragma unroll
;                 for (int bj = 0; bj < 2; ++bj) { const f32x4 v0 = acc[ai][bj][m][0] * f, v1 = acc[ai][bj][m][1] * f; u32x4 w; PACK8(w, v0, v1);
;                     *(u32x4*)(rb + lo + bj * 256) = w; } }
	v_max3_f32 v112, v106, v108, v96
	v_sub_f32_e32 v96, v106, v112
	v_sub_f32_e32 v97, v108, v112
	v_exp_f32_e32 v96, v96
	v_exp_f32_e32 v97, v97
	v_sub_f32_e32 v102, v102, v112
	v_exp_f32_e32 v111, v102
	v_sub_f32_e32 v102, v104, v112
	v_exp_f32_e32 v110, v102
	v_mov_b32_e32 v108, v107
	v_pk_mul_f32 v[96:97], v[108:109], v[96:97]
	v_mov_b32_e32 v102, v105
	v_add_f32_e32 v96, v96, v97
	v_sub_f32_e32 v97, v168, v112
	v_exp_f32_e32 v104, v97
	v_pk_mul_f32 v[102:103], v[102:103], v[110:111]
	s_nop 0
	v_add_f32_e32 v96, v103, v96
	v_add_f32_e32 v102, v102, v96
	v_div_scale_f32 v103, s[8:9], v102, v102, v104
	v_rcp_f32_e32 v105, v103
	v_lshl_add_u64 v[96:97], s[42:43], 0, v[192:193]
	v_fma_f32 v98, -v103, v105, 1.0
	v_fmac_f32_e32 v105, v98, v105
	v_div_scale_f32 v98, vcc, v104, v102, v104
	v_mul_f32_e32 v99, v98, v105
	v_fma_f32 v100, -v103, v99, v98
	v_fmac_f32_e32 v99, v100, v105
	v_fma_f32 v98, -v103, v99, v98
	v_div_fmas_f32 v98, v98, v105, v99
	v_div_fixup_f32 v98, v98, v102, v104
	v_pk_mul_f32 v[92:93], v[92:93], v[98:99] op_sel_hi:[1,0]
	v_pk_mul_f32 v[100:101], v[90:91], v[98:99] op_sel_hi:[1,0]
	v_pk_mul_f32 v[90:91], v[88:89], v[98:99] op_sel_hi:[1,0]
	v_cvt_pk_bf16_f32 v88, v92, v93
	v_add_co_u32_e32 v92, vcc, s25, v96
	v_pk_mul_f32 v[94:95], v[94:95], v[98:99] op_sel_hi:[1,0]
	s_nop 0
	v_addc_co_u32_e32 v93, vcc, 0, v97, vcc
	v_cvt_pk_bf16_f32 v89, v94, v95
	v_cvt_pk_bf16_f32 v90, v90, v91
	v_cvt_pk_bf16_f32 v91, v100, v101
	global_store_dwordx4 v[92:93], v[88:91], off
	v_pk_mul_f32 v[86:87], v[86:87], v[98:99] op_sel_hi:[1,0]
	v_pk_mul_f32 v[84:85], v[84:85], v[98:99] op_sel_hi:[1,0]
	v_pk_mul_f32 v[88:89], v[82:83], v[98:99] op_sel_hi:[1,0]
	v_pk_mul_f32 v[82:83], v[80:81], v[98:99] op_sel_hi:[1,0]
	v_cvt_pk_bf16_f32 v80, v84, v85
	v_cvt_pk_bf16_f32 v81, v86, v87
	s_nop 0
	v_cvt_pk_bf16_f32 v82, v82, v83
	v_cvt_pk_bf16_f32 v83, v88, v89
	ds_read_b128 v[84:87], v121 offset:112
	ds_read_b128 v[88:91], v121 offset:96
	global_store_dwordx4 v[92:93], v[80:83], off offset:256
	s_waitcnt lgkmcnt(1)
	v_max_f32_e32 v94, v86, v86
	v_max_f32_e32 v95, v84, v84
	v_max_f32_e32 v94, v95, v94
	s_waitcnt lgkmcnt(0)
	v_max3_f32 v100, v88, v90, v94
	v_sub_f32_e32 v88, v88, v100
	v_exp_f32_e32 v94, v88
	v_sub_f32_e32 v88, v90, v100
	v_sub_f32_e32 v84, v84, v100
	v_exp_f32_e32 v95, v88
	v_exp_f32_e32 v99, v84
	v_sub_f32_e32 v84, v86, v100
	v_exp_f32_e32 v98, v84
	v_mov_b32_e32 v90, v89
	v_mov_b32_e32 v84, v87
	v_sub_f32_e32 v87, v160, v100
	v_pk_mul_f32 v[88:89], v[90:91], v[94:95]
	v_exp_f32_e32 v87, v87
	v_pk_mul_f32 v[84:85], v[84:85], v[98:99]
	v_add_f32_e32 v86, v88, v89
	v_add_f32_e32 v85, v85, v86
	v_add_f32_e32 v84, v84, v85
	v_div_scale_f32 v85, s[8:9], v84, v84, v87
	v_rcp_f32_e32 v86, v85
	s_nop 0
	v_fma_f32 v80, -v85, v86, 1.0
	v_fmac_f32_e32 v86, v80, v86
	v_div_scale_f32 v80, vcc, v87, v84, v87
	v_mul_f32_e32 v81, v80, v86
	v_fma_f32 v82, -v85, v81, v80
	v_fmac_f32_e32 v81, v82, v86
	v_fma_f32 v80, -v85, v81, v80
	v_div_fmas_f32 v80, v80, v86, v81
	v_div_fixup_f32 v80, v80, v84, v87
	v_pk_mul_f32 v[78:79], v[78:79], v[80:81] op_sel_hi:[1,0]
	v_pk_mul_f32 v[76:77], v[76:77], v[80:81] op_sel_hi:[1,0]
	v_pk_mul_f32 v[82:83], v[74:75], v[80:81] op_sel_hi:[1,0]
	v_pk_mul_f32 v[74:75], v[72:73], v[80:81] op_sel_hi:[1,0]
	v_cvt_pk_bf16_f32 v72, v76, v77
	v_cvt_pk_bf16_f32 v73, v78, v79
	v_pk_mul_f32 v[70:71], v[70:71], v[80:81] op_sel_hi:[1,0]
	v_cvt_pk_bf16_f32 v74, v74, v75
	v_cvt_pk_bf16_f32 v75, v82, v83
	global_store_dwordx4 v[92:93], v[72:75], off offset:2048
	v_pk_mul_f32 v[68:69], v[68:69], v[80:81] op_sel_hi:[1,0]
	s_nop 0
	v_pk_mul_f32 v[72:73], v[66:67], v[80:81] op_sel_hi:[1,0]
	v_pk_mul_f32 v[66:67], v[64:65], v[80:81] op_sel_hi:[1,0]
	v_cvt_pk_bf16_f32 v64, v68, v69
	v_cvt_pk_bf16_f32 v65, v70, v71
	s_nop 0
	v_cvt_pk_bf16_f32 v66, v66, v67
	v_cvt_pk_bf16_f32 v67, v72, v73
	v_lshl_add_u32 v72, v154, 5, s6
	ds_read_b128 v[68:71], v72 offset:16
	ds_read_b128 v[72:75], v72
	global_store_dwordx4 v[92:93], v[64:67], off offset:2304
	s_waitcnt lgkmcnt(1)
	v_max_f32_e32 v76, v70, v70
	v_max_f32_e32 v77, v68, v68
	v_max_f32_e32 v76, v77, v76
	s_waitcnt lgkmcnt(0)
	v_max3_f32 v80, v72, v74, v76
	v_sub_f32_e32 v72, v72, v80
	v_exp_f32_e32 v76, v72
	v_sub_f32_e32 v72, v74, v80
	v_sub_f32_e32 v68, v68, v80
	v_exp_f32_e32 v77, v72
	v_exp_f32_e32 v79, v68
	v_sub_f32_e32 v68, v70, v80
	v_exp_f32_e32 v78, v68
	v_mov_b32_e32 v74, v73
	v_mov_b32_e32 v68, v71
	v_sub_f32_e32 v71, v152, v80
	v_pk_mul_f32 v[72:73], v[74:75], v[76:77]
	v_exp_f32_e32 v71, v71
	v_pk_mul_f32 v[68:69], v[68:69], v[78:79]
	v_add_f32_e32 v70, v72, v73
	v_add_f32_e32 v69, v69, v70
	v_add_f32_e32 v68, v68, v69
	v_div_scale_f32 v69, s[8:9], v68, v68, v71
	v_rcp_f32_e32 v70, v69
	s_nop 0
	v_fma_f32 v64, -v69, v70, 1.0
	v_fmac_f32_e32 v70, v64, v70
	v_div_scale_f32 v64, vcc, v71, v68, v71
	v_mul_f32_e32 v65, v64, v70
	v_fma_f32 v66, -v69, v65, v64
	v_fmac_f32_e32 v65, v66, v70
	v_fma_f32 v64, -v69, v65, v64
	v_div_fmas_f32 v64, v64, v70, v65
	v_div_fixup_f32 v64, v64, v68, v71
	v_pk_mul_f32 v[60:61], v[60:61], v[64:65] op_sel_hi:[1,0]
	v_pk_mul_f32 v[56:57], v[56:57], v[64:65] op_sel_hi:[1,0]
	v_pk_mul_f32 v[62:63], v[62:63], v[64:65] op_sel_hi:[1,0]
	v_pk_mul_f32 v[66:67], v[58:59], v[64:65] op_sel_hi:[1,0]
	v_cvt_pk_bf16_f32 v58, v60, v61
	v_cvt_pk_bf16_f32 v59, v62, v63
	v_cvt_pk_bf16_f32 v60, v56, v57
	v_add_co_u32_e32 v56, vcc, s54, v96
	v_cvt_pk_bf16_f32 v61, v66, v67
	v_pk_mul_f32 v[54:55], v[54:55], v[64:65] op_sel_hi:[1,0]
	s_nop 0
	v_addc_co_u32_e32 v57, vcc, 0, v97, vcc
	global_store_dwordx4 v[56:57], v[58:61], off offset:-4096
	v_pk_mul_f32 v[52:53], v[52:53], v[64:65] op_sel_hi:[1,0]
	s_nop 0
	v_pk_mul_f32 v[58:59], v[50:51], v[64:65] op_sel_hi:[1,0]
	v_pk_mul_f32 v[50:51], v[48:49], v[64:65] op_sel_hi:[1,0]
	v_cvt_pk_bf16_f32 v48, v52, v53
	v_cvt_pk_bf16_f32 v49, v54, v55
	s_nop 0
	v_cvt_pk_bf16_f32 v50, v50, v51
	v_cvt_pk_bf16_f32 v51, v58, v59
	ds_read_b128 v[52:55], v121 offset:4144
	ds_read_b128 v[58:61], v121 offset:4128
	s_waitcnt lgkmcnt(1)
; #define PACK8(w, v0, v1) do { w.x = cvt_pk_bf16(v0[0], v0[1]); w.y = cvt_pk_bf16(v0[2], v0[3]); w.z = cvt_pk_bf16(v1[0], v1[1]); w.w = cvt_pk_bf16(v1[2], v1[3]); } while (0)
; #define PG8_BAR __builtin_amdgcn_s_barrier()
;     __device__ __forceinline__ void operator()(EPI_ARGS) const {
;     ...
;             for (int m = 0; m < 4; ++m) { const int r = ai * HALF + wr * 64 + 4 * fr + m;
;                 const f32x2 a = X[r * 4 + 0], b = X[r * 4 + 1], c = X[r * 4 + 2], d = X[r * 4 + 3];
;                 const float mt = fmaxf(fmaxf(a.x, b.x), fmaxf(c.x, d.x));
;                 const float l = a.y * __builtin_amdgcn_exp2f(a.x - mt) + b.y * __builtin_amdgcn_exp2f(b.x - mt) + c.y * __builtin_amdgcn_exp2f(c.x - mt) + d.y * __builtin_amdgcn_exp2f(d.x - mt);
;                 const float f = __builtin_amdgcn_exp2f(mw[ai][m] - mt) / l;
;                 char* rb = ub + (size_t)(ai * HALF + m) * ldc * 2;
; #pragma unroll
;                 for (int bj = 0; bj < 2; ++bj) { const f32x4 v0 = acc[ai][bj][m][0] * f, v1 = acc[ai][bj][m][1] * f; u32x4 w; PACK8(w, v0, v1);
;                     *(u32x4*)(rb + lo + bj * 256) = w; } }
; template <class Epi>
; __device__ __forceinline__ void gemm_phase(PG8_LAS unsigned char* lds, PG8_LAS unsigned char* xl, const Gemm g, const Sched& S, const Epi& E, const int wid) {
;     ...
;         if (!has_next) break;
; #pragma unroll
;         for (int a = 0; a < 2; ++a)
; #pragma unroll
;             for (int b = 0; b < 2; ++b)
; #pragma unroll
;                 for (int m = 0; m < 4; ++m)
; #pragma unroll
;                     for (int n = 0; n < 2; ++n) acc[a][b][m][n] = (f32x4){0.f, 0.f, 0.f, 0.f};
;         cur = nxt; cA = nA; cB = nB; ++ui;
;         if (wr == 1) PG8_BAR;
	v_max_f32_e32 v62, v54, v54
	v_max_f32_e32 v63, v52, v52
	v_max_f32_e32 v62, v63, v62
	s_waitcnt lgkmcnt(0)
	v_max3_f32 v66, v58, v60, v62
	v_sub_f32_e32 v58, v58, v66
	v_exp_f32_e32 v62, v58
	v_sub_f32_e32 v58, v60, v66
	v_sub_f32_e32 v52, v52, v66
	v_exp_f32_e32 v63, v58
	v_exp_f32_e32 v65, v52
	v_sub_f32_e32 v52, v54, v66
	v_exp_f32_e32 v64, v52
	v_mov_b32_e32 v60, v59
	v_mov_b32_e32 v52, v55
	v_sub_f32_e32 v55, v144, v66
	v_pk_mul_f32 v[58:59], v[60:61], v[62:63]
	v_exp_f32_e32 v55, v55
	v_pk_mul_f32 v[52:53], v[52:53], v[64:65]
	v_add_f32_e32 v54, v58, v59
	v_add_f32_e32 v53, v53, v54
	v_add_f32_e32 v54, v52, v53
	v_div_scale_f32 v58, s[8:9], v54, v54, v55
	v_rcp_f32_e32 v59, v58
	v_add_co_u32_e32 v52, vcc, s5, v96
	s_nop 1
	v_addc_co_u32_e32 v53, vcc, 0, v97, vcc
	global_store_dwordx4 v[52:53], v[48:51], off offset:256
	s_nop 1
	v_fma_f32 v48, -v58, v59, 1.0
	v_fmac_f32_e32 v59, v48, v59
	v_div_scale_f32 v48, vcc, v55, v54, v55
	v_mul_f32_e32 v49, v48, v59
	v_fma_f32 v50, -v58, v49, v48
	v_fmac_f32_e32 v49, v50, v59
	v_fma_f32 v48, -v58, v49, v48
	v_div_fmas_f32 v48, v48, v59, v49
	v_div_fixup_f32 v48, v48, v54, v55
	v_pk_mul_f32 v[46:47], v[46:47], v[48:49] op_sel_hi:[1,0]
	v_pk_mul_f32 v[44:45], v[44:45], v[48:49] op_sel_hi:[1,0]
	v_pk_mul_f32 v[50:51], v[42:43], v[48:49] op_sel_hi:[1,0]
	v_pk_mul_f32 v[42:43], v[40:41], v[48:49] op_sel_hi:[1,0]
	v_cvt_pk_bf16_f32 v40, v44, v45
	v_cvt_pk_bf16_f32 v41, v46, v47
	v_pk_mul_f32 v[38:39], v[38:39], v[48:49] op_sel_hi:[1,0]
	v_cvt_pk_bf16_f32 v42, v42, v43
	v_cvt_pk_bf16_f32 v43, v50, v51
	global_store_dwordx4 v[52:53], v[40:43], off offset:2048
	v_pk_mul_f32 v[36:37], v[36:37], v[48:49] op_sel_hi:[1,0]
	s_nop 0
	v_pk_mul_f32 v[40:41], v[34:35], v[48:49] op_sel_hi:[1,0]
	v_pk_mul_f32 v[34:35], v[32:33], v[48:49] op_sel_hi:[1,0]
	v_cvt_pk_bf16_f32 v32, v36, v37
	v_cvt_pk_bf16_f32 v33, v38, v39
	s_nop 0
	v_cvt_pk_bf16_f32 v34, v34, v35
	v_cvt_pk_bf16_f32 v35, v40, v41
	ds_read_b128 v[36:39], v121 offset:4176
	ds_read_b128 v[40:43], v121 offset:4160
	global_store_dwordx4 v[52:53], v[32:35], off offset:2304
	s_waitcnt lgkmcnt(1)
	v_max_f32_e32 v44, v38, v38
	v_max_f32_e32 v45, v36, v36
	v_max_f32_e32 v44, v45, v44
	s_waitcnt lgkmcnt(0)
	v_max3_f32 v48, v40, v42, v44
	v_sub_f32_e32 v40, v40, v48
	v_exp_f32_e32 v44, v40
	v_sub_f32_e32 v40, v42, v48
	v_sub_f32_e32 v36, v36, v48
	v_exp_f32_e32 v45, v40
	v_exp_f32_e32 v47, v36
	v_sub_f32_e32 v36, v38, v48
	v_exp_f32_e32 v46, v36
	v_mov_b32_e32 v42, v41
	v_mov_b32_e32 v36, v39
	v_sub_f32_e32 v39, v136, v48
	v_pk_mul_f32 v[40:41], v[42:43], v[44:45]
	v_exp_f32_e32 v39, v39
	v_pk_mul_f32 v[36:37], v[36:37], v[46:47]
	v_add_f32_e32 v38, v40, v41
	v_add_f32_e32 v37, v37, v38
	v_add_f32_e32 v36, v36, v37
	v_div_scale_f32 v37, s[8:9], v36, v36, v39
	v_rcp_f32_e32 v38, v37
	s_nop 0
	v_fma_f32 v32, -v37, v38, 1.0
	v_fmac_f32_e32 v38, v32, v38
	v_div_scale_f32 v32, vcc, v39, v36, v39
	v_mul_f32_e32 v33, v32, v38
	v_fma_f32 v34, -v37, v33, v32
	v_fmac_f32_e32 v33, v34, v38
	v_fma_f32 v32, -v37, v33, v32
	v_div_fmas_f32 v32, v32, v38, v33
	v_div_fixup_f32 v32, v32, v36, v39
	v_pk_mul_f32 v[30:31], v[30:31], v[32:33] op_sel_hi:[1,0]
	v_pk_mul_f32 v[28:29], v[28:29], v[32:33] op_sel_hi:[1,0]
	v_pk_mul_f32 v[34:35], v[26:27], v[32:33] op_sel_hi:[1,0]
	v_pk_mul_f32 v[26:27], v[24:25], v[32:33] op_sel_hi:[1,0]
	v_cvt_pk_bf16_f32 v24, v28, v29
	v_cvt_pk_bf16_f32 v25, v30, v31
	v_pk_mul_f32 v[22:23], v[22:23], v[32:33] op_sel_hi:[1,0]
	v_cvt_pk_bf16_f32 v26, v26, v27
	v_cvt_pk_bf16_f32 v27, v34, v35
	global_store_dwordx4 v[56:57], v[24:27], off
	v_pk_mul_f32 v[20:21], v[20:21], v[32:33] op_sel_hi:[1,0]
	s_nop 0
	v_pk_mul_f32 v[24:25], v[18:19], v[32:33] op_sel_hi:[1,0]
	v_pk_mul_f32 v[18:19], v[16:17], v[32:33] op_sel_hi:[1,0]
	v_cvt_pk_bf16_f32 v16, v20, v21
	v_cvt_pk_bf16_f32 v17, v22, v23
	s_nop 0
	v_cvt_pk_bf16_f32 v18, v18, v19
	v_cvt_pk_bf16_f32 v19, v24, v25
	v_add_u32_e32 v24, s6, v122
	ds_read2_b64 v[20:23], v24 offset0:2 offset1:3
	ds_read2_b64 v[24:27], v24 offset1:1
	global_store_dwordx4 v[56:57], v[16:19], off offset:256
	s_waitcnt lgkmcnt(1)
	v_max_f32_e32 v28, v22, v22
	v_max_f32_e32 v29, v20, v20
	v_max_f32_e32 v28, v29, v28
	s_waitcnt lgkmcnt(0)
	v_max3_f32 v32, v24, v26, v28
	v_sub_f32_e32 v24, v24, v32
	v_exp_f32_e32 v28, v24
	v_sub_f32_e32 v24, v26, v32
	v_sub_f32_e32 v20, v20, v32
	v_exp_f32_e32 v29, v24
	v_exp_f32_e32 v31, v20
	v_sub_f32_e32 v20, v22, v32
	v_exp_f32_e32 v30, v20
	v_mov_b32_e32 v26, v25
	v_mov_b32_e32 v20, v23
	v_sub_f32_e32 v23, v120, v32
	v_pk_mul_f32 v[24:25], v[26:27], v[28:29]
	v_exp_f32_e32 v23, v23
	v_pk_mul_f32 v[20:21], v[20:21], v[30:31]
	v_add_f32_e32 v22, v24, v25
	v_add_f32_e32 v21, v21, v22
	v_add_f32_e32 v20, v20, v21
	v_div_scale_f32 v21, s[8:9], v20, v20, v23
	v_rcp_f32_e32 v22, v21
	s_mov_b64 s[8:9], -1
	v_fma_f32 v16, -v21, v22, 1.0
	v_fmac_f32_e32 v22, v16, v22
	v_div_scale_f32 v16, vcc, v23, v20, v23
	v_mul_f32_e32 v17, v16, v22
	v_fma_f32 v18, -v21, v17, v16
	v_fmac_f32_e32 v17, v18, v22
	v_fma_f32 v16, -v21, v17, v16
	v_div_fmas_f32 v16, v16, v22, v17
	v_div_fixup_f32 v16, v16, v20, v23
	v_pk_mul_f32 v[14:15], v[14:15], v[16:17] op_sel_hi:[1,0]
	v_pk_mul_f32 v[12:13], v[12:13], v[16:17] op_sel_hi:[1,0]
	v_pk_mul_f32 v[18:19], v[10:11], v[16:17] op_sel_hi:[1,0]
	v_pk_mul_f32 v[10:11], v[8:9], v[16:17] op_sel_hi:[1,0]
	v_cvt_pk_bf16_f32 v8, v12, v13
	v_cvt_pk_bf16_f32 v9, v14, v15
	s_and_b64 vcc, exec, s[44:45]
	v_cvt_pk_bf16_f32 v10, v10, v11
	v_cvt_pk_bf16_f32 v11, v18, v19
	global_store_dwordx4 v[56:57], v[8:11], off offset:2048
	v_pk_mul_f32 v[6:7], v[6:7], v[16:17] op_sel_hi:[1,0]
	v_pk_mul_f32 v[4:5], v[4:5], v[16:17] op_sel_hi:[1,0]
	v_pk_mul_f32 v[8:9], v[2:3], v[16:17] op_sel_hi:[1,0]
	v_pk_mul_f32 v[2:3], v[0:1], v[16:17] op_sel_hi:[1,0]
	v_cvt_pk_bf16_f32 v0, v4, v5
	v_cvt_pk_bf16_f32 v1, v6, v7
	s_nop 0
	v_cvt_pk_bf16_f32 v2, v2, v3
	v_cvt_pk_bf16_f32 v3, v8, v9
	global_store_dwordx4 v[56:57], v[0:3], off offset:2304
	s_cbranch_vccnz .LBB0_851
	s_and_b64 vcc, exec, s[38:39]
	s_cbranch_vccnz .LBB0_850
	s_mov_b32 s100, 1
	s_branch .LBB0_850

; #define PG8_STAGE(bufoff, gbase, voff) do { _Pragma("unroll") for (int _i = 0; _i < 2; ++_i) \
;         __builtin_amdgcn_global_load_lds((const unsigned*)((const char*)(gbase) + (voff)[_i]), (PG8_LAS unsigned*)(lds + (bufoff) + ldsw + _i * 8192), 16, 0, 0); } while (0)
; #define PG8_LDA(dst, b, h) do { _Pragma("unroll") for (int m = 0; m < 4; ++m) _Pragma("unroll") for (int k = 0; k < 2; ++k) dst[m][k] = *(const PG8_LAS bf16x8*)(lds + PG8_SA(b, h) + aoff + m * 2048 + k * 1024); } while (0)
; #define PG8_LDB(dst, b, h) do { _Pragma("unroll") for (int n = 0; n < 2; ++n) _Pragma("unroll") for (int k = 0; k < 2; ++k) dst[n][k] = *(const PG8_LAS bf16x8*)(lds + PG8_SB(b, h) + boff + n * 2048 + k * 1024); } while (0)
; #define PG8_MMA(ai, bj, At, Bt) do { __builtin_amdgcn_s_setprio(1); _Pragma("unroll") for (int m = 0; m < 4; ++m) _Pragma("unroll") for (int n = 0; n < 2; ++n) _Pragma("unroll") for (int k = 0; k < 2; ++k) \
;         acc[ai][bj][m][n] = __builtin_amdgcn_mfma_f32_16x16x32_bf16(Bt[n][k], At[m][k], acc[ai][bj][m][n], 0, 0, 0); __builtin_amdgcn_s_setprio(0); } while (0)
; #define PG8_WAIT_V(n) asm volatile("s_waitcnt vmcnt(" #n ")" ::: "memory")
; #define PG8_WAIT_L(n) asm volatile("s_waitcnt lgkmcnt(" #n ")" ::: "memory")
; #define PG8_BAR __builtin_amdgcn_s_barrier()
; template <class Epi>
; __device__ __forceinline__ void gemm_phase(PG8_LAS unsigned char* lds, PG8_LAS unsigned char* xl, const Gemm g, const Sched& S, const Epi& E, const int wid) {
;     ...
;             const char* a1 = cA + (size_t)(t + 1) * kstep + j1;
;             const char* a2 = last ? nA : cA + (size_t)(t + 2) * kstep + ja2; const char* b2 = last ? nB : cB + (size_t)(t + 2) * kstep + jb2;
;             const char* a3 = a2 + kstep; const char* b3 = b2 + kstep;
;             PG8_LDB(B0, 0, 0); PG8_LDB(B1, 0, 1); PG8_SCHED; PG8_LDA(At, 0, 0); PG8_STAGE(PG8_SA(1, 1), a1 + hstepA, voffA);
;             PG8_WAIT_V(8); PG8_WAIT_L(0); PG8_BAR; if (do0) { PG8_MMA(0, 0, At, B0); PG8_MMA(0, 1, At, B1); } PG8_BAR; PG8_SCHED;
;     ...
;         for (int a = 0; a < 2; ++a)
; #pragma unroll
;             for (int b = 0; b < 2; ++b)
; #pragma unroll
;                 for (int m = 0; m < 4; ++m)
; #pragma unroll
;                     for (int n = 0; n < 2; ++n) acc[a][b][m][n] = (f32x4){0.f, 0.f, 0.f, 0.f};
;         cur = nxt; cA = nA; cB = nB; ++ui;
;         if (wr == 1) PG8_BAR;
.LBB0_958:
	s_add_u32 s8, s56, 0x100
	v_mov_b32_e32 v0, 0
	s_addc_u32 s9, s57, 0
	s_mov_b32 s10, -2
	s_waitcnt lgkmcnt(0)
	v_mov_b32_e32 v1, v0
	v_mov_b32_e32 v2, v0
	v_mov_b32_e32 v3, v0
	v_mov_b32_e32 v4, v0
	v_mov_b32_e32 v5, v0
	v_mov_b32_e32 v6, v0
	v_mov_b32_e32 v7, v0
	v_mov_b32_e32 v16, v0
	v_mov_b32_e32 v17, v0
	v_mov_b32_e32 v18, v0
	v_mov_b32_e32 v19, v0
	v_mov_b32_e32 v20, v0
	v_mov_b32_e32 v21, v0
	v_mov_b32_e32 v22, v0
	v_mov_b32_e32 v23, v0
	v_mov_b32_e32 v32, v0
	v_mov_b32_e32 v33, v0
	v_mov_b32_e32 v34, v0
	v_mov_b32_e32 v35, v0
	v_mov_b32_e32 v36, v0
	v_mov_b32_e32 v37, v0
	v_mov_b32_e32 v38, v0
	v_mov_b32_e32 v39, v0
	v_mov_b32_e32 v48, v0
	v_mov_b32_e32 v49, v0
	v_mov_b32_e32 v50, v0
	v_mov_b32_e32 v51, v0
	v_mov_b32_e32 v52, v0
	v_mov_b32_e32 v53, v0
	v_mov_b32_e32 v54, v0
	v_mov_b32_e32 v55, v0
	v_mov_b32_e32 v8, v0
	v_mov_b32_e32 v9, v0
	v_mov_b32_e32 v10, v0
	v_mov_b32_e32 v11, v0
	v_mov_b32_e32 v12, v0
	v_mov_b32_e32 v13, v0
	v_mov_b32_e32 v14, v0
	v_mov_b32_e32 v15, v0
	v_mov_b32_e32 v24, v0
	v_mov_b32_e32 v25, v0
	v_mov_b32_e32 v26, v0
	v_mov_b32_e32 v27, v0
	v_mov_b32_e32 v28, v0
	v_mov_b32_e32 v29, v0
	v_mov_b32_e32 v30, v0
	v_mov_b32_e32 v31, v0
	v_mov_b32_e32 v40, v0
	v_mov_b32_e32 v41, v0
	v_mov_b32_e32 v42, v0
	v_mov_b32_e32 v43, v0
	v_mov_b32_e32 v44, v0
	v_mov_b32_e32 v45, v0
	v_mov_b32_e32 v46, v0
	v_mov_b32_e32 v47, v0
	v_mov_b32_e32 v56, v0
	v_mov_b32_e32 v57, v0
	v_mov_b32_e32 v58, v0
	v_mov_b32_e32 v59, v0
	v_mov_b32_e32 v60, v0
	v_mov_b32_e32 v61, v0
	v_mov_b32_e32 v62, v0
	v_mov_b32_e32 v63, v0
	v_mov_b32_e32 v64, v0
	v_mov_b32_e32 v65, v0
	v_mov_b32_e32 v66, v0
	v_mov_b32_e32 v67, v0
	v_mov_b32_e32 v68, v0
	v_mov_b32_e32 v69, v0
	v_mov_b32_e32 v70, v0
	v_mov_b32_e32 v71, v0
	v_mov_b32_e32 v80, v0
	v_mov_b32_e32 v81, v0
	v_mov_b32_e32 v82, v0
	v_mov_b32_e32 v83, v0
	v_mov_b32_e32 v84, v0
	v_mov_b32_e32 v85, v0
	v_mov_b32_e32 v86, v0
	v_mov_b32_e32 v87, v0
	v_mov_b32_e32 v96, v0
	v_mov_b32_e32 v97, v0
	v_mov_b32_e32 v98, v0
	v_mov_b32_e32 v99, v0
	v_mov_b32_e32 v100, v0
	v_mov_b32_e32 v101, v0
	v_mov_b32_e32 v102, v0
	v_mov_b32_e32 v103, v0
	v_mov_b32_e32 v112, v0
	v_mov_b32_e32 v113, v0
	v_mov_b32_e32 v114, v0
	v_mov_b32_e32 v115, v0
	v_mov_b32_e32 v116, v0
	v_mov_b32_e32 v117, v0
	v_mov_b32_e32 v118, v0
	v_mov_b32_e32 v119, v0
	v_mov_b32_e32 v72, v0
	v_mov_b32_e32 v73, v0
	v_mov_b32_e32 v74, v0
	v_mov_b32_e32 v75, v0
	v_mov_b32_e32 v76, v0
	v_mov_b32_e32 v77, v0
	v_mov_b32_e32 v78, v0
	v_mov_b32_e32 v79, v0
	v_mov_b32_e32 v88, v0
	v_mov_b32_e32 v89, v0
	v_mov_b32_e32 v90, v0
	v_mov_b32_e32 v91, v0
	v_mov_b32_e32 v92, v0
	v_mov_b32_e32 v93, v0
	v_mov_b32_e32 v94, v0
	v_mov_b32_e32 v95, v0
	v_mov_b32_e32 v104, v0
	v_mov_b32_e32 v105, v0
	v_mov_b32_e32 v106, v0
	v_mov_b32_e32 v107, v0
	v_mov_b32_e32 v108, v0
	v_mov_b32_e32 v109, v0
	v_mov_b32_e32 v110, v0
	v_mov_b32_e32 v111, v0
	v_mov_b32_e32 v120, v0
	v_mov_b32_e32 v121, v0
	v_mov_b32_e32 v122, v0
	v_mov_b32_e32 v123, v0
	v_mov_b32_e32 v132, v0
	v_mov_b32_e32 v133, v0
	v_mov_b32_e32 v134, v0
	v_mov_b32_e32 v135, v0
	s_cmp_lg_u32 s100, 1
	s_cbranch_scc1 .Ldefbar_skip_8
	s_mov_b32 s100, 0
	s_barrier
.Ldefbar_skip_8:
.LBB0_959:
	s_add_u32 s56, s52, 0x100
	s_addc_u32 s57, s53, 0
	s_add_i32 s11, 0, 0x10000
	s_cmp_eq_u32 s10, 12
	s_cselect_b32 s61, s47, s57
	s_cselect_b32 s60, s46, s56
	s_cselect_b32 s59, s51, s9
	s_cselect_b32 s58, s50, s8
	s_add_i32 s13, 0, 0x14000
	v_add_u32_e32 v140, s11, v195
	v_add_u32_e32 v156, s13, v195
	ds_read_b128 v[124:127], v140
	ds_read_b128 v[128:131], v140 offset:1024
	ds_read_b128 v[136:139], v140 offset:2048
	ds_read_b128 v[140:143], v140 offset:3072
	ds_read_b128 v[144:147], v156
	ds_read_b128 v[148:151], v156 offset:1024
	ds_read_b128 v[152:155], v156 offset:2048
	ds_read_b128 v[156:159], v156 offset:3072
	v_lshl_add_u64 v[204:205], s[52:53], 0, v[214:215]
	s_add_i32 m0, s66, 0xc000
	ds_read_b128 v[160:163], v220
	ds_read_b128 v[164:167], v220 offset:1024
	ds_read_b128 v[168:171], v220 offset:2048
	ds_read_b128 v[172:175], v220 offset:3072
	ds_read_b128 v[176:179], v220 offset:4096
	ds_read_b128 v[180:183], v220 offset:5120
	ds_read_b128 v[184:187], v220 offset:6144
	ds_read_b128 v[222:225], v220 offset:7168
	global_load_lds_dwordx4 v[204:205], off
	v_lshl_add_u64 v[204:205], s[52:53], 0, v[216:217]
	s_add_i32 m0, s66, 0xe000
	s_nop 0
	global_load_lds_dwordx4 v[204:205], off
	s_waitcnt vmcnt(8)
	s_waitcnt lgkmcnt(0)
	s_setprio 1
	s_barrier
	v_mfma_f32_16x16x32_bf16 v[132:135], v[124:127], v[160:163], v[132:135]
	v_mfma_f32_16x16x32_bf16 v[120:123], v[136:139], v[160:163], v[120:123]
	v_mfma_f32_16x16x32_bf16 v[108:111], v[124:127], v[168:171], v[108:111]
	v_mfma_f32_16x16x32_bf16 v[104:107], v[136:139], v[168:171], v[104:107]
	v_mfma_f32_16x16x32_bf16 v[92:95], v[124:127], v[176:179], v[92:95]
	v_mfma_f32_16x16x32_bf16 v[88:91], v[136:139], v[176:179], v[88:91]
	v_mfma_f32_16x16x32_bf16 v[76:79], v[124:127], v[184:187], v[76:79]
	v_mfma_f32_16x16x32_bf16 v[72:75], v[136:139], v[184:187], v[72:75]
	v_mfma_f32_16x16x32_bf16 v[132:135], v[128:131], v[164:167], v[132:135]
	v_mfma_f32_16x16x32_bf16 v[120:123], v[140:143], v[164:167], v[120:123]
	v_mfma_f32_16x16x32_bf16 v[108:111], v[128:131], v[172:175], v[108:111]
	v_mfma_f32_16x16x32_bf16 v[104:107], v[140:143], v[172:175], v[104:107]
	v_mfma_f32_16x16x32_bf16 v[92:95], v[128:131], v[180:183], v[92:95]
	v_mfma_f32_16x16x32_bf16 v[88:91], v[140:143], v[180:183], v[88:91]
	v_mfma_f32_16x16x32_bf16 v[76:79], v[128:131], v[222:225], v[76:79]
	v_mfma_f32_16x16x32_bf16 v[72:75], v[140:143], v[222:225], v[72:75]
	s_setprio 0
	s_setprio 1
	v_mfma_f32_16x16x32_bf16 v[116:119], v[144:147], v[160:163], v[116:119]
	v_mfma_f32_16x16x32_bf16 v[112:115], v[152:155], v[160:163], v[112:115]
	v_mfma_f32_16x16x32_bf16 v[100:103], v[144:147], v[168:171], v[100:103]
	v_mfma_f32_16x16x32_bf16 v[96:99], v[152:155], v[168:171], v[96:99]
	v_mfma_f32_16x16x32_bf16 v[84:87], v[144:147], v[176:179], v[84:87]
	v_mfma_f32_16x16x32_bf16 v[80:83], v[152:155], v[176:179], v[80:83]
	v_mfma_f32_16x16x32_bf16 v[68:71], v[144:147], v[184:187], v[68:71]
	v_mfma_f32_16x16x32_bf16 v[64:67], v[152:155], v[184:187], v[64:67]
	v_mfma_f32_16x16x32_bf16 v[116:119], v[148:151], v[164:167], v[116:119]
	v_mfma_f32_16x16x32_bf16 v[112:115], v[156:159], v[164:167], v[112:115]
	v_mfma_f32_16x16x32_bf16 v[100:103], v[148:151], v[172:175], v[100:103]
	v_mfma_f32_16x16x32_bf16 v[96:99], v[156:159], v[172:175], v[96:99]
	v_mfma_f32_16x16x32_bf16 v[84:87], v[148:151], v[180:183], v[84:87]
	v_mfma_f32_16x16x32_bf16 v[80:83], v[156:159], v[180:183], v[80:83]
	v_mfma_f32_16x16x32_bf16 v[68:71], v[148:151], v[222:225], v[68:71]
	v_mfma_f32_16x16x32_bf16 v[64:67], v[156:159], v[222:225], v[64:67]
	s_barrier
; #define PG8_STAGE(bufoff, gbase, voff) do { _Pragma("unroll") for (int _i = 0; _i < 2; ++_i) \
;         __builtin_amdgcn_global_load_lds((const unsigned*)((const char*)(gbase) + (voff)[_i]), (PG8_LAS unsigned*)(lds + (bufoff) + ldsw + _i * 8192), 16, 0, 0); } while (0)
; #define PG8_LDA(dst, b, h) do { _Pragma("unroll") for (int m = 0; m < 4; ++m) _Pragma("unroll") for (int k = 0; k < 2; ++k) dst[m][k] = *(const PG8_LAS bf16x8*)(lds + PG8_SA(b, h) + aoff + m * 2048 + k * 1024); } while (0)
; #define PG8_LDB(dst, b, h) do { _Pragma("unroll") for (int n = 0; n < 2; ++n) _Pragma("unroll") for (int k = 0; k < 2; ++k) dst[n][k] = *(const PG8_LAS bf16x8*)(lds + PG8_SB(b, h) + boff + n * 2048 + k * 1024); } while (0)
; #define PG8_MMA(ai, bj, At, Bt) do { __builtin_amdgcn_s_setprio(1); _Pragma("unroll") for (int m = 0; m < 4; ++m) _Pragma("unroll") for (int n = 0; n < 2; ++n) _Pragma("unroll") for (int k = 0; k < 2; ++k) \
;         acc[ai][bj][m][n] = __builtin_amdgcn_mfma_f32_16x16x32_bf16(Bt[n][k], At[m][k], acc[ai][bj][m][n], 0, 0, 0); __builtin_amdgcn_s_setprio(0); } while (0)
; #define PG8_WAIT_V(n) asm volatile("s_waitcnt vmcnt(" #n ")" ::: "memory")
; #define PG8_WAIT_L(n) asm volatile("s_waitcnt lgkmcnt(" #n ")" ::: "memory")
; #define PG8_BAR __builtin_amdgcn_s_barrier()
; #define PG8_SCHED __builtin_amdgcn_sched_barrier(0)
; template <class Epi>
; __device__ __forceinline__ void gemm_phase(PG8_LAS unsigned char* lds, PG8_LAS unsigned char* xl, const Gemm g, const Sched& S, const Epi& E, const int wid) {
;     ...
;             PG8_WAIT_V(8); PG8_WAIT_L(0); PG8_BAR; if (do0) { PG8_MMA(0, 0, At, B0); PG8_MMA(0, 1, At, B1); } PG8_BAR; PG8_SCHED;
;             PG8_LDA(At, 0, 1); PG8_STAGE(PG8_SB(0, 0), b2, voffB); PG8_STAGE(PG8_SB(0, 1), b2 + hstepB, voffB); PG8_STAGE(PG8_SA(0, 0), a2, voffA);
;             PG8_WAIT_V(8); PG8_WAIT_L(0); PG8_BAR; if (do1) { PG8_MMA(1, 0, At, B0); PG8_MMA(1, 1, At, B1); } PG8_BAR; PG8_SCHED;
;             PG8_LDB(B0, 1, 0); PG8_LDB(B1, 1, 1); PG8_SCHED; PG8_LDA(At, 1, 0); PG8_STAGE(PG8_SA(0, 1), a2 + hstepA, voffA);
;             PG8_WAIT_V(8); PG8_WAIT_L(0); PG8_BAR; if (do0) { PG8_MMA(0, 0, At, B0); PG8_MMA(0, 1, At, B1); } PG8_BAR; PG8_SCHED;
	s_setprio 0
	s_add_i32 s11, s11, s29
	v_lshl_add_u64 v[204:205], s[58:59], 0, v[190:191]
	s_mov_b32 m0, s11
	ds_read_b128 v[160:163], v220 offset:16384
	ds_read_b128 v[164:167], v220 offset:17408
	ds_read_b128 v[168:171], v220 offset:18432
	ds_read_b128 v[172:175], v220 offset:19456
	ds_read_b128 v[176:179], v220 offset:20480
	ds_read_b128 v[180:183], v220 offset:21504
	ds_read_b128 v[184:187], v220 offset:22528
	ds_read_b128 v[222:225], v220 offset:23552
	global_load_lds_dwordx4 v[204:205], off
	s_add_i32 m0, s11, 0x2000
	s_add_u32 s52, s58, 0x40000
	v_lshl_add_u64 v[218:219], s[58:59], 0, v[212:213]
	s_addc_u32 s53, s59, 0
	s_add_i32 s11, s13, s29
	global_load_lds_dwordx4 v[218:219], off
	v_lshl_add_u64 v[226:227], s[52:53], 0, v[190:191]
	s_mov_b32 m0, s11
	v_lshl_add_u64 v[228:229], s[60:61], 0, v[210:211]
	global_load_lds_dwordx4 v[226:227], off
	v_lshl_add_u64 v[226:227], s[52:53], 0, v[212:213]
	s_add_i32 m0, s11, 0x2000
	s_nop 0
	global_load_lds_dwordx4 v[226:227], off
	v_lshl_add_u64 v[226:227], s[60:61], 0, v[188:189]
	s_mov_b32 m0, s66
	s_nop 0
	global_load_lds_dwordx4 v[226:227], off
	s_mov_b32 m0, s67
	s_nop 0
	global_load_lds_dwordx4 v[228:229], off
	s_waitcnt vmcnt(8)
	s_waitcnt lgkmcnt(0)
	s_setprio 1
	s_barrier
	v_mfma_f32_16x16x32_bf16 v[60:63], v[124:127], v[160:163], v[60:63]
	v_mfma_f32_16x16x32_bf16 v[56:59], v[136:139], v[160:163], v[56:59]
	v_mfma_f32_16x16x32_bf16 v[44:47], v[124:127], v[168:171], v[44:47]
	v_mfma_f32_16x16x32_bf16 v[40:43], v[136:139], v[168:171], v[40:43]
	v_mfma_f32_16x16x32_bf16 v[28:31], v[124:127], v[176:179], v[28:31]
	v_mfma_f32_16x16x32_bf16 v[24:27], v[136:139], v[176:179], v[24:27]
	v_mfma_f32_16x16x32_bf16 v[12:15], v[124:127], v[184:187], v[12:15]
	v_mfma_f32_16x16x32_bf16 v[8:11], v[136:139], v[184:187], v[8:11]
	v_mfma_f32_16x16x32_bf16 v[60:63], v[128:131], v[164:167], v[60:63]
	v_mfma_f32_16x16x32_bf16 v[56:59], v[140:143], v[164:167], v[56:59]
	v_mfma_f32_16x16x32_bf16 v[44:47], v[128:131], v[172:175], v[44:47]
	v_mfma_f32_16x16x32_bf16 v[40:43], v[140:143], v[172:175], v[40:43]
	v_mfma_f32_16x16x32_bf16 v[28:31], v[128:131], v[180:183], v[28:31]
	v_mfma_f32_16x16x32_bf16 v[24:27], v[140:143], v[180:183], v[24:27]
	v_mfma_f32_16x16x32_bf16 v[12:15], v[128:131], v[222:225], v[12:15]
	v_mfma_f32_16x16x32_bf16 v[8:11], v[140:143], v[222:225], v[8:11]
	s_setprio 0
	s_setprio 1
	v_mfma_f32_16x16x32_bf16 v[52:55], v[144:147], v[160:163], v[52:55]
	v_mfma_f32_16x16x32_bf16 v[48:51], v[152:155], v[160:163], v[48:51]
	v_mfma_f32_16x16x32_bf16 v[36:39], v[144:147], v[168:171], v[36:39]
	v_mfma_f32_16x16x32_bf16 v[32:35], v[152:155], v[168:171], v[32:35]
	v_mfma_f32_16x16x32_bf16 v[20:23], v[144:147], v[176:179], v[20:23]
	v_mfma_f32_16x16x32_bf16 v[16:19], v[152:155], v[176:179], v[16:19]
	v_mfma_f32_16x16x32_bf16 v[4:7], v[144:147], v[184:187], v[4:7]
	v_mfma_f32_16x16x32_bf16 v[0:3], v[152:155], v[184:187], v[0:3]
	v_mfma_f32_16x16x32_bf16 v[52:55], v[148:151], v[164:167], v[52:55]
	v_mfma_f32_16x16x32_bf16 v[48:51], v[156:159], v[164:167], v[48:51]
	v_mfma_f32_16x16x32_bf16 v[36:39], v[148:151], v[172:175], v[36:39]
	v_mfma_f32_16x16x32_bf16 v[32:35], v[156:159], v[172:175], v[32:35]
	v_mfma_f32_16x16x32_bf16 v[20:23], v[148:151], v[180:183], v[20:23]
	v_mfma_f32_16x16x32_bf16 v[16:19], v[156:159], v[180:183], v[16:19]
	v_mfma_f32_16x16x32_bf16 v[4:7], v[148:151], v[222:225], v[4:7]
	v_mfma_f32_16x16x32_bf16 v[0:3], v[156:159], v[222:225], v[0:3]
	s_barrier
	s_setprio 0
	s_add_i32 s11, 0, 0x18000
	s_add_i32 s13, 0, 0x1c000
	v_add_u32_e32 v140, s11, v195
	v_add_u32_e32 v156, s13, v195
	ds_read_b128 v[124:127], v140
	ds_read_b128 v[128:131], v140 offset:1024
	ds_read_b128 v[136:139], v140 offset:2048
	ds_read_b128 v[140:143], v140 offset:3072
	ds_read_b128 v[144:147], v156
	ds_read_b128 v[148:151], v156 offset:1024
	ds_read_b128 v[152:155], v156 offset:2048
	ds_read_b128 v[156:159], v156 offset:3072
	s_add_u32 s52, s60, 0x40000
	s_addc_u32 s53, s61, 0
	s_mov_b32 m0, s68
	v_lshl_add_u64 v[230:231], s[52:53], 0, v[188:189]
	ds_read_b128 v[160:163], v220 offset:32768
	ds_read_b128 v[164:167], v220 offset:33792
	ds_read_b128 v[168:171], v220 offset:34816
	ds_read_b128 v[172:175], v220 offset:35840
	ds_read_b128 v[176:179], v220 offset:36864
	ds_read_b128 v[180:183], v220 offset:37888
	ds_read_b128 v[184:187], v220 offset:38912
	ds_read_b128 v[222:225], v220 offset:39936
	global_load_lds_dwordx4 v[230:231], off
	v_lshl_add_u64 v[230:231], s[52:53], 0, v[210:211]
	s_mov_b32 m0, s69
	s_nop 0
	global_load_lds_dwordx4 v[230:231], off
	s_waitcnt vmcnt(8)
	s_waitcnt lgkmcnt(0)
	s_setprio 1
	s_barrier
; #define PG8_STAGE(bufoff, gbase, voff) do { _Pragma("unroll") for (int _i = 0; _i < 2; ++_i) \
;         __builtin_amdgcn_global_load_lds((const unsigned*)((const char*)(gbase) + (voff)[_i]), (PG8_LAS unsigned*)(lds + (bufoff) + ldsw + _i * 8192), 16, 0, 0); } while (0)
; #define PG8_LDA(dst, b, h) do { _Pragma("unroll") for (int m = 0; m < 4; ++m) _Pragma("unroll") for (int k = 0; k < 2; ++k) dst[m][k] = *(const PG8_LAS bf16x8*)(lds + PG8_SA(b, h) + aoff + m * 2048 + k * 1024); } while (0)
; #define PG8_MMA(ai, bj, At, Bt) do { __builtin_amdgcn_s_setprio(1); _Pragma("unroll") for (int m = 0; m < 4; ++m) _Pragma("unroll") for (int n = 0; n < 2; ++n) _Pragma("unroll") for (int k = 0; k < 2; ++k) \
;         acc[ai][bj][m][n] = __builtin_amdgcn_mfma_f32_16x16x32_bf16(Bt[n][k], At[m][k], acc[ai][bj][m][n], 0, 0, 0); __builtin_amdgcn_s_setprio(0); } while (0)
; #define PG8_WAIT_V(n) asm volatile("s_waitcnt vmcnt(" #n ")" ::: "memory")
; #define PG8_WAIT_L(n) asm volatile("s_waitcnt lgkmcnt(" #n ")" ::: "memory")
; #define PG8_BAR __builtin_amdgcn_s_barrier()
; #define PG8_SCHED __builtin_amdgcn_sched_barrier(0)
; template <class Epi>
; __device__ __forceinline__ void gemm_phase(PG8_LAS unsigned char* lds, PG8_LAS unsigned char* xl, const Gemm g, const Sched& S, const Epi& E, const int wid) {
;     ...
;             PG8_WAIT_V(8); PG8_WAIT_L(0); PG8_BAR; if (do0) { PG8_MMA(0, 0, At, B0); PG8_MMA(0, 1, At, B1); } PG8_BAR; PG8_SCHED;
;             PG8_LDA(At, 1, 1); PG8_STAGE(PG8_SB(1, 0), b3, voffB); PG8_STAGE(PG8_SB(1, 1), b3 + hstepB, voffB); PG8_STAGE(PG8_SA(1, 0), a3, voffA);
;             PG8_WAIT_V(8); PG8_WAIT_L(0); PG8_BAR; if (do1) { PG8_MMA(1, 0, At, B0); PG8_MMA(1, 1, At, B1); } PG8_BAR; PG8_SCHED;
;         }
;         if (wr == 0) PG8_BAR;
	v_mfma_f32_16x16x32_bf16 v[132:135], v[124:127], v[160:163], v[132:135]
	v_mfma_f32_16x16x32_bf16 v[120:123], v[136:139], v[160:163], v[120:123]
	v_mfma_f32_16x16x32_bf16 v[108:111], v[124:127], v[168:171], v[108:111]
	v_mfma_f32_16x16x32_bf16 v[104:107], v[136:139], v[168:171], v[104:107]
	v_mfma_f32_16x16x32_bf16 v[92:95], v[124:127], v[176:179], v[92:95]
	v_mfma_f32_16x16x32_bf16 v[88:91], v[136:139], v[176:179], v[88:91]
	v_mfma_f32_16x16x32_bf16 v[76:79], v[124:127], v[184:187], v[76:79]
	v_mfma_f32_16x16x32_bf16 v[72:75], v[136:139], v[184:187], v[72:75]
	v_mfma_f32_16x16x32_bf16 v[132:135], v[128:131], v[164:167], v[132:135]
	v_mfma_f32_16x16x32_bf16 v[120:123], v[140:143], v[164:167], v[120:123]
	v_mfma_f32_16x16x32_bf16 v[108:111], v[128:131], v[172:175], v[108:111]
	v_mfma_f32_16x16x32_bf16 v[104:107], v[140:143], v[172:175], v[104:107]
	v_mfma_f32_16x16x32_bf16 v[92:95], v[128:131], v[180:183], v[92:95]
	v_mfma_f32_16x16x32_bf16 v[88:91], v[140:143], v[180:183], v[88:91]
	v_mfma_f32_16x16x32_bf16 v[76:79], v[128:131], v[222:225], v[76:79]
	v_mfma_f32_16x16x32_bf16 v[72:75], v[140:143], v[222:225], v[72:75]
	s_setprio 0
	s_setprio 1
	v_mfma_f32_16x16x32_bf16 v[116:119], v[144:147], v[160:163], v[116:119]
	v_mfma_f32_16x16x32_bf16 v[112:115], v[152:155], v[160:163], v[112:115]
	v_mfma_f32_16x16x32_bf16 v[100:103], v[144:147], v[168:171], v[100:103]
	v_mfma_f32_16x16x32_bf16 v[96:99], v[152:155], v[168:171], v[96:99]
	v_mfma_f32_16x16x32_bf16 v[84:87], v[144:147], v[176:179], v[84:87]
	v_mfma_f32_16x16x32_bf16 v[80:83], v[152:155], v[176:179], v[80:83]
	v_mfma_f32_16x16x32_bf16 v[68:71], v[144:147], v[184:187], v[68:71]
	v_mfma_f32_16x16x32_bf16 v[64:67], v[152:155], v[184:187], v[64:67]
	v_mfma_f32_16x16x32_bf16 v[116:119], v[148:151], v[164:167], v[116:119]
	v_mfma_f32_16x16x32_bf16 v[112:115], v[156:159], v[164:167], v[112:115]
	v_mfma_f32_16x16x32_bf16 v[100:103], v[148:151], v[172:175], v[100:103]
	v_mfma_f32_16x16x32_bf16 v[96:99], v[156:159], v[172:175], v[96:99]
	v_mfma_f32_16x16x32_bf16 v[84:87], v[148:151], v[180:183], v[84:87]
	v_mfma_f32_16x16x32_bf16 v[80:83], v[156:159], v[180:183], v[80:83]
	v_mfma_f32_16x16x32_bf16 v[68:71], v[148:151], v[222:225], v[68:71]
	v_mfma_f32_16x16x32_bf16 v[64:67], v[156:159], v[222:225], v[64:67]
	s_barrier
	s_setprio 0
	s_add_i32 s11, s11, s29
	v_lshl_add_u64 v[204:205], v[204:205], 0, s[22:23]
	s_mov_b32 m0, s11
	ds_read_b128 v[160:163], v220 offset:49152
	ds_read_b128 v[164:167], v220 offset:50176
	ds_read_b128 v[168:171], v220 offset:51200
	ds_read_b128 v[172:175], v220 offset:52224
	ds_read_b128 v[176:179], v220 offset:53248
	ds_read_b128 v[180:183], v220 offset:54272
	ds_read_b128 v[184:187], v220 offset:55296
	ds_read_b128 v[222:225], v220 offset:56320
	global_load_lds_dwordx4 v[204:205], off
	s_add_i32 m0, s11, 0x2000
	s_add_u32 s52, s58, 0x40080
	v_lshl_add_u64 v[204:205], v[218:219], 0, s[22:23]
	s_addc_u32 s53, s59, 0
	s_add_i32 s11, s13, s29
	global_load_lds_dwordx4 v[204:205], off
	v_lshl_add_u64 v[204:205], s[52:53], 0, v[190:191]
	s_mov_b32 m0, s11
	s_nop 0
	global_load_lds_dwordx4 v[204:205], off
	v_lshl_add_u64 v[204:205], s[52:53], 0, v[212:213]
	s_add_i32 m0, s11, 0x2000
	s_nop 0
	global_load_lds_dwordx4 v[204:205], off
	v_lshl_add_u64 v[204:205], v[226:227], 0, s[22:23]
	s_mov_b32 m0, s87
	s_nop 0
	global_load_lds_dwordx4 v[204:205], off
	v_lshl_add_u64 v[204:205], v[228:229], 0, s[22:23]
	s_mov_b32 m0, s88
	s_nop 0
	global_load_lds_dwordx4 v[204:205], off
	s_waitcnt vmcnt(8)
	s_waitcnt lgkmcnt(0)
	s_setprio 1
	s_barrier
	v_mfma_f32_16x16x32_bf16 v[60:63], v[124:127], v[160:163], v[60:63]
	v_mfma_f32_16x16x32_bf16 v[56:59], v[136:139], v[160:163], v[56:59]
	v_mfma_f32_16x16x32_bf16 v[44:47], v[124:127], v[168:171], v[44:47]
	v_mfma_f32_16x16x32_bf16 v[40:43], v[136:139], v[168:171], v[40:43]
	v_mfma_f32_16x16x32_bf16 v[28:31], v[124:127], v[176:179], v[28:31]
	v_mfma_f32_16x16x32_bf16 v[24:27], v[136:139], v[176:179], v[24:27]
	v_mfma_f32_16x16x32_bf16 v[12:15], v[124:127], v[184:187], v[12:15]
	v_mfma_f32_16x16x32_bf16 v[8:11], v[136:139], v[184:187], v[8:11]
	v_mfma_f32_16x16x32_bf16 v[60:63], v[128:131], v[164:167], v[60:63]
	v_mfma_f32_16x16x32_bf16 v[56:59], v[140:143], v[164:167], v[56:59]
	v_mfma_f32_16x16x32_bf16 v[44:47], v[128:131], v[172:175], v[44:47]
	v_mfma_f32_16x16x32_bf16 v[40:43], v[140:143], v[172:175], v[40:43]
	v_mfma_f32_16x16x32_bf16 v[28:31], v[128:131], v[180:183], v[28:31]
	v_mfma_f32_16x16x32_bf16 v[24:27], v[140:143], v[180:183], v[24:27]
	v_mfma_f32_16x16x32_bf16 v[12:15], v[128:131], v[222:225], v[12:15]
	v_mfma_f32_16x16x32_bf16 v[8:11], v[140:143], v[222:225], v[8:11]
	s_setprio 0
	s_setprio 1
	v_mfma_f32_16x16x32_bf16 v[52:55], v[144:147], v[160:163], v[52:55]
	v_mfma_f32_16x16x32_bf16 v[48:51], v[152:155], v[160:163], v[48:51]
	v_mfma_f32_16x16x32_bf16 v[36:39], v[144:147], v[168:171], v[36:39]
	v_mfma_f32_16x16x32_bf16 v[32:35], v[152:155], v[168:171], v[32:35]
	v_mfma_f32_16x16x32_bf16 v[20:23], v[144:147], v[176:179], v[20:23]
	v_mfma_f32_16x16x32_bf16 v[16:19], v[152:155], v[176:179], v[16:19]
	v_mfma_f32_16x16x32_bf16 v[4:7], v[144:147], v[184:187], v[4:7]
	v_mfma_f32_16x16x32_bf16 v[0:3], v[152:155], v[184:187], v[0:3]
	v_mfma_f32_16x16x32_bf16 v[52:55], v[148:151], v[164:167], v[52:55]
	v_mfma_f32_16x16x32_bf16 v[48:51], v[156:159], v[164:167], v[48:51]
	v_mfma_f32_16x16x32_bf16 v[36:39], v[148:151], v[172:175], v[36:39]
	v_mfma_f32_16x16x32_bf16 v[32:35], v[156:159], v[172:175], v[32:35]
	v_mfma_f32_16x16x32_bf16 v[20:23], v[148:151], v[180:183], v[20:23]
	v_mfma_f32_16x16x32_bf16 v[16:19], v[156:159], v[180:183], v[16:19]
	v_mfma_f32_16x16x32_bf16 v[4:7], v[148:151], v[222:225], v[4:7]
	v_mfma_f32_16x16x32_bf16 v[0:3], v[156:159], v[222:225], v[0:3]
	s_barrier
	s_setprio 0
	s_add_i32 s10, s10, 2
	s_add_u32 s8, s8, 0x100
	s_addc_u32 s9, s9, 0
	s_cmp_gt_u32 s10, 13
	s_mov_b64 s[52:53], s[56:57]
	s_cbranch_scc0 .LBB0_959
	s_and_b64 vcc, exec, s[14:15]
	s_cbranch_vccz .LBB0_962
	s_barrier
; #define PG8_LAS __attribute__((address_space(3)))
; #define PACK8(w, v0, v1) do { w.x = cvt_pk_bf16(v0[0], v0[1]); w.y = cvt_pk_bf16(v0[2], v0[3]); w.z = cvt_pk_bf16(v1[0], v1[1]); w.w = cvt_pk_bf16(v1[2], v1[3]); } while (0)
; #define ADD8(v0, v1, g) do { v0[0] += bf_lo(g.x); v0[1] += bf_hi(g.x); v0[2] += bf_lo(g.y); v0[3] += bf_hi(g.y); v1[0] += bf_lo(g.z); v1[1] += bf_hi(g.z); v1[2] += bf_lo(g.w); v1[3] += bf_hi(g.w); } while (0)
;     __device__ __forceinline__ void operator()(EPI_ARGS) const {
;         char* ub = (char*)(XB + (long)u.z1 * cS1 + (long)u.pm * BM * ldc + u.pn * BM);
;         const unsigned lo = (unsigned)((wr * 64 + 4 * fr) * ldc + wc * 32 + 8 * fq) * 2u;
;         PG8_LAS float* XS = (PG8_LAS float*)xl;
;         const int ln = fq * 16 + fr;
;         u32x4 xq[2][4][2];
; #pragma unroll
;         for (int ai = 0; ai < 2; ++ai)
; #pragma unroll
;             for (int m = 0; m < 4; ++m)
; #pragma unroll
;                 for (int bj = 0; bj < 2; ++bj) xq[ai][m][bj] = *(const u32x4*)(ub + (size_t)(ai * HALF + m) * ldc * 2 + lo + bj * 256);
;         asm volatile("" ::: "memory");
; #pragma unroll
;         for (int ai = 0; ai < 2; ++ai)
; #pragma unroll
;             for (int m = 0; m < 4; ++m) { float ss = 0.f;
; #pragma unroll
;                 for (int bj = 0; bj < 2; ++bj) { f32x4 v0 = acc[ai][bj][m][0], v1 = acc[ai][bj][m][1];
;                     ADD8(v0, v1, xq[ai][m][bj]);
;                     u32x4 w; PACK8(w, v0, v1); *(u32x4*)(ub + (size_t)(ai * HALF + m) * ldc * 2 + lo + bj * 256) = w;
;                     ss += (v0[0] * v0[0] + v0[1] * v0[1]) + (v0[2] * v0[2] + v0[3] * v0[3]) + (v1[0] * v1[0] + v1[1] * v1[1]) + (v1[2] * v1[2] + v1[3] * v1[3]); }
.LBB0_962:
	s_ashr_i32 s31, s30, 31
	s_lshl_b64 s[8:9], s[30:31], 23
	s_add_u32 s10, s70, s8
	s_addc_u32 s11, s71, s9
	s_ashr_i32 s21, s20, 31
	s_lshl_b64 s[8:9], s[20:21], 20
	s_add_u32 s10, s10, s8
	s_addc_u32 s11, s11, s9
	s_lshl_b32 s8, s12, 8
	v_mbcnt_lo_u32_b32 v221, -1, 0
	v_mbcnt_hi_u32_b32 v221, -1, v221
	s_ashr_i32 s9, s8, 31
	v_lshlrev_b32_e32 v204, 2, v221
	s_lshl_b64 s[8:9], s[8:9], 1
	v_and_or_b32 v205, v204, 60, s3
	s_add_u32 s52, s10, s8
	v_and_b32_e32 v124, -16, v221
	v_lshlrev_b32_e32 v125, 12, v205
	s_addc_u32 s53, s11, s9
	v_add3_u32 v192, v124, s75, v125
	global_load_dwordx4 v[224:227], v192, s[52:53]
	global_load_dwordx4 v[184:187], v192, s[52:53] offset:256
	v_lshl_add_u64 v[218:219], s[52:53], 0, v[192:193]
	v_add_co_u32_e32 v124, vcc, s25, v218
	s_mov_b32 s4, 0x80000
	s_nop 0
	v_addc_co_u32_e32 v125, vcc, 0, v219, vcc
	v_add_co_u32_e32 v126, vcc, s78, v218
	v_xor_b32_e32 v223, 64, v204
	s_nop 0
	v_addc_co_u32_e32 v127, vcc, 0, v219, vcc
	global_load_dwordx4 v[180:183], v[126:127], off offset:-4096
	global_load_dwordx4 v[176:179], v[124:125], off offset:256
	global_load_dwordx4 v[172:175], v[126:127], off
	global_load_dwordx4 v[168:171], v[126:127], off offset:256
	v_add_co_u32_e32 v124, vcc, s79, v218
	v_xor_b32_e32 v222, 0x80, v204
	s_nop 0
	v_addc_co_u32_e32 v125, vcc, 0, v219, vcc
	global_load_dwordx4 v[164:167], v[124:125], off
	global_load_dwordx4 v[160:163], v[124:125], off offset:256
	v_add_co_u32_e32 v124, vcc, s4, v218
	s_mov_b32 s4, 0x82000
	s_nop 0
	v_addc_co_u32_e32 v125, vcc, 0, v219, vcc
	v_add_co_u32_e32 v126, vcc, s95, v218
	s_nop 1
	v_addc_co_u32_e32 v127, vcc, 0, v219, vcc
	global_load_dwordx4 v[156:159], v[126:127], off offset:-4096
	global_load_dwordx4 v[152:155], v[124:125], off offset:256
	global_load_dwordx4 v[148:151], v[126:127], off
	global_load_dwordx4 v[140:143], v[126:127], off offset:256
	v_add_co_u32_e32 v124, vcc, s4, v218
	s_mov_b32 s4, 0x83000
	s_nop 0
	v_addc_co_u32_e32 v125, vcc, 0, v219, vcc
	v_add_co_u32_e32 v126, vcc, s4, v218
	s_nop 0
	s_nop 0
	v_addc_co_u32_e32 v127, vcc, 0, v219, vcc
	global_load_dwordx4 v[144:147], v[126:127], off offset:-4096
	global_load_dwordx4 v[136:139], v[124:125], off offset:256
	global_load_dwordx4 v[128:131], v[126:127], off
	s_nop 0
	global_load_dwordx4 v[124:127], v[126:127], off offset:256
	s_waitcnt vmcnt(8)
	v_lshlrev_b32_e32 v204, 16, v224
	v_add_f32_e32 v132, v132, v204
	v_and_b32_e32 v204, 0xffff0000, v224
	v_add_f32_e32 v133, v133, v204
	v_lshlrev_b32_e32 v204, 16, v225
	v_add_f32_e32 v134, v134, v204
	v_and_b32_e32 v204, 0xffff0000, v225
	v_add_f32_e32 v135, v135, v204
	v_lshlrev_b32_e32 v204, 16, v226
	v_add_f32_e32 v204, v120, v204
	v_and_b32_e32 v120, 0xffff0000, v226
	v_add_f32_e32 v224, v121, v120
	v_lshlrev_b32_e32 v120, 16, v227
	v_add_f32_e32 v225, v122, v120
	v_and_b32_e32 v120, 0xffff0000, v227
	v_add_f32_e32 v226, v123, v120
	v_cvt_pk_bf16_f32 v120, v132, v133
	v_cvt_pk_bf16_f32 v121, v134, v135
	v_cvt_pk_bf16_f32 v122, v204, v224
	v_cvt_pk_bf16_f32 v123, v225, v226
	global_store_dwordx4 v192, v[120:123], s[52:53]
	v_cmp_gt_u32_e32 vcc, 16, v221
	s_nop 0
	v_mul_f32_e32 v120, v133, v133
	v_mul_f32_e32 v121, v135, v135
	v_fmac_f32_e32 v120, v132, v132
	v_fmac_f32_e32 v121, v134, v134
	v_add_f32_e32 v120, v120, v121
	v_mul_f32_e32 v121, v224, v224
	v_fmac_f32_e32 v121, v204, v204
	v_add_f32_e32 v120, v121, v120
	v_mul_f32_e32 v121, v226, v226
	v_fmac_f32_e32 v121, v225, v225
	v_add_f32_e32 v120, v121, v120
	v_lshlrev_b32_e32 v121, 16, v184
	v_add_f32_e32 v116, v116, v121
	v_and_b32_e32 v121, 0xffff0000, v184
	v_add_f32_e32 v117, v117, v121
	v_lshlrev_b32_e32 v121, 16, v185
	v_add_f32_e32 v118, v118, v121
	v_and_b32_e32 v121, 0xffff0000, v185
	v_add_f32_e32 v119, v119, v121
	v_lshlrev_b32_e32 v121, 16, v186
	v_add_f32_e32 v121, v112, v121
	v_and_b32_e32 v112, 0xffff0000, v186
	v_add_f32_e32 v122, v113, v112
	v_lshlrev_b32_e32 v112, 16, v187
	v_add_f32_e32 v123, v114, v112
	v_and_b32_e32 v112, 0xffff0000, v187
	v_add_f32_e32 v132, v115, v112
	v_cvt_pk_bf16_f32 v112, v116, v117
	v_cvt_pk_bf16_f32 v113, v118, v119
	v_cvt_pk_bf16_f32 v114, v121, v122
	v_cvt_pk_bf16_f32 v115, v123, v132
	global_store_dwordx4 v192, v[112:115], s[52:53] offset:256
	s_nop 1
	v_mul_f32_e32 v112, v117, v117
	v_mul_f32_e32 v113, v119, v119
	v_fmac_f32_e32 v112, v116, v116
	v_fmac_f32_e32 v113, v118, v118
	v_add_f32_e32 v112, v112, v113
	v_mul_f32_e32 v113, v122, v122
	v_fmac_f32_e32 v113, v121, v121
	v_add_f32_e32 v112, v113, v112
	v_mul_f32_e32 v113, v132, v132
	v_fmac_f32_e32 v113, v123, v123
	v_add_f32_e32 v112, v113, v112
	v_add_f32_e32 v112, v120, v112
	ds_bpermute_b32 v113, v223, v112
	s_waitcnt lgkmcnt(0)
	v_add_f32_e32 v113, v112, v113
	ds_bpermute_b32 v114, v222, v113
	v_lshl_add_u32 v112, v205, 4, s64
	s_and_saveexec_b64 s[8:9], vcc
	s_cbranch_execz .LBB0_964
	s_waitcnt lgkmcnt(0)
	v_add_f32_e32 v113, v113, v114
	ds_write_b32 v112, v113

; #define PG8_BAR __builtin_amdgcn_s_barrier()
; template <class Epi>
; __device__ __forceinline__ void gemm_phase(PG8_LAS unsigned char* lds, PG8_LAS unsigned char* xl, const Gemm g, const Sched& S, const Epi& E, const int wid) {
;     ...
;         if (!has_next) break;
; #pragma unroll
;         for (int a = 0; a < 2; ++a)
; #pragma unroll
;             for (int b = 0; b < 2; ++b)
; #pragma unroll
;                 for (int m = 0; m < 4; ++m)
; #pragma unroll
;                     for (int n = 0; n < 2; ++n) acc[a][b][m][n] = (f32x4){0.f, 0.f, 0.f, 0.f};
;         cur = nxt; cA = nA; cB = nB; ++ui;
;         if (wr == 1) PG8_BAR;
.LBB0_980:
	s_or_b64 exec, exec, s[10:11]
	s_and_b64 vcc, exec, s[44:45]
	s_mov_b64 s[8:9], -1
	s_cbranch_vccnz .LBB0_951
	s_and_b64 vcc, exec, s[38:39]
	s_cbranch_vccnz .LBB0_950
	s_mov_b32 s100, 1
	s_branch .LBB0_950

; #define PG8_STAGE(bufoff, gbase, voff) do { _Pragma("unroll") for (int _i = 0; _i < 2; ++_i) \
;         __builtin_amdgcn_global_load_lds((const unsigned*)((const char*)(gbase) + (voff)[_i]), (PG8_LAS unsigned*)(lds + (bufoff) + ldsw + _i * 8192), 16, 0, 0); } while (0)
; #define PG8_LDA(dst, b, h) do { _Pragma("unroll") for (int m = 0; m < 4; ++m) _Pragma("unroll") for (int k = 0; k < 2; ++k) dst[m][k] = *(const PG8_LAS bf16x8*)(lds + PG8_SA(b, h) + aoff + m * 2048 + k * 1024); } while (0)
; #define PG8_LDB(dst, b, h) do { _Pragma("unroll") for (int n = 0; n < 2; ++n) _Pragma("unroll") for (int k = 0; k < 2; ++k) dst[n][k] = *(const PG8_LAS bf16x8*)(lds + PG8_SB(b, h) + boff + n * 2048 + k * 1024); } while (0)
; #define PG8_MMA(ai, bj, At, Bt) do { __builtin_amdgcn_s_setprio(1); _Pragma("unroll") for (int m = 0; m < 4; ++m) _Pragma("unroll") for (int n = 0; n < 2; ++n) _Pragma("unroll") for (int k = 0; k < 2; ++k) \
;         acc[ai][bj][m][n] = __builtin_amdgcn_mfma_f32_16x16x32_bf16(Bt[n][k], At[m][k], acc[ai][bj][m][n], 0, 0, 0); __builtin_amdgcn_s_setprio(0); } while (0)
; #define PG8_WAIT_V(n) asm volatile("s_waitcnt vmcnt(" #n ")" ::: "memory")
; #define PG8_WAIT_L(n) asm volatile("s_waitcnt lgkmcnt(" #n ")" ::: "memory")
; #define PG8_BAR __builtin_amdgcn_s_barrier()
; template <class Epi>
; __device__ __forceinline__ void gemm_phase(PG8_LAS unsigned char* lds, PG8_LAS unsigned char* xl, const Gemm g, const Sched& S, const Epi& E, const int wid) {
;     ...
;             const char* a1 = cA + (size_t)(t + 1) * kstep + j1;
;             const char* a2 = last ? nA : cA + (size_t)(t + 2) * kstep + ja2; const char* b2 = last ? nB : cB + (size_t)(t + 2) * kstep + jb2;
;             const char* a3 = a2 + kstep; const char* b3 = b2 + kstep;
;             PG8_LDB(B0, 0, 0); PG8_LDB(B1, 0, 1); PG8_SCHED; PG8_LDA(At, 0, 0); PG8_STAGE(PG8_SA(1, 1), a1 + hstepA, voffA);
;             PG8_WAIT_V(8); PG8_WAIT_L(0); PG8_BAR; if (do0) { PG8_MMA(0, 0, At, B0); PG8_MMA(0, 1, At, B1); } PG8_BAR; PG8_SCHED;
;     ...
;         for (int a = 0; a < 2; ++a)
; #pragma unroll
;             for (int b = 0; b < 2; ++b)
; #pragma unroll
;                 for (int m = 0; m < 4; ++m)
; #pragma unroll
;                     for (int n = 0; n < 2; ++n) acc[a][b][m][n] = (f32x4){0.f, 0.f, 0.f, 0.f};
;         cur = nxt; cA = nA; cB = nB; ++ui;
;         if (wr == 1) PG8_BAR;
.LBB0_1105:
	s_ashr_i32 s51, s50, 31
	s_lshl_b64 s[8:9], s[50:51], 20
	s_add_u32 s56, s62, s8
	s_addc_u32 s57, s69, s9
	s_and_b64 s[8:9], s[46:47], exec
	s_cselect_b32 s8, s57, s45
	s_cselect_b32 s9, s56, s44
	s_ashr_i32 s49, s48, 31
	s_lshl_b64 s[10:11], s[48:49], 20
	s_add_u32 s58, s88, s10
	s_addc_u32 s59, s89, s11
	s_and_b64 s[10:11], s[46:47], exec
	s_cselect_b32 s49, s59, s77
	s_cselect_b32 s61, s58, s76
	s_add_u32 s72, s76, 0x100
	v_mov_b32_e32 v64, 0
	s_addc_u32 s73, s77, 0
	s_mov_b32 s54, -2
	v_mov_b32_e32 v65, v64
	v_mov_b32_e32 v66, v64
	v_mov_b32_e32 v67, v64
	v_mov_b32_e32 v128, v64
	v_mov_b32_e32 v129, v64
	v_mov_b32_e32 v130, v64
	v_mov_b32_e32 v131, v64
	v_mov_b32_e32 v68, v64
	v_mov_b32_e32 v69, v64
	v_mov_b32_e32 v70, v64
	v_mov_b32_e32 v71, v64
	v_mov_b32_e32 v72, v64
	v_mov_b32_e32 v73, v64
	v_mov_b32_e32 v74, v64
	v_mov_b32_e32 v75, v64
	v_mov_b32_e32 v12, v64
	v_mov_b32_e32 v13, v64
	v_mov_b32_e32 v14, v64
	v_mov_b32_e32 v15, v64
	v_mov_b32_e32 v16, v64
	v_mov_b32_e32 v17, v64
	v_mov_b32_e32 v18, v64
	v_mov_b32_e32 v19, v64
	v_mov_b32_e32 v20, v64
	v_mov_b32_e32 v21, v64
	v_mov_b32_e32 v22, v64
	v_mov_b32_e32 v23, v64
	v_mov_b32_e32 v24, v64
	v_mov_b32_e32 v25, v64
	v_mov_b32_e32 v26, v64
	v_mov_b32_e32 v27, v64
	v_mov_b32_e32 v28, v64
	v_mov_b32_e32 v29, v64
	v_mov_b32_e32 v30, v64
	v_mov_b32_e32 v31, v64
	v_mov_b32_e32 v32, v64
	v_mov_b32_e32 v33, v64
	v_mov_b32_e32 v34, v64
	v_mov_b32_e32 v35, v64
	v_mov_b32_e32 v44, v64
	v_mov_b32_e32 v45, v64
	v_mov_b32_e32 v46, v64
	v_mov_b32_e32 v47, v64
	v_mov_b32_e32 v48, v64
	v_mov_b32_e32 v49, v64
	v_mov_b32_e32 v50, v64
	v_mov_b32_e32 v51, v64
	v_mov_b32_e32 v168, v64
	v_mov_b32_e32 v169, v64
	v_mov_b32_e32 v170, v64
	v_mov_b32_e32 v171, v64
	v_mov_b32_e32 v36, v64
	v_mov_b32_e32 v37, v64
	v_mov_b32_e32 v38, v64
	v_mov_b32_e32 v39, v64
	v_mov_b32_e32 v40, v64
	v_mov_b32_e32 v41, v64
	v_mov_b32_e32 v42, v64
	v_mov_b32_e32 v43, v64
	v_mov_b32_e32 v52, v64
	v_mov_b32_e32 v53, v64
	v_mov_b32_e32 v54, v64
	v_mov_b32_e32 v55, v64
	v_mov_b32_e32 v56, v64
	v_mov_b32_e32 v57, v64
	v_mov_b32_e32 v58, v64
	v_mov_b32_e32 v59, v64
	v_mov_b32_e32 v132, v64
	v_mov_b32_e32 v133, v64
	v_mov_b32_e32 v134, v64
	v_mov_b32_e32 v135, v64
	v_mov_b32_e32 v136, v64
	v_mov_b32_e32 v137, v64
	v_mov_b32_e32 v138, v64
	v_mov_b32_e32 v139, v64
	v_mov_b32_e32 v140, v64
	v_mov_b32_e32 v141, v64
	v_mov_b32_e32 v142, v64
	v_mov_b32_e32 v143, v64
	v_mov_b32_e32 v144, v64
	v_mov_b32_e32 v145, v64
	v_mov_b32_e32 v146, v64
	v_mov_b32_e32 v147, v64
	v_mov_b32_e32 v148, v64
	v_mov_b32_e32 v149, v64
	v_mov_b32_e32 v150, v64
	v_mov_b32_e32 v151, v64
	v_mov_b32_e32 v152, v64
	v_mov_b32_e32 v153, v64
	v_mov_b32_e32 v154, v64
	v_mov_b32_e32 v155, v64
	v_mov_b32_e32 v156, v64
	v_mov_b32_e32 v157, v64
	v_mov_b32_e32 v158, v64
	v_mov_b32_e32 v159, v64
	v_mov_b32_e32 v116, v64
	v_mov_b32_e32 v117, v64
	v_mov_b32_e32 v118, v64
	v_mov_b32_e32 v119, v64
	v_mov_b32_e32 v112, v64
	v_mov_b32_e32 v113, v64
	v_mov_b32_e32 v114, v64
	v_mov_b32_e32 v115, v64
	v_mov_b32_e32 v80, v64
	v_mov_b32_e32 v81, v64
	v_mov_b32_e32 v82, v64
	v_mov_b32_e32 v83, v64
	v_mov_b32_e32 v160, v64
	v_mov_b32_e32 v161, v64
	v_mov_b32_e32 v162, v64
	v_mov_b32_e32 v163, v64
	v_mov_b32_e32 v164, v64
	v_mov_b32_e32 v165, v64
	v_mov_b32_e32 v166, v64
	v_mov_b32_e32 v167, v64
	v_mov_b32_e32 v124, v64
	v_mov_b32_e32 v125, v64
	v_mov_b32_e32 v126, v64
	v_mov_b32_e32 v127, v64
	v_mov_b32_e32 v120, v64
	v_mov_b32_e32 v121, v64
	v_mov_b32_e32 v122, v64
	v_mov_b32_e32 v123, v64
	v_mov_b32_e32 v60, v64
	v_mov_b32_e32 v61, v64
	v_mov_b32_e32 v62, v64
	v_mov_b32_e32 v63, v64
	s_cmp_lg_u32 s100, 1
	s_cbranch_scc1 .Ldefbar_skip_9
	s_mov_b32 s100, 0
	s_barrier
.Ldefbar_skip_9:
.LBB0_1106:
	s_add_u32 s76, s44, 0x100
	s_addc_u32 s77, s45, 0
	s_add_i32 s55, 0, 0x10000
	s_cmp_eq_u32 s54, 28
	s_cselect_b32 s11, s8, s77
	s_cselect_b32 s10, s9, s76
	v_add_u32_e32 v1, s55, v195
	s_cselect_b32 vcc_hi, s49, s73
	s_cselect_b32 vcc_lo, s61, s72
	s_add_i32 s4, 0, 0x14000
	ds_read_b128 v[4:7], v1
	ds_read_b128 v[8:11], v1 offset:1024
	ds_read_b128 v[84:87], v1 offset:2048
	ds_read_b128 v[88:91], v1 offset:3072
	v_add_u32_e32 v1, s4, v195
	ds_read_b128 v[92:95], v1
	ds_read_b128 v[96:99], v1 offset:1024
	ds_read_b128 v[100:103], v1 offset:2048
	ds_read_b128 v[104:107], v1 offset:3072
	v_lshl_add_u64 v[204:205], s[44:45], 0, v[218:219]
	s_add_i32 m0, s90, 0xc000
	ds_read_b128 v[108:111], v225
	ds_read_b128 v[172:175], v225 offset:1024
	ds_read_b128 v[176:179], v225 offset:2048
	ds_read_b128 v[180:183], v225 offset:3072
	ds_read_b128 v[184:187], v225 offset:4096
	ds_read_b128 v[188:191], v225 offset:5120
	ds_read_b128 v[230:233], v225 offset:6144
	ds_read_b128 v[234:237], v225 offset:7168
	global_load_lds_dwordx4 v[204:205], off
	v_lshl_add_u64 v[204:205], s[44:45], 0, v[220:221]
	s_add_i32 m0, s90, 0xe000
	s_nop 0
	global_load_lds_dwordx4 v[204:205], off
	s_waitcnt vmcnt(8)
	s_waitcnt lgkmcnt(0)
	s_setprio 1
	s_barrier
; #define PG8_STAGE(bufoff, gbase, voff) do { _Pragma("unroll") for (int _i = 0; _i < 2; ++_i) \
;         __builtin_amdgcn_global_load_lds((const unsigned*)((const char*)(gbase) + (voff)[_i]), (PG8_LAS unsigned*)(lds + (bufoff) + ldsw + _i * 8192), 16, 0, 0); } while (0)
; #define PG8_LDA(dst, b, h) do { _Pragma("unroll") for (int m = 0; m < 4; ++m) _Pragma("unroll") for (int k = 0; k < 2; ++k) dst[m][k] = *(const PG8_LAS bf16x8*)(lds + PG8_SA(b, h) + aoff + m * 2048 + k * 1024); } while (0)
; #define PG8_MMA(ai, bj, At, Bt) do { __builtin_amdgcn_s_setprio(1); _Pragma("unroll") for (int m = 0; m < 4; ++m) _Pragma("unroll") for (int n = 0; n < 2; ++n) _Pragma("unroll") for (int k = 0; k < 2; ++k) \
;         acc[ai][bj][m][n] = __builtin_amdgcn_mfma_f32_16x16x32_bf16(Bt[n][k], At[m][k], acc[ai][bj][m][n], 0, 0, 0); __builtin_amdgcn_s_setprio(0); } while (0)
; #define PG8_WAIT_V(n) asm volatile("s_waitcnt vmcnt(" #n ")" ::: "memory")
; #define PG8_WAIT_L(n) asm volatile("s_waitcnt lgkmcnt(" #n ")" ::: "memory")
; #define PG8_BAR __builtin_amdgcn_s_barrier()
; #define PG8_SCHED __builtin_amdgcn_sched_barrier(0)
; template <class Epi>
; __device__ __forceinline__ void gemm_phase(PG8_LAS unsigned char* lds, PG8_LAS unsigned char* xl, const Gemm g, const Sched& S, const Epi& E, const int wid) {
;     ...
;             PG8_WAIT_V(8); PG8_WAIT_L(0); PG8_BAR; if (do0) { PG8_MMA(0, 0, At, B0); PG8_MMA(0, 1, At, B1); } PG8_BAR; PG8_SCHED;
;             PG8_LDA(At, 0, 1); PG8_STAGE(PG8_SB(0, 0), b2, voffB); PG8_STAGE(PG8_SB(0, 1), b2 + hstepB, voffB); PG8_STAGE(PG8_SA(0, 0), a2, voffA);
;             PG8_WAIT_V(8); PG8_WAIT_L(0); PG8_BAR; if (do1) { PG8_MMA(1, 0, At, B0); PG8_MMA(1, 1, At, B1); } PG8_BAR; PG8_SCHED;
	v_mfma_f32_16x16x32_bf16 v[60:63], v[4:7], v[108:111], v[60:63]
	v_mfma_f32_16x16x32_bf16 v[64:67], v[84:87], v[108:111], v[64:67]
	v_mfma_f32_16x16x32_bf16 v[120:123], v[4:7], v[176:179], v[120:123]
	v_mfma_f32_16x16x32_bf16 v[124:127], v[84:87], v[176:179], v[124:127]
	v_mfma_f32_16x16x32_bf16 v[164:167], v[4:7], v[184:187], v[164:167]
	v_mfma_f32_16x16x32_bf16 v[160:163], v[84:87], v[184:187], v[160:163]
	v_mfma_f32_16x16x32_bf16 v[80:83], v[4:7], v[230:233], v[80:83]
	v_mfma_f32_16x16x32_bf16 v[128:131], v[84:87], v[230:233], v[128:131]
	v_mfma_f32_16x16x32_bf16 v[60:63], v[8:11], v[172:175], v[60:63]
	v_mfma_f32_16x16x32_bf16 v[64:67], v[88:91], v[172:175], v[64:67]
	v_mfma_f32_16x16x32_bf16 v[120:123], v[8:11], v[180:183], v[120:123]
	v_mfma_f32_16x16x32_bf16 v[124:127], v[88:91], v[180:183], v[124:127]
	v_mfma_f32_16x16x32_bf16 v[164:167], v[8:11], v[188:191], v[164:167]
	v_mfma_f32_16x16x32_bf16 v[160:163], v[88:91], v[188:191], v[160:163]
	v_mfma_f32_16x16x32_bf16 v[80:83], v[8:11], v[234:237], v[80:83]
	v_mfma_f32_16x16x32_bf16 v[128:131], v[88:91], v[234:237], v[128:131]
	s_setprio 0
	s_setprio 1
	v_mfma_f32_16x16x32_bf16 v[112:115], v[92:95], v[108:111], v[112:115]
	v_mfma_f32_16x16x32_bf16 v[108:111], v[100:103], v[108:111], v[116:119]
	v_mfma_f32_16x16x32_bf16 v[116:119], v[92:95], v[176:179], v[156:159]
	v_mfma_f32_16x16x32_bf16 v[156:159], v[96:99], v[180:183], v[116:119]
	v_mfma_f32_16x16x32_bf16 v[116:119], v[100:103], v[176:179], v[152:155]
	v_mfma_f32_16x16x32_bf16 v[152:155], v[104:107], v[180:183], v[116:119]
	v_mfma_f32_16x16x32_bf16 v[116:119], v[92:95], v[184:187], v[148:151]
	v_mfma_f32_16x16x32_bf16 v[148:151], v[96:99], v[188:191], v[116:119]
	v_mfma_f32_16x16x32_bf16 v[116:119], v[100:103], v[184:187], v[144:147]
	v_mfma_f32_16x16x32_bf16 v[144:147], v[104:107], v[188:191], v[116:119]
	v_mfma_f32_16x16x32_bf16 v[116:119], v[92:95], v[230:233], v[140:143]
	v_mfma_f32_16x16x32_bf16 v[140:143], v[96:99], v[234:237], v[116:119]
	v_mfma_f32_16x16x32_bf16 v[116:119], v[100:103], v[230:233], v[136:139]
	v_mfma_f32_16x16x32_bf16 v[112:115], v[96:99], v[172:175], v[112:115]
	v_mfma_f32_16x16x32_bf16 v[136:139], v[104:107], v[234:237], v[116:119]
	v_mfma_f32_16x16x32_bf16 v[108:111], v[104:107], v[172:175], v[108:111]
	s_barrier
	s_setprio 0
	s_add_i32 s5, s55, s29
	v_lshl_add_u64 v[204:205], vcc, 0, v[212:213]
	s_mov_b32 m0, s5
	ds_read_b128 v[116:119], v225 offset:16384
	ds_read_b128 v[172:175], v225 offset:17408
	ds_read_b128 v[176:179], v225 offset:18432
	ds_read_b128 v[180:183], v225 offset:19456
	ds_read_b128 v[184:187], v225 offset:20480
	ds_read_b128 v[188:191], v225 offset:21504
	ds_read_b128 v[230:233], v225 offset:22528
	ds_read_b128 v[234:237], v225 offset:23552
	global_load_lds_dwordx4 v[204:205], off
	s_add_i32 m0, s5, 0x2000
	s_add_u32 s44, vcc_lo, 0x80000
	v_lshl_add_u64 v[226:227], vcc, 0, v[216:217]
	s_addc_u32 s45, vcc_hi, 0
	s_add_i32 s4, s4, s29
	global_load_lds_dwordx4 v[226:227], off
	v_lshl_add_u64 v[238:239], s[44:45], 0, v[212:213]
	s_mov_b32 m0, s4
	v_lshl_add_u64 v[248:249], s[10:11], 0, v[210:211]
	global_load_lds_dwordx4 v[238:239], off
	v_lshl_add_u64 v[238:239], s[44:45], 0, v[216:217]
	s_add_i32 m0, s4, 0x2000
	v_lshl_add_u64 v[250:251], s[10:11], 0, v[214:215]
	global_load_lds_dwordx4 v[238:239], off
	s_mov_b32 m0, s90
	s_nop 0
	global_load_lds_dwordx4 v[248:249], off
	s_mov_b32 m0, s13
	s_nop 0
	global_load_lds_dwordx4 v[250:251], off
	s_waitcnt vmcnt(8)
	s_waitcnt lgkmcnt(0)
	s_setprio 1
	s_barrier
	v_mfma_f32_16x16x32_bf16 v[132:135], v[4:7], v[116:119], v[132:135]
	v_mfma_f32_16x16x32_bf16 v[68:71], v[84:87], v[116:119], v[68:71]
	v_mfma_f32_16x16x32_bf16 v[56:59], v[4:7], v[176:179], v[56:59]
	v_mfma_f32_16x16x32_bf16 v[52:55], v[84:87], v[176:179], v[52:55]
	v_mfma_f32_16x16x32_bf16 v[40:43], v[4:7], v[184:187], v[40:43]
	v_mfma_f32_16x16x32_bf16 v[36:39], v[84:87], v[184:187], v[36:39]
	v_mfma_f32_16x16x32_bf16 v[4:7], v[4:7], v[230:233], v[168:171]
	v_mfma_f32_16x16x32_bf16 v[132:135], v[8:11], v[172:175], v[132:135]
	v_mfma_f32_16x16x32_bf16 v[68:71], v[88:91], v[172:175], v[68:71]
	v_mfma_f32_16x16x32_bf16 v[56:59], v[8:11], v[180:183], v[56:59]
	v_mfma_f32_16x16x32_bf16 v[52:55], v[88:91], v[180:183], v[52:55]
	v_mfma_f32_16x16x32_bf16 v[40:43], v[8:11], v[188:191], v[40:43]
	v_mfma_f32_16x16x32_bf16 v[36:39], v[88:91], v[188:191], v[36:39]
	v_mfma_f32_16x16x32_bf16 v[4:7], v[8:11], v[234:237], v[4:7]
	v_mfma_f32_16x16x32_bf16 v[8:11], v[84:87], v[230:233], v[72:75]
	v_mfma_f32_16x16x32_bf16 v[8:11], v[88:91], v[234:237], v[8:11]
	s_setprio 0
	s_setprio 1
	v_mfma_f32_16x16x32_bf16 v[48:51], v[92:95], v[116:119], v[48:51]
	v_mfma_f32_16x16x32_bf16 v[44:47], v[100:103], v[116:119], v[44:47]
	v_mfma_f32_16x16x32_bf16 v[32:35], v[92:95], v[176:179], v[32:35]
	v_mfma_f32_16x16x32_bf16 v[28:31], v[100:103], v[176:179], v[28:31]
	v_mfma_f32_16x16x32_bf16 v[24:27], v[92:95], v[184:187], v[24:27]
	v_mfma_f32_16x16x32_bf16 v[20:23], v[100:103], v[184:187], v[20:23]
	v_mfma_f32_16x16x32_bf16 v[16:19], v[92:95], v[230:233], v[16:19]
	v_mfma_f32_16x16x32_bf16 v[12:15], v[100:103], v[230:233], v[12:15]
	v_mfma_f32_16x16x32_bf16 v[48:51], v[96:99], v[172:175], v[48:51]
	v_mfma_f32_16x16x32_bf16 v[44:47], v[104:107], v[172:175], v[44:47]
	v_mfma_f32_16x16x32_bf16 v[32:35], v[96:99], v[180:183], v[32:35]
	v_mfma_f32_16x16x32_bf16 v[28:31], v[104:107], v[180:183], v[28:31]
	v_mfma_f32_16x16x32_bf16 v[24:27], v[96:99], v[188:191], v[24:27]
	v_mfma_f32_16x16x32_bf16 v[20:23], v[104:107], v[188:191], v[20:23]
	v_mfma_f32_16x16x32_bf16 v[16:19], v[96:99], v[234:237], v[16:19]
	v_mfma_f32_16x16x32_bf16 v[12:15], v[104:107], v[234:237], v[12:15]
	s_barrier
; #define PG8_STAGE(bufoff, gbase, voff) do { _Pragma("unroll") for (int _i = 0; _i < 2; ++_i) \
;         __builtin_amdgcn_global_load_lds((const unsigned*)((const char*)(gbase) + (voff)[_i]), (PG8_LAS unsigned*)(lds + (bufoff) + ldsw + _i * 8192), 16, 0, 0); } while (0)
; #define PG8_LDA(dst, b, h) do { _Pragma("unroll") for (int m = 0; m < 4; ++m) _Pragma("unroll") for (int k = 0; k < 2; ++k) dst[m][k] = *(const PG8_LAS bf16x8*)(lds + PG8_SA(b, h) + aoff + m * 2048 + k * 1024); } while (0)
; #define PG8_LDB(dst, b, h) do { _Pragma("unroll") for (int n = 0; n < 2; ++n) _Pragma("unroll") for (int k = 0; k < 2; ++k) dst[n][k] = *(const PG8_LAS bf16x8*)(lds + PG8_SB(b, h) + boff + n * 2048 + k * 1024); } while (0)
; #define PG8_MMA(ai, bj, At, Bt) do { __builtin_amdgcn_s_setprio(1); _Pragma("unroll") for (int m = 0; m < 4; ++m) _Pragma("unroll") for (int n = 0; n < 2; ++n) _Pragma("unroll") for (int k = 0; k < 2; ++k) \
;         acc[ai][bj][m][n] = __builtin_amdgcn_mfma_f32_16x16x32_bf16(Bt[n][k], At[m][k], acc[ai][bj][m][n], 0, 0, 0); __builtin_amdgcn_s_setprio(0); } while (0)
; #define PG8_WAIT_V(n) asm volatile("s_waitcnt vmcnt(" #n ")" ::: "memory")
; #define PG8_WAIT_L(n) asm volatile("s_waitcnt lgkmcnt(" #n ")" ::: "memory")
; #define PG8_BAR __builtin_amdgcn_s_barrier()
; #define PG8_SCHED __builtin_amdgcn_sched_barrier(0)
; template <class Epi>
; __device__ __forceinline__ void gemm_phase(PG8_LAS unsigned char* lds, PG8_LAS unsigned char* xl, const Gemm g, const Sched& S, const Epi& E, const int wid) {
;     ...
;             PG8_LDB(B0, 1, 0); PG8_LDB(B1, 1, 1); PG8_SCHED; PG8_LDA(At, 1, 0); PG8_STAGE(PG8_SA(0, 1), a2 + hstepA, voffA);
;             PG8_WAIT_V(8); PG8_WAIT_L(0); PG8_BAR; if (do0) { PG8_MMA(0, 0, At, B0); PG8_MMA(0, 1, At, B1); } PG8_BAR; PG8_SCHED;
;             PG8_LDA(At, 1, 1); PG8_STAGE(PG8_SB(1, 0), b3, voffB); PG8_STAGE(PG8_SB(1, 1), b3 + hstepB, voffB); PG8_STAGE(PG8_SA(1, 0), a3, voffA);
;             PG8_WAIT_V(8); PG8_WAIT_L(0); PG8_BAR; if (do1) { PG8_MMA(1, 0, At, B0); PG8_MMA(1, 1, At, B1); } PG8_BAR; PG8_SCHED;
	s_setprio 0
	s_add_i32 s4, 0, 0x18000
	v_add_u32_e32 v1, s4, v195
	s_add_i32 s5, 0, 0x1c000
	ds_read_b128 v[72:75], v1
	ds_read_b128 v[84:87], v1 offset:1024
	ds_read_b128 v[88:91], v1 offset:2048
	ds_read_b128 v[92:95], v1 offset:3072
	v_add_u32_e32 v1, s5, v195
	ds_read_b128 v[96:99], v1
	ds_read_b128 v[100:103], v1 offset:1024
	ds_read_b128 v[104:107], v1 offset:2048
	ds_read_b128 v[172:175], v1 offset:3072
	s_add_u32 s10, s10, 0x80000
	s_addc_u32 s11, s11, 0
	s_mov_b32 m0, s91
	v_lshl_add_u64 v[238:239], s[10:11], 0, v[210:211]
	ds_read_b128 v[116:119], v225 offset:32768
	ds_read_b128 v[168:171], v225 offset:33792
	ds_read_b128 v[176:179], v225 offset:34816
	ds_read_b128 v[180:183], v225 offset:35840
	ds_read_b128 v[184:187], v225 offset:36864
	ds_read_b128 v[188:191], v225 offset:37888
	ds_read_b128 v[230:233], v225 offset:38912
	ds_read_b128 v[234:237], v225 offset:39936
	global_load_lds_dwordx4 v[238:239], off
	v_lshl_add_u64 v[238:239], s[10:11], 0, v[214:215]
	s_mov_b32 m0, s92
	s_nop 0
	global_load_lds_dwordx4 v[238:239], off
	s_waitcnt vmcnt(8)
	s_waitcnt lgkmcnt(0)
	s_setprio 1
	s_barrier
	v_mfma_f32_16x16x32_bf16 v[60:63], v[72:75], v[116:119], v[60:63]
	v_mfma_f32_16x16x32_bf16 v[64:67], v[88:91], v[116:119], v[64:67]
	v_mfma_f32_16x16x32_bf16 v[120:123], v[72:75], v[176:179], v[120:123]
	v_mfma_f32_16x16x32_bf16 v[124:127], v[88:91], v[176:179], v[124:127]
	v_mfma_f32_16x16x32_bf16 v[164:167], v[72:75], v[184:187], v[164:167]
	v_mfma_f32_16x16x32_bf16 v[160:163], v[88:91], v[184:187], v[160:163]
	v_mfma_f32_16x16x32_bf16 v[80:83], v[72:75], v[230:233], v[80:83]
	v_mfma_f32_16x16x32_bf16 v[128:131], v[88:91], v[230:233], v[128:131]
	v_mfma_f32_16x16x32_bf16 v[60:63], v[84:87], v[168:171], v[60:63]
	v_mfma_f32_16x16x32_bf16 v[64:67], v[92:95], v[168:171], v[64:67]
	v_mfma_f32_16x16x32_bf16 v[120:123], v[84:87], v[180:183], v[120:123]
	v_mfma_f32_16x16x32_bf16 v[124:127], v[92:95], v[180:183], v[124:127]
	v_mfma_f32_16x16x32_bf16 v[164:167], v[84:87], v[188:191], v[164:167]
	v_mfma_f32_16x16x32_bf16 v[160:163], v[92:95], v[188:191], v[160:163]
	v_mfma_f32_16x16x32_bf16 v[80:83], v[84:87], v[234:237], v[80:83]
	v_mfma_f32_16x16x32_bf16 v[128:131], v[92:95], v[234:237], v[128:131]
	s_setprio 0
	s_setprio 1
	v_mfma_f32_16x16x32_bf16 v[108:111], v[104:107], v[116:119], v[108:111]
	v_mfma_f32_16x16x32_bf16 v[112:115], v[96:99], v[116:119], v[112:115]
	v_mfma_f32_16x16x32_bf16 v[116:119], v[172:175], v[168:171], v[108:111]
	v_mfma_f32_16x16x32_bf16 v[108:111], v[96:99], v[176:179], v[156:159]
	v_mfma_f32_16x16x32_bf16 v[156:159], v[100:103], v[180:183], v[108:111]
	v_mfma_f32_16x16x32_bf16 v[108:111], v[104:107], v[176:179], v[152:155]
	v_mfma_f32_16x16x32_bf16 v[152:155], v[172:175], v[180:183], v[108:111]
	v_mfma_f32_16x16x32_bf16 v[108:111], v[96:99], v[184:187], v[148:151]
	v_mfma_f32_16x16x32_bf16 v[148:151], v[100:103], v[188:191], v[108:111]
	v_mfma_f32_16x16x32_bf16 v[108:111], v[104:107], v[184:187], v[144:147]
	v_mfma_f32_16x16x32_bf16 v[144:147], v[172:175], v[188:191], v[108:111]
	v_mfma_f32_16x16x32_bf16 v[108:111], v[96:99], v[230:233], v[140:143]
	v_mfma_f32_16x16x32_bf16 v[140:143], v[100:103], v[234:237], v[108:111]
	v_mfma_f32_16x16x32_bf16 v[108:111], v[104:107], v[230:233], v[136:139]
	v_mfma_f32_16x16x32_bf16 v[112:115], v[100:103], v[168:171], v[112:115]
	v_mfma_f32_16x16x32_bf16 v[136:139], v[172:175], v[234:237], v[108:111]
	s_barrier
; #define PG8_STAGE(bufoff, gbase, voff) do { _Pragma("unroll") for (int _i = 0; _i < 2; ++_i) \
;         __builtin_amdgcn_global_load_lds((const unsigned*)((const char*)(gbase) + (voff)[_i]), (PG8_LAS unsigned*)(lds + (bufoff) + ldsw + _i * 8192), 16, 0, 0); } while (0)
; #define PG8_LDA(dst, b, h) do { _Pragma("unroll") for (int m = 0; m < 4; ++m) _Pragma("unroll") for (int k = 0; k < 2; ++k) dst[m][k] = *(const PG8_LAS bf16x8*)(lds + PG8_SA(b, h) + aoff + m * 2048 + k * 1024); } while (0)
; #define PG8_MMA(ai, bj, At, Bt) do { __builtin_amdgcn_s_setprio(1); _Pragma("unroll") for (int m = 0; m < 4; ++m) _Pragma("unroll") for (int n = 0; n < 2; ++n) _Pragma("unroll") for (int k = 0; k < 2; ++k) \
;         acc[ai][bj][m][n] = __builtin_amdgcn_mfma_f32_16x16x32_bf16(Bt[n][k], At[m][k], acc[ai][bj][m][n], 0, 0, 0); __builtin_amdgcn_s_setprio(0); } while (0)
; #define PG8_WAIT_V(n) asm volatile("s_waitcnt vmcnt(" #n ")" ::: "memory")
; #define PG8_WAIT_L(n) asm volatile("s_waitcnt lgkmcnt(" #n ")" ::: "memory")
; #define PG8_BAR __builtin_amdgcn_s_barrier()
; #define PG8_SCHED __builtin_amdgcn_sched_barrier(0)
; template <class Epi>
; __device__ __forceinline__ void gemm_phase(PG8_LAS unsigned char* lds, PG8_LAS unsigned char* xl, const Gemm g, const Sched& S, const Epi& E, const int wid) {
;     ...
;             PG8_LDA(At, 1, 1); PG8_STAGE(PG8_SB(1, 0), b3, voffB); PG8_STAGE(PG8_SB(1, 1), b3 + hstepB, voffB); PG8_STAGE(PG8_SA(1, 0), a3, voffA);
;             PG8_WAIT_V(8); PG8_WAIT_L(0); PG8_BAR; if (do1) { PG8_MMA(1, 0, At, B0); PG8_MMA(1, 1, At, B1); } PG8_BAR; PG8_SCHED;
;         }
;         if (wr == 0) PG8_BAR;
	s_setprio 0
	s_add_i32 s4, s4, s29
	v_lshl_add_u64 v[168:169], v[204:205], 0, s[22:23]
	s_mov_b32 m0, s4
	s_nop 0
	ds_read_b128 v[108:111], v225 offset:49152
	ds_read_b128 v[176:179], v225 offset:50176
	ds_read_b128 v[180:183], v225 offset:51200
	ds_read_b128 v[184:187], v225 offset:52224
	ds_read_b128 v[188:191], v225 offset:53248
	ds_read_b128 v[230:233], v225 offset:54272
	ds_read_b128 v[234:237], v225 offset:55296
	ds_read_b128 v[238:241], v225 offset:56320
	global_load_lds_dwordx4 v[168:169], off
	s_add_i32 m0, s4, 0x2000
	s_add_u32 s10, vcc_lo, 0x80080
	v_lshl_add_u64 v[168:169], v[226:227], 0, s[22:23]
	s_addc_u32 s11, vcc_hi, 0
	s_add_i32 s4, s5, s29
	global_load_lds_dwordx4 v[168:169], off
	v_lshl_add_u64 v[168:169], s[10:11], 0, v[212:213]
	s_mov_b32 m0, s4
	s_nop 0
	global_load_lds_dwordx4 v[168:169], off
	v_lshl_add_u64 v[168:169], s[10:11], 0, v[216:217]
	s_add_i32 m0, s4, 0x2000
	s_nop 0
	global_load_lds_dwordx4 v[168:169], off
	v_lshl_add_u64 v[168:169], v[248:249], 0, s[22:23]
	s_mov_b32 m0, s40
	s_nop 0
	global_load_lds_dwordx4 v[168:169], off
	v_lshl_add_u64 v[168:169], v[250:251], 0, s[22:23]
	s_mov_b32 m0, s41
	s_nop 0
	global_load_lds_dwordx4 v[168:169], off
	s_waitcnt vmcnt(8)
	s_waitcnt lgkmcnt(0)
	s_setprio 1
	s_barrier
	v_mfma_f32_16x16x32_bf16 v[4:7], v[72:75], v[234:237], v[4:7]
	v_mfma_f32_16x16x32_bf16 v[132:135], v[72:75], v[108:111], v[132:135]
	v_mfma_f32_16x16x32_bf16 v[68:71], v[88:91], v[108:111], v[68:71]
	v_mfma_f32_16x16x32_bf16 v[56:59], v[72:75], v[180:183], v[56:59]
	v_mfma_f32_16x16x32_bf16 v[52:55], v[88:91], v[180:183], v[52:55]
	v_mfma_f32_16x16x32_bf16 v[40:43], v[72:75], v[188:191], v[40:43]
	v_mfma_f32_16x16x32_bf16 v[36:39], v[88:91], v[188:191], v[36:39]
	v_mfma_f32_16x16x32_bf16 v[168:171], v[84:87], v[238:241], v[4:7]
	v_mfma_f32_16x16x32_bf16 v[4:7], v[88:91], v[234:237], v[8:11]
	v_mfma_f32_16x16x32_bf16 v[132:135], v[84:87], v[176:179], v[132:135]
	v_mfma_f32_16x16x32_bf16 v[68:71], v[92:95], v[176:179], v[68:71]
	v_mfma_f32_16x16x32_bf16 v[56:59], v[84:87], v[184:187], v[56:59]
	v_mfma_f32_16x16x32_bf16 v[52:55], v[92:95], v[184:187], v[52:55]
	v_mfma_f32_16x16x32_bf16 v[40:43], v[84:87], v[230:233], v[40:43]
	v_mfma_f32_16x16x32_bf16 v[36:39], v[92:95], v[230:233], v[36:39]
	v_mfma_f32_16x16x32_bf16 v[72:75], v[92:95], v[238:241], v[4:7]
	s_setprio 0
	s_setprio 1
	v_mfma_f32_16x16x32_bf16 v[4:7], v[96:99], v[108:111], v[48:51]
	v_mfma_f32_16x16x32_bf16 v[48:51], v[100:103], v[176:179], v[4:7]
	v_mfma_f32_16x16x32_bf16 v[4:7], v[104:107], v[108:111], v[44:47]
	v_mfma_f32_16x16x32_bf16 v[44:47], v[172:175], v[176:179], v[4:7]
	v_mfma_f32_16x16x32_bf16 v[4:7], v[96:99], v[180:183], v[32:35]
	v_mfma_f32_16x16x32_bf16 v[32:35], v[100:103], v[184:187], v[4:7]
	v_mfma_f32_16x16x32_bf16 v[4:7], v[104:107], v[180:183], v[28:31]
	v_mfma_f32_16x16x32_bf16 v[28:31], v[172:175], v[184:187], v[4:7]
	v_mfma_f32_16x16x32_bf16 v[4:7], v[96:99], v[188:191], v[24:27]
	v_mfma_f32_16x16x32_bf16 v[24:27], v[100:103], v[230:233], v[4:7]
	v_mfma_f32_16x16x32_bf16 v[4:7], v[104:107], v[188:191], v[20:23]
	v_mfma_f32_16x16x32_bf16 v[20:23], v[172:175], v[230:233], v[4:7]
	v_mfma_f32_16x16x32_bf16 v[4:7], v[96:99], v[234:237], v[16:19]
	v_mfma_f32_16x16x32_bf16 v[16:19], v[100:103], v[238:241], v[4:7]
	v_mfma_f32_16x16x32_bf16 v[4:7], v[104:107], v[234:237], v[12:15]
	v_mfma_f32_16x16x32_bf16 v[12:15], v[172:175], v[238:241], v[4:7]
	s_barrier
	s_setprio 0
	s_add_i32 s54, s54, 2
	s_add_u32 s72, s72, 0x100
	s_addc_u32 s73, s73, 0
	s_cmp_gt_u32 s54, 29
	s_mov_b64 s[44:45], s[76:77]
	s_cbranch_scc0 .LBB0_1106
	s_and_b64 vcc, exec, s[14:15]
	s_cbranch_vccz .LBB0_1109
	s_barrier

; #define PG8_STAGE(bufoff, gbase, voff) do { _Pragma("unroll") for (int _i = 0; _i < 2; ++_i) \
;         __builtin_amdgcn_global_load_lds((const unsigned*)((const char*)(gbase) + (voff)[_i]), (PG8_LAS unsigned*)(lds + (bufoff) + ldsw + _i * 8192), 16, 0, 0); } while (0)
; #define PG8_LDA(dst, b, h) do { _Pragma("unroll") for (int m = 0; m < 4; ++m) _Pragma("unroll") for (int k = 0; k < 2; ++k) dst[m][k] = *(const PG8_LAS bf16x8*)(lds + PG8_SA(b, h) + aoff + m * 2048 + k * 1024); } while (0)
; #define PG8_LDB(dst, b, h) do { _Pragma("unroll") for (int n = 0; n < 2; ++n) _Pragma("unroll") for (int k = 0; k < 2; ++k) dst[n][k] = *(const PG8_LAS bf16x8*)(lds + PG8_SB(b, h) + boff + n * 2048 + k * 1024); } while (0)
; #define PG8_MMA(ai, bj, At, Bt) do { __builtin_amdgcn_s_setprio(1); _Pragma("unroll") for (int m = 0; m < 4; ++m) _Pragma("unroll") for (int n = 0; n < 2; ++n) _Pragma("unroll") for (int k = 0; k < 2; ++k) \
;         acc[ai][bj][m][n] = __builtin_amdgcn_mfma_f32_16x16x32_bf16(Bt[n][k], At[m][k], acc[ai][bj][m][n], 0, 0, 0); __builtin_amdgcn_s_setprio(0); } while (0)
; #define PG8_WAIT_V(n) asm volatile("s_waitcnt vmcnt(" #n ")" ::: "memory")
; #define PG8_WAIT_L(n) asm volatile("s_waitcnt lgkmcnt(" #n ")" ::: "memory")
; #define PG8_BAR __builtin_amdgcn_s_barrier()
; template <class Epi>
; __device__ __forceinline__ void gemm_phase(PG8_LAS unsigned char* lds, PG8_LAS unsigned char* xl, const Gemm g, const Sched& S, const Epi& E, const int wid) {
;     ...
;             const char* a1 = cA + (size_t)(t + 1) * kstep + j1;
;             const char* a2 = last ? nA : cA + (size_t)(t + 2) * kstep + ja2; const char* b2 = last ? nB : cB + (size_t)(t + 2) * kstep + jb2;
;             const char* a3 = a2 + kstep; const char* b3 = b2 + kstep;
;             PG8_LDB(B0, 0, 0); PG8_LDB(B1, 0, 1); PG8_SCHED; PG8_LDA(At, 0, 0); PG8_STAGE(PG8_SA(1, 1), a1 + hstepA, voffA);
;             PG8_WAIT_V(8); PG8_WAIT_L(0); PG8_BAR; if (do0) { PG8_MMA(0, 0, At, B0); PG8_MMA(0, 1, At, B1); } PG8_BAR; PG8_SCHED;
;     ...
;         for (int a = 0; a < 2; ++a)
; #pragma unroll
;             for (int b = 0; b < 2; ++b)
; #pragma unroll
;                 for (int m = 0; m < 4; ++m)
; #pragma unroll
;                     for (int n = 0; n < 2; ++n) acc[a][b][m][n] = (f32x4){0.f, 0.f, 0.f, 0.f};
;         cur = nxt; cA = nA; cB = nB; ++ui;
;         if (wr == 1) PG8_BAR;
.LBB0_1303:
	s_add_u32 s36, s36, 0x160080
	s_addc_u32 s37, s37, 0
	s_add_u32 s1, s40, 0x100
	v_mov_b32_e32 v0, 0
	s_addc_u32 s8, s41, 0
	s_mov_b32 s9, -2
	s_waitcnt lgkmcnt(0)
	v_mov_b32_e32 v1, v0
	v_mov_b32_e32 v2, v0
	v_mov_b32_e32 v3, v0
	v_mov_b32_e32 v4, v0
	v_mov_b32_e32 v5, v0
	v_mov_b32_e32 v6, v0
	v_mov_b32_e32 v7, v0
	v_mov_b32_e32 v16, v0
	v_mov_b32_e32 v17, v0
	v_mov_b32_e32 v18, v0
	v_mov_b32_e32 v19, v0
	v_mov_b32_e32 v20, v0
	v_mov_b32_e32 v21, v0
	v_mov_b32_e32 v22, v0
	v_mov_b32_e32 v23, v0
	v_mov_b32_e32 v32, v0
	v_mov_b32_e32 v33, v0
	v_mov_b32_e32 v34, v0
	v_mov_b32_e32 v35, v0
	v_mov_b32_e32 v36, v0
	v_mov_b32_e32 v37, v0
	v_mov_b32_e32 v38, v0
	v_mov_b32_e32 v39, v0
	v_mov_b32_e32 v48, v0
	v_mov_b32_e32 v49, v0
	v_mov_b32_e32 v50, v0
	v_mov_b32_e32 v51, v0
	v_mov_b32_e32 v52, v0
	v_mov_b32_e32 v53, v0
	v_mov_b32_e32 v54, v0
	v_mov_b32_e32 v55, v0
	v_mov_b32_e32 v8, v0
	v_mov_b32_e32 v9, v0
	v_mov_b32_e32 v10, v0
	v_mov_b32_e32 v11, v0
	v_mov_b32_e32 v12, v0
	v_mov_b32_e32 v13, v0
	v_mov_b32_e32 v14, v0
	v_mov_b32_e32 v15, v0
	v_mov_b32_e32 v24, v0
	v_mov_b32_e32 v25, v0
	v_mov_b32_e32 v26, v0
	v_mov_b32_e32 v27, v0
	v_mov_b32_e32 v28, v0
	v_mov_b32_e32 v29, v0
	v_mov_b32_e32 v30, v0
	v_mov_b32_e32 v31, v0
	v_mov_b32_e32 v40, v0
	v_mov_b32_e32 v41, v0
	v_mov_b32_e32 v42, v0
	v_mov_b32_e32 v43, v0
	v_mov_b32_e32 v44, v0
	v_mov_b32_e32 v45, v0
	v_mov_b32_e32 v46, v0
	v_mov_b32_e32 v47, v0
	v_mov_b32_e32 v56, v0
	v_mov_b32_e32 v57, v0
	v_mov_b32_e32 v58, v0
	v_mov_b32_e32 v59, v0
	v_mov_b32_e32 v60, v0
	v_mov_b32_e32 v61, v0
	v_mov_b32_e32 v62, v0
	v_mov_b32_e32 v63, v0
	v_mov_b32_e32 v64, v0
	v_mov_b32_e32 v65, v0
	v_mov_b32_e32 v66, v0
	v_mov_b32_e32 v67, v0
	v_mov_b32_e32 v68, v0
	v_mov_b32_e32 v69, v0
	v_mov_b32_e32 v70, v0
	v_mov_b32_e32 v71, v0
	v_mov_b32_e32 v80, v0
	v_mov_b32_e32 v81, v0
	v_mov_b32_e32 v82, v0
	v_mov_b32_e32 v83, v0
	v_mov_b32_e32 v84, v0
	v_mov_b32_e32 v85, v0
	v_mov_b32_e32 v86, v0
	v_mov_b32_e32 v87, v0
	v_mov_b32_e32 v96, v0
	v_mov_b32_e32 v97, v0
	v_mov_b32_e32 v98, v0
	v_mov_b32_e32 v99, v0
	v_mov_b32_e32 v100, v0
	v_mov_b32_e32 v101, v0
	v_mov_b32_e32 v102, v0
	v_mov_b32_e32 v103, v0
	v_mov_b32_e32 v112, v0
	v_mov_b32_e32 v113, v0
	v_mov_b32_e32 v114, v0
	v_mov_b32_e32 v115, v0
	v_mov_b32_e32 v116, v0
	v_mov_b32_e32 v117, v0
	v_mov_b32_e32 v118, v0
	v_mov_b32_e32 v119, v0
	v_mov_b32_e32 v72, v0
	v_mov_b32_e32 v73, v0
	v_mov_b32_e32 v74, v0
	v_mov_b32_e32 v75, v0
	v_mov_b32_e32 v76, v0
	v_mov_b32_e32 v77, v0
	v_mov_b32_e32 v78, v0
	v_mov_b32_e32 v79, v0
	v_mov_b32_e32 v88, v0
	v_mov_b32_e32 v89, v0
	v_mov_b32_e32 v90, v0
	v_mov_b32_e32 v91, v0
	v_mov_b32_e32 v92, v0
	v_mov_b32_e32 v93, v0
	v_mov_b32_e32 v94, v0
	v_mov_b32_e32 v95, v0
	v_mov_b32_e32 v104, v0
	v_mov_b32_e32 v105, v0
	v_mov_b32_e32 v106, v0
	v_mov_b32_e32 v107, v0
	v_mov_b32_e32 v108, v0
	v_mov_b32_e32 v109, v0
	v_mov_b32_e32 v110, v0
	v_mov_b32_e32 v111, v0
	v_mov_b32_e32 v132, v0
	v_mov_b32_e32 v133, v0
	v_mov_b32_e32 v134, v0
	v_mov_b32_e32 v135, v0
	v_mov_b32_e32 v140, v0
	v_mov_b32_e32 v141, v0
	v_mov_b32_e32 v142, v0
	v_mov_b32_e32 v143, v0
	s_cmp_lg_u32 s100, 1
	s_cbranch_scc1 .Ldefbar_skip_10
	s_mov_b32 s100, 0
	s_barrier
.Ldefbar_skip_10:
.LBB0_1304:
	s_add_u32 s4, s36, 0xffea0080
	s_addc_u32 s5, s37, -1
	s_add_i32 s13, 0, 0x10000
	s_cmpk_eq_i32 s9, 0x54
	s_cselect_b32 s11, s21, s5
	s_cselect_b32 s10, s20, s4
	s_cselect_b32 s41, s31, s8
	s_cselect_b32 s40, s30, s1
	s_add_i32 s4, 0, 0x14000
	v_add_u32_e32 v136, s13, v195
	v_add_u32_e32 v156, s4, v195
	ds_read_b128 v[120:123], v136
	ds_read_b128 v[124:127], v136 offset:1024
	ds_read_b128 v[128:131], v136 offset:2048
	ds_read_b128 v[136:139], v136 offset:3072
	ds_read_b128 v[144:147], v156
	ds_read_b128 v[148:151], v156 offset:1024
	ds_read_b128 v[152:155], v156 offset:2048
	ds_read_b128 v[156:159], v156 offset:3072
	v_lshl_add_u64 v[204:205], s[36:37], 0, v[214:215]
	s_add_i32 m0, s51, 0xc000
	ds_read_b128 v[160:163], v220
	ds_read_b128 v[164:167], v220 offset:1024
	ds_read_b128 v[168:171], v220 offset:2048
	ds_read_b128 v[172:175], v220 offset:3072
	ds_read_b128 v[176:179], v220 offset:4096
	ds_read_b128 v[180:183], v220 offset:5120
	ds_read_b128 v[184:187], v220 offset:6144
	ds_read_b128 v[222:225], v220 offset:7168
	global_load_lds_dwordx4 v[204:205], off
	v_lshl_add_u64 v[204:205], s[36:37], 0, v[216:217]
	s_add_i32 m0, s51, 0xe000
	s_nop 0
	global_load_lds_dwordx4 v[204:205], off
	s_waitcnt vmcnt(8)
	s_waitcnt lgkmcnt(0)
	s_setprio 1
	s_barrier
; #define PG8_STAGE(bufoff, gbase, voff) do { _Pragma("unroll") for (int _i = 0; _i < 2; ++_i) \
;         __builtin_amdgcn_global_load_lds((const unsigned*)((const char*)(gbase) + (voff)[_i]), (PG8_LAS unsigned*)(lds + (bufoff) + ldsw + _i * 8192), 16, 0, 0); } while (0)
; #define PG8_LDA(dst, b, h) do { _Pragma("unroll") for (int m = 0; m < 4; ++m) _Pragma("unroll") for (int k = 0; k < 2; ++k) dst[m][k] = *(const PG8_LAS bf16x8*)(lds + PG8_SA(b, h) + aoff + m * 2048 + k * 1024); } while (0)
; #define PG8_MMA(ai, bj, At, Bt) do { __builtin_amdgcn_s_setprio(1); _Pragma("unroll") for (int m = 0; m < 4; ++m) _Pragma("unroll") for (int n = 0; n < 2; ++n) _Pragma("unroll") for (int k = 0; k < 2; ++k) \
;         acc[ai][bj][m][n] = __builtin_amdgcn_mfma_f32_16x16x32_bf16(Bt[n][k], At[m][k], acc[ai][bj][m][n], 0, 0, 0); __builtin_amdgcn_s_setprio(0); } while (0)
; #define PG8_WAIT_V(n) asm volatile("s_waitcnt vmcnt(" #n ")" ::: "memory")
; #define PG8_WAIT_L(n) asm volatile("s_waitcnt lgkmcnt(" #n ")" ::: "memory")
; #define PG8_BAR __builtin_amdgcn_s_barrier()
; #define PG8_SCHED __builtin_amdgcn_sched_barrier(0)
; template <class Epi>
; __device__ __forceinline__ void gemm_phase(PG8_LAS unsigned char* lds, PG8_LAS unsigned char* xl, const Gemm g, const Sched& S, const Epi& E, const int wid) {
;     ...
;             PG8_WAIT_V(8); PG8_WAIT_L(0); PG8_BAR; if (do0) { PG8_MMA(0, 0, At, B0); PG8_MMA(0, 1, At, B1); } PG8_BAR; PG8_SCHED;
;             PG8_LDA(At, 0, 1); PG8_STAGE(PG8_SB(0, 0), b2, voffB); PG8_STAGE(PG8_SB(0, 1), b2 + hstepB, voffB); PG8_STAGE(PG8_SA(0, 0), a2, voffA);
;             PG8_WAIT_V(8); PG8_WAIT_L(0); PG8_BAR; if (do1) { PG8_MMA(1, 0, At, B0); PG8_MMA(1, 1, At, B1); } PG8_BAR; PG8_SCHED;
	v_mfma_f32_16x16x32_bf16 v[140:143], v[120:123], v[160:163], v[140:143]
	v_mfma_f32_16x16x32_bf16 v[132:135], v[128:131], v[160:163], v[132:135]
	v_mfma_f32_16x16x32_bf16 v[108:111], v[120:123], v[168:171], v[108:111]
	v_mfma_f32_16x16x32_bf16 v[104:107], v[128:131], v[168:171], v[104:107]
	v_mfma_f32_16x16x32_bf16 v[92:95], v[120:123], v[176:179], v[92:95]
	v_mfma_f32_16x16x32_bf16 v[88:91], v[128:131], v[176:179], v[88:91]
	v_mfma_f32_16x16x32_bf16 v[76:79], v[120:123], v[184:187], v[76:79]
	v_mfma_f32_16x16x32_bf16 v[72:75], v[128:131], v[184:187], v[72:75]
	v_mfma_f32_16x16x32_bf16 v[140:143], v[124:127], v[164:167], v[140:143]
	v_mfma_f32_16x16x32_bf16 v[132:135], v[136:139], v[164:167], v[132:135]
	v_mfma_f32_16x16x32_bf16 v[108:111], v[124:127], v[172:175], v[108:111]
	v_mfma_f32_16x16x32_bf16 v[104:107], v[136:139], v[172:175], v[104:107]
	v_mfma_f32_16x16x32_bf16 v[92:95], v[124:127], v[180:183], v[92:95]
	v_mfma_f32_16x16x32_bf16 v[88:91], v[136:139], v[180:183], v[88:91]
	v_mfma_f32_16x16x32_bf16 v[76:79], v[124:127], v[222:225], v[76:79]
	v_mfma_f32_16x16x32_bf16 v[72:75], v[136:139], v[222:225], v[72:75]
	s_setprio 0
	s_setprio 1
	v_mfma_f32_16x16x32_bf16 v[116:119], v[144:147], v[160:163], v[116:119]
	v_mfma_f32_16x16x32_bf16 v[112:115], v[152:155], v[160:163], v[112:115]
	v_mfma_f32_16x16x32_bf16 v[100:103], v[144:147], v[168:171], v[100:103]
	v_mfma_f32_16x16x32_bf16 v[96:99], v[152:155], v[168:171], v[96:99]
	v_mfma_f32_16x16x32_bf16 v[84:87], v[144:147], v[176:179], v[84:87]
	v_mfma_f32_16x16x32_bf16 v[80:83], v[152:155], v[176:179], v[80:83]
	v_mfma_f32_16x16x32_bf16 v[68:71], v[144:147], v[184:187], v[68:71]
	v_mfma_f32_16x16x32_bf16 v[64:67], v[152:155], v[184:187], v[64:67]
	v_mfma_f32_16x16x32_bf16 v[116:119], v[148:151], v[164:167], v[116:119]
	v_mfma_f32_16x16x32_bf16 v[112:115], v[156:159], v[164:167], v[112:115]
	v_mfma_f32_16x16x32_bf16 v[100:103], v[148:151], v[172:175], v[100:103]
	v_mfma_f32_16x16x32_bf16 v[96:99], v[156:159], v[172:175], v[96:99]
	v_mfma_f32_16x16x32_bf16 v[84:87], v[148:151], v[180:183], v[84:87]
	v_mfma_f32_16x16x32_bf16 v[80:83], v[156:159], v[180:183], v[80:83]
	v_mfma_f32_16x16x32_bf16 v[68:71], v[148:151], v[222:225], v[68:71]
	v_mfma_f32_16x16x32_bf16 v[64:67], v[156:159], v[222:225], v[64:67]
	s_barrier
	s_setprio 0
	s_add_i32 s5, s13, s29
	v_lshl_add_u64 v[204:205], s[40:41], 0, v[190:191]
	s_mov_b32 m0, s5
	ds_read_b128 v[160:163], v220 offset:16384
	ds_read_b128 v[164:167], v220 offset:17408
	ds_read_b128 v[168:171], v220 offset:18432
	ds_read_b128 v[172:175], v220 offset:19456
	ds_read_b128 v[176:179], v220 offset:20480
	ds_read_b128 v[180:183], v220 offset:21504
	ds_read_b128 v[184:187], v220 offset:22528
	ds_read_b128 v[222:225], v220 offset:23552
	global_load_lds_dwordx4 v[204:205], off
	s_add_i32 m0, s5, 0x2000
	s_add_u32 s44, s40, 0x160000
	v_lshl_add_u64 v[218:219], s[40:41], 0, v[212:213]
	s_addc_u32 s45, s41, 0
	s_add_i32 s4, s4, s29
	global_load_lds_dwordx4 v[218:219], off
	v_lshl_add_u64 v[226:227], s[44:45], 0, v[190:191]
	s_mov_b32 m0, s4
	v_lshl_add_u64 v[228:229], s[10:11], 0, v[210:211]
	global_load_lds_dwordx4 v[226:227], off
	v_lshl_add_u64 v[226:227], s[44:45], 0, v[212:213]
	s_add_i32 m0, s4, 0x2000
	s_nop 0
	global_load_lds_dwordx4 v[226:227], off
	v_lshl_add_u64 v[226:227], s[10:11], 0, v[188:189]
	s_mov_b32 m0, s51
	s_nop 0
	global_load_lds_dwordx4 v[226:227], off
	s_mov_b32 m0, s52
	s_nop 0
	global_load_lds_dwordx4 v[228:229], off
	s_waitcnt vmcnt(8)
	s_waitcnt lgkmcnt(0)
	s_setprio 1
	s_barrier
	v_mfma_f32_16x16x32_bf16 v[60:63], v[120:123], v[160:163], v[60:63]
	v_mfma_f32_16x16x32_bf16 v[56:59], v[128:131], v[160:163], v[56:59]
	v_mfma_f32_16x16x32_bf16 v[44:47], v[120:123], v[168:171], v[44:47]
	v_mfma_f32_16x16x32_bf16 v[40:43], v[128:131], v[168:171], v[40:43]
	v_mfma_f32_16x16x32_bf16 v[28:31], v[120:123], v[176:179], v[28:31]
	v_mfma_f32_16x16x32_bf16 v[24:27], v[128:131], v[176:179], v[24:27]
	v_mfma_f32_16x16x32_bf16 v[12:15], v[120:123], v[184:187], v[12:15]
	v_mfma_f32_16x16x32_bf16 v[8:11], v[128:131], v[184:187], v[8:11]
	v_mfma_f32_16x16x32_bf16 v[60:63], v[124:127], v[164:167], v[60:63]
	v_mfma_f32_16x16x32_bf16 v[56:59], v[136:139], v[164:167], v[56:59]
	v_mfma_f32_16x16x32_bf16 v[44:47], v[124:127], v[172:175], v[44:47]
	v_mfma_f32_16x16x32_bf16 v[40:43], v[136:139], v[172:175], v[40:43]
	v_mfma_f32_16x16x32_bf16 v[28:31], v[124:127], v[180:183], v[28:31]
	v_mfma_f32_16x16x32_bf16 v[24:27], v[136:139], v[180:183], v[24:27]
	v_mfma_f32_16x16x32_bf16 v[12:15], v[124:127], v[222:225], v[12:15]
	v_mfma_f32_16x16x32_bf16 v[8:11], v[136:139], v[222:225], v[8:11]
	s_setprio 0
	s_setprio 1
	v_mfma_f32_16x16x32_bf16 v[52:55], v[144:147], v[160:163], v[52:55]
	v_mfma_f32_16x16x32_bf16 v[48:51], v[152:155], v[160:163], v[48:51]
	v_mfma_f32_16x16x32_bf16 v[36:39], v[144:147], v[168:171], v[36:39]
	v_mfma_f32_16x16x32_bf16 v[32:35], v[152:155], v[168:171], v[32:35]
	v_mfma_f32_16x16x32_bf16 v[20:23], v[144:147], v[176:179], v[20:23]
	v_mfma_f32_16x16x32_bf16 v[16:19], v[152:155], v[176:179], v[16:19]
	v_mfma_f32_16x16x32_bf16 v[4:7], v[144:147], v[184:187], v[4:7]
	v_mfma_f32_16x16x32_bf16 v[0:3], v[152:155], v[184:187], v[0:3]
	v_mfma_f32_16x16x32_bf16 v[52:55], v[148:151], v[164:167], v[52:55]
	v_mfma_f32_16x16x32_bf16 v[48:51], v[156:159], v[164:167], v[48:51]
	v_mfma_f32_16x16x32_bf16 v[36:39], v[148:151], v[172:175], v[36:39]
	v_mfma_f32_16x16x32_bf16 v[32:35], v[156:159], v[172:175], v[32:35]
	v_mfma_f32_16x16x32_bf16 v[20:23], v[148:151], v[180:183], v[20:23]
	v_mfma_f32_16x16x32_bf16 v[16:19], v[156:159], v[180:183], v[16:19]
	v_mfma_f32_16x16x32_bf16 v[4:7], v[148:151], v[222:225], v[4:7]
	v_mfma_f32_16x16x32_bf16 v[0:3], v[156:159], v[222:225], v[0:3]
	s_barrier
; #define PG8_STAGE(bufoff, gbase, voff) do { _Pragma("unroll") for (int _i = 0; _i < 2; ++_i) \
;         __builtin_amdgcn_global_load_lds((const unsigned*)((const char*)(gbase) + (voff)[_i]), (PG8_LAS unsigned*)(lds + (bufoff) + ldsw + _i * 8192), 16, 0, 0); } while (0)
; #define PG8_LDA(dst, b, h) do { _Pragma("unroll") for (int m = 0; m < 4; ++m) _Pragma("unroll") for (int k = 0; k < 2; ++k) dst[m][k] = *(const PG8_LAS bf16x8*)(lds + PG8_SA(b, h) + aoff + m * 2048 + k * 1024); } while (0)
; #define PG8_LDB(dst, b, h) do { _Pragma("unroll") for (int n = 0; n < 2; ++n) _Pragma("unroll") for (int k = 0; k < 2; ++k) dst[n][k] = *(const PG8_LAS bf16x8*)(lds + PG8_SB(b, h) + boff + n * 2048 + k * 1024); } while (0)
; #define PG8_MMA(ai, bj, At, Bt) do { __builtin_amdgcn_s_setprio(1); _Pragma("unroll") for (int m = 0; m < 4; ++m) _Pragma("unroll") for (int n = 0; n < 2; ++n) _Pragma("unroll") for (int k = 0; k < 2; ++k) \
;         acc[ai][bj][m][n] = __builtin_amdgcn_mfma_f32_16x16x32_bf16(Bt[n][k], At[m][k], acc[ai][bj][m][n], 0, 0, 0); __builtin_amdgcn_s_setprio(0); } while (0)
; #define PG8_WAIT_V(n) asm volatile("s_waitcnt vmcnt(" #n ")" ::: "memory")
; #define PG8_WAIT_L(n) asm volatile("s_waitcnt lgkmcnt(" #n ")" ::: "memory")
; #define PG8_BAR __builtin_amdgcn_s_barrier()
; #define PG8_SCHED __builtin_amdgcn_sched_barrier(0)
; template <class Epi>
; __device__ __forceinline__ void gemm_phase(PG8_LAS unsigned char* lds, PG8_LAS unsigned char* xl, const Gemm g, const Sched& S, const Epi& E, const int wid) {
;     ...
;             PG8_LDB(B0, 1, 0); PG8_LDB(B1, 1, 1); PG8_SCHED; PG8_LDA(At, 1, 0); PG8_STAGE(PG8_SA(0, 1), a2 + hstepA, voffA);
;             PG8_WAIT_V(8); PG8_WAIT_L(0); PG8_BAR; if (do0) { PG8_MMA(0, 0, At, B0); PG8_MMA(0, 1, At, B1); } PG8_BAR; PG8_SCHED;
;             PG8_LDA(At, 1, 1); PG8_STAGE(PG8_SB(1, 0), b3, voffB); PG8_STAGE(PG8_SB(1, 1), b3 + hstepB, voffB); PG8_STAGE(PG8_SA(1, 0), a3, voffA);
	s_setprio 0
	s_add_i32 s4, 0, 0x18000
	s_add_i32 s5, 0, 0x1c000
	v_add_u32_e32 v136, s4, v195
	v_add_u32_e32 v156, s5, v195
	ds_read_b128 v[120:123], v136
	ds_read_b128 v[124:127], v136 offset:1024
	ds_read_b128 v[128:131], v136 offset:2048
	ds_read_b128 v[136:139], v136 offset:3072
	ds_read_b128 v[144:147], v156
	ds_read_b128 v[148:151], v156 offset:1024
	ds_read_b128 v[152:155], v156 offset:2048
	ds_read_b128 v[156:159], v156 offset:3072
	s_add_u32 s10, s10, 0x160000
	s_addc_u32 s11, s11, 0
	s_mov_b32 m0, s53
	v_lshl_add_u64 v[230:231], s[10:11], 0, v[188:189]
	ds_read_b128 v[160:163], v220 offset:32768
	ds_read_b128 v[164:167], v220 offset:33792
	ds_read_b128 v[168:171], v220 offset:34816
	ds_read_b128 v[172:175], v220 offset:35840
	ds_read_b128 v[176:179], v220 offset:36864
	ds_read_b128 v[180:183], v220 offset:37888
	ds_read_b128 v[184:187], v220 offset:38912
	ds_read_b128 v[222:225], v220 offset:39936
	global_load_lds_dwordx4 v[230:231], off
	v_lshl_add_u64 v[230:231], s[10:11], 0, v[210:211]
	s_mov_b32 m0, s56
	s_nop 0
	global_load_lds_dwordx4 v[230:231], off
	s_waitcnt vmcnt(8)
	s_waitcnt lgkmcnt(0)
	s_setprio 1
	s_barrier
	v_mfma_f32_16x16x32_bf16 v[140:143], v[120:123], v[160:163], v[140:143]
	v_mfma_f32_16x16x32_bf16 v[132:135], v[128:131], v[160:163], v[132:135]
	v_mfma_f32_16x16x32_bf16 v[108:111], v[120:123], v[168:171], v[108:111]
	v_mfma_f32_16x16x32_bf16 v[104:107], v[128:131], v[168:171], v[104:107]
	v_mfma_f32_16x16x32_bf16 v[92:95], v[120:123], v[176:179], v[92:95]
	v_mfma_f32_16x16x32_bf16 v[88:91], v[128:131], v[176:179], v[88:91]
	v_mfma_f32_16x16x32_bf16 v[76:79], v[120:123], v[184:187], v[76:79]
	v_mfma_f32_16x16x32_bf16 v[72:75], v[128:131], v[184:187], v[72:75]
	v_mfma_f32_16x16x32_bf16 v[140:143], v[124:127], v[164:167], v[140:143]
	v_mfma_f32_16x16x32_bf16 v[132:135], v[136:139], v[164:167], v[132:135]
	v_mfma_f32_16x16x32_bf16 v[108:111], v[124:127], v[172:175], v[108:111]
	v_mfma_f32_16x16x32_bf16 v[104:107], v[136:139], v[172:175], v[104:107]
	v_mfma_f32_16x16x32_bf16 v[92:95], v[124:127], v[180:183], v[92:95]
	v_mfma_f32_16x16x32_bf16 v[88:91], v[136:139], v[180:183], v[88:91]
	v_mfma_f32_16x16x32_bf16 v[76:79], v[124:127], v[222:225], v[76:79]
	v_mfma_f32_16x16x32_bf16 v[72:75], v[136:139], v[222:225], v[72:75]
	s_setprio 0
	s_setprio 1
	v_mfma_f32_16x16x32_bf16 v[116:119], v[144:147], v[160:163], v[116:119]
	v_mfma_f32_16x16x32_bf16 v[112:115], v[152:155], v[160:163], v[112:115]
	v_mfma_f32_16x16x32_bf16 v[100:103], v[144:147], v[168:171], v[100:103]
	v_mfma_f32_16x16x32_bf16 v[96:99], v[152:155], v[168:171], v[96:99]
	v_mfma_f32_16x16x32_bf16 v[84:87], v[144:147], v[176:179], v[84:87]
	v_mfma_f32_16x16x32_bf16 v[80:83], v[152:155], v[176:179], v[80:83]
	v_mfma_f32_16x16x32_bf16 v[68:71], v[144:147], v[184:187], v[68:71]
	v_mfma_f32_16x16x32_bf16 v[64:67], v[152:155], v[184:187], v[64:67]
	v_mfma_f32_16x16x32_bf16 v[116:119], v[148:151], v[164:167], v[116:119]
	v_mfma_f32_16x16x32_bf16 v[112:115], v[156:159], v[164:167], v[112:115]
	v_mfma_f32_16x16x32_bf16 v[100:103], v[148:151], v[172:175], v[100:103]
	v_mfma_f32_16x16x32_bf16 v[96:99], v[156:159], v[172:175], v[96:99]
	v_mfma_f32_16x16x32_bf16 v[84:87], v[148:151], v[180:183], v[84:87]
	v_mfma_f32_16x16x32_bf16 v[80:83], v[156:159], v[180:183], v[80:83]
	v_mfma_f32_16x16x32_bf16 v[68:71], v[148:151], v[222:225], v[68:71]
	v_mfma_f32_16x16x32_bf16 v[64:67], v[156:159], v[222:225], v[64:67]
	s_barrier
	s_setprio 0
	s_add_i32 s4, s4, s29
	v_lshl_add_u64 v[204:205], v[204:205], 0, s[22:23]
	s_mov_b32 m0, s4
	ds_read_b128 v[160:163], v220 offset:49152
	ds_read_b128 v[164:167], v220 offset:50176
	ds_read_b128 v[168:171], v220 offset:51200
	ds_read_b128 v[172:175], v220 offset:52224
	ds_read_b128 v[176:179], v220 offset:53248
	ds_read_b128 v[180:183], v220 offset:54272
	ds_read_b128 v[184:187], v220 offset:55296
	ds_read_b128 v[222:225], v220 offset:56320
	global_load_lds_dwordx4 v[204:205], off
	s_add_i32 m0, s4, 0x2000
	s_add_u32 s10, s40, 0x160080
	v_lshl_add_u64 v[204:205], v[218:219], 0, s[22:23]
	s_addc_u32 s11, s41, 0
	s_add_i32 s4, s5, s29
	global_load_lds_dwordx4 v[204:205], off
	v_lshl_add_u64 v[204:205], s[10:11], 0, v[190:191]
	s_mov_b32 m0, s4
	s_nop 0
	global_load_lds_dwordx4 v[204:205], off
	v_lshl_add_u64 v[204:205], s[10:11], 0, v[212:213]
	s_add_i32 m0, s4, 0x2000
	s_nop 0
	global_load_lds_dwordx4 v[204:205], off
	v_lshl_add_u64 v[204:205], v[226:227], 0, s[22:23]
	s_mov_b32 m0, s61
	s_nop 0
	global_load_lds_dwordx4 v[204:205], off
	v_lshl_add_u64 v[204:205], v[228:229], 0, s[22:23]
	s_mov_b32 m0, s62
	s_nop 0
	global_load_lds_dwordx4 v[204:205], off
	s_waitcnt vmcnt(8)
	s_waitcnt lgkmcnt(0)
	s_setprio 1
	s_barrier
; #define PG8_MMA(ai, bj, At, Bt) do { __builtin_amdgcn_s_setprio(1); _Pragma("unroll") for (int m = 0; m < 4; ++m) _Pragma("unroll") for (int n = 0; n < 2; ++n) _Pragma("unroll") for (int k = 0; k < 2; ++k) \
;         acc[ai][bj][m][n] = __builtin_amdgcn_mfma_f32_16x16x32_bf16(Bt[n][k], At[m][k], acc[ai][bj][m][n], 0, 0, 0); __builtin_amdgcn_s_setprio(0); } while (0)
; #define PG8_WAIT_V(n) asm volatile("s_waitcnt vmcnt(" #n ")" ::: "memory")
; #define PG8_WAIT_L(n) asm volatile("s_waitcnt lgkmcnt(" #n ")" ::: "memory")
; #define PG8_BAR __builtin_amdgcn_s_barrier()
; #define PG8_SCHED __builtin_amdgcn_sched_barrier(0)
; template <class Epi>
; __device__ __forceinline__ void gemm_phase(PG8_LAS unsigned char* lds, PG8_LAS unsigned char* xl, const Gemm g, const Sched& S, const Epi& E, const int wid) {
;     ...
;             PG8_WAIT_V(8); PG8_WAIT_L(0); PG8_BAR; if (do1) { PG8_MMA(1, 0, At, B0); PG8_MMA(1, 1, At, B1); } PG8_BAR; PG8_SCHED;
;         }
;         if (wr == 0) PG8_BAR;
	v_mfma_f32_16x16x32_bf16 v[60:63], v[120:123], v[160:163], v[60:63]
	v_mfma_f32_16x16x32_bf16 v[56:59], v[128:131], v[160:163], v[56:59]
	v_mfma_f32_16x16x32_bf16 v[44:47], v[120:123], v[168:171], v[44:47]
	v_mfma_f32_16x16x32_bf16 v[40:43], v[128:131], v[168:171], v[40:43]
	v_mfma_f32_16x16x32_bf16 v[28:31], v[120:123], v[176:179], v[28:31]
	v_mfma_f32_16x16x32_bf16 v[24:27], v[128:131], v[176:179], v[24:27]
	v_mfma_f32_16x16x32_bf16 v[12:15], v[120:123], v[184:187], v[12:15]
	v_mfma_f32_16x16x32_bf16 v[8:11], v[128:131], v[184:187], v[8:11]
	v_mfma_f32_16x16x32_bf16 v[60:63], v[124:127], v[164:167], v[60:63]
	v_mfma_f32_16x16x32_bf16 v[56:59], v[136:139], v[164:167], v[56:59]
	v_mfma_f32_16x16x32_bf16 v[44:47], v[124:127], v[172:175], v[44:47]
	v_mfma_f32_16x16x32_bf16 v[40:43], v[136:139], v[172:175], v[40:43]
	v_mfma_f32_16x16x32_bf16 v[28:31], v[124:127], v[180:183], v[28:31]
	v_mfma_f32_16x16x32_bf16 v[24:27], v[136:139], v[180:183], v[24:27]
	v_mfma_f32_16x16x32_bf16 v[12:15], v[124:127], v[222:225], v[12:15]
	v_mfma_f32_16x16x32_bf16 v[8:11], v[136:139], v[222:225], v[8:11]
	s_setprio 0
	s_setprio 1
	v_mfma_f32_16x16x32_bf16 v[52:55], v[144:147], v[160:163], v[52:55]
	v_mfma_f32_16x16x32_bf16 v[48:51], v[152:155], v[160:163], v[48:51]
	v_mfma_f32_16x16x32_bf16 v[36:39], v[144:147], v[168:171], v[36:39]
	v_mfma_f32_16x16x32_bf16 v[32:35], v[152:155], v[168:171], v[32:35]
	v_mfma_f32_16x16x32_bf16 v[20:23], v[144:147], v[176:179], v[20:23]
	v_mfma_f32_16x16x32_bf16 v[16:19], v[152:155], v[176:179], v[16:19]
	v_mfma_f32_16x16x32_bf16 v[4:7], v[144:147], v[184:187], v[4:7]
	v_mfma_f32_16x16x32_bf16 v[0:3], v[152:155], v[184:187], v[0:3]
	v_mfma_f32_16x16x32_bf16 v[52:55], v[148:151], v[164:167], v[52:55]
	v_mfma_f32_16x16x32_bf16 v[48:51], v[156:159], v[164:167], v[48:51]
	v_mfma_f32_16x16x32_bf16 v[36:39], v[148:151], v[172:175], v[36:39]
	v_mfma_f32_16x16x32_bf16 v[32:35], v[156:159], v[172:175], v[32:35]
	v_mfma_f32_16x16x32_bf16 v[20:23], v[148:151], v[180:183], v[20:23]
	v_mfma_f32_16x16x32_bf16 v[16:19], v[156:159], v[180:183], v[16:19]
	v_mfma_f32_16x16x32_bf16 v[4:7], v[148:151], v[222:225], v[4:7]
	v_mfma_f32_16x16x32_bf16 v[0:3], v[156:159], v[222:225], v[0:3]
	s_barrier
	s_setprio 0
	s_add_i32 s9, s9, 2
	s_add_u32 s36, s36, 0x100
	s_addc_u32 s37, s37, 0
	s_add_u32 s1, s1, 0x100
	s_addc_u32 s8, s8, 0
	s_cmpk_gt_u32 s9, 0x55
	s_cbranch_scc0 .LBB0_1304
	s_and_b64 vcc, exec, s[14:15]
	s_cbranch_vccz .LBB0_1307
	s_barrier
; __device__ __forceinline__ float shx(float v, int mask, int lane) { return __int_as_float(__builtin_amdgcn_ds_bpermute((lane ^ mask) << 2, __float_as_int(v))); }
; #define PACK8(w, v0, v1) do { w.x = cvt_pk_bf16(v0[0], v0[1]); w.y = cvt_pk_bf16(v0[2], v0[3]); w.z = cvt_pk_bf16(v1[0], v1[1]); w.w = cvt_pk_bf16(v1[2], v1[3]); } while (0)
; #define ADD8(v0, v1, g) do { v0[0] += bf_lo(g.x); v0[1] += bf_hi(g.x); v0[2] += bf_lo(g.y); v0[3] += bf_hi(g.y); v1[0] += bf_lo(g.z); v1[1] += bf_hi(g.z); v1[2] += bf_lo(g.w); v1[3] += bf_hi(g.w); } while (0)
;     __device__ __forceinline__ void operator()(EPI_ARGS) const {
;     ...
;         u32x4 xq[2][4][2];
; #pragma unroll
;         for (int ai = 0; ai < 2; ++ai)
; #pragma unroll
;             for (int m = 0; m < 4; ++m)
; #pragma unroll
;                 for (int bj = 0; bj < 2; ++bj) xq[ai][m][bj] = *(const u32x4*)(ub + (size_t)(ai * HALF + m) * ldc * 2 + lo + bj * 256);
;         asm volatile("" ::: "memory");
; #pragma unroll
;         for (int ai = 0; ai < 2; ++ai)
; #pragma unroll
;             for (int m = 0; m < 4; ++m) { float ss = 0.f;
; #pragma unroll
;                 for (int bj = 0; bj < 2; ++bj) { f32x4 v0 = acc[ai][bj][m][0], v1 = acc[ai][bj][m][1];
;                     ADD8(v0, v1, xq[ai][m][bj]);
;                     u32x4 w; PACK8(w, v0, v1); *(u32x4*)(ub + (size_t)(ai * HALF + m) * ldc * 2 + lo + bj * 256) = w;
;                     ss += (v0[0] * v0[0] + v0[1] * v0[1]) + (v0[2] * v0[2] + v0[3] * v0[3]) + (v1[0] * v1[0] + v1[1] * v1[1]) + (v1[2] * v1[2] + v1[3] * v1[3]); }
;                 ss += shx(ss, 16, ln); ss += shx(ss, 32, ln); if (fq == 0) XS[(ai * HALF + wr * 64 + 4 * fr + m) * 4 + wc] = ss; }
.LBB0_1307:
	s_ashr_i32 s13, s12, 31
	s_lshl_b64 s[8:9], s[12:13], 20
	s_add_u32 s1, s57, s8
	s_addc_u32 s4, s58, s9
	s_lshl_b32 s8, s0, 8
	v_mbcnt_lo_u32_b32 v221, -1, 0
	v_mbcnt_hi_u32_b32 v221, -1, v221
	s_ashr_i32 s9, s8, 31
	v_lshlrev_b32_e32 v204, 2, v221
	s_lshl_b64 s[8:9], s[8:9], 1
	v_and_or_b32 v205, v204, 60, s3
	s_add_u32 s36, s1, s8
	v_and_b32_e32 v120, -16, v221
	v_lshlrev_b32_e32 v121, 12, v205
	s_addc_u32 s37, s4, s9
	v_add3_u32 v192, v120, s75, v121
	global_load_dwordx4 v[224:227], v192, s[36:37]
	global_load_dwordx4 v[184:187], v192, s[36:37] offset:256
	v_lshl_add_u64 v[218:219], s[36:37], 0, v[192:193]
	v_add_co_u32_e32 v120, vcc, s25, v218
	s_mov_b32 s1, 0x80000
	s_nop 0
	v_addc_co_u32_e32 v121, vcc, 0, v219, vcc
	v_add_co_u32_e32 v122, vcc, s78, v218
	v_xor_b32_e32 v223, 64, v204
	s_nop 0
	v_addc_co_u32_e32 v123, vcc, 0, v219, vcc
	global_load_dwordx4 v[180:183], v[122:123], off offset:-4096
	global_load_dwordx4 v[176:179], v[120:121], off offset:256
	global_load_dwordx4 v[172:175], v[122:123], off
	global_load_dwordx4 v[168:171], v[122:123], off offset:256
	v_add_co_u32_e32 v120, vcc, s79, v218
	v_xor_b32_e32 v222, 0x80, v204
	s_nop 0
	v_addc_co_u32_e32 v121, vcc, 0, v219, vcc
	global_load_dwordx4 v[164:167], v[120:121], off
	global_load_dwordx4 v[160:163], v[120:121], off offset:256
	v_add_co_u32_e32 v120, vcc, s1, v218
	s_mov_b32 s1, 0x82000
	s_nop 0
	v_addc_co_u32_e32 v121, vcc, 0, v219, vcc
	v_add_co_u32_e32 v122, vcc, s95, v218
	s_nop 1
	v_addc_co_u32_e32 v123, vcc, 0, v219, vcc
	global_load_dwordx4 v[156:159], v[122:123], off offset:-4096
	global_load_dwordx4 v[152:155], v[120:121], off offset:256
	global_load_dwordx4 v[148:151], v[122:123], off
	global_load_dwordx4 v[136:139], v[122:123], off offset:256
	v_add_co_u32_e32 v120, vcc, s1, v218
	s_mov_b32 s1, 0x83000
	s_nop 0
	v_addc_co_u32_e32 v121, vcc, 0, v219, vcc
	v_add_co_u32_e32 v122, vcc, s1, v218
	s_nop 0
	s_nop 0
	v_addc_co_u32_e32 v123, vcc, 0, v219, vcc
	global_load_dwordx4 v[144:147], v[122:123], off offset:-4096
	global_load_dwordx4 v[128:131], v[120:121], off offset:256
	global_load_dwordx4 v[124:127], v[122:123], off
	s_nop 0
	global_load_dwordx4 v[120:123], v[122:123], off offset:256
	s_waitcnt vmcnt(8)
	v_lshlrev_b32_e32 v204, 16, v224
	v_add_f32_e32 v140, v140, v204
	v_and_b32_e32 v204, 0xffff0000, v224
	v_add_f32_e32 v141, v141, v204
	v_lshlrev_b32_e32 v204, 16, v225
	v_add_f32_e32 v142, v142, v204
	v_and_b32_e32 v204, 0xffff0000, v225
	v_add_f32_e32 v143, v143, v204
	v_lshlrev_b32_e32 v204, 16, v226
	v_add_f32_e32 v204, v132, v204
	v_and_b32_e32 v132, 0xffff0000, v226
	v_add_f32_e32 v224, v133, v132
	v_lshlrev_b32_e32 v132, 16, v227
	v_add_f32_e32 v225, v134, v132
	v_and_b32_e32 v132, 0xffff0000, v227
	v_add_f32_e32 v226, v135, v132
	v_cvt_pk_bf16_f32 v132, v140, v141
	v_cvt_pk_bf16_f32 v133, v142, v143
	v_cvt_pk_bf16_f32 v134, v204, v224
	v_cvt_pk_bf16_f32 v135, v225, v226
	global_store_dwordx4 v192, v[132:135], s[36:37]
	v_cmp_gt_u32_e32 vcc, 16, v221
	s_nop 0
	v_mul_f32_e32 v132, v141, v141
	v_mul_f32_e32 v133, v143, v143
	v_fmac_f32_e32 v132, v140, v140
	v_fmac_f32_e32 v133, v142, v142
	v_add_f32_e32 v132, v132, v133
	v_mul_f32_e32 v133, v224, v224
	v_fmac_f32_e32 v133, v204, v204
	v_add_f32_e32 v132, v133, v132
	v_mul_f32_e32 v133, v226, v226
	v_fmac_f32_e32 v133, v225, v225
	v_add_f32_e32 v132, v133, v132
	v_lshlrev_b32_e32 v133, 16, v184
	v_add_f32_e32 v116, v116, v133
	v_and_b32_e32 v133, 0xffff0000, v184
	v_add_f32_e32 v117, v117, v133
	v_lshlrev_b32_e32 v133, 16, v185
	v_add_f32_e32 v118, v118, v133
	v_and_b32_e32 v133, 0xffff0000, v185
	v_add_f32_e32 v119, v119, v133
	v_lshlrev_b32_e32 v133, 16, v186
	v_add_f32_e32 v133, v112, v133
	v_and_b32_e32 v112, 0xffff0000, v186
	v_add_f32_e32 v134, v113, v112
	v_lshlrev_b32_e32 v112, 16, v187
	v_add_f32_e32 v135, v114, v112
	v_and_b32_e32 v112, 0xffff0000, v187
	v_add_f32_e32 v140, v115, v112
	v_cvt_pk_bf16_f32 v112, v116, v117
	v_cvt_pk_bf16_f32 v113, v118, v119
	v_cvt_pk_bf16_f32 v114, v133, v134
	v_cvt_pk_bf16_f32 v115, v135, v140
	global_store_dwordx4 v192, v[112:115], s[36:37] offset:256
	s_nop 1
	v_mul_f32_e32 v112, v117, v117
	v_mul_f32_e32 v113, v119, v119
	v_fmac_f32_e32 v112, v116, v116
	v_fmac_f32_e32 v113, v118, v118
	v_add_f32_e32 v112, v112, v113
	v_mul_f32_e32 v113, v134, v134
	v_fmac_f32_e32 v113, v133, v133
	v_add_f32_e32 v112, v113, v112
	v_mul_f32_e32 v113, v140, v140
	v_fmac_f32_e32 v113, v135, v135
	v_add_f32_e32 v112, v113, v112
	v_add_f32_e32 v112, v132, v112
	ds_bpermute_b32 v113, v223, v112
	s_waitcnt lgkmcnt(0)
	v_add_f32_e32 v113, v112, v113
	ds_bpermute_b32 v114, v222, v113
	v_lshl_add_u32 v112, v205, 4, s64
	s_and_saveexec_b64 s[8:9], vcc
	s_cbranch_execz .LBB0_1309
	s_waitcnt lgkmcnt(0)
	v_add_f32_e32 v113, v113, v114
	ds_write_b32 v112, v113

; #define PG8_BAR __builtin_amdgcn_s_barrier()
; template <class Epi>
; __device__ __forceinline__ void gemm_phase(PG8_LAS unsigned char* lds, PG8_LAS unsigned char* xl, const Gemm g, const Sched& S, const Epi& E, const int wid) {
;     ...
;         if (!has_next) break;
; #pragma unroll
;         for (int a = 0; a < 2; ++a)
; #pragma unroll
;             for (int b = 0; b < 2; ++b)
; #pragma unroll
;                 for (int m = 0; m < 4; ++m)
; #pragma unroll
;                     for (int n = 0; n < 2; ++n) acc[a][b][m][n] = (f32x4){0.f, 0.f, 0.f, 0.f};
;         cur = nxt; cA = nA; cB = nB; ++ui;
;         if (wr == 1) PG8_BAR;
.LBB0_1325:
	s_or_b64 exec, exec, s[10:11]
	s_and_b64 vcc, exec, s[42:43]
	s_mov_b64 s[0:1], -1
	s_cbranch_vccnz .LBB0_1296
	s_and_b64 vcc, exec, s[38:39]
	s_cbranch_vccnz .LBB0_1295
	s_mov_b32 s100, 1
	s_branch .LBB0_1295

; __global__ void __launch_bounds__(512, 2) fwd_kernel(Args args) {
	.amdhsa_kernel _Z10fwd_kernel4Args
		.amdhsa_group_segment_fixed_size 0
		.amdhsa_private_segment_fixed_size 0
		.amdhsa_kernarg_size 480
		.amdhsa_user_sgpr_count 2
		.amdhsa_user_sgpr_dispatch_ptr 0
		.amdhsa_user_sgpr_queue_ptr 0
		.amdhsa_user_sgpr_kernarg_segment_ptr 1
		.amdhsa_user_sgpr_dispatch_id 0
		.amdhsa_user_sgpr_kernarg_preload_length 0
		.amdhsa_user_sgpr_kernarg_preload_offset 0
		.amdhsa_user_sgpr_private_segment_size 0
		.amdhsa_uses_dynamic_stack 0
		.amdhsa_enable_private_segment 0
		.amdhsa_system_sgpr_workgroup_id_x 1
		.amdhsa_system_sgpr_workgroup_id_y 0
		.amdhsa_system_sgpr_workgroup_id_z 0
		.amdhsa_system_sgpr_workgroup_info 0
		.amdhsa_system_vgpr_workitem_id 0
		.amdhsa_next_free_vgpr 255
		.amdhsa_next_free_sgpr 102
		.amdhsa_accum_offset 256
		.amdhsa_reserve_vcc 1
		.amdhsa_float_round_mode_32 0
		.amdhsa_float_round_mode_16_64 0
		.amdhsa_float_denorm_mode_32 3
		.amdhsa_float_denorm_mode_16_64 3
		.amdhsa_dx10_clamp 1
		.amdhsa_ieee_mode 1
		.amdhsa_fp16_overflow 0
		.amdhsa_tg_split 0
		.amdhsa_exception_fp_ieee_invalid_op 0
		.amdhsa_exception_fp_denorm_src 0
		.amdhsa_exception_fp_ieee_div_zero 0
		.amdhsa_exception_fp_ieee_overflow 0
		.amdhsa_exception_fp_ieee_underflow 0
		.amdhsa_exception_fp_ieee_inexact 0
		.amdhsa_exception_int_div_zero 0
	.end_amdhsa_kernel

; __global__ void __launch_bounds__(512, 2) fwd_kernel(Args args) {
amdhsa.kernels:
  - .agpr_count:     0
    .args:
      - .offset:         0
        .size:           224
        .value_kind:     by_value
      - .offset:         224
        .size:           4
        .value_kind:     hidden_block_count_x
      - .offset:         228
        .size:           4
        .value_kind:     hidden_block_count_y
      - .offset:         232
        .size:           4
        .value_kind:     hidden_block_count_z
      - .offset:         236
        .size:           2
        .value_kind:     hidden_group_size_x
      - .offset:         238
        .size:           2
        .value_kind:     hidden_group_size_y
      - .offset:         240
        .size:           2
        .value_kind:     hidden_group_size_z
      - .offset:         242
        .size:           2
        .value_kind:     hidden_remainder_x
      - .offset:         244
        .size:           2
        .value_kind:     hidden_remainder_y
      - .offset:         246
        .size:           2
        .value_kind:     hidden_remainder_z
      - .offset:         264
        .size:           8
        .value_kind:     hidden_global_offset_x
      - .offset:         272
        .size:           8
        .value_kind:     hidden_global_offset_y
      - .offset:         280
        .size:           8
        .value_kind:     hidden_global_offset_z
      - .offset:         288
        .size:           2
        .value_kind:     hidden_grid_dims
      - .offset:         344
        .size:           4
        .value_kind:     hidden_dynamic_lds_size
    .group_segment_fixed_size: 0
    .kernarg_segment_align: 8
    .kernarg_segment_size: 480
    .language:       OpenCL C
    .language_version:
      - 2
      - 0
    .max_flat_workgroup_size: 512
    .name:           _Z10fwd_kernel4Args
    .private_segment_fixed_size: 0
    .sgpr_count:     108
    .sgpr_spill_count: 190
    .symbol:         _Z10fwd_kernel4Args.kd
    .uniform_work_group_size: 1
    .uses_dynamic_stack: false
    .vgpr_count:     255
    .vgpr_spill_count: 0
    .wavefront_size: 64
